# K-loops: MFMAs within each group of 8 issued in snake order so that exactly one source fragment changes between consecutive MFMAs (same accumulation order per accumulator)
# speedup vs baseline: 1.0110x; 1.0012x over previous
; #define PG8_STAGEA(bufoff, gbase) PG8_STAGE_(bufoff, gbase, voffA)
; #define PG8_LDA(dst, b, h) do { _Pragma("unroll") for (int m = 0; m < 4; ++m) _Pragma("unroll") for (int k = 0; k < 2; ++k) dst[m][k] = *(const LAS bf16x8*)(lds + PG8_SA(b, h) + aoff + m * 2048 + k * 1024); } while (0)
; #define PG8_LDB(dst, b, h) do { _Pragma("unroll") for (int n = 0; n < 2; ++n) _Pragma("unroll") for (int k = 0; k < 2; ++k) dst[n][k] = *(const LAS bf16x8*)(lds + PG8_SB(b, h) + boff + n * 2048 + k * 1024); } while (0)
; #define PG8_MMA(ai, bj, At, Bt_) do { __builtin_amdgcn_s_setprio(1); _Pragma("unroll") for (int m = 0; m < 4; ++m) _Pragma("unroll") for (int n = 0; n < 2; ++n) _Pragma("unroll") for (int k = 0; k < 2; ++k) \
;         acc[ai][bj][m][n] = __builtin_amdgcn_mfma_f32_16x16x32_bf16(Bt_[n][k], At[m][k], acc[ai][bj][m][n], 0, 0, 0); __builtin_amdgcn_s_setprio(0); } while (0)
; #define PG8_WAIT_V(n) asm volatile("s_waitcnt vmcnt(" #n ")" ::: "memory")
; #define PG8_WAIT_L(n) asm volatile("s_waitcnt lgkmcnt(" #n ")" ::: "memory")
; #define PG8_BAR __builtin_amdgcn_s_barrier()
; #define PG8_SCHED __builtin_amdgcn_sched_barrier(0)
; template <int EK, int SK = -1>
; __device__ __forceinline__ void gemm_phase(LAS unsigned char* lds, const bf16_t* A, const bf16_t* Bt, int nM, int N, int K, const EpiArgs& E) {
;     ...
;         const bool has_next = S.next(ui + 1, nxt);
;         const char* nA = has_next ? (const char*)A + (size_t)nxt.pm * tstep : cA; const char* nB = has_next ? (const char*)Bt + (size_t)nxt.pn * tstep : cB;
;         for (int t = 0; t < nt; t += 2) {
;             const bool last = (t == nt - 2);
;             const char* a1 = cA + (size_t)(t + 1) * kstep;
;             const char* a2 = last ? nA : cA + (size_t)(t + 2) * kstep; const char* b2 = last ? nB : cB + (size_t)(t + 2) * kstep;
;             const char* a3 = a2 + kstep; const char* b3 = b2 + kstep;
;             PG8_LDB(B0, 0, 0); PG8_LDB(B1, 0, 1); PG8_SCHED; PG8_LDA(At, 0, 0); PG8_STAGEA(PG8_SA(1, 1), a1 + hstep);
;             PG8_WAIT_V(8); PG8_WAIT_L(0); PG8_BAR; PG8_MMA(0, 0, At, B0); PG8_MMA(0, 1, At, B1); PG8_BAR; PG8_SCHED;
.LBB0_197:
	s_add_u32 s58, s78, 0x100
	s_addc_u32 s59, s79, 0
	s_ashr_i32 s75, s74, 31
	s_lshl_b64 s[76:77], s[74:75], 19
	s_add_u32 s80, s62, s76
	s_addc_u32 s81, s63, s77
	s_and_b64 s[76:77], s[6:7], exec
	s_cselect_b32 s75, s81, s71
	s_cselect_b32 s90, s80, s70
	s_ashr_i32 s73, s72, 31
	s_lshl_b64 s[76:77], s[72:73], 19
	s_add_u32 s76, s30, s76
	s_addc_u32 s77, s31, s77
	s_and_b64 s[82:83], s[6:7], exec
	s_cselect_b32 s73, s77, s79
	s_cselect_b32 s91, s76, s78
	v_lshl_add_u64 v[146:147], s[70:71], 0, v[138:139]
	v_lshl_add_u64 v[148:149], s[70:71], 0, v[140:141]
	s_mov_b32 s92, -2
	s_mov_b64 s[78:79], 0
	v_add_u32_e32 v150, s54, v152
	ds_read_b128 v[156:159], v150
	ds_read_b128 v[160:163], v150 offset:1024
	ds_read_b128 v[164:167], v150 offset:2048
	ds_read_b128 v[168:171], v150 offset:3072
	v_add_u32_e32 v150, s55, v152
	s_add_u32 s82, s70, s78
	ds_read_b128 v[172:175], v150
	ds_read_b128 v[176:179], v150 offset:1024
	ds_read_b128 v[180:183], v150 offset:2048
	ds_read_b128 v[184:187], v150 offset:3072
	s_addc_u32 s83, s71, s79
	s_add_u32 s82, s82, 0x100
	s_addc_u32 s83, s83, 0
	s_add_u32 s93, s58, s78
	s_addc_u32 s94, s59, s79
	s_cmpk_eq_i32 s78, 0x700
	s_cselect_b32 s85, s75, s83
	s_cselect_b32 s84, s90, s82
	s_cselect_b32 s83, s73, s94
	s_cselect_b32 s82, s91, s93
	v_lshl_add_u64 v[150:151], v[146:147], 0, s[78:79]
	s_add_i32 m0, s67, 0xc000
	ds_read_b128 v[188:191], v155
	ds_read_b128 v[192:195], v155 offset:1024
	ds_read_b128 v[196:199], v155 offset:2048
	ds_read_b128 v[200:203], v155 offset:3072
	ds_read_b128 v[204:207], v155 offset:4096
	ds_read_b128 v[208:211], v155 offset:5120
	ds_read_b128 v[212:215], v155 offset:6144
	ds_read_b128 v[216:219], v155 offset:7168
	global_load_lds_dwordx4 v[150:151], off
	v_lshl_add_u64 v[150:151], v[148:149], 0, s[78:79]
	s_add_i32 m0, s67, 0xe000
	s_nop 0
	global_load_lds_dwordx4 v[150:151], off
	s_waitcnt vmcnt(8)
	s_waitcnt lgkmcnt(0)
	s_barrier
	s_waitcnt lgkmcnt(0)
	v_mfma_f32_16x16x32_bf16 v[110:113], v[156:159], v[188:191], 0
	v_mfma_f32_16x16x32_bf16 v[106:109], v[164:167], v[188:191], 0
	v_mfma_f32_16x16x32_bf16 v[98:101], v[164:167], v[196:199], 0
	v_mfma_f32_16x16x32_bf16 v[102:105], v[156:159], v[196:199], 0
	v_mfma_f32_16x16x32_bf16 v[94:97], v[156:159], v[204:207], 0
	v_mfma_f32_16x16x32_bf16 v[90:93], v[164:167], v[204:207], 0
	v_mfma_f32_16x16x32_bf16 v[82:85], v[164:167], v[212:215], 0
	v_mfma_f32_16x16x32_bf16 v[86:89], v[156:159], v[212:215], 0
	v_mfma_f32_16x16x32_bf16 v[110:113], v[160:163], v[192:195], v[110:113]
	v_mfma_f32_16x16x32_bf16 v[106:109], v[168:171], v[192:195], v[106:109]
	v_mfma_f32_16x16x32_bf16 v[98:101], v[168:171], v[200:203], v[98:101]
	v_mfma_f32_16x16x32_bf16 v[102:105], v[160:163], v[200:203], v[102:105]
	v_mfma_f32_16x16x32_bf16 v[94:97], v[160:163], v[208:211], v[94:97]
	v_mfma_f32_16x16x32_bf16 v[90:93], v[168:171], v[208:211], v[90:93]
	v_mfma_f32_16x16x32_bf16 v[82:85], v[168:171], v[216:219], v[82:85]
	v_mfma_f32_16x16x32_bf16 v[86:89], v[160:163], v[216:219], v[86:89]
	v_mfma_f32_16x16x32_bf16 v[78:81], v[172:175], v[188:191], 0
	v_mfma_f32_16x16x32_bf16 v[74:77], v[180:183], v[188:191], 0
	v_mfma_f32_16x16x32_bf16 v[66:69], v[180:183], v[196:199], 0
	v_mfma_f32_16x16x32_bf16 v[70:73], v[172:175], v[196:199], 0
	v_mfma_f32_16x16x32_bf16 v[62:65], v[172:175], v[204:207], 0
	v_mfma_f32_16x16x32_bf16 v[58:61], v[180:183], v[204:207], 0
	v_mfma_f32_16x16x32_bf16 v[50:53], v[180:183], v[212:215], 0
	v_mfma_f32_16x16x32_bf16 v[54:57], v[172:175], v[212:215], 0
	v_mfma_f32_16x16x32_bf16 v[78:81], v[176:179], v[192:195], v[78:81]
	v_mfma_f32_16x16x32_bf16 v[74:77], v[184:187], v[192:195], v[74:77]
	v_mfma_f32_16x16x32_bf16 v[66:69], v[184:187], v[200:203], v[66:69]
	v_mfma_f32_16x16x32_bf16 v[70:73], v[176:179], v[200:203], v[70:73]
	v_mfma_f32_16x16x32_bf16 v[62:65], v[176:179], v[208:211], v[62:65]
	v_mfma_f32_16x16x32_bf16 v[58:61], v[184:187], v[208:211], v[58:61]
	v_mfma_f32_16x16x32_bf16 v[50:53], v[184:187], v[216:219], v[50:53]
	v_mfma_f32_16x16x32_bf16 v[54:57], v[176:179], v[216:219], v[54:57]
	s_barrier
	s_add_i32 s93, s54, s87
	v_lshl_add_u64 v[150:151], s[82:83], 0, v[132:133]
	s_mov_b32 m0, s93
	ds_read_b128 v[188:191], v155 offset:16384
	ds_read_b128 v[192:195], v155 offset:17408
	ds_read_b128 v[196:199], v155 offset:18432
	ds_read_b128 v[200:203], v155 offset:19456
	ds_read_b128 v[204:207], v155 offset:20480
	ds_read_b128 v[208:211], v155 offset:21504
	ds_read_b128 v[212:215], v155 offset:22528
	ds_read_b128 v[216:219], v155 offset:23552
	global_load_lds_dwordx4 v[150:151], off
	s_add_i32 m0, s93, 0x2000
	s_add_u32 s94, s82, 0x40000
	v_lshl_add_u64 v[220:221], s[82:83], 0, v[136:137]
	s_addc_u32 s95, s83, 0
	s_add_i32 s93, s55, s87
	global_load_lds_dwordx4 v[220:221], off
	v_lshl_add_u64 v[222:223], s[94:95], 0, v[132:133]
	s_mov_b32 m0, s93
	v_lshl_add_u64 v[224:225], s[84:85], 0, v[134:135]
	global_load_lds_dwordx4 v[222:223], off
	v_lshl_add_u64 v[222:223], s[94:95], 0, v[136:137]
	s_add_i32 m0, s93, 0x2000
	s_nop 0
	global_load_lds_dwordx4 v[222:223], off
	v_lshl_add_u64 v[222:223], s[84:85], 0, v[130:131]
	s_mov_b32 m0, s67
	s_nop 0
	global_load_lds_dwordx4 v[222:223], off
	s_mov_b32 m0, s69
	s_nop 0
	global_load_lds_dwordx4 v[224:225], off
	s_waitcnt vmcnt(8)
	s_waitcnt lgkmcnt(0)
	s_barrier
; #define PG8_STAGEA(bufoff, gbase) PG8_STAGE_(bufoff, gbase, voffA)
; #define PG8_STAGEB(bufoff, gbase) PG8_STAGE_(bufoff, gbase, voffB)
; #define PG8_LDA(dst, b, h) do { _Pragma("unroll") for (int m = 0; m < 4; ++m) _Pragma("unroll") for (int k = 0; k < 2; ++k) dst[m][k] = *(const LAS bf16x8*)(lds + PG8_SA(b, h) + aoff + m * 2048 + k * 1024); } while (0)
; #define PG8_LDB(dst, b, h) do { _Pragma("unroll") for (int n = 0; n < 2; ++n) _Pragma("unroll") for (int k = 0; k < 2; ++k) dst[n][k] = *(const LAS bf16x8*)(lds + PG8_SB(b, h) + boff + n * 2048 + k * 1024); } while (0)
; #define PG8_MMA(ai, bj, At, Bt_) do { __builtin_amdgcn_s_setprio(1); _Pragma("unroll") for (int m = 0; m < 4; ++m) _Pragma("unroll") for (int n = 0; n < 2; ++n) _Pragma("unroll") for (int k = 0; k < 2; ++k) \
;         acc[ai][bj][m][n] = __builtin_amdgcn_mfma_f32_16x16x32_bf16(Bt_[n][k], At[m][k], acc[ai][bj][m][n], 0, 0, 0); __builtin_amdgcn_s_setprio(0); } while (0)
; #define PG8_WAIT_V(n) asm volatile("s_waitcnt vmcnt(" #n ")" ::: "memory")
; #define PG8_WAIT_L(n) asm volatile("s_waitcnt lgkmcnt(" #n ")" ::: "memory")
; #define PG8_BAR __builtin_amdgcn_s_barrier()
; #define PG8_SCHED __builtin_amdgcn_sched_barrier(0)
; template <int EK, int SK = -1>
; __device__ __forceinline__ void gemm_phase(LAS unsigned char* lds, const bf16_t* A, const bf16_t* Bt, int nM, int N, int K, const EpiArgs& E) {
;     ...
;             PG8_WAIT_V(8); PG8_WAIT_L(0); PG8_BAR; PG8_MMA(0, 0, At, B0); PG8_MMA(0, 1, At, B1); PG8_BAR; PG8_SCHED;
;             PG8_LDA(At, 0, 1); PG8_STAGEB(PG8_SB(0, 0), b2); PG8_STAGEB(PG8_SB(0, 1), b2 + hstep); PG8_STAGEA(PG8_SA(0, 0), a2);
;             PG8_WAIT_V(8); PG8_WAIT_L(0); PG8_BAR; PG8_MMA(1, 0, At, B0); PG8_MMA(1, 1, At, B1); PG8_BAR; PG8_SCHED;
;             PG8_LDB(B0, 1, 0); PG8_LDB(B1, 1, 1); PG8_SCHED; PG8_LDA(At, 1, 0); PG8_STAGEA(PG8_SA(0, 1), a2 + hstep);
;             PG8_WAIT_V(8); PG8_WAIT_L(0); PG8_BAR; PG8_MMA(0, 0, At, B0); PG8_MMA(0, 1, At, B1); PG8_BAR; PG8_SCHED;
	s_waitcnt lgkmcnt(0)
	v_mfma_f32_16x16x32_bf16 v[46:49], v[156:159], v[188:191], 0
	v_mfma_f32_16x16x32_bf16 v[42:45], v[164:167], v[188:191], 0
	v_mfma_f32_16x16x32_bf16 v[34:37], v[164:167], v[196:199], 0
	v_mfma_f32_16x16x32_bf16 v[38:41], v[156:159], v[196:199], 0
	v_mfma_f32_16x16x32_bf16 v[30:33], v[156:159], v[204:207], 0
	v_mfma_f32_16x16x32_bf16 v[26:29], v[164:167], v[204:207], 0
	v_mfma_f32_16x16x32_bf16 v[18:21], v[164:167], v[212:215], 0
	v_mfma_f32_16x16x32_bf16 v[22:25], v[156:159], v[212:215], 0
	v_mfma_f32_16x16x32_bf16 v[46:49], v[160:163], v[192:195], v[46:49]
	v_mfma_f32_16x16x32_bf16 v[42:45], v[168:171], v[192:195], v[42:45]
	v_mfma_f32_16x16x32_bf16 v[34:37], v[168:171], v[200:203], v[34:37]
	v_mfma_f32_16x16x32_bf16 v[38:41], v[160:163], v[200:203], v[38:41]
	v_mfma_f32_16x16x32_bf16 v[30:33], v[160:163], v[208:211], v[30:33]
	v_mfma_f32_16x16x32_bf16 v[26:29], v[168:171], v[208:211], v[26:29]
	v_mfma_f32_16x16x32_bf16 v[18:21], v[168:171], v[216:219], v[18:21]
	v_mfma_f32_16x16x32_bf16 v[22:25], v[160:163], v[216:219], v[22:25]
	v_mfma_f32_16x16x32_bf16 v[14:17], v[172:175], v[188:191], 0
	v_mfma_f32_16x16x32_bf16 v[10:13], v[180:183], v[188:191], 0
	v_mfma_f32_16x16x32_bf16 v[2:5], v[180:183], v[196:199], 0
	v_mfma_f32_16x16x32_bf16 v[6:9], v[172:175], v[196:199], 0
	v_mfma_f32_16x16x32_bf16 v[114:117], v[172:175], v[204:207], 0
	v_mfma_f32_16x16x32_bf16 v[118:121], v[180:183], v[204:207], 0
	v_mfma_f32_16x16x32_bf16 v[126:129], v[180:183], v[212:215], 0
	v_mfma_f32_16x16x32_bf16 v[122:125], v[172:175], v[212:215], 0
	v_mfma_f32_16x16x32_bf16 v[14:17], v[176:179], v[192:195], v[14:17]
	v_mfma_f32_16x16x32_bf16 v[10:13], v[184:187], v[192:195], v[10:13]
	v_mfma_f32_16x16x32_bf16 v[2:5], v[184:187], v[200:203], v[2:5]
	v_mfma_f32_16x16x32_bf16 v[6:9], v[176:179], v[200:203], v[6:9]
	v_mfma_f32_16x16x32_bf16 v[114:117], v[176:179], v[208:211], v[114:117]
	v_mfma_f32_16x16x32_bf16 v[118:121], v[184:187], v[208:211], v[118:121]
	v_mfma_f32_16x16x32_bf16 v[126:129], v[184:187], v[216:219], v[126:129]
	v_mfma_f32_16x16x32_bf16 v[122:125], v[176:179], v[216:219], v[122:125]
	s_barrier
	s_add_i32 s93, 0, 0x18000
	s_add_i32 s94, 0, 0x1c000
	v_add_u32_e32 v168, s93, v152
	v_add_u32_e32 v184, s94, v152
	ds_read_b128 v[156:159], v168
	ds_read_b128 v[160:163], v168 offset:1024
	ds_read_b128 v[164:167], v168 offset:2048
	ds_read_b128 v[168:171], v168 offset:3072
	ds_read_b128 v[172:175], v184
	ds_read_b128 v[176:179], v184 offset:1024
	ds_read_b128 v[180:183], v184 offset:2048
	ds_read_b128 v[184:187], v184 offset:3072
	s_add_u32 s84, s84, 0x40000
	s_addc_u32 s85, s85, 0
	s_mov_b32 m0, s88
	v_lshl_add_u64 v[226:227], s[84:85], 0, v[130:131]
	ds_read_b128 v[188:191], v155 offset:32768
	ds_read_b128 v[192:195], v155 offset:33792
	ds_read_b128 v[196:199], v155 offset:34816
	ds_read_b128 v[200:203], v155 offset:35840
	ds_read_b128 v[204:207], v155 offset:36864
	ds_read_b128 v[208:211], v155 offset:37888
	ds_read_b128 v[212:215], v155 offset:38912
	ds_read_b128 v[216:219], v155 offset:39936
	global_load_lds_dwordx4 v[226:227], off
	v_lshl_add_u64 v[226:227], s[84:85], 0, v[134:135]
	s_mov_b32 m0, s89
	s_nop 0
	global_load_lds_dwordx4 v[226:227], off
	s_waitcnt vmcnt(8)
	s_waitcnt lgkmcnt(0)
	s_barrier
	s_waitcnt lgkmcnt(0)
	v_mfma_f32_16x16x32_bf16 v[110:113], v[156:159], v[188:191], v[110:113]
	v_mfma_f32_16x16x32_bf16 v[106:109], v[164:167], v[188:191], v[106:109]
	v_mfma_f32_16x16x32_bf16 v[98:101], v[164:167], v[196:199], v[98:101]
	v_mfma_f32_16x16x32_bf16 v[102:105], v[156:159], v[196:199], v[102:105]
	v_mfma_f32_16x16x32_bf16 v[94:97], v[156:159], v[204:207], v[94:97]
	v_mfma_f32_16x16x32_bf16 v[90:93], v[164:167], v[204:207], v[90:93]
	v_mfma_f32_16x16x32_bf16 v[82:85], v[164:167], v[212:215], v[82:85]
	v_mfma_f32_16x16x32_bf16 v[86:89], v[156:159], v[212:215], v[86:89]
	v_mfma_f32_16x16x32_bf16 v[110:113], v[160:163], v[192:195], v[110:113]
	v_mfma_f32_16x16x32_bf16 v[106:109], v[168:171], v[192:195], v[106:109]
	v_mfma_f32_16x16x32_bf16 v[98:101], v[168:171], v[200:203], v[98:101]
	v_mfma_f32_16x16x32_bf16 v[102:105], v[160:163], v[200:203], v[102:105]
	v_mfma_f32_16x16x32_bf16 v[94:97], v[160:163], v[208:211], v[94:97]
	v_mfma_f32_16x16x32_bf16 v[90:93], v[168:171], v[208:211], v[90:93]
	v_mfma_f32_16x16x32_bf16 v[82:85], v[168:171], v[216:219], v[82:85]
	v_mfma_f32_16x16x32_bf16 v[86:89], v[160:163], v[216:219], v[86:89]
	v_mfma_f32_16x16x32_bf16 v[78:81], v[172:175], v[188:191], v[78:81]
	v_mfma_f32_16x16x32_bf16 v[74:77], v[180:183], v[188:191], v[74:77]
	v_mfma_f32_16x16x32_bf16 v[66:69], v[180:183], v[196:199], v[66:69]
	v_mfma_f32_16x16x32_bf16 v[70:73], v[172:175], v[196:199], v[70:73]
	v_mfma_f32_16x16x32_bf16 v[62:65], v[172:175], v[204:207], v[62:65]
	v_mfma_f32_16x16x32_bf16 v[58:61], v[180:183], v[204:207], v[58:61]
	v_mfma_f32_16x16x32_bf16 v[50:53], v[180:183], v[212:215], v[50:53]
	v_mfma_f32_16x16x32_bf16 v[54:57], v[172:175], v[212:215], v[54:57]
	v_mfma_f32_16x16x32_bf16 v[78:81], v[176:179], v[192:195], v[78:81]
	v_mfma_f32_16x16x32_bf16 v[74:77], v[184:187], v[192:195], v[74:77]
	v_mfma_f32_16x16x32_bf16 v[66:69], v[184:187], v[200:203], v[66:69]
	v_mfma_f32_16x16x32_bf16 v[70:73], v[176:179], v[200:203], v[70:73]
	v_mfma_f32_16x16x32_bf16 v[62:65], v[176:179], v[208:211], v[62:65]
	v_mfma_f32_16x16x32_bf16 v[58:61], v[184:187], v[208:211], v[58:61]
	v_mfma_f32_16x16x32_bf16 v[50:53], v[184:187], v[216:219], v[50:53]
	v_mfma_f32_16x16x32_bf16 v[54:57], v[176:179], v[216:219], v[54:57]
	s_barrier
; #define PG8_STAGEA(bufoff, gbase) PG8_STAGE_(bufoff, gbase, voffA)
; #define PG8_STAGEB(bufoff, gbase) PG8_STAGE_(bufoff, gbase, voffB)
; #define PG8_LDA(dst, b, h) do { _Pragma("unroll") for (int m = 0; m < 4; ++m) _Pragma("unroll") for (int k = 0; k < 2; ++k) dst[m][k] = *(const LAS bf16x8*)(lds + PG8_SA(b, h) + aoff + m * 2048 + k * 1024); } while (0)
; #define PG8_LDB(dst, b, h) do { _Pragma("unroll") for (int n = 0; n < 2; ++n) _Pragma("unroll") for (int k = 0; k < 2; ++k) dst[n][k] = *(const LAS bf16x8*)(lds + PG8_SB(b, h) + boff + n * 2048 + k * 1024); } while (0)
; #define PG8_MMA(ai, bj, At, Bt_) do { __builtin_amdgcn_s_setprio(1); _Pragma("unroll") for (int m = 0; m < 4; ++m) _Pragma("unroll") for (int n = 0; n < 2; ++n) _Pragma("unroll") for (int k = 0; k < 2; ++k) \
;         acc[ai][bj][m][n] = __builtin_amdgcn_mfma_f32_16x16x32_bf16(Bt_[n][k], At[m][k], acc[ai][bj][m][n], 0, 0, 0); __builtin_amdgcn_s_setprio(0); } while (0)
; #define PG8_WAIT_V(n) asm volatile("s_waitcnt vmcnt(" #n ")" ::: "memory")
; #define PG8_WAIT_L(n) asm volatile("s_waitcnt lgkmcnt(" #n ")" ::: "memory")
; #define PG8_BAR __builtin_amdgcn_s_barrier()
; #define PG8_SCHED __builtin_amdgcn_sched_barrier(0)
; template <int EK, int SK = -1>
; __device__ __forceinline__ void gemm_phase(LAS unsigned char* lds, const bf16_t* A, const bf16_t* Bt, int nM, int N, int K, const EpiArgs& E) {
;     ...
;             PG8_LDB(B0, 0, 0); PG8_LDB(B1, 0, 1); PG8_SCHED; PG8_LDA(At, 0, 0); PG8_STAGEA(PG8_SA(1, 1), a1 + hstep);
;             PG8_WAIT_V(8); PG8_WAIT_L(0); PG8_BAR; PG8_MMA(0, 0, At, B0); PG8_MMA(0, 1, At, B1); PG8_BAR; PG8_SCHED;
;             PG8_LDA(At, 0, 1); PG8_STAGEB(PG8_SB(0, 0), b2); PG8_STAGEB(PG8_SB(0, 1), b2 + hstep); PG8_STAGEA(PG8_SA(0, 0), a2);
;             PG8_WAIT_V(8); PG8_WAIT_L(0); PG8_BAR; PG8_MMA(1, 0, At, B0); PG8_MMA(1, 1, At, B1); PG8_BAR; PG8_SCHED;
;             PG8_LDB(B0, 1, 0); PG8_LDB(B1, 1, 1); PG8_SCHED; PG8_LDA(At, 1, 0); PG8_STAGEA(PG8_SA(0, 1), a2 + hstep);
;             PG8_WAIT_V(8); PG8_WAIT_L(0); PG8_BAR; PG8_MMA(0, 0, At, B0); PG8_MMA(0, 1, At, B1); PG8_BAR; PG8_SCHED;
;             PG8_LDA(At, 1, 1); PG8_STAGEB(PG8_SB(1, 0), b3); PG8_STAGEB(PG8_SB(1, 1), b3 + hstep); PG8_STAGEA(PG8_SA(1, 0), a3);
;             PG8_WAIT_V(8); PG8_WAIT_L(0); PG8_BAR; PG8_MMA(1, 0, At, B0); PG8_MMA(1, 1, At, B1); PG8_BAR; PG8_SCHED;
	s_add_i32 s84, s93, s87
	v_lshl_add_u64 v[150:151], v[150:151], 0, s[10:11]
	s_mov_b32 m0, s84
	ds_read_b128 v[188:191], v155 offset:49152
	ds_read_b128 v[192:195], v155 offset:50176
	ds_read_b128 v[196:199], v155 offset:51200
	ds_read_b128 v[200:203], v155 offset:52224
	ds_read_b128 v[204:207], v155 offset:53248
	ds_read_b128 v[208:211], v155 offset:54272
	ds_read_b128 v[212:215], v155 offset:55296
	ds_read_b128 v[216:219], v155 offset:56320
	global_load_lds_dwordx4 v[150:151], off
	s_add_i32 m0, s84, 0x2000
	s_add_u32 s82, s82, 0x40080
	v_lshl_add_u64 v[150:151], v[220:221], 0, s[10:11]
	s_addc_u32 s83, s83, 0
	s_add_i32 s84, s94, s87
	global_load_lds_dwordx4 v[150:151], off
	v_lshl_add_u64 v[150:151], s[82:83], 0, v[132:133]
	s_mov_b32 m0, s84
	s_nop 0
	global_load_lds_dwordx4 v[150:151], off
	v_lshl_add_u64 v[150:151], s[82:83], 0, v[136:137]
	s_add_i32 m0, s84, 0x2000
	s_nop 0
	global_load_lds_dwordx4 v[150:151], off
	v_lshl_add_u64 v[150:151], v[222:223], 0, s[10:11]
	s_mov_b32 m0, s52
	s_nop 0
	global_load_lds_dwordx4 v[150:151], off
	v_lshl_add_u64 v[150:151], v[224:225], 0, s[10:11]
	s_mov_b32 m0, s53
	s_nop 0
	global_load_lds_dwordx4 v[150:151], off
	s_waitcnt vmcnt(8)
	s_waitcnt lgkmcnt(0)
	s_barrier
	s_waitcnt lgkmcnt(0)
	v_mfma_f32_16x16x32_bf16 v[46:49], v[156:159], v[188:191], v[46:49]
	v_mfma_f32_16x16x32_bf16 v[42:45], v[164:167], v[188:191], v[42:45]
	v_mfma_f32_16x16x32_bf16 v[34:37], v[164:167], v[196:199], v[34:37]
	v_mfma_f32_16x16x32_bf16 v[38:41], v[156:159], v[196:199], v[38:41]
	v_mfma_f32_16x16x32_bf16 v[30:33], v[156:159], v[204:207], v[30:33]
	v_mfma_f32_16x16x32_bf16 v[26:29], v[164:167], v[204:207], v[26:29]
	v_mfma_f32_16x16x32_bf16 v[18:21], v[164:167], v[212:215], v[18:21]
	v_mfma_f32_16x16x32_bf16 v[22:25], v[156:159], v[212:215], v[22:25]
	v_mfma_f32_16x16x32_bf16 v[46:49], v[160:163], v[192:195], v[46:49]
	v_mfma_f32_16x16x32_bf16 v[42:45], v[168:171], v[192:195], v[42:45]
	v_mfma_f32_16x16x32_bf16 v[34:37], v[168:171], v[200:203], v[34:37]
	v_mfma_f32_16x16x32_bf16 v[38:41], v[160:163], v[200:203], v[38:41]
	v_mfma_f32_16x16x32_bf16 v[30:33], v[160:163], v[208:211], v[30:33]
	v_mfma_f32_16x16x32_bf16 v[26:29], v[168:171], v[208:211], v[26:29]
	v_mfma_f32_16x16x32_bf16 v[18:21], v[168:171], v[216:219], v[18:21]
	v_mfma_f32_16x16x32_bf16 v[22:25], v[160:163], v[216:219], v[22:25]
	v_mfma_f32_16x16x32_bf16 v[14:17], v[172:175], v[188:191], v[14:17]
	v_mfma_f32_16x16x32_bf16 v[10:13], v[180:183], v[188:191], v[10:13]
	v_mfma_f32_16x16x32_bf16 v[2:5], v[180:183], v[196:199], v[2:5]
	v_mfma_f32_16x16x32_bf16 v[6:9], v[172:175], v[196:199], v[6:9]
	v_mfma_f32_16x16x32_bf16 v[114:117], v[172:175], v[204:207], v[114:117]
	v_mfma_f32_16x16x32_bf16 v[118:121], v[180:183], v[204:207], v[118:121]
	v_mfma_f32_16x16x32_bf16 v[126:129], v[180:183], v[212:215], v[126:129]
	v_mfma_f32_16x16x32_bf16 v[122:125], v[172:175], v[212:215], v[122:125]
	v_mfma_f32_16x16x32_bf16 v[14:17], v[176:179], v[192:195], v[14:17]
	v_mfma_f32_16x16x32_bf16 v[10:13], v[184:187], v[192:195], v[10:13]
	v_mfma_f32_16x16x32_bf16 v[2:5], v[184:187], v[200:203], v[2:5]
	v_mfma_f32_16x16x32_bf16 v[6:9], v[176:179], v[200:203], v[6:9]
	v_mfma_f32_16x16x32_bf16 v[114:117], v[176:179], v[208:211], v[114:117]
	v_mfma_f32_16x16x32_bf16 v[118:121], v[184:187], v[208:211], v[118:121]
	v_mfma_f32_16x16x32_bf16 v[126:129], v[184:187], v[216:219], v[126:129]
	v_mfma_f32_16x16x32_bf16 v[122:125], v[176:179], v[216:219], v[122:125]
	s_barrier
	s_add_i32 s92, s92, 2
	s_add_u32 s78, s78, 0x100
	s_addc_u32 s79, s79, 0
	s_cmp_gt_u32 s92, 13
	s_cbranch_scc0 .LBB0_198
	s_branch .Lmy_kexit_0
.LBB0_198:
	v_add_u32_e32 v150, s54, v152
	ds_read_b128 v[156:159], v150
	ds_read_b128 v[160:163], v150 offset:1024
	ds_read_b128 v[164:167], v150 offset:2048
	ds_read_b128 v[168:171], v150 offset:3072
	v_add_u32_e32 v150, s55, v152
	s_add_u32 s82, s70, s78
	ds_read_b128 v[172:175], v150
	ds_read_b128 v[176:179], v150 offset:1024
	ds_read_b128 v[180:183], v150 offset:2048
	ds_read_b128 v[184:187], v150 offset:3072
	s_addc_u32 s83, s71, s79
	s_add_u32 s82, s82, 0x100
	s_addc_u32 s83, s83, 0
	s_add_u32 s93, s58, s78
	s_addc_u32 s94, s59, s79
	s_cmpk_eq_i32 s78, 0x700
	s_cselect_b32 s85, s75, s83
	s_cselect_b32 s84, s90, s82
	s_cselect_b32 s83, s73, s94
	s_cselect_b32 s82, s91, s93
	v_lshl_add_u64 v[150:151], v[146:147], 0, s[78:79]
	s_add_i32 m0, s67, 0xc000
	ds_read_b128 v[188:191], v155
	ds_read_b128 v[192:195], v155 offset:1024
	ds_read_b128 v[196:199], v155 offset:2048
	ds_read_b128 v[200:203], v155 offset:3072
	ds_read_b128 v[204:207], v155 offset:4096
	ds_read_b128 v[208:211], v155 offset:5120
	ds_read_b128 v[212:215], v155 offset:6144
	ds_read_b128 v[216:219], v155 offset:7168
	global_load_lds_dwordx4 v[150:151], off
	v_lshl_add_u64 v[150:151], v[148:149], 0, s[78:79]
	s_add_i32 m0, s67, 0xe000
	s_nop 0
	global_load_lds_dwordx4 v[150:151], off
	s_waitcnt vmcnt(8)
	s_waitcnt lgkmcnt(0)
	s_barrier
; #define PG8_STAGEA(bufoff, gbase) PG8_STAGE_(bufoff, gbase, voffA)
; #define PG8_STAGEB(bufoff, gbase) PG8_STAGE_(bufoff, gbase, voffB)
; #define PG8_LDA(dst, b, h) do { _Pragma("unroll") for (int m = 0; m < 4; ++m) _Pragma("unroll") for (int k = 0; k < 2; ++k) dst[m][k] = *(const LAS bf16x8*)(lds + PG8_SA(b, h) + aoff + m * 2048 + k * 1024); } while (0)
; #define PG8_LDB(dst, b, h) do { _Pragma("unroll") for (int n = 0; n < 2; ++n) _Pragma("unroll") for (int k = 0; k < 2; ++k) dst[n][k] = *(const LAS bf16x8*)(lds + PG8_SB(b, h) + boff + n * 2048 + k * 1024); } while (0)
; #define PG8_MMA(ai, bj, At, Bt_) do { __builtin_amdgcn_s_setprio(1); _Pragma("unroll") for (int m = 0; m < 4; ++m) _Pragma("unroll") for (int n = 0; n < 2; ++n) _Pragma("unroll") for (int k = 0; k < 2; ++k) \
;         acc[ai][bj][m][n] = __builtin_amdgcn_mfma_f32_16x16x32_bf16(Bt_[n][k], At[m][k], acc[ai][bj][m][n], 0, 0, 0); __builtin_amdgcn_s_setprio(0); } while (0)
; #define PG8_WAIT_V(n) asm volatile("s_waitcnt vmcnt(" #n ")" ::: "memory")
; #define PG8_WAIT_L(n) asm volatile("s_waitcnt lgkmcnt(" #n ")" ::: "memory")
; #define PG8_BAR __builtin_amdgcn_s_barrier()
; #define PG8_SCHED __builtin_amdgcn_sched_barrier(0)
; template <int EK, int SK = -1>
; __device__ __forceinline__ void gemm_phase(LAS unsigned char* lds, const bf16_t* A, const bf16_t* Bt, int nM, int N, int K, const EpiArgs& E) {
;     ...
;             PG8_LDB(B0, 0, 0); PG8_LDB(B1, 0, 1); PG8_SCHED; PG8_LDA(At, 0, 0); PG8_STAGEA(PG8_SA(1, 1), a1 + hstep);
;             PG8_WAIT_V(8); PG8_WAIT_L(0); PG8_BAR; PG8_MMA(0, 0, At, B0); PG8_MMA(0, 1, At, B1); PG8_BAR; PG8_SCHED;
;             PG8_LDA(At, 0, 1); PG8_STAGEB(PG8_SB(0, 0), b2); PG8_STAGEB(PG8_SB(0, 1), b2 + hstep); PG8_STAGEA(PG8_SA(0, 0), a2);
;             PG8_WAIT_V(8); PG8_WAIT_L(0); PG8_BAR; PG8_MMA(1, 0, At, B0); PG8_MMA(1, 1, At, B1); PG8_BAR; PG8_SCHED;
	s_waitcnt lgkmcnt(0)
	v_mfma_f32_16x16x32_bf16 v[110:113], v[156:159], v[188:191], v[110:113]
	v_mfma_f32_16x16x32_bf16 v[106:109], v[164:167], v[188:191], v[106:109]
	v_mfma_f32_16x16x32_bf16 v[98:101], v[164:167], v[196:199], v[98:101]
	v_mfma_f32_16x16x32_bf16 v[102:105], v[156:159], v[196:199], v[102:105]
	v_mfma_f32_16x16x32_bf16 v[94:97], v[156:159], v[204:207], v[94:97]
	v_mfma_f32_16x16x32_bf16 v[90:93], v[164:167], v[204:207], v[90:93]
	v_mfma_f32_16x16x32_bf16 v[82:85], v[164:167], v[212:215], v[82:85]
	v_mfma_f32_16x16x32_bf16 v[86:89], v[156:159], v[212:215], v[86:89]
	v_mfma_f32_16x16x32_bf16 v[110:113], v[160:163], v[192:195], v[110:113]
	v_mfma_f32_16x16x32_bf16 v[106:109], v[168:171], v[192:195], v[106:109]
	v_mfma_f32_16x16x32_bf16 v[98:101], v[168:171], v[200:203], v[98:101]
	v_mfma_f32_16x16x32_bf16 v[102:105], v[160:163], v[200:203], v[102:105]
	v_mfma_f32_16x16x32_bf16 v[94:97], v[160:163], v[208:211], v[94:97]
	v_mfma_f32_16x16x32_bf16 v[90:93], v[168:171], v[208:211], v[90:93]
	v_mfma_f32_16x16x32_bf16 v[82:85], v[168:171], v[216:219], v[82:85]
	v_mfma_f32_16x16x32_bf16 v[86:89], v[160:163], v[216:219], v[86:89]
	v_mfma_f32_16x16x32_bf16 v[78:81], v[172:175], v[188:191], v[78:81]
	v_mfma_f32_16x16x32_bf16 v[74:77], v[180:183], v[188:191], v[74:77]
	v_mfma_f32_16x16x32_bf16 v[66:69], v[180:183], v[196:199], v[66:69]
	v_mfma_f32_16x16x32_bf16 v[70:73], v[172:175], v[196:199], v[70:73]
	v_mfma_f32_16x16x32_bf16 v[62:65], v[172:175], v[204:207], v[62:65]
	v_mfma_f32_16x16x32_bf16 v[58:61], v[180:183], v[204:207], v[58:61]
	v_mfma_f32_16x16x32_bf16 v[50:53], v[180:183], v[212:215], v[50:53]
	v_mfma_f32_16x16x32_bf16 v[54:57], v[172:175], v[212:215], v[54:57]
	v_mfma_f32_16x16x32_bf16 v[78:81], v[176:179], v[192:195], v[78:81]
	v_mfma_f32_16x16x32_bf16 v[74:77], v[184:187], v[192:195], v[74:77]
	v_mfma_f32_16x16x32_bf16 v[66:69], v[184:187], v[200:203], v[66:69]
	v_mfma_f32_16x16x32_bf16 v[70:73], v[176:179], v[200:203], v[70:73]
	v_mfma_f32_16x16x32_bf16 v[62:65], v[176:179], v[208:211], v[62:65]
	v_mfma_f32_16x16x32_bf16 v[58:61], v[184:187], v[208:211], v[58:61]
	v_mfma_f32_16x16x32_bf16 v[50:53], v[184:187], v[216:219], v[50:53]
	v_mfma_f32_16x16x32_bf16 v[54:57], v[176:179], v[216:219], v[54:57]
	s_barrier
	s_add_i32 s93, s54, s87
	v_lshl_add_u64 v[150:151], s[82:83], 0, v[132:133]
	s_mov_b32 m0, s93
	ds_read_b128 v[188:191], v155 offset:16384
	ds_read_b128 v[192:195], v155 offset:17408
	ds_read_b128 v[196:199], v155 offset:18432
	ds_read_b128 v[200:203], v155 offset:19456
	ds_read_b128 v[204:207], v155 offset:20480
	ds_read_b128 v[208:211], v155 offset:21504
	ds_read_b128 v[212:215], v155 offset:22528
	ds_read_b128 v[216:219], v155 offset:23552
	global_load_lds_dwordx4 v[150:151], off
	s_add_i32 m0, s93, 0x2000
	s_add_u32 s94, s82, 0x40000
	v_lshl_add_u64 v[220:221], s[82:83], 0, v[136:137]
	s_addc_u32 s95, s83, 0
	s_add_i32 s93, s55, s87
	global_load_lds_dwordx4 v[220:221], off
	v_lshl_add_u64 v[222:223], s[94:95], 0, v[132:133]
	s_mov_b32 m0, s93
	v_lshl_add_u64 v[224:225], s[84:85], 0, v[134:135]
	global_load_lds_dwordx4 v[222:223], off
	v_lshl_add_u64 v[222:223], s[94:95], 0, v[136:137]
	s_add_i32 m0, s93, 0x2000
	s_nop 0
	global_load_lds_dwordx4 v[222:223], off
	v_lshl_add_u64 v[222:223], s[84:85], 0, v[130:131]
	s_mov_b32 m0, s67
	s_nop 0
	global_load_lds_dwordx4 v[222:223], off
	s_mov_b32 m0, s69
	s_nop 0
	global_load_lds_dwordx4 v[224:225], off
	s_waitcnt vmcnt(8)
	s_waitcnt lgkmcnt(0)
	s_barrier
	s_waitcnt lgkmcnt(0)
	v_mfma_f32_16x16x32_bf16 v[46:49], v[156:159], v[188:191], v[46:49]
	v_mfma_f32_16x16x32_bf16 v[42:45], v[164:167], v[188:191], v[42:45]
	v_mfma_f32_16x16x32_bf16 v[34:37], v[164:167], v[196:199], v[34:37]
	v_mfma_f32_16x16x32_bf16 v[38:41], v[156:159], v[196:199], v[38:41]
	v_mfma_f32_16x16x32_bf16 v[30:33], v[156:159], v[204:207], v[30:33]
	v_mfma_f32_16x16x32_bf16 v[26:29], v[164:167], v[204:207], v[26:29]
	v_mfma_f32_16x16x32_bf16 v[18:21], v[164:167], v[212:215], v[18:21]
	v_mfma_f32_16x16x32_bf16 v[22:25], v[156:159], v[212:215], v[22:25]
	v_mfma_f32_16x16x32_bf16 v[46:49], v[160:163], v[192:195], v[46:49]
	v_mfma_f32_16x16x32_bf16 v[42:45], v[168:171], v[192:195], v[42:45]
	v_mfma_f32_16x16x32_bf16 v[34:37], v[168:171], v[200:203], v[34:37]
	v_mfma_f32_16x16x32_bf16 v[38:41], v[160:163], v[200:203], v[38:41]
	v_mfma_f32_16x16x32_bf16 v[30:33], v[160:163], v[208:211], v[30:33]
	v_mfma_f32_16x16x32_bf16 v[26:29], v[168:171], v[208:211], v[26:29]
	v_mfma_f32_16x16x32_bf16 v[18:21], v[168:171], v[216:219], v[18:21]
	v_mfma_f32_16x16x32_bf16 v[22:25], v[160:163], v[216:219], v[22:25]
	v_mfma_f32_16x16x32_bf16 v[14:17], v[172:175], v[188:191], v[14:17]
	v_mfma_f32_16x16x32_bf16 v[10:13], v[180:183], v[188:191], v[10:13]
	v_mfma_f32_16x16x32_bf16 v[2:5], v[180:183], v[196:199], v[2:5]
	v_mfma_f32_16x16x32_bf16 v[6:9], v[172:175], v[196:199], v[6:9]
	v_mfma_f32_16x16x32_bf16 v[114:117], v[172:175], v[204:207], v[114:117]
	v_mfma_f32_16x16x32_bf16 v[118:121], v[180:183], v[204:207], v[118:121]
	v_mfma_f32_16x16x32_bf16 v[126:129], v[180:183], v[212:215], v[126:129]
	v_mfma_f32_16x16x32_bf16 v[122:125], v[172:175], v[212:215], v[122:125]
	v_mfma_f32_16x16x32_bf16 v[14:17], v[176:179], v[192:195], v[14:17]
	v_mfma_f32_16x16x32_bf16 v[10:13], v[184:187], v[192:195], v[10:13]
	v_mfma_f32_16x16x32_bf16 v[2:5], v[184:187], v[200:203], v[2:5]
	v_mfma_f32_16x16x32_bf16 v[6:9], v[176:179], v[200:203], v[6:9]
	v_mfma_f32_16x16x32_bf16 v[114:117], v[176:179], v[208:211], v[114:117]
	v_mfma_f32_16x16x32_bf16 v[118:121], v[184:187], v[208:211], v[118:121]
	v_mfma_f32_16x16x32_bf16 v[126:129], v[184:187], v[216:219], v[126:129]
	v_mfma_f32_16x16x32_bf16 v[122:125], v[176:179], v[216:219], v[122:125]
	s_barrier
; #define PG8_STAGEA(bufoff, gbase) PG8_STAGE_(bufoff, gbase, voffA)
; #define PG8_STAGEB(bufoff, gbase) PG8_STAGE_(bufoff, gbase, voffB)
; #define PG8_LDA(dst, b, h) do { _Pragma("unroll") for (int m = 0; m < 4; ++m) _Pragma("unroll") for (int k = 0; k < 2; ++k) dst[m][k] = *(const LAS bf16x8*)(lds + PG8_SA(b, h) + aoff + m * 2048 + k * 1024); } while (0)
; #define PG8_LDB(dst, b, h) do { _Pragma("unroll") for (int n = 0; n < 2; ++n) _Pragma("unroll") for (int k = 0; k < 2; ++k) dst[n][k] = *(const LAS bf16x8*)(lds + PG8_SB(b, h) + boff + n * 2048 + k * 1024); } while (0)
; #define PG8_MMA(ai, bj, At, Bt_) do { __builtin_amdgcn_s_setprio(1); _Pragma("unroll") for (int m = 0; m < 4; ++m) _Pragma("unroll") for (int n = 0; n < 2; ++n) _Pragma("unroll") for (int k = 0; k < 2; ++k) \
;         acc[ai][bj][m][n] = __builtin_amdgcn_mfma_f32_16x16x32_bf16(Bt_[n][k], At[m][k], acc[ai][bj][m][n], 0, 0, 0); __builtin_amdgcn_s_setprio(0); } while (0)
; #define PG8_WAIT_V(n) asm volatile("s_waitcnt vmcnt(" #n ")" ::: "memory")
; #define PG8_WAIT_L(n) asm volatile("s_waitcnt lgkmcnt(" #n ")" ::: "memory")
; #define PG8_BAR __builtin_amdgcn_s_barrier()
; #define PG8_SCHED __builtin_amdgcn_sched_barrier(0)
; template <int EK, int SK = -1>
; __device__ __forceinline__ void gemm_phase(LAS unsigned char* lds, const bf16_t* A, const bf16_t* Bt, int nM, int N, int K, const EpiArgs& E) {
;     ...
;             PG8_LDB(B0, 1, 0); PG8_LDB(B1, 1, 1); PG8_SCHED; PG8_LDA(At, 1, 0); PG8_STAGEA(PG8_SA(0, 1), a2 + hstep);
;             PG8_WAIT_V(8); PG8_WAIT_L(0); PG8_BAR; PG8_MMA(0, 0, At, B0); PG8_MMA(0, 1, At, B1); PG8_BAR; PG8_SCHED;
;             PG8_LDA(At, 1, 1); PG8_STAGEB(PG8_SB(1, 0), b3); PG8_STAGEB(PG8_SB(1, 1), b3 + hstep); PG8_STAGEA(PG8_SA(1, 0), a3);
;             PG8_WAIT_V(8); PG8_WAIT_L(0); PG8_BAR; PG8_MMA(1, 0, At, B0); PG8_MMA(1, 1, At, B1); PG8_BAR; PG8_SCHED;
;         }
	s_add_i32 s93, 0, 0x18000
	s_add_i32 s94, 0, 0x1c000
	v_add_u32_e32 v168, s93, v152
	v_add_u32_e32 v184, s94, v152
	ds_read_b128 v[156:159], v168
	ds_read_b128 v[160:163], v168 offset:1024
	ds_read_b128 v[164:167], v168 offset:2048
	ds_read_b128 v[168:171], v168 offset:3072
	ds_read_b128 v[172:175], v184
	ds_read_b128 v[176:179], v184 offset:1024
	ds_read_b128 v[180:183], v184 offset:2048
	ds_read_b128 v[184:187], v184 offset:3072
	s_add_u32 s84, s84, 0x40000
	s_addc_u32 s85, s85, 0
	s_mov_b32 m0, s88
	v_lshl_add_u64 v[226:227], s[84:85], 0, v[130:131]
	ds_read_b128 v[188:191], v155 offset:32768
	ds_read_b128 v[192:195], v155 offset:33792
	ds_read_b128 v[196:199], v155 offset:34816
	ds_read_b128 v[200:203], v155 offset:35840
	ds_read_b128 v[204:207], v155 offset:36864
	ds_read_b128 v[208:211], v155 offset:37888
	ds_read_b128 v[212:215], v155 offset:38912
	ds_read_b128 v[216:219], v155 offset:39936
	global_load_lds_dwordx4 v[226:227], off
	v_lshl_add_u64 v[226:227], s[84:85], 0, v[134:135]
	s_mov_b32 m0, s89
	s_nop 0
	global_load_lds_dwordx4 v[226:227], off
	s_waitcnt vmcnt(8)
	s_waitcnt lgkmcnt(0)
	s_barrier
	s_waitcnt lgkmcnt(0)
	v_mfma_f32_16x16x32_bf16 v[110:113], v[156:159], v[188:191], v[110:113]
	v_mfma_f32_16x16x32_bf16 v[106:109], v[164:167], v[188:191], v[106:109]
	v_mfma_f32_16x16x32_bf16 v[98:101], v[164:167], v[196:199], v[98:101]
	v_mfma_f32_16x16x32_bf16 v[102:105], v[156:159], v[196:199], v[102:105]
	v_mfma_f32_16x16x32_bf16 v[94:97], v[156:159], v[204:207], v[94:97]
	v_mfma_f32_16x16x32_bf16 v[90:93], v[164:167], v[204:207], v[90:93]
	v_mfma_f32_16x16x32_bf16 v[82:85], v[164:167], v[212:215], v[82:85]
	v_mfma_f32_16x16x32_bf16 v[86:89], v[156:159], v[212:215], v[86:89]
	v_mfma_f32_16x16x32_bf16 v[110:113], v[160:163], v[192:195], v[110:113]
	v_mfma_f32_16x16x32_bf16 v[106:109], v[168:171], v[192:195], v[106:109]
	v_mfma_f32_16x16x32_bf16 v[98:101], v[168:171], v[200:203], v[98:101]
	v_mfma_f32_16x16x32_bf16 v[102:105], v[160:163], v[200:203], v[102:105]
	v_mfma_f32_16x16x32_bf16 v[94:97], v[160:163], v[208:211], v[94:97]
	v_mfma_f32_16x16x32_bf16 v[90:93], v[168:171], v[208:211], v[90:93]
	v_mfma_f32_16x16x32_bf16 v[82:85], v[168:171], v[216:219], v[82:85]
	v_mfma_f32_16x16x32_bf16 v[86:89], v[160:163], v[216:219], v[86:89]
	v_mfma_f32_16x16x32_bf16 v[78:81], v[172:175], v[188:191], v[78:81]
	v_mfma_f32_16x16x32_bf16 v[74:77], v[180:183], v[188:191], v[74:77]
	v_mfma_f32_16x16x32_bf16 v[66:69], v[180:183], v[196:199], v[66:69]
	v_mfma_f32_16x16x32_bf16 v[70:73], v[172:175], v[196:199], v[70:73]
	v_mfma_f32_16x16x32_bf16 v[62:65], v[172:175], v[204:207], v[62:65]
	v_mfma_f32_16x16x32_bf16 v[58:61], v[180:183], v[204:207], v[58:61]
	v_mfma_f32_16x16x32_bf16 v[50:53], v[180:183], v[212:215], v[50:53]
	v_mfma_f32_16x16x32_bf16 v[54:57], v[172:175], v[212:215], v[54:57]
	v_mfma_f32_16x16x32_bf16 v[78:81], v[176:179], v[192:195], v[78:81]
	v_mfma_f32_16x16x32_bf16 v[74:77], v[184:187], v[192:195], v[74:77]
	v_mfma_f32_16x16x32_bf16 v[66:69], v[184:187], v[200:203], v[66:69]
	v_mfma_f32_16x16x32_bf16 v[70:73], v[176:179], v[200:203], v[70:73]
	v_mfma_f32_16x16x32_bf16 v[62:65], v[176:179], v[208:211], v[62:65]
	v_mfma_f32_16x16x32_bf16 v[58:61], v[184:187], v[208:211], v[58:61]
	v_mfma_f32_16x16x32_bf16 v[50:53], v[184:187], v[216:219], v[50:53]
	v_mfma_f32_16x16x32_bf16 v[54:57], v[176:179], v[216:219], v[54:57]
	s_barrier
	s_add_i32 s84, s93, s87
	v_lshl_add_u64 v[150:151], v[150:151], 0, s[10:11]
	s_mov_b32 m0, s84
	ds_read_b128 v[188:191], v155 offset:49152
	ds_read_b128 v[192:195], v155 offset:50176
	ds_read_b128 v[196:199], v155 offset:51200
	ds_read_b128 v[200:203], v155 offset:52224
	ds_read_b128 v[204:207], v155 offset:53248
	ds_read_b128 v[208:211], v155 offset:54272
	ds_read_b128 v[212:215], v155 offset:55296
	ds_read_b128 v[216:219], v155 offset:56320
	global_load_lds_dwordx4 v[150:151], off
	s_add_i32 m0, s84, 0x2000
	s_add_u32 s82, s82, 0x40080
	v_lshl_add_u64 v[150:151], v[220:221], 0, s[10:11]
	s_addc_u32 s83, s83, 0
	s_add_i32 s84, s94, s87
	global_load_lds_dwordx4 v[150:151], off
	v_lshl_add_u64 v[150:151], s[82:83], 0, v[132:133]
	s_mov_b32 m0, s84
	s_nop 0
	global_load_lds_dwordx4 v[150:151], off
	v_lshl_add_u64 v[150:151], s[82:83], 0, v[136:137]
	s_add_i32 m0, s84, 0x2000
	s_nop 0
	global_load_lds_dwordx4 v[150:151], off
	v_lshl_add_u64 v[150:151], v[222:223], 0, s[10:11]
	s_mov_b32 m0, s52
	s_nop 0
	global_load_lds_dwordx4 v[150:151], off
	v_lshl_add_u64 v[150:151], v[224:225], 0, s[10:11]
	s_mov_b32 m0, s53
	s_nop 0
	global_load_lds_dwordx4 v[150:151], off
	s_waitcnt vmcnt(8)
	s_waitcnt lgkmcnt(0)
	s_barrier
	s_waitcnt lgkmcnt(0)
	v_mfma_f32_16x16x32_bf16 v[46:49], v[156:159], v[188:191], v[46:49]
	v_mfma_f32_16x16x32_bf16 v[42:45], v[164:167], v[188:191], v[42:45]
	v_mfma_f32_16x16x32_bf16 v[34:37], v[164:167], v[196:199], v[34:37]
	v_mfma_f32_16x16x32_bf16 v[38:41], v[156:159], v[196:199], v[38:41]
	v_mfma_f32_16x16x32_bf16 v[30:33], v[156:159], v[204:207], v[30:33]
	v_mfma_f32_16x16x32_bf16 v[26:29], v[164:167], v[204:207], v[26:29]
	v_mfma_f32_16x16x32_bf16 v[18:21], v[164:167], v[212:215], v[18:21]
	v_mfma_f32_16x16x32_bf16 v[22:25], v[156:159], v[212:215], v[22:25]
	v_mfma_f32_16x16x32_bf16 v[46:49], v[160:163], v[192:195], v[46:49]
	v_mfma_f32_16x16x32_bf16 v[42:45], v[168:171], v[192:195], v[42:45]
	v_mfma_f32_16x16x32_bf16 v[34:37], v[168:171], v[200:203], v[34:37]
	v_mfma_f32_16x16x32_bf16 v[38:41], v[160:163], v[200:203], v[38:41]
	v_mfma_f32_16x16x32_bf16 v[30:33], v[160:163], v[208:211], v[30:33]
	v_mfma_f32_16x16x32_bf16 v[26:29], v[168:171], v[208:211], v[26:29]
	v_mfma_f32_16x16x32_bf16 v[18:21], v[168:171], v[216:219], v[18:21]
	v_mfma_f32_16x16x32_bf16 v[22:25], v[160:163], v[216:219], v[22:25]
	v_mfma_f32_16x16x32_bf16 v[14:17], v[172:175], v[188:191], v[14:17]
	v_mfma_f32_16x16x32_bf16 v[10:13], v[180:183], v[188:191], v[10:13]
	v_mfma_f32_16x16x32_bf16 v[2:5], v[180:183], v[196:199], v[2:5]
	v_mfma_f32_16x16x32_bf16 v[6:9], v[172:175], v[196:199], v[6:9]
	v_mfma_f32_16x16x32_bf16 v[114:117], v[172:175], v[204:207], v[114:117]
	v_mfma_f32_16x16x32_bf16 v[118:121], v[180:183], v[204:207], v[118:121]
	v_mfma_f32_16x16x32_bf16 v[126:129], v[180:183], v[212:215], v[126:129]
	v_mfma_f32_16x16x32_bf16 v[122:125], v[172:175], v[212:215], v[122:125]
	v_mfma_f32_16x16x32_bf16 v[14:17], v[176:179], v[192:195], v[14:17]
	v_mfma_f32_16x16x32_bf16 v[10:13], v[184:187], v[192:195], v[10:13]
	v_mfma_f32_16x16x32_bf16 v[2:5], v[184:187], v[200:203], v[2:5]
	v_mfma_f32_16x16x32_bf16 v[6:9], v[176:179], v[200:203], v[6:9]
	v_mfma_f32_16x16x32_bf16 v[114:117], v[176:179], v[208:211], v[114:117]
	v_mfma_f32_16x16x32_bf16 v[118:121], v[184:187], v[208:211], v[118:121]
	v_mfma_f32_16x16x32_bf16 v[126:129], v[184:187], v[216:219], v[126:129]
	v_mfma_f32_16x16x32_bf16 v[122:125], v[176:179], v[216:219], v[122:125]
	s_barrier
	s_add_i32 s92, s92, 2
	s_add_u32 s78, s78, 0x100
	s_addc_u32 s79, s79, 0
	s_cmp_gt_u32 s92, 13
	s_cbranch_scc0 .LBB0_198

; #define PG8_STAGEA(bufoff, gbase) PG8_STAGE_(bufoff, gbase, voffA)
; #define PG8_LDA(dst, b, h) do { _Pragma("unroll") for (int m = 0; m < 4; ++m) _Pragma("unroll") for (int k = 0; k < 2; ++k) dst[m][k] = *(const LAS bf16x8*)(lds + PG8_SA(b, h) + aoff + m * 2048 + k * 1024); } while (0)
; #define PG8_LDB(dst, b, h) do { _Pragma("unroll") for (int n = 0; n < 2; ++n) _Pragma("unroll") for (int k = 0; k < 2; ++k) dst[n][k] = *(const LAS bf16x8*)(lds + PG8_SB(b, h) + boff + n * 2048 + k * 1024); } while (0)
; #define PG8_MMA(ai, bj, At, Bt_) do { __builtin_amdgcn_s_setprio(1); _Pragma("unroll") for (int m = 0; m < 4; ++m) _Pragma("unroll") for (int n = 0; n < 2; ++n) _Pragma("unroll") for (int k = 0; k < 2; ++k) \
;         acc[ai][bj][m][n] = __builtin_amdgcn_mfma_f32_16x16x32_bf16(Bt_[n][k], At[m][k], acc[ai][bj][m][n], 0, 0, 0); __builtin_amdgcn_s_setprio(0); } while (0)
; #define PG8_WAIT_V(n) asm volatile("s_waitcnt vmcnt(" #n ")" ::: "memory")
; #define PG8_WAIT_L(n) asm volatile("s_waitcnt lgkmcnt(" #n ")" ::: "memory")
; #define PG8_BAR __builtin_amdgcn_s_barrier()
; #define PG8_SCHED __builtin_amdgcn_sched_barrier(0)
; template <int EK, int SK = -1>
; __device__ __forceinline__ void gemm_phase(LAS unsigned char* lds, const bf16_t* A, const bf16_t* Bt, int nM, int N, int K, const EpiArgs& E) {
;     ...
;         const bool has_next = S.next(ui + 1, nxt);
;         const char* nA = has_next ? (const char*)A + (size_t)nxt.pm * tstep : cA; const char* nB = has_next ? (const char*)Bt + (size_t)nxt.pn * tstep : cB;
;         for (int t = 0; t < nt; t += 2) {
;             const bool last = (t == nt - 2);
;             const char* a1 = cA + (size_t)(t + 1) * kstep;
;             const char* a2 = last ? nA : cA + (size_t)(t + 2) * kstep; const char* b2 = last ? nB : cB + (size_t)(t + 2) * kstep;
;             const char* a3 = a2 + kstep; const char* b3 = b2 + kstep;
;             PG8_LDB(B0, 0, 0); PG8_LDB(B1, 0, 1); PG8_SCHED; PG8_LDA(At, 0, 0); PG8_STAGEA(PG8_SA(1, 1), a1 + hstep);
;             PG8_WAIT_V(8); PG8_WAIT_L(0); PG8_BAR; PG8_MMA(0, 0, At, B0); PG8_MMA(0, 1, At, B1); PG8_BAR; PG8_SCHED;
.LBB0_412:
	s_add_u32 s53, s80, 0x100
	s_addc_u32 s54, s81, 0
	s_ashr_i32 s75, s74, 31
	s_lshl_b64 s[56:57], s[74:75], 19
	s_add_u32 s78, s66, s56
	s_addc_u32 s79, s67, s57
	s_and_b64 s[56:57], s[8:9], exec
	s_cselect_b32 s40, s79, s19
	s_cselect_b32 s55, s78, s18
	s_ashr_i32 s73, s72, 31
	s_lshl_b64 s[56:57], s[72:73], 19
	s_add_u32 s76, s86, s56
	s_addc_u32 s77, s87, s57
	s_and_b64 s[56:57], s[8:9], exec
	s_cselect_b32 s56, s77, s81
	s_cselect_b32 s57, s76, s80
	v_lshl_add_u64 v[146:147], s[18:19], 0, v[138:139]
	v_lshl_add_u64 v[148:149], s[18:19], 0, v[140:141]
	s_mov_b32 s58, -2
	s_mov_b64 s[80:81], 0
	v_add_u32_e32 v150, s95, v152
	ds_read_b128 v[156:159], v150
	ds_read_b128 v[160:163], v150 offset:1024
	ds_read_b128 v[164:167], v150 offset:2048
	ds_read_b128 v[168:171], v150 offset:3072
	v_add_u32_e32 v150, s96, v152
	s_add_u32 s59, s18, s80
	ds_read_b128 v[172:175], v150
	ds_read_b128 v[176:179], v150 offset:1024
	ds_read_b128 v[180:183], v150 offset:2048
	ds_read_b128 v[184:187], v150 offset:3072
	s_addc_u32 s73, s19, s81
	s_add_u32 s59, s59, 0x100
	s_addc_u32 s73, s73, 0
	s_add_u32 s75, s53, s80
	s_addc_u32 s82, s54, s81
	s_cmpk_eq_i32 s80, 0x700
	s_cselect_b32 s85, s40, s73
	s_cselect_b32 s84, s55, s59
	s_cselect_b32 s83, s56, s82
	s_cselect_b32 s82, s57, s75
	v_lshl_add_u64 v[150:151], v[146:147], 0, s[80:81]
	s_add_i32 m0, s15, 0xc000
	ds_read_b128 v[188:191], v154
	ds_read_b128 v[192:195], v154 offset:1024
	ds_read_b128 v[196:199], v154 offset:2048
	ds_read_b128 v[200:203], v154 offset:3072
	ds_read_b128 v[204:207], v154 offset:4096
	ds_read_b128 v[208:211], v154 offset:5120
	ds_read_b128 v[212:215], v154 offset:6144
	ds_read_b128 v[216:219], v154 offset:7168
	global_load_lds_dwordx4 v[150:151], off
	v_lshl_add_u64 v[150:151], v[148:149], 0, s[80:81]
	s_add_i32 m0, s15, 0xe000
	s_nop 0
	global_load_lds_dwordx4 v[150:151], off
	s_waitcnt vmcnt(8)
	s_waitcnt lgkmcnt(0)
	s_barrier
	s_waitcnt lgkmcnt(0)
	v_mfma_f32_16x16x32_bf16 v[126:129], v[156:159], v[188:191], 0
	v_mfma_f32_16x16x32_bf16 v[122:125], v[164:167], v[188:191], 0
	v_mfma_f32_16x16x32_bf16 v[114:117], v[164:167], v[196:199], 0
	v_mfma_f32_16x16x32_bf16 v[118:121], v[156:159], v[196:199], 0
	v_mfma_f32_16x16x32_bf16 v[110:113], v[156:159], v[204:207], 0
	v_mfma_f32_16x16x32_bf16 v[106:109], v[164:167], v[204:207], 0
	v_mfma_f32_16x16x32_bf16 v[98:101], v[164:167], v[212:215], 0
	v_mfma_f32_16x16x32_bf16 v[102:105], v[156:159], v[212:215], 0
	v_mfma_f32_16x16x32_bf16 v[126:129], v[160:163], v[192:195], v[126:129]
	v_mfma_f32_16x16x32_bf16 v[122:125], v[168:171], v[192:195], v[122:125]
	v_mfma_f32_16x16x32_bf16 v[114:117], v[168:171], v[200:203], v[114:117]
	v_mfma_f32_16x16x32_bf16 v[118:121], v[160:163], v[200:203], v[118:121]
	v_mfma_f32_16x16x32_bf16 v[110:113], v[160:163], v[208:211], v[110:113]
	v_mfma_f32_16x16x32_bf16 v[106:109], v[168:171], v[208:211], v[106:109]
	v_mfma_f32_16x16x32_bf16 v[98:101], v[168:171], v[216:219], v[98:101]
	v_mfma_f32_16x16x32_bf16 v[102:105], v[160:163], v[216:219], v[102:105]
	v_mfma_f32_16x16x32_bf16 v[94:97], v[172:175], v[188:191], 0
	v_mfma_f32_16x16x32_bf16 v[90:93], v[180:183], v[188:191], 0
	v_mfma_f32_16x16x32_bf16 v[82:85], v[180:183], v[196:199], 0
	v_mfma_f32_16x16x32_bf16 v[86:89], v[172:175], v[196:199], 0
	v_mfma_f32_16x16x32_bf16 v[78:81], v[172:175], v[204:207], 0
	v_mfma_f32_16x16x32_bf16 v[74:77], v[180:183], v[204:207], 0
	v_mfma_f32_16x16x32_bf16 v[66:69], v[180:183], v[212:215], 0
	v_mfma_f32_16x16x32_bf16 v[70:73], v[172:175], v[212:215], 0
	v_mfma_f32_16x16x32_bf16 v[94:97], v[176:179], v[192:195], v[94:97]
	v_mfma_f32_16x16x32_bf16 v[90:93], v[184:187], v[192:195], v[90:93]
	v_mfma_f32_16x16x32_bf16 v[82:85], v[184:187], v[200:203], v[82:85]
	v_mfma_f32_16x16x32_bf16 v[86:89], v[176:179], v[200:203], v[86:89]
	v_mfma_f32_16x16x32_bf16 v[78:81], v[176:179], v[208:211], v[78:81]
	v_mfma_f32_16x16x32_bf16 v[74:77], v[184:187], v[208:211], v[74:77]
	v_mfma_f32_16x16x32_bf16 v[66:69], v[184:187], v[216:219], v[66:69]
	v_mfma_f32_16x16x32_bf16 v[70:73], v[176:179], v[216:219], v[70:73]
	s_barrier
	s_add_i32 s59, s95, s88
	v_lshl_add_u64 v[150:151], s[82:83], 0, v[132:133]
	s_mov_b32 m0, s59
	ds_read_b128 v[188:191], v154 offset:16384
	ds_read_b128 v[192:195], v154 offset:17408
	ds_read_b128 v[196:199], v154 offset:18432
	ds_read_b128 v[200:203], v154 offset:19456
	ds_read_b128 v[204:207], v154 offset:20480
	ds_read_b128 v[208:211], v154 offset:21504
	ds_read_b128 v[212:215], v154 offset:22528
	ds_read_b128 v[216:219], v154 offset:23552
	global_load_lds_dwordx4 v[150:151], off
	s_add_i32 m0, s59, 0x2000
	s_add_u32 vcc_lo, s82, 0x40000
	v_lshl_add_u64 v[220:221], s[82:83], 0, v[136:137]
	s_addc_u32 vcc_hi, s83, 0
	s_add_i32 s59, s96, s88
	global_load_lds_dwordx4 v[220:221], off
	v_lshl_add_u64 v[222:223], vcc, 0, v[132:133]
	s_mov_b32 m0, s59
	v_lshl_add_u64 v[224:225], s[84:85], 0, v[134:135]
	global_load_lds_dwordx4 v[222:223], off
	v_lshl_add_u64 v[222:223], vcc, 0, v[136:137]
	s_add_i32 m0, s59, 0x2000
	s_nop 0
	global_load_lds_dwordx4 v[222:223], off
	v_lshl_add_u64 v[222:223], s[84:85], 0, v[130:131]
	s_mov_b32 m0, s15
	s_nop 0
	global_load_lds_dwordx4 v[222:223], off
	s_mov_b32 m0, s17
	s_nop 0
	global_load_lds_dwordx4 v[224:225], off
	s_waitcnt vmcnt(8)
	s_waitcnt lgkmcnt(0)
	s_barrier
; #define PG8_STAGEA(bufoff, gbase) PG8_STAGE_(bufoff, gbase, voffA)
; #define PG8_STAGEB(bufoff, gbase) PG8_STAGE_(bufoff, gbase, voffB)
; #define PG8_LDA(dst, b, h) do { _Pragma("unroll") for (int m = 0; m < 4; ++m) _Pragma("unroll") for (int k = 0; k < 2; ++k) dst[m][k] = *(const LAS bf16x8*)(lds + PG8_SA(b, h) + aoff + m * 2048 + k * 1024); } while (0)
; #define PG8_LDB(dst, b, h) do { _Pragma("unroll") for (int n = 0; n < 2; ++n) _Pragma("unroll") for (int k = 0; k < 2; ++k) dst[n][k] = *(const LAS bf16x8*)(lds + PG8_SB(b, h) + boff + n * 2048 + k * 1024); } while (0)
; #define PG8_MMA(ai, bj, At, Bt_) do { __builtin_amdgcn_s_setprio(1); _Pragma("unroll") for (int m = 0; m < 4; ++m) _Pragma("unroll") for (int n = 0; n < 2; ++n) _Pragma("unroll") for (int k = 0; k < 2; ++k) \
;         acc[ai][bj][m][n] = __builtin_amdgcn_mfma_f32_16x16x32_bf16(Bt_[n][k], At[m][k], acc[ai][bj][m][n], 0, 0, 0); __builtin_amdgcn_s_setprio(0); } while (0)
; #define PG8_WAIT_V(n) asm volatile("s_waitcnt vmcnt(" #n ")" ::: "memory")
; #define PG8_WAIT_L(n) asm volatile("s_waitcnt lgkmcnt(" #n ")" ::: "memory")
; #define PG8_BAR __builtin_amdgcn_s_barrier()
; #define PG8_SCHED __builtin_amdgcn_sched_barrier(0)
; template <int EK, int SK = -1>
; __device__ __forceinline__ void gemm_phase(LAS unsigned char* lds, const bf16_t* A, const bf16_t* Bt, int nM, int N, int K, const EpiArgs& E) {
;     ...
;             PG8_WAIT_V(8); PG8_WAIT_L(0); PG8_BAR; PG8_MMA(0, 0, At, B0); PG8_MMA(0, 1, At, B1); PG8_BAR; PG8_SCHED;
;             PG8_LDA(At, 0, 1); PG8_STAGEB(PG8_SB(0, 0), b2); PG8_STAGEB(PG8_SB(0, 1), b2 + hstep); PG8_STAGEA(PG8_SA(0, 0), a2);
;             PG8_WAIT_V(8); PG8_WAIT_L(0); PG8_BAR; PG8_MMA(1, 0, At, B0); PG8_MMA(1, 1, At, B1); PG8_BAR; PG8_SCHED;
;             PG8_LDB(B0, 1, 0); PG8_LDB(B1, 1, 1); PG8_SCHED; PG8_LDA(At, 1, 0); PG8_STAGEA(PG8_SA(0, 1), a2 + hstep);
;             PG8_WAIT_V(8); PG8_WAIT_L(0); PG8_BAR; PG8_MMA(0, 0, At, B0); PG8_MMA(0, 1, At, B1); PG8_BAR; PG8_SCHED;
	s_waitcnt lgkmcnt(0)
	v_mfma_f32_16x16x32_bf16 v[62:65], v[156:159], v[188:191], 0
	v_mfma_f32_16x16x32_bf16 v[58:61], v[164:167], v[188:191], 0
	v_mfma_f32_16x16x32_bf16 v[50:53], v[164:167], v[196:199], 0
	v_mfma_f32_16x16x32_bf16 v[54:57], v[156:159], v[196:199], 0
	v_mfma_f32_16x16x32_bf16 v[46:49], v[156:159], v[204:207], 0
	v_mfma_f32_16x16x32_bf16 v[42:45], v[164:167], v[204:207], 0
	v_mfma_f32_16x16x32_bf16 v[34:37], v[164:167], v[212:215], 0
	v_mfma_f32_16x16x32_bf16 v[38:41], v[156:159], v[212:215], 0
	v_mfma_f32_16x16x32_bf16 v[62:65], v[160:163], v[192:195], v[62:65]
	v_mfma_f32_16x16x32_bf16 v[58:61], v[168:171], v[192:195], v[58:61]
	v_mfma_f32_16x16x32_bf16 v[50:53], v[168:171], v[200:203], v[50:53]
	v_mfma_f32_16x16x32_bf16 v[54:57], v[160:163], v[200:203], v[54:57]
	v_mfma_f32_16x16x32_bf16 v[46:49], v[160:163], v[208:211], v[46:49]
	v_mfma_f32_16x16x32_bf16 v[42:45], v[168:171], v[208:211], v[42:45]
	v_mfma_f32_16x16x32_bf16 v[34:37], v[168:171], v[216:219], v[34:37]
	v_mfma_f32_16x16x32_bf16 v[38:41], v[160:163], v[216:219], v[38:41]
	v_mfma_f32_16x16x32_bf16 v[30:33], v[172:175], v[188:191], 0
	v_mfma_f32_16x16x32_bf16 v[26:29], v[180:183], v[188:191], 0
	v_mfma_f32_16x16x32_bf16 v[18:21], v[180:183], v[196:199], 0
	v_mfma_f32_16x16x32_bf16 v[22:25], v[172:175], v[196:199], 0
	v_mfma_f32_16x16x32_bf16 v[14:17], v[172:175], v[204:207], 0
	v_mfma_f32_16x16x32_bf16 v[10:13], v[180:183], v[204:207], 0
	v_mfma_f32_16x16x32_bf16 v[2:5], v[180:183], v[212:215], 0
	v_mfma_f32_16x16x32_bf16 v[6:9], v[172:175], v[212:215], 0
	v_mfma_f32_16x16x32_bf16 v[30:33], v[176:179], v[192:195], v[30:33]
	v_mfma_f32_16x16x32_bf16 v[26:29], v[184:187], v[192:195], v[26:29]
	v_mfma_f32_16x16x32_bf16 v[18:21], v[184:187], v[200:203], v[18:21]
	v_mfma_f32_16x16x32_bf16 v[22:25], v[176:179], v[200:203], v[22:25]
	v_mfma_f32_16x16x32_bf16 v[14:17], v[176:179], v[208:211], v[14:17]
	v_mfma_f32_16x16x32_bf16 v[10:13], v[184:187], v[208:211], v[10:13]
	v_mfma_f32_16x16x32_bf16 v[2:5], v[184:187], v[216:219], v[2:5]
	v_mfma_f32_16x16x32_bf16 v[6:9], v[176:179], v[216:219], v[6:9]
	s_barrier
	s_add_i32 s59, 0, 0x18000
	s_add_i32 s73, 0, 0x1c000
	v_add_u32_e32 v168, s59, v152
	v_add_u32_e32 v184, s73, v152
	ds_read_b128 v[156:159], v168
	ds_read_b128 v[160:163], v168 offset:1024
	ds_read_b128 v[164:167], v168 offset:2048
	ds_read_b128 v[168:171], v168 offset:3072
	ds_read_b128 v[172:175], v184
	ds_read_b128 v[176:179], v184 offset:1024
	ds_read_b128 v[180:183], v184 offset:2048
	ds_read_b128 v[184:187], v184 offset:3072
	s_add_u32 s84, s84, 0x40000
	s_addc_u32 s85, s85, 0
	s_mov_b32 m0, s89
	v_lshl_add_u64 v[226:227], s[84:85], 0, v[130:131]
	ds_read_b128 v[188:191], v154 offset:32768
	ds_read_b128 v[192:195], v154 offset:33792
	ds_read_b128 v[196:199], v154 offset:34816
	ds_read_b128 v[200:203], v154 offset:35840
	ds_read_b128 v[204:207], v154 offset:36864
	ds_read_b128 v[208:211], v154 offset:37888
	ds_read_b128 v[212:215], v154 offset:38912
	ds_read_b128 v[216:219], v154 offset:39936
	global_load_lds_dwordx4 v[226:227], off
	v_lshl_add_u64 v[226:227], s[84:85], 0, v[134:135]
	s_mov_b32 m0, s90
	s_nop 0
	global_load_lds_dwordx4 v[226:227], off
	s_waitcnt vmcnt(8)
	s_waitcnt lgkmcnt(0)
	s_barrier
	s_waitcnt lgkmcnt(0)
	v_mfma_f32_16x16x32_bf16 v[126:129], v[156:159], v[188:191], v[126:129]
	v_mfma_f32_16x16x32_bf16 v[122:125], v[164:167], v[188:191], v[122:125]
	v_mfma_f32_16x16x32_bf16 v[114:117], v[164:167], v[196:199], v[114:117]
	v_mfma_f32_16x16x32_bf16 v[118:121], v[156:159], v[196:199], v[118:121]
	v_mfma_f32_16x16x32_bf16 v[110:113], v[156:159], v[204:207], v[110:113]
	v_mfma_f32_16x16x32_bf16 v[106:109], v[164:167], v[204:207], v[106:109]
	v_mfma_f32_16x16x32_bf16 v[98:101], v[164:167], v[212:215], v[98:101]
	v_mfma_f32_16x16x32_bf16 v[102:105], v[156:159], v[212:215], v[102:105]
	v_mfma_f32_16x16x32_bf16 v[126:129], v[160:163], v[192:195], v[126:129]
	v_mfma_f32_16x16x32_bf16 v[122:125], v[168:171], v[192:195], v[122:125]
	v_mfma_f32_16x16x32_bf16 v[114:117], v[168:171], v[200:203], v[114:117]
	v_mfma_f32_16x16x32_bf16 v[118:121], v[160:163], v[200:203], v[118:121]
	v_mfma_f32_16x16x32_bf16 v[110:113], v[160:163], v[208:211], v[110:113]
	v_mfma_f32_16x16x32_bf16 v[106:109], v[168:171], v[208:211], v[106:109]
	v_mfma_f32_16x16x32_bf16 v[98:101], v[168:171], v[216:219], v[98:101]
	v_mfma_f32_16x16x32_bf16 v[102:105], v[160:163], v[216:219], v[102:105]
	v_mfma_f32_16x16x32_bf16 v[94:97], v[172:175], v[188:191], v[94:97]
	v_mfma_f32_16x16x32_bf16 v[90:93], v[180:183], v[188:191], v[90:93]
	v_mfma_f32_16x16x32_bf16 v[82:85], v[180:183], v[196:199], v[82:85]
	v_mfma_f32_16x16x32_bf16 v[86:89], v[172:175], v[196:199], v[86:89]
	v_mfma_f32_16x16x32_bf16 v[78:81], v[172:175], v[204:207], v[78:81]
	v_mfma_f32_16x16x32_bf16 v[74:77], v[180:183], v[204:207], v[74:77]
	v_mfma_f32_16x16x32_bf16 v[66:69], v[180:183], v[212:215], v[66:69]
	v_mfma_f32_16x16x32_bf16 v[70:73], v[172:175], v[212:215], v[70:73]
	v_mfma_f32_16x16x32_bf16 v[94:97], v[176:179], v[192:195], v[94:97]
	v_mfma_f32_16x16x32_bf16 v[90:93], v[184:187], v[192:195], v[90:93]
	v_mfma_f32_16x16x32_bf16 v[82:85], v[184:187], v[200:203], v[82:85]
	v_mfma_f32_16x16x32_bf16 v[86:89], v[176:179], v[200:203], v[86:89]
	v_mfma_f32_16x16x32_bf16 v[78:81], v[176:179], v[208:211], v[78:81]
	v_mfma_f32_16x16x32_bf16 v[74:77], v[184:187], v[208:211], v[74:77]
	v_mfma_f32_16x16x32_bf16 v[66:69], v[184:187], v[216:219], v[66:69]
	v_mfma_f32_16x16x32_bf16 v[70:73], v[176:179], v[216:219], v[70:73]
	s_barrier
; #define PG8_STAGEA(bufoff, gbase) PG8_STAGE_(bufoff, gbase, voffA)
; #define PG8_STAGEB(bufoff, gbase) PG8_STAGE_(bufoff, gbase, voffB)
; #define PG8_LDA(dst, b, h) do { _Pragma("unroll") for (int m = 0; m < 4; ++m) _Pragma("unroll") for (int k = 0; k < 2; ++k) dst[m][k] = *(const LAS bf16x8*)(lds + PG8_SA(b, h) + aoff + m * 2048 + k * 1024); } while (0)
; #define PG8_LDB(dst, b, h) do { _Pragma("unroll") for (int n = 0; n < 2; ++n) _Pragma("unroll") for (int k = 0; k < 2; ++k) dst[n][k] = *(const LAS bf16x8*)(lds + PG8_SB(b, h) + boff + n * 2048 + k * 1024); } while (0)
; #define PG8_MMA(ai, bj, At, Bt_) do { __builtin_amdgcn_s_setprio(1); _Pragma("unroll") for (int m = 0; m < 4; ++m) _Pragma("unroll") for (int n = 0; n < 2; ++n) _Pragma("unroll") for (int k = 0; k < 2; ++k) \
;         acc[ai][bj][m][n] = __builtin_amdgcn_mfma_f32_16x16x32_bf16(Bt_[n][k], At[m][k], acc[ai][bj][m][n], 0, 0, 0); __builtin_amdgcn_s_setprio(0); } while (0)
; #define PG8_WAIT_V(n) asm volatile("s_waitcnt vmcnt(" #n ")" ::: "memory")
; #define PG8_WAIT_L(n) asm volatile("s_waitcnt lgkmcnt(" #n ")" ::: "memory")
; #define PG8_BAR __builtin_amdgcn_s_barrier()
; #define PG8_SCHED __builtin_amdgcn_sched_barrier(0)
; template <int EK, int SK = -1>
; __device__ __forceinline__ void gemm_phase(LAS unsigned char* lds, const bf16_t* A, const bf16_t* Bt, int nM, int N, int K, const EpiArgs& E) {
;     ...
;             PG8_LDB(B0, 0, 0); PG8_LDB(B1, 0, 1); PG8_SCHED; PG8_LDA(At, 0, 0); PG8_STAGEA(PG8_SA(1, 1), a1 + hstep);
;             PG8_WAIT_V(8); PG8_WAIT_L(0); PG8_BAR; PG8_MMA(0, 0, At, B0); PG8_MMA(0, 1, At, B1); PG8_BAR; PG8_SCHED;
;             PG8_LDA(At, 0, 1); PG8_STAGEB(PG8_SB(0, 0), b2); PG8_STAGEB(PG8_SB(0, 1), b2 + hstep); PG8_STAGEA(PG8_SA(0, 0), a2);
;             PG8_WAIT_V(8); PG8_WAIT_L(0); PG8_BAR; PG8_MMA(1, 0, At, B0); PG8_MMA(1, 1, At, B1); PG8_BAR; PG8_SCHED;
;             PG8_LDB(B0, 1, 0); PG8_LDB(B1, 1, 1); PG8_SCHED; PG8_LDA(At, 1, 0); PG8_STAGEA(PG8_SA(0, 1), a2 + hstep);
;             PG8_WAIT_V(8); PG8_WAIT_L(0); PG8_BAR; PG8_MMA(0, 0, At, B0); PG8_MMA(0, 1, At, B1); PG8_BAR; PG8_SCHED;
;             PG8_LDA(At, 1, 1); PG8_STAGEB(PG8_SB(1, 0), b3); PG8_STAGEB(PG8_SB(1, 1), b3 + hstep); PG8_STAGEA(PG8_SA(1, 0), a3);
;             PG8_WAIT_V(8); PG8_WAIT_L(0); PG8_BAR; PG8_MMA(1, 0, At, B0); PG8_MMA(1, 1, At, B1); PG8_BAR; PG8_SCHED;
	s_add_i32 s59, s59, s88
	v_lshl_add_u64 v[150:151], v[150:151], 0, s[68:69]
	s_mov_b32 m0, s59
	ds_read_b128 v[188:191], v154 offset:49152
	ds_read_b128 v[192:195], v154 offset:50176
	ds_read_b128 v[196:199], v154 offset:51200
	ds_read_b128 v[200:203], v154 offset:52224
	ds_read_b128 v[204:207], v154 offset:53248
	ds_read_b128 v[208:211], v154 offset:54272
	ds_read_b128 v[212:215], v154 offset:55296
	ds_read_b128 v[216:219], v154 offset:56320
	global_load_lds_dwordx4 v[150:151], off
	s_add_i32 m0, s59, 0x2000
	s_add_u32 s82, s82, 0x40080
	v_lshl_add_u64 v[150:151], v[220:221], 0, s[68:69]
	s_addc_u32 s83, s83, 0
	s_add_i32 s59, s73, s88
	global_load_lds_dwordx4 v[150:151], off
	v_lshl_add_u64 v[150:151], s[82:83], 0, v[132:133]
	s_mov_b32 m0, s59
	s_nop 0
	global_load_lds_dwordx4 v[150:151], off
	v_lshl_add_u64 v[150:151], s[82:83], 0, v[136:137]
	s_add_i32 m0, s59, 0x2000
	s_nop 0
	global_load_lds_dwordx4 v[150:151], off
	v_lshl_add_u64 v[150:151], v[222:223], 0, s[68:69]
	s_mov_b32 m0, s93
	s_nop 0
	global_load_lds_dwordx4 v[150:151], off
	v_lshl_add_u64 v[150:151], v[224:225], 0, s[68:69]
	s_mov_b32 m0, s94
	s_nop 0
	global_load_lds_dwordx4 v[150:151], off
	s_waitcnt vmcnt(8)
	s_waitcnt lgkmcnt(0)
	s_barrier
	s_waitcnt lgkmcnt(0)
	v_mfma_f32_16x16x32_bf16 v[62:65], v[156:159], v[188:191], v[62:65]
	v_mfma_f32_16x16x32_bf16 v[58:61], v[164:167], v[188:191], v[58:61]
	v_mfma_f32_16x16x32_bf16 v[50:53], v[164:167], v[196:199], v[50:53]
	v_mfma_f32_16x16x32_bf16 v[54:57], v[156:159], v[196:199], v[54:57]
	v_mfma_f32_16x16x32_bf16 v[46:49], v[156:159], v[204:207], v[46:49]
	v_mfma_f32_16x16x32_bf16 v[42:45], v[164:167], v[204:207], v[42:45]
	v_mfma_f32_16x16x32_bf16 v[34:37], v[164:167], v[212:215], v[34:37]
	v_mfma_f32_16x16x32_bf16 v[38:41], v[156:159], v[212:215], v[38:41]
	v_mfma_f32_16x16x32_bf16 v[62:65], v[160:163], v[192:195], v[62:65]
	v_mfma_f32_16x16x32_bf16 v[58:61], v[168:171], v[192:195], v[58:61]
	v_mfma_f32_16x16x32_bf16 v[50:53], v[168:171], v[200:203], v[50:53]
	v_mfma_f32_16x16x32_bf16 v[54:57], v[160:163], v[200:203], v[54:57]
	v_mfma_f32_16x16x32_bf16 v[46:49], v[160:163], v[208:211], v[46:49]
	v_mfma_f32_16x16x32_bf16 v[42:45], v[168:171], v[208:211], v[42:45]
	v_mfma_f32_16x16x32_bf16 v[34:37], v[168:171], v[216:219], v[34:37]
	v_mfma_f32_16x16x32_bf16 v[38:41], v[160:163], v[216:219], v[38:41]
	v_mfma_f32_16x16x32_bf16 v[30:33], v[172:175], v[188:191], v[30:33]
	v_mfma_f32_16x16x32_bf16 v[26:29], v[180:183], v[188:191], v[26:29]
	v_mfma_f32_16x16x32_bf16 v[18:21], v[180:183], v[196:199], v[18:21]
	v_mfma_f32_16x16x32_bf16 v[22:25], v[172:175], v[196:199], v[22:25]
	v_mfma_f32_16x16x32_bf16 v[14:17], v[172:175], v[204:207], v[14:17]
	v_mfma_f32_16x16x32_bf16 v[10:13], v[180:183], v[204:207], v[10:13]
	v_mfma_f32_16x16x32_bf16 v[2:5], v[180:183], v[212:215], v[2:5]
	v_mfma_f32_16x16x32_bf16 v[6:9], v[172:175], v[212:215], v[6:9]
	v_mfma_f32_16x16x32_bf16 v[30:33], v[176:179], v[192:195], v[30:33]
	v_mfma_f32_16x16x32_bf16 v[26:29], v[184:187], v[192:195], v[26:29]
	v_mfma_f32_16x16x32_bf16 v[18:21], v[184:187], v[200:203], v[18:21]
	v_mfma_f32_16x16x32_bf16 v[22:25], v[176:179], v[200:203], v[22:25]
	v_mfma_f32_16x16x32_bf16 v[14:17], v[176:179], v[208:211], v[14:17]
	v_mfma_f32_16x16x32_bf16 v[10:13], v[184:187], v[208:211], v[10:13]
	v_mfma_f32_16x16x32_bf16 v[2:5], v[184:187], v[216:219], v[2:5]
	v_mfma_f32_16x16x32_bf16 v[6:9], v[176:179], v[216:219], v[6:9]
	s_barrier
	s_add_i32 s58, s58, 2
	s_add_u32 s80, s80, 0x100
	s_addc_u32 s81, s81, 0
	s_cmp_gt_u32 s58, 13
	s_cbranch_scc0 .LBB0_413
	s_branch .Lmy_kexit_1
.LBB0_413:
	v_add_u32_e32 v150, s95, v152
	ds_read_b128 v[156:159], v150
	ds_read_b128 v[160:163], v150 offset:1024
	ds_read_b128 v[164:167], v150 offset:2048
	ds_read_b128 v[168:171], v150 offset:3072
	v_add_u32_e32 v150, s96, v152
	s_add_u32 s59, s18, s80
	ds_read_b128 v[172:175], v150
	ds_read_b128 v[176:179], v150 offset:1024
	ds_read_b128 v[180:183], v150 offset:2048
	ds_read_b128 v[184:187], v150 offset:3072
	s_addc_u32 s73, s19, s81
	s_add_u32 s59, s59, 0x100
	s_addc_u32 s73, s73, 0
	s_add_u32 s75, s53, s80
	s_addc_u32 s82, s54, s81
	s_cmpk_eq_i32 s80, 0x700
	s_cselect_b32 s85, s40, s73
	s_cselect_b32 s84, s55, s59
	s_cselect_b32 s83, s56, s82
	s_cselect_b32 s82, s57, s75
	v_lshl_add_u64 v[150:151], v[146:147], 0, s[80:81]
	s_add_i32 m0, s15, 0xc000
	ds_read_b128 v[188:191], v154
	ds_read_b128 v[192:195], v154 offset:1024
	ds_read_b128 v[196:199], v154 offset:2048
	ds_read_b128 v[200:203], v154 offset:3072
	ds_read_b128 v[204:207], v154 offset:4096
	ds_read_b128 v[208:211], v154 offset:5120
	ds_read_b128 v[212:215], v154 offset:6144
	ds_read_b128 v[216:219], v154 offset:7168
	global_load_lds_dwordx4 v[150:151], off
	v_lshl_add_u64 v[150:151], v[148:149], 0, s[80:81]
	s_add_i32 m0, s15, 0xe000
	s_nop 0
	global_load_lds_dwordx4 v[150:151], off
	s_waitcnt vmcnt(8)
	s_waitcnt lgkmcnt(0)
	s_barrier
; #define PG8_STAGEA(bufoff, gbase) PG8_STAGE_(bufoff, gbase, voffA)
; #define PG8_STAGEB(bufoff, gbase) PG8_STAGE_(bufoff, gbase, voffB)
; #define PG8_LDA(dst, b, h) do { _Pragma("unroll") for (int m = 0; m < 4; ++m) _Pragma("unroll") for (int k = 0; k < 2; ++k) dst[m][k] = *(const LAS bf16x8*)(lds + PG8_SA(b, h) + aoff + m * 2048 + k * 1024); } while (0)
; #define PG8_LDB(dst, b, h) do { _Pragma("unroll") for (int n = 0; n < 2; ++n) _Pragma("unroll") for (int k = 0; k < 2; ++k) dst[n][k] = *(const LAS bf16x8*)(lds + PG8_SB(b, h) + boff + n * 2048 + k * 1024); } while (0)
; #define PG8_MMA(ai, bj, At, Bt_) do { __builtin_amdgcn_s_setprio(1); _Pragma("unroll") for (int m = 0; m < 4; ++m) _Pragma("unroll") for (int n = 0; n < 2; ++n) _Pragma("unroll") for (int k = 0; k < 2; ++k) \
;         acc[ai][bj][m][n] = __builtin_amdgcn_mfma_f32_16x16x32_bf16(Bt_[n][k], At[m][k], acc[ai][bj][m][n], 0, 0, 0); __builtin_amdgcn_s_setprio(0); } while (0)
; #define PG8_WAIT_V(n) asm volatile("s_waitcnt vmcnt(" #n ")" ::: "memory")
; #define PG8_WAIT_L(n) asm volatile("s_waitcnt lgkmcnt(" #n ")" ::: "memory")
; #define PG8_BAR __builtin_amdgcn_s_barrier()
; #define PG8_SCHED __builtin_amdgcn_sched_barrier(0)
; template <int EK, int SK = -1>
; __device__ __forceinline__ void gemm_phase(LAS unsigned char* lds, const bf16_t* A, const bf16_t* Bt, int nM, int N, int K, const EpiArgs& E) {
;     ...
;             PG8_LDB(B0, 0, 0); PG8_LDB(B1, 0, 1); PG8_SCHED; PG8_LDA(At, 0, 0); PG8_STAGEA(PG8_SA(1, 1), a1 + hstep);
;             PG8_WAIT_V(8); PG8_WAIT_L(0); PG8_BAR; PG8_MMA(0, 0, At, B0); PG8_MMA(0, 1, At, B1); PG8_BAR; PG8_SCHED;
;             PG8_LDA(At, 0, 1); PG8_STAGEB(PG8_SB(0, 0), b2); PG8_STAGEB(PG8_SB(0, 1), b2 + hstep); PG8_STAGEA(PG8_SA(0, 0), a2);
;             PG8_WAIT_V(8); PG8_WAIT_L(0); PG8_BAR; PG8_MMA(1, 0, At, B0); PG8_MMA(1, 1, At, B1); PG8_BAR; PG8_SCHED;
	s_waitcnt lgkmcnt(0)
	v_mfma_f32_16x16x32_bf16 v[126:129], v[156:159], v[188:191], v[126:129]
	v_mfma_f32_16x16x32_bf16 v[122:125], v[164:167], v[188:191], v[122:125]
	v_mfma_f32_16x16x32_bf16 v[114:117], v[164:167], v[196:199], v[114:117]
	v_mfma_f32_16x16x32_bf16 v[118:121], v[156:159], v[196:199], v[118:121]
	v_mfma_f32_16x16x32_bf16 v[110:113], v[156:159], v[204:207], v[110:113]
	v_mfma_f32_16x16x32_bf16 v[106:109], v[164:167], v[204:207], v[106:109]
	v_mfma_f32_16x16x32_bf16 v[98:101], v[164:167], v[212:215], v[98:101]
	v_mfma_f32_16x16x32_bf16 v[102:105], v[156:159], v[212:215], v[102:105]
	v_mfma_f32_16x16x32_bf16 v[126:129], v[160:163], v[192:195], v[126:129]
	v_mfma_f32_16x16x32_bf16 v[122:125], v[168:171], v[192:195], v[122:125]
	v_mfma_f32_16x16x32_bf16 v[114:117], v[168:171], v[200:203], v[114:117]
	v_mfma_f32_16x16x32_bf16 v[118:121], v[160:163], v[200:203], v[118:121]
	v_mfma_f32_16x16x32_bf16 v[110:113], v[160:163], v[208:211], v[110:113]
	v_mfma_f32_16x16x32_bf16 v[106:109], v[168:171], v[208:211], v[106:109]
	v_mfma_f32_16x16x32_bf16 v[98:101], v[168:171], v[216:219], v[98:101]
	v_mfma_f32_16x16x32_bf16 v[102:105], v[160:163], v[216:219], v[102:105]
	v_mfma_f32_16x16x32_bf16 v[94:97], v[172:175], v[188:191], v[94:97]
	v_mfma_f32_16x16x32_bf16 v[90:93], v[180:183], v[188:191], v[90:93]
	v_mfma_f32_16x16x32_bf16 v[82:85], v[180:183], v[196:199], v[82:85]
	v_mfma_f32_16x16x32_bf16 v[86:89], v[172:175], v[196:199], v[86:89]
	v_mfma_f32_16x16x32_bf16 v[78:81], v[172:175], v[204:207], v[78:81]
	v_mfma_f32_16x16x32_bf16 v[74:77], v[180:183], v[204:207], v[74:77]
	v_mfma_f32_16x16x32_bf16 v[66:69], v[180:183], v[212:215], v[66:69]
	v_mfma_f32_16x16x32_bf16 v[70:73], v[172:175], v[212:215], v[70:73]
	v_mfma_f32_16x16x32_bf16 v[94:97], v[176:179], v[192:195], v[94:97]
	v_mfma_f32_16x16x32_bf16 v[90:93], v[184:187], v[192:195], v[90:93]
	v_mfma_f32_16x16x32_bf16 v[82:85], v[184:187], v[200:203], v[82:85]
	v_mfma_f32_16x16x32_bf16 v[86:89], v[176:179], v[200:203], v[86:89]
	v_mfma_f32_16x16x32_bf16 v[78:81], v[176:179], v[208:211], v[78:81]
	v_mfma_f32_16x16x32_bf16 v[74:77], v[184:187], v[208:211], v[74:77]
	v_mfma_f32_16x16x32_bf16 v[66:69], v[184:187], v[216:219], v[66:69]
	v_mfma_f32_16x16x32_bf16 v[70:73], v[176:179], v[216:219], v[70:73]
	s_barrier
	s_add_i32 s59, s95, s88
	v_lshl_add_u64 v[150:151], s[82:83], 0, v[132:133]
	s_mov_b32 m0, s59
	ds_read_b128 v[188:191], v154 offset:16384
	ds_read_b128 v[192:195], v154 offset:17408
	ds_read_b128 v[196:199], v154 offset:18432
	ds_read_b128 v[200:203], v154 offset:19456
	ds_read_b128 v[204:207], v154 offset:20480
	ds_read_b128 v[208:211], v154 offset:21504
	ds_read_b128 v[212:215], v154 offset:22528
	ds_read_b128 v[216:219], v154 offset:23552
	global_load_lds_dwordx4 v[150:151], off
	s_add_i32 m0, s59, 0x2000
	s_add_u32 vcc_lo, s82, 0x40000
	v_lshl_add_u64 v[220:221], s[82:83], 0, v[136:137]
	s_addc_u32 vcc_hi, s83, 0
	s_add_i32 s59, s96, s88
	global_load_lds_dwordx4 v[220:221], off
	v_lshl_add_u64 v[222:223], vcc, 0, v[132:133]
	s_mov_b32 m0, s59
	v_lshl_add_u64 v[224:225], s[84:85], 0, v[134:135]
	global_load_lds_dwordx4 v[222:223], off
	v_lshl_add_u64 v[222:223], vcc, 0, v[136:137]
	s_add_i32 m0, s59, 0x2000
	s_nop 0
	global_load_lds_dwordx4 v[222:223], off
	v_lshl_add_u64 v[222:223], s[84:85], 0, v[130:131]
	s_mov_b32 m0, s15
	s_nop 0
	global_load_lds_dwordx4 v[222:223], off
	s_mov_b32 m0, s17
	s_nop 0
	global_load_lds_dwordx4 v[224:225], off
	s_waitcnt vmcnt(8)
	s_waitcnt lgkmcnt(0)
	s_barrier
	s_waitcnt lgkmcnt(0)
	v_mfma_f32_16x16x32_bf16 v[62:65], v[156:159], v[188:191], v[62:65]
	v_mfma_f32_16x16x32_bf16 v[58:61], v[164:167], v[188:191], v[58:61]
	v_mfma_f32_16x16x32_bf16 v[50:53], v[164:167], v[196:199], v[50:53]
	v_mfma_f32_16x16x32_bf16 v[54:57], v[156:159], v[196:199], v[54:57]
	v_mfma_f32_16x16x32_bf16 v[46:49], v[156:159], v[204:207], v[46:49]
	v_mfma_f32_16x16x32_bf16 v[42:45], v[164:167], v[204:207], v[42:45]
	v_mfma_f32_16x16x32_bf16 v[34:37], v[164:167], v[212:215], v[34:37]
	v_mfma_f32_16x16x32_bf16 v[38:41], v[156:159], v[212:215], v[38:41]
	v_mfma_f32_16x16x32_bf16 v[62:65], v[160:163], v[192:195], v[62:65]
	v_mfma_f32_16x16x32_bf16 v[58:61], v[168:171], v[192:195], v[58:61]
	v_mfma_f32_16x16x32_bf16 v[50:53], v[168:171], v[200:203], v[50:53]
	v_mfma_f32_16x16x32_bf16 v[54:57], v[160:163], v[200:203], v[54:57]
	v_mfma_f32_16x16x32_bf16 v[46:49], v[160:163], v[208:211], v[46:49]
	v_mfma_f32_16x16x32_bf16 v[42:45], v[168:171], v[208:211], v[42:45]
	v_mfma_f32_16x16x32_bf16 v[34:37], v[168:171], v[216:219], v[34:37]
	v_mfma_f32_16x16x32_bf16 v[38:41], v[160:163], v[216:219], v[38:41]
	v_mfma_f32_16x16x32_bf16 v[30:33], v[172:175], v[188:191], v[30:33]
	v_mfma_f32_16x16x32_bf16 v[26:29], v[180:183], v[188:191], v[26:29]
	v_mfma_f32_16x16x32_bf16 v[18:21], v[180:183], v[196:199], v[18:21]
	v_mfma_f32_16x16x32_bf16 v[22:25], v[172:175], v[196:199], v[22:25]
	v_mfma_f32_16x16x32_bf16 v[14:17], v[172:175], v[204:207], v[14:17]
	v_mfma_f32_16x16x32_bf16 v[10:13], v[180:183], v[204:207], v[10:13]
	v_mfma_f32_16x16x32_bf16 v[2:5], v[180:183], v[212:215], v[2:5]
	v_mfma_f32_16x16x32_bf16 v[6:9], v[172:175], v[212:215], v[6:9]
	v_mfma_f32_16x16x32_bf16 v[30:33], v[176:179], v[192:195], v[30:33]
	v_mfma_f32_16x16x32_bf16 v[26:29], v[184:187], v[192:195], v[26:29]
	v_mfma_f32_16x16x32_bf16 v[18:21], v[184:187], v[200:203], v[18:21]
	v_mfma_f32_16x16x32_bf16 v[22:25], v[176:179], v[200:203], v[22:25]
	v_mfma_f32_16x16x32_bf16 v[14:17], v[176:179], v[208:211], v[14:17]
	v_mfma_f32_16x16x32_bf16 v[10:13], v[184:187], v[208:211], v[10:13]
	v_mfma_f32_16x16x32_bf16 v[2:5], v[184:187], v[216:219], v[2:5]
	v_mfma_f32_16x16x32_bf16 v[6:9], v[176:179], v[216:219], v[6:9]
	s_barrier
; #define PG8_STAGEA(bufoff, gbase) PG8_STAGE_(bufoff, gbase, voffA)
; #define PG8_STAGEB(bufoff, gbase) PG8_STAGE_(bufoff, gbase, voffB)
; #define PG8_LDA(dst, b, h) do { _Pragma("unroll") for (int m = 0; m < 4; ++m) _Pragma("unroll") for (int k = 0; k < 2; ++k) dst[m][k] = *(const LAS bf16x8*)(lds + PG8_SA(b, h) + aoff + m * 2048 + k * 1024); } while (0)
; #define PG8_LDB(dst, b, h) do { _Pragma("unroll") for (int n = 0; n < 2; ++n) _Pragma("unroll") for (int k = 0; k < 2; ++k) dst[n][k] = *(const LAS bf16x8*)(lds + PG8_SB(b, h) + boff + n * 2048 + k * 1024); } while (0)
; #define PG8_MMA(ai, bj, At, Bt_) do { __builtin_amdgcn_s_setprio(1); _Pragma("unroll") for (int m = 0; m < 4; ++m) _Pragma("unroll") for (int n = 0; n < 2; ++n) _Pragma("unroll") for (int k = 0; k < 2; ++k) \
;         acc[ai][bj][m][n] = __builtin_amdgcn_mfma_f32_16x16x32_bf16(Bt_[n][k], At[m][k], acc[ai][bj][m][n], 0, 0, 0); __builtin_amdgcn_s_setprio(0); } while (0)
; #define PG8_WAIT_V(n) asm volatile("s_waitcnt vmcnt(" #n ")" ::: "memory")
; #define PG8_WAIT_L(n) asm volatile("s_waitcnt lgkmcnt(" #n ")" ::: "memory")
; #define PG8_BAR __builtin_amdgcn_s_barrier()
; #define PG8_SCHED __builtin_amdgcn_sched_barrier(0)
; template <int EK, int SK = -1>
; __device__ __forceinline__ void gemm_phase(LAS unsigned char* lds, const bf16_t* A, const bf16_t* Bt, int nM, int N, int K, const EpiArgs& E) {
;     ...
;             PG8_LDB(B0, 1, 0); PG8_LDB(B1, 1, 1); PG8_SCHED; PG8_LDA(At, 1, 0); PG8_STAGEA(PG8_SA(0, 1), a2 + hstep);
;             PG8_WAIT_V(8); PG8_WAIT_L(0); PG8_BAR; PG8_MMA(0, 0, At, B0); PG8_MMA(0, 1, At, B1); PG8_BAR; PG8_SCHED;
;             PG8_LDA(At, 1, 1); PG8_STAGEB(PG8_SB(1, 0), b3); PG8_STAGEB(PG8_SB(1, 1), b3 + hstep); PG8_STAGEA(PG8_SA(1, 0), a3);
;             PG8_WAIT_V(8); PG8_WAIT_L(0); PG8_BAR; PG8_MMA(1, 0, At, B0); PG8_MMA(1, 1, At, B1); PG8_BAR; PG8_SCHED;
;         }
	s_add_i32 s59, 0, 0x18000
	s_add_i32 s73, 0, 0x1c000
	v_add_u32_e32 v168, s59, v152
	v_add_u32_e32 v184, s73, v152
	ds_read_b128 v[156:159], v168
	ds_read_b128 v[160:163], v168 offset:1024
	ds_read_b128 v[164:167], v168 offset:2048
	ds_read_b128 v[168:171], v168 offset:3072
	ds_read_b128 v[172:175], v184
	ds_read_b128 v[176:179], v184 offset:1024
	ds_read_b128 v[180:183], v184 offset:2048
	ds_read_b128 v[184:187], v184 offset:3072
	s_add_u32 s84, s84, 0x40000
	s_addc_u32 s85, s85, 0
	s_mov_b32 m0, s89
	v_lshl_add_u64 v[226:227], s[84:85], 0, v[130:131]
	ds_read_b128 v[188:191], v154 offset:32768
	ds_read_b128 v[192:195], v154 offset:33792
	ds_read_b128 v[196:199], v154 offset:34816
	ds_read_b128 v[200:203], v154 offset:35840
	ds_read_b128 v[204:207], v154 offset:36864
	ds_read_b128 v[208:211], v154 offset:37888
	ds_read_b128 v[212:215], v154 offset:38912
	ds_read_b128 v[216:219], v154 offset:39936
	global_load_lds_dwordx4 v[226:227], off
	v_lshl_add_u64 v[226:227], s[84:85], 0, v[134:135]
	s_mov_b32 m0, s90
	s_nop 0
	global_load_lds_dwordx4 v[226:227], off
	s_waitcnt vmcnt(8)
	s_waitcnt lgkmcnt(0)
	s_barrier
	s_waitcnt lgkmcnt(0)
	v_mfma_f32_16x16x32_bf16 v[126:129], v[156:159], v[188:191], v[126:129]
	v_mfma_f32_16x16x32_bf16 v[122:125], v[164:167], v[188:191], v[122:125]
	v_mfma_f32_16x16x32_bf16 v[114:117], v[164:167], v[196:199], v[114:117]
	v_mfma_f32_16x16x32_bf16 v[118:121], v[156:159], v[196:199], v[118:121]
	v_mfma_f32_16x16x32_bf16 v[110:113], v[156:159], v[204:207], v[110:113]
	v_mfma_f32_16x16x32_bf16 v[106:109], v[164:167], v[204:207], v[106:109]
	v_mfma_f32_16x16x32_bf16 v[98:101], v[164:167], v[212:215], v[98:101]
	v_mfma_f32_16x16x32_bf16 v[102:105], v[156:159], v[212:215], v[102:105]
	v_mfma_f32_16x16x32_bf16 v[126:129], v[160:163], v[192:195], v[126:129]
	v_mfma_f32_16x16x32_bf16 v[122:125], v[168:171], v[192:195], v[122:125]
	v_mfma_f32_16x16x32_bf16 v[114:117], v[168:171], v[200:203], v[114:117]
	v_mfma_f32_16x16x32_bf16 v[118:121], v[160:163], v[200:203], v[118:121]
	v_mfma_f32_16x16x32_bf16 v[110:113], v[160:163], v[208:211], v[110:113]
	v_mfma_f32_16x16x32_bf16 v[106:109], v[168:171], v[208:211], v[106:109]
	v_mfma_f32_16x16x32_bf16 v[98:101], v[168:171], v[216:219], v[98:101]
	v_mfma_f32_16x16x32_bf16 v[102:105], v[160:163], v[216:219], v[102:105]
	v_mfma_f32_16x16x32_bf16 v[94:97], v[172:175], v[188:191], v[94:97]
	v_mfma_f32_16x16x32_bf16 v[90:93], v[180:183], v[188:191], v[90:93]
	v_mfma_f32_16x16x32_bf16 v[82:85], v[180:183], v[196:199], v[82:85]
	v_mfma_f32_16x16x32_bf16 v[86:89], v[172:175], v[196:199], v[86:89]
	v_mfma_f32_16x16x32_bf16 v[78:81], v[172:175], v[204:207], v[78:81]
	v_mfma_f32_16x16x32_bf16 v[74:77], v[180:183], v[204:207], v[74:77]
	v_mfma_f32_16x16x32_bf16 v[66:69], v[180:183], v[212:215], v[66:69]
	v_mfma_f32_16x16x32_bf16 v[70:73], v[172:175], v[212:215], v[70:73]
	v_mfma_f32_16x16x32_bf16 v[94:97], v[176:179], v[192:195], v[94:97]
	v_mfma_f32_16x16x32_bf16 v[90:93], v[184:187], v[192:195], v[90:93]
	v_mfma_f32_16x16x32_bf16 v[82:85], v[184:187], v[200:203], v[82:85]
	v_mfma_f32_16x16x32_bf16 v[86:89], v[176:179], v[200:203], v[86:89]
	v_mfma_f32_16x16x32_bf16 v[78:81], v[176:179], v[208:211], v[78:81]
	v_mfma_f32_16x16x32_bf16 v[74:77], v[184:187], v[208:211], v[74:77]
	v_mfma_f32_16x16x32_bf16 v[66:69], v[184:187], v[216:219], v[66:69]
	v_mfma_f32_16x16x32_bf16 v[70:73], v[176:179], v[216:219], v[70:73]
	s_barrier
	s_add_i32 s59, s59, s88
	v_lshl_add_u64 v[150:151], v[150:151], 0, s[68:69]
	s_mov_b32 m0, s59
	ds_read_b128 v[188:191], v154 offset:49152
	ds_read_b128 v[192:195], v154 offset:50176
	ds_read_b128 v[196:199], v154 offset:51200
	ds_read_b128 v[200:203], v154 offset:52224
	ds_read_b128 v[204:207], v154 offset:53248
	ds_read_b128 v[208:211], v154 offset:54272
	ds_read_b128 v[212:215], v154 offset:55296
	ds_read_b128 v[216:219], v154 offset:56320
	global_load_lds_dwordx4 v[150:151], off
	s_add_i32 m0, s59, 0x2000
	s_add_u32 s82, s82, 0x40080
	v_lshl_add_u64 v[150:151], v[220:221], 0, s[68:69]
	s_addc_u32 s83, s83, 0
	s_add_i32 s59, s73, s88
	global_load_lds_dwordx4 v[150:151], off
	v_lshl_add_u64 v[150:151], s[82:83], 0, v[132:133]
	s_mov_b32 m0, s59
	s_nop 0
	global_load_lds_dwordx4 v[150:151], off
	v_lshl_add_u64 v[150:151], s[82:83], 0, v[136:137]
	s_add_i32 m0, s59, 0x2000
	s_nop 0
	global_load_lds_dwordx4 v[150:151], off
	v_lshl_add_u64 v[150:151], v[222:223], 0, s[68:69]
	s_mov_b32 m0, s93
	s_nop 0
	global_load_lds_dwordx4 v[150:151], off
	v_lshl_add_u64 v[150:151], v[224:225], 0, s[68:69]
	s_mov_b32 m0, s94
	s_nop 0
	global_load_lds_dwordx4 v[150:151], off
	s_waitcnt vmcnt(8)
	s_waitcnt lgkmcnt(0)
	s_barrier
	s_waitcnt lgkmcnt(0)
	v_mfma_f32_16x16x32_bf16 v[62:65], v[156:159], v[188:191], v[62:65]
	v_mfma_f32_16x16x32_bf16 v[58:61], v[164:167], v[188:191], v[58:61]
	v_mfma_f32_16x16x32_bf16 v[50:53], v[164:167], v[196:199], v[50:53]
	v_mfma_f32_16x16x32_bf16 v[54:57], v[156:159], v[196:199], v[54:57]
	v_mfma_f32_16x16x32_bf16 v[46:49], v[156:159], v[204:207], v[46:49]
	v_mfma_f32_16x16x32_bf16 v[42:45], v[164:167], v[204:207], v[42:45]
	v_mfma_f32_16x16x32_bf16 v[34:37], v[164:167], v[212:215], v[34:37]
	v_mfma_f32_16x16x32_bf16 v[38:41], v[156:159], v[212:215], v[38:41]
	v_mfma_f32_16x16x32_bf16 v[62:65], v[160:163], v[192:195], v[62:65]
	v_mfma_f32_16x16x32_bf16 v[58:61], v[168:171], v[192:195], v[58:61]
	v_mfma_f32_16x16x32_bf16 v[50:53], v[168:171], v[200:203], v[50:53]
	v_mfma_f32_16x16x32_bf16 v[54:57], v[160:163], v[200:203], v[54:57]
	v_mfma_f32_16x16x32_bf16 v[46:49], v[160:163], v[208:211], v[46:49]
	v_mfma_f32_16x16x32_bf16 v[42:45], v[168:171], v[208:211], v[42:45]
	v_mfma_f32_16x16x32_bf16 v[34:37], v[168:171], v[216:219], v[34:37]
	v_mfma_f32_16x16x32_bf16 v[38:41], v[160:163], v[216:219], v[38:41]
	v_mfma_f32_16x16x32_bf16 v[30:33], v[172:175], v[188:191], v[30:33]
	v_mfma_f32_16x16x32_bf16 v[26:29], v[180:183], v[188:191], v[26:29]
	v_mfma_f32_16x16x32_bf16 v[18:21], v[180:183], v[196:199], v[18:21]
	v_mfma_f32_16x16x32_bf16 v[22:25], v[172:175], v[196:199], v[22:25]
	v_mfma_f32_16x16x32_bf16 v[14:17], v[172:175], v[204:207], v[14:17]
	v_mfma_f32_16x16x32_bf16 v[10:13], v[180:183], v[204:207], v[10:13]
	v_mfma_f32_16x16x32_bf16 v[2:5], v[180:183], v[212:215], v[2:5]
	v_mfma_f32_16x16x32_bf16 v[6:9], v[172:175], v[212:215], v[6:9]
	v_mfma_f32_16x16x32_bf16 v[30:33], v[176:179], v[192:195], v[30:33]
	v_mfma_f32_16x16x32_bf16 v[26:29], v[184:187], v[192:195], v[26:29]
	v_mfma_f32_16x16x32_bf16 v[18:21], v[184:187], v[200:203], v[18:21]
	v_mfma_f32_16x16x32_bf16 v[22:25], v[176:179], v[200:203], v[22:25]
	v_mfma_f32_16x16x32_bf16 v[14:17], v[176:179], v[208:211], v[14:17]
	v_mfma_f32_16x16x32_bf16 v[10:13], v[184:187], v[208:211], v[10:13]
	v_mfma_f32_16x16x32_bf16 v[2:5], v[184:187], v[216:219], v[2:5]
	v_mfma_f32_16x16x32_bf16 v[6:9], v[176:179], v[216:219], v[6:9]
	s_barrier
	s_add_i32 s58, s58, 2
	s_add_u32 s80, s80, 0x100
	s_addc_u32 s81, s81, 0
	s_cmp_gt_u32 s58, 13
	s_cbranch_scc0 .LBB0_413

; #define PG8_STAGEA(bufoff, gbase) PG8_STAGE_(bufoff, gbase, voffA)
; #define PG8_LDA(dst, b, h) do { _Pragma("unroll") for (int m = 0; m < 4; ++m) _Pragma("unroll") for (int k = 0; k < 2; ++k) dst[m][k] = *(const LAS bf16x8*)(lds + PG8_SA(b, h) + aoff + m * 2048 + k * 1024); } while (0)
; #define PG8_LDB(dst, b, h) do { _Pragma("unroll") for (int n = 0; n < 2; ++n) _Pragma("unroll") for (int k = 0; k < 2; ++k) dst[n][k] = *(const LAS bf16x8*)(lds + PG8_SB(b, h) + boff + n * 2048 + k * 1024); } while (0)
; #define PG8_MMA(ai, bj, At, Bt_) do { __builtin_amdgcn_s_setprio(1); _Pragma("unroll") for (int m = 0; m < 4; ++m) _Pragma("unroll") for (int n = 0; n < 2; ++n) _Pragma("unroll") for (int k = 0; k < 2; ++k) \
;         acc[ai][bj][m][n] = __builtin_amdgcn_mfma_f32_16x16x32_bf16(Bt_[n][k], At[m][k], acc[ai][bj][m][n], 0, 0, 0); __builtin_amdgcn_s_setprio(0); } while (0)
; #define PG8_WAIT_V(n) asm volatile("s_waitcnt vmcnt(" #n ")" ::: "memory")
; #define PG8_WAIT_L(n) asm volatile("s_waitcnt lgkmcnt(" #n ")" ::: "memory")
; #define PG8_BAR __builtin_amdgcn_s_barrier()
; #define PG8_SCHED __builtin_amdgcn_sched_barrier(0)
; template <int EK, int SK = -1>
; __device__ __forceinline__ void gemm_phase(LAS unsigned char* lds, const bf16_t* A, const bf16_t* Bt, int nM, int N, int K, const EpiArgs& E) {
;     ...
;         const bool has_next = S.next(ui + 1, nxt);
;         const char* nA = has_next ? (const char*)A + (size_t)nxt.pm * tstep : cA; const char* nB = has_next ? (const char*)Bt + (size_t)nxt.pn * tstep : cB;
;         for (int t = 0; t < nt; t += 2) {
;             const bool last = (t == nt - 2);
;             const char* a1 = cA + (size_t)(t + 1) * kstep;
;             const char* a2 = last ? nA : cA + (size_t)(t + 2) * kstep; const char* b2 = last ? nB : cB + (size_t)(t + 2) * kstep;
;             const char* a3 = a2 + kstep; const char* b3 = b2 + kstep;
;             PG8_LDB(B0, 0, 0); PG8_LDB(B1, 0, 1); PG8_SCHED; PG8_LDA(At, 0, 0); PG8_STAGEA(PG8_SA(1, 1), a1 + hstep);
;             PG8_WAIT_V(8); PG8_WAIT_L(0); PG8_BAR; PG8_MMA(0, 0, At, B0); PG8_MMA(0, 1, At, B1); PG8_BAR; PG8_SCHED;
.LBB0_537:
	s_add_u32 s54, s74, 0x100
	s_addc_u32 s55, s75, 0
	s_ashr_i32 s69, s68, 31
	s_lshl_b64 s[56:57], s[68:69], 19
	s_add_u32 s72, s62, s56
	s_addc_u32 s73, s63, s57
	s_and_b64 s[56:57], s[6:7], exec
	s_cselect_b32 s56, s73, s39
	s_cselect_b32 s57, s72, s38
	s_ashr_i32 s41, s40, 31
	s_lshl_b64 s[58:59], s[40:41], 19
	s_add_u32 s70, s81, s58
	s_addc_u32 s71, s82, s59
	s_and_b64 s[58:59], s[6:7], exec
	s_cselect_b32 s41, s71, s75
	s_cselect_b32 s58, s70, s74
	v_lshl_add_u64 v[146:147], s[38:39], 0, v[138:139]
	v_lshl_add_u64 v[148:149], s[38:39], 0, v[140:141]
	s_mov_b32 s59, -2
	s_mov_b64 s[74:75], 0
	v_add_u32_e32 v154, s88, v159
	ds_read_b128 v[150:153], v154
	ds_read_b128 v[164:167], v154 offset:1024
	ds_read_b128 v[168:171], v154 offset:2048
	ds_read_b128 v[172:175], v154 offset:3072
	v_add_u32_e32 v154, s89, v159
	s_add_u32 s69, s38, s74
	ds_read_b128 v[176:179], v154
	ds_read_b128 v[180:183], v154 offset:1024
	ds_read_b128 v[184:187], v154 offset:2048
	ds_read_b128 v[188:191], v154 offset:3072
	s_addc_u32 s76, s39, s75
	s_add_u32 s69, s69, 0x100
	s_addc_u32 s76, s76, 0
	s_add_u32 s91, s54, s74
	s_addc_u32 s77, s55, s75
	s_cmpk_eq_i32 s74, 0x700
	s_cselect_b32 s79, s56, s76
	s_cselect_b32 s78, s57, s69
	s_cselect_b32 s77, s41, s77
	s_cselect_b32 s76, s58, s91
	v_lshl_add_u64 v[154:155], v[146:147], 0, s[74:75]
	s_add_i32 m0, s15, 0xc000
	ds_read_b128 v[192:195], v162
	ds_read_b128 v[196:199], v162 offset:1024
	ds_read_b128 v[200:203], v162 offset:2048
	ds_read_b128 v[204:207], v162 offset:3072
	ds_read_b128 v[208:211], v162 offset:4096
	ds_read_b128 v[212:215], v162 offset:5120
	ds_read_b128 v[216:219], v162 offset:6144
	ds_read_b128 v[220:223], v162 offset:7168
	global_load_lds_dwordx4 v[154:155], off
	v_lshl_add_u64 v[154:155], v[148:149], 0, s[74:75]
	s_add_i32 m0, s15, 0xe000
	s_nop 0
	global_load_lds_dwordx4 v[154:155], off
	s_waitcnt vmcnt(8)
	s_waitcnt lgkmcnt(0)
	s_barrier
	s_waitcnt lgkmcnt(0)
	v_mfma_f32_16x16x32_bf16 v[110:113], v[150:153], v[192:195], 0
	v_mfma_f32_16x16x32_bf16 v[106:109], v[168:171], v[192:195], 0
	v_mfma_f32_16x16x32_bf16 v[98:101], v[168:171], v[200:203], 0
	v_mfma_f32_16x16x32_bf16 v[102:105], v[150:153], v[200:203], 0
	v_mfma_f32_16x16x32_bf16 v[94:97], v[150:153], v[208:211], 0
	v_mfma_f32_16x16x32_bf16 v[90:93], v[168:171], v[208:211], 0
	v_mfma_f32_16x16x32_bf16 v[82:85], v[168:171], v[216:219], 0
	v_mfma_f32_16x16x32_bf16 v[86:89], v[150:153], v[216:219], 0
	v_mfma_f32_16x16x32_bf16 v[110:113], v[164:167], v[196:199], v[110:113]
	v_mfma_f32_16x16x32_bf16 v[106:109], v[172:175], v[196:199], v[106:109]
	v_mfma_f32_16x16x32_bf16 v[98:101], v[172:175], v[204:207], v[98:101]
	v_mfma_f32_16x16x32_bf16 v[102:105], v[164:167], v[204:207], v[102:105]
	v_mfma_f32_16x16x32_bf16 v[94:97], v[164:167], v[212:215], v[94:97]
	v_mfma_f32_16x16x32_bf16 v[90:93], v[172:175], v[212:215], v[90:93]
	v_mfma_f32_16x16x32_bf16 v[82:85], v[172:175], v[220:223], v[82:85]
	v_mfma_f32_16x16x32_bf16 v[86:89], v[164:167], v[220:223], v[86:89]
	v_mfma_f32_16x16x32_bf16 v[78:81], v[176:179], v[192:195], 0
	v_mfma_f32_16x16x32_bf16 v[74:77], v[184:187], v[192:195], 0
	v_mfma_f32_16x16x32_bf16 v[66:69], v[184:187], v[200:203], 0
	v_mfma_f32_16x16x32_bf16 v[70:73], v[176:179], v[200:203], 0
	v_mfma_f32_16x16x32_bf16 v[62:65], v[176:179], v[208:211], 0
	v_mfma_f32_16x16x32_bf16 v[58:61], v[184:187], v[208:211], 0
	v_mfma_f32_16x16x32_bf16 v[50:53], v[184:187], v[216:219], 0
	v_mfma_f32_16x16x32_bf16 v[54:57], v[176:179], v[216:219], 0
	v_mfma_f32_16x16x32_bf16 v[78:81], v[180:183], v[196:199], v[78:81]
	v_mfma_f32_16x16x32_bf16 v[74:77], v[188:191], v[196:199], v[74:77]
	v_mfma_f32_16x16x32_bf16 v[66:69], v[188:191], v[204:207], v[66:69]
	v_mfma_f32_16x16x32_bf16 v[70:73], v[180:183], v[204:207], v[70:73]
	v_mfma_f32_16x16x32_bf16 v[62:65], v[180:183], v[212:215], v[62:65]
	v_mfma_f32_16x16x32_bf16 v[58:61], v[188:191], v[212:215], v[58:61]
	v_mfma_f32_16x16x32_bf16 v[50:53], v[188:191], v[220:223], v[50:53]
	v_mfma_f32_16x16x32_bf16 v[54:57], v[180:183], v[220:223], v[54:57]
	s_barrier
	s_add_i32 s69, s88, s83
	v_lshl_add_u64 v[154:155], s[76:77], 0, v[132:133]
	s_mov_b32 m0, s69
	ds_read_b128 v[192:195], v162 offset:16384
	ds_read_b128 v[196:199], v162 offset:17408
	ds_read_b128 v[200:203], v162 offset:18432
	ds_read_b128 v[204:207], v162 offset:19456
	ds_read_b128 v[208:211], v162 offset:20480
	ds_read_b128 v[212:215], v162 offset:21504
	ds_read_b128 v[216:219], v162 offset:22528
	ds_read_b128 v[220:223], v162 offset:23552
	global_load_lds_dwordx4 v[154:155], off
	s_add_i32 m0, s69, 0x2000
	s_add_u32 s92, s76, 0x40000
	v_lshl_add_u64 v[224:225], s[76:77], 0, v[136:137]
	s_addc_u32 s93, s77, 0
	s_add_i32 s69, s89, s83
	global_load_lds_dwordx4 v[224:225], off
	v_lshl_add_u64 v[226:227], s[92:93], 0, v[132:133]
	s_mov_b32 m0, s69
	v_lshl_add_u64 v[228:229], s[78:79], 0, v[134:135]
	global_load_lds_dwordx4 v[226:227], off
	v_lshl_add_u64 v[226:227], s[92:93], 0, v[136:137]
	s_add_i32 m0, s69, 0x2000
	s_nop 0
	global_load_lds_dwordx4 v[226:227], off
	v_lshl_add_u64 v[226:227], s[78:79], 0, v[130:131]
	s_mov_b32 m0, s15
	s_nop 0
	global_load_lds_dwordx4 v[226:227], off
	s_mov_b32 m0, s17
	s_nop 0
	global_load_lds_dwordx4 v[228:229], off
	s_waitcnt vmcnt(8)
	s_waitcnt lgkmcnt(0)
	s_barrier
; #define PG8_STAGEA(bufoff, gbase) PG8_STAGE_(bufoff, gbase, voffA)
; #define PG8_STAGEB(bufoff, gbase) PG8_STAGE_(bufoff, gbase, voffB)
; #define PG8_LDA(dst, b, h) do { _Pragma("unroll") for (int m = 0; m < 4; ++m) _Pragma("unroll") for (int k = 0; k < 2; ++k) dst[m][k] = *(const LAS bf16x8*)(lds + PG8_SA(b, h) + aoff + m * 2048 + k * 1024); } while (0)
; #define PG8_LDB(dst, b, h) do { _Pragma("unroll") for (int n = 0; n < 2; ++n) _Pragma("unroll") for (int k = 0; k < 2; ++k) dst[n][k] = *(const LAS bf16x8*)(lds + PG8_SB(b, h) + boff + n * 2048 + k * 1024); } while (0)
; #define PG8_MMA(ai, bj, At, Bt_) do { __builtin_amdgcn_s_setprio(1); _Pragma("unroll") for (int m = 0; m < 4; ++m) _Pragma("unroll") for (int n = 0; n < 2; ++n) _Pragma("unroll") for (int k = 0; k < 2; ++k) \
;         acc[ai][bj][m][n] = __builtin_amdgcn_mfma_f32_16x16x32_bf16(Bt_[n][k], At[m][k], acc[ai][bj][m][n], 0, 0, 0); __builtin_amdgcn_s_setprio(0); } while (0)
; #define PG8_WAIT_V(n) asm volatile("s_waitcnt vmcnt(" #n ")" ::: "memory")
; #define PG8_WAIT_L(n) asm volatile("s_waitcnt lgkmcnt(" #n ")" ::: "memory")
; #define PG8_BAR __builtin_amdgcn_s_barrier()
; #define PG8_SCHED __builtin_amdgcn_sched_barrier(0)
; template <int EK, int SK = -1>
; __device__ __forceinline__ void gemm_phase(LAS unsigned char* lds, const bf16_t* A, const bf16_t* Bt, int nM, int N, int K, const EpiArgs& E) {
;     ...
;             PG8_WAIT_V(8); PG8_WAIT_L(0); PG8_BAR; PG8_MMA(0, 0, At, B0); PG8_MMA(0, 1, At, B1); PG8_BAR; PG8_SCHED;
;             PG8_LDA(At, 0, 1); PG8_STAGEB(PG8_SB(0, 0), b2); PG8_STAGEB(PG8_SB(0, 1), b2 + hstep); PG8_STAGEA(PG8_SA(0, 0), a2);
;             PG8_WAIT_V(8); PG8_WAIT_L(0); PG8_BAR; PG8_MMA(1, 0, At, B0); PG8_MMA(1, 1, At, B1); PG8_BAR; PG8_SCHED;
;             PG8_LDB(B0, 1, 0); PG8_LDB(B1, 1, 1); PG8_SCHED; PG8_LDA(At, 1, 0); PG8_STAGEA(PG8_SA(0, 1), a2 + hstep);
;             PG8_WAIT_V(8); PG8_WAIT_L(0); PG8_BAR; PG8_MMA(0, 0, At, B0); PG8_MMA(0, 1, At, B1); PG8_BAR; PG8_SCHED;
	s_waitcnt lgkmcnt(0)
	v_mfma_f32_16x16x32_bf16 v[46:49], v[150:153], v[192:195], 0
	v_mfma_f32_16x16x32_bf16 v[42:45], v[168:171], v[192:195], 0
	v_mfma_f32_16x16x32_bf16 v[34:37], v[168:171], v[200:203], 0
	v_mfma_f32_16x16x32_bf16 v[38:41], v[150:153], v[200:203], 0
	v_mfma_f32_16x16x32_bf16 v[30:33], v[150:153], v[208:211], 0
	v_mfma_f32_16x16x32_bf16 v[26:29], v[168:171], v[208:211], 0
	v_mfma_f32_16x16x32_bf16 v[18:21], v[168:171], v[216:219], 0
	v_mfma_f32_16x16x32_bf16 v[22:25], v[150:153], v[216:219], 0
	v_mfma_f32_16x16x32_bf16 v[46:49], v[164:167], v[196:199], v[46:49]
	v_mfma_f32_16x16x32_bf16 v[42:45], v[172:175], v[196:199], v[42:45]
	v_mfma_f32_16x16x32_bf16 v[34:37], v[172:175], v[204:207], v[34:37]
	v_mfma_f32_16x16x32_bf16 v[38:41], v[164:167], v[204:207], v[38:41]
	v_mfma_f32_16x16x32_bf16 v[30:33], v[164:167], v[212:215], v[30:33]
	v_mfma_f32_16x16x32_bf16 v[26:29], v[172:175], v[212:215], v[26:29]
	v_mfma_f32_16x16x32_bf16 v[18:21], v[172:175], v[220:223], v[18:21]
	v_mfma_f32_16x16x32_bf16 v[22:25], v[164:167], v[220:223], v[22:25]
	v_mfma_f32_16x16x32_bf16 v[14:17], v[176:179], v[192:195], 0
	v_mfma_f32_16x16x32_bf16 v[10:13], v[184:187], v[192:195], 0
	v_mfma_f32_16x16x32_bf16 v[2:5], v[184:187], v[200:203], 0
	v_mfma_f32_16x16x32_bf16 v[6:9], v[176:179], v[200:203], 0
	v_mfma_f32_16x16x32_bf16 v[114:117], v[176:179], v[208:211], 0
	v_mfma_f32_16x16x32_bf16 v[118:121], v[184:187], v[208:211], 0
	v_mfma_f32_16x16x32_bf16 v[126:129], v[184:187], v[216:219], 0
	v_mfma_f32_16x16x32_bf16 v[122:125], v[176:179], v[216:219], 0
	v_mfma_f32_16x16x32_bf16 v[14:17], v[180:183], v[196:199], v[14:17]
	v_mfma_f32_16x16x32_bf16 v[10:13], v[188:191], v[196:199], v[10:13]
	v_mfma_f32_16x16x32_bf16 v[2:5], v[188:191], v[204:207], v[2:5]
	v_mfma_f32_16x16x32_bf16 v[6:9], v[180:183], v[204:207], v[6:9]
	v_mfma_f32_16x16x32_bf16 v[114:117], v[180:183], v[212:215], v[114:117]
	v_mfma_f32_16x16x32_bf16 v[118:121], v[188:191], v[212:215], v[118:121]
	v_mfma_f32_16x16x32_bf16 v[126:129], v[188:191], v[220:223], v[126:129]
	v_mfma_f32_16x16x32_bf16 v[122:125], v[180:183], v[220:223], v[122:125]
	s_barrier
	s_add_i32 s69, 0, 0x18000
	v_add_u32_e32 v163, s69, v159
	s_add_i32 s91, 0, 0x1c000
	ds_read_b128 v[150:153], v163
	ds_read_b128 v[164:167], v163 offset:1024
	ds_read_b128 v[168:171], v163 offset:2048
	ds_read_b128 v[172:175], v163 offset:3072
	v_add_u32_e32 v163, s91, v159
	ds_read_b128 v[176:179], v163
	ds_read_b128 v[180:183], v163 offset:1024
	ds_read_b128 v[184:187], v163 offset:2048
	ds_read_b128 v[188:191], v163 offset:3072
	s_add_u32 s78, s78, 0x40000
	s_addc_u32 s79, s79, 0
	s_mov_b32 m0, s84
	v_lshl_add_u64 v[230:231], s[78:79], 0, v[130:131]
	ds_read_b128 v[192:195], v162 offset:32768
	ds_read_b128 v[196:199], v162 offset:33792
	ds_read_b128 v[200:203], v162 offset:34816
	ds_read_b128 v[204:207], v162 offset:35840
	ds_read_b128 v[208:211], v162 offset:36864
	ds_read_b128 v[212:215], v162 offset:37888
	ds_read_b128 v[216:219], v162 offset:38912
	ds_read_b128 v[220:223], v162 offset:39936
	global_load_lds_dwordx4 v[230:231], off
	v_lshl_add_u64 v[230:231], s[78:79], 0, v[134:135]
	s_mov_b32 m0, s85
	s_nop 0
	global_load_lds_dwordx4 v[230:231], off
	s_waitcnt vmcnt(8)
	s_waitcnt lgkmcnt(0)
	s_barrier
	s_waitcnt lgkmcnt(0)
	v_mfma_f32_16x16x32_bf16 v[110:113], v[150:153], v[192:195], v[110:113]
	v_mfma_f32_16x16x32_bf16 v[106:109], v[168:171], v[192:195], v[106:109]
	v_mfma_f32_16x16x32_bf16 v[98:101], v[168:171], v[200:203], v[98:101]
	v_mfma_f32_16x16x32_bf16 v[102:105], v[150:153], v[200:203], v[102:105]
	v_mfma_f32_16x16x32_bf16 v[94:97], v[150:153], v[208:211], v[94:97]
	v_mfma_f32_16x16x32_bf16 v[90:93], v[168:171], v[208:211], v[90:93]
	v_mfma_f32_16x16x32_bf16 v[82:85], v[168:171], v[216:219], v[82:85]
	v_mfma_f32_16x16x32_bf16 v[86:89], v[150:153], v[216:219], v[86:89]
	v_mfma_f32_16x16x32_bf16 v[110:113], v[164:167], v[196:199], v[110:113]
	v_mfma_f32_16x16x32_bf16 v[106:109], v[172:175], v[196:199], v[106:109]
	v_mfma_f32_16x16x32_bf16 v[98:101], v[172:175], v[204:207], v[98:101]
	v_mfma_f32_16x16x32_bf16 v[102:105], v[164:167], v[204:207], v[102:105]
	v_mfma_f32_16x16x32_bf16 v[94:97], v[164:167], v[212:215], v[94:97]
	v_mfma_f32_16x16x32_bf16 v[90:93], v[172:175], v[212:215], v[90:93]
	v_mfma_f32_16x16x32_bf16 v[82:85], v[172:175], v[220:223], v[82:85]
	v_mfma_f32_16x16x32_bf16 v[86:89], v[164:167], v[220:223], v[86:89]
	v_mfma_f32_16x16x32_bf16 v[78:81], v[176:179], v[192:195], v[78:81]
	v_mfma_f32_16x16x32_bf16 v[74:77], v[184:187], v[192:195], v[74:77]
	v_mfma_f32_16x16x32_bf16 v[66:69], v[184:187], v[200:203], v[66:69]
	v_mfma_f32_16x16x32_bf16 v[70:73], v[176:179], v[200:203], v[70:73]
	v_mfma_f32_16x16x32_bf16 v[62:65], v[176:179], v[208:211], v[62:65]
	v_mfma_f32_16x16x32_bf16 v[58:61], v[184:187], v[208:211], v[58:61]
	v_mfma_f32_16x16x32_bf16 v[50:53], v[184:187], v[216:219], v[50:53]
	v_mfma_f32_16x16x32_bf16 v[54:57], v[176:179], v[216:219], v[54:57]
	v_mfma_f32_16x16x32_bf16 v[78:81], v[180:183], v[196:199], v[78:81]
	v_mfma_f32_16x16x32_bf16 v[74:77], v[188:191], v[196:199], v[74:77]
	v_mfma_f32_16x16x32_bf16 v[66:69], v[188:191], v[204:207], v[66:69]
	v_mfma_f32_16x16x32_bf16 v[70:73], v[180:183], v[204:207], v[70:73]
	v_mfma_f32_16x16x32_bf16 v[62:65], v[180:183], v[212:215], v[62:65]
	v_mfma_f32_16x16x32_bf16 v[58:61], v[188:191], v[212:215], v[58:61]
	v_mfma_f32_16x16x32_bf16 v[50:53], v[188:191], v[220:223], v[50:53]
	v_mfma_f32_16x16x32_bf16 v[54:57], v[180:183], v[220:223], v[54:57]
	s_barrier
; #define PG8_STAGEA(bufoff, gbase) PG8_STAGE_(bufoff, gbase, voffA)
; #define PG8_STAGEB(bufoff, gbase) PG8_STAGE_(bufoff, gbase, voffB)
; #define PG8_LDA(dst, b, h) do { _Pragma("unroll") for (int m = 0; m < 4; ++m) _Pragma("unroll") for (int k = 0; k < 2; ++k) dst[m][k] = *(const LAS bf16x8*)(lds + PG8_SA(b, h) + aoff + m * 2048 + k * 1024); } while (0)
; #define PG8_LDB(dst, b, h) do { _Pragma("unroll") for (int n = 0; n < 2; ++n) _Pragma("unroll") for (int k = 0; k < 2; ++k) dst[n][k] = *(const LAS bf16x8*)(lds + PG8_SB(b, h) + boff + n * 2048 + k * 1024); } while (0)
; #define PG8_MMA(ai, bj, At, Bt_) do { __builtin_amdgcn_s_setprio(1); _Pragma("unroll") for (int m = 0; m < 4; ++m) _Pragma("unroll") for (int n = 0; n < 2; ++n) _Pragma("unroll") for (int k = 0; k < 2; ++k) \
;         acc[ai][bj][m][n] = __builtin_amdgcn_mfma_f32_16x16x32_bf16(Bt_[n][k], At[m][k], acc[ai][bj][m][n], 0, 0, 0); __builtin_amdgcn_s_setprio(0); } while (0)
; #define PG8_WAIT_V(n) asm volatile("s_waitcnt vmcnt(" #n ")" ::: "memory")
; #define PG8_WAIT_L(n) asm volatile("s_waitcnt lgkmcnt(" #n ")" ::: "memory")
; #define PG8_BAR __builtin_amdgcn_s_barrier()
; #define PG8_SCHED __builtin_amdgcn_sched_barrier(0)
; template <int EK, int SK = -1>
; __device__ __forceinline__ void gemm_phase(LAS unsigned char* lds, const bf16_t* A, const bf16_t* Bt, int nM, int N, int K, const EpiArgs& E) {
;     ...
;             PG8_LDB(B0, 0, 0); PG8_LDB(B1, 0, 1); PG8_SCHED; PG8_LDA(At, 0, 0); PG8_STAGEA(PG8_SA(1, 1), a1 + hstep);
;             PG8_WAIT_V(8); PG8_WAIT_L(0); PG8_BAR; PG8_MMA(0, 0, At, B0); PG8_MMA(0, 1, At, B1); PG8_BAR; PG8_SCHED;
;             PG8_LDA(At, 0, 1); PG8_STAGEB(PG8_SB(0, 0), b2); PG8_STAGEB(PG8_SB(0, 1), b2 + hstep); PG8_STAGEA(PG8_SA(0, 0), a2);
;             PG8_WAIT_V(8); PG8_WAIT_L(0); PG8_BAR; PG8_MMA(1, 0, At, B0); PG8_MMA(1, 1, At, B1); PG8_BAR; PG8_SCHED;
;             PG8_LDB(B0, 1, 0); PG8_LDB(B1, 1, 1); PG8_SCHED; PG8_LDA(At, 1, 0); PG8_STAGEA(PG8_SA(0, 1), a2 + hstep);
;             PG8_WAIT_V(8); PG8_WAIT_L(0); PG8_BAR; PG8_MMA(0, 0, At, B0); PG8_MMA(0, 1, At, B1); PG8_BAR; PG8_SCHED;
;             PG8_LDA(At, 1, 1); PG8_STAGEB(PG8_SB(1, 0), b3); PG8_STAGEB(PG8_SB(1, 1), b3 + hstep); PG8_STAGEA(PG8_SA(1, 0), a3);
;             PG8_WAIT_V(8); PG8_WAIT_L(0); PG8_BAR; PG8_MMA(1, 0, At, B0); PG8_MMA(1, 1, At, B1); PG8_BAR; PG8_SCHED;
	s_add_i32 s69, s69, s83
	v_lshl_add_u64 v[154:155], v[154:155], 0, s[10:11]
	s_mov_b32 m0, s69
	ds_read_b128 v[192:195], v162 offset:49152
	ds_read_b128 v[196:199], v162 offset:50176
	ds_read_b128 v[200:203], v162 offset:51200
	ds_read_b128 v[204:207], v162 offset:52224
	ds_read_b128 v[208:211], v162 offset:53248
	ds_read_b128 v[212:215], v162 offset:54272
	ds_read_b128 v[216:219], v162 offset:55296
	ds_read_b128 v[220:223], v162 offset:56320
	global_load_lds_dwordx4 v[154:155], off
	s_add_i32 m0, s69, 0x2000
	s_add_u32 s76, s76, 0x40080
	v_lshl_add_u64 v[154:155], v[224:225], 0, s[10:11]
	s_addc_u32 s77, s77, 0
	s_add_i32 s69, s91, s83
	global_load_lds_dwordx4 v[154:155], off
	v_lshl_add_u64 v[154:155], s[76:77], 0, v[132:133]
	s_mov_b32 m0, s69
	s_nop 0
	global_load_lds_dwordx4 v[154:155], off
	v_lshl_add_u64 v[154:155], s[76:77], 0, v[136:137]
	s_add_i32 m0, s69, 0x2000
	s_nop 0
	global_load_lds_dwordx4 v[154:155], off
	v_lshl_add_u64 v[154:155], v[226:227], 0, s[10:11]
	s_mov_b32 m0, s86
	s_nop 0
	global_load_lds_dwordx4 v[154:155], off
	v_lshl_add_u64 v[154:155], v[228:229], 0, s[10:11]
	s_mov_b32 m0, s87
	s_nop 0
	global_load_lds_dwordx4 v[154:155], off
	s_waitcnt vmcnt(8)
	s_waitcnt lgkmcnt(0)
	s_barrier
	s_waitcnt lgkmcnt(0)
	v_mfma_f32_16x16x32_bf16 v[46:49], v[150:153], v[192:195], v[46:49]
	v_mfma_f32_16x16x32_bf16 v[42:45], v[168:171], v[192:195], v[42:45]
	v_mfma_f32_16x16x32_bf16 v[34:37], v[168:171], v[200:203], v[34:37]
	v_mfma_f32_16x16x32_bf16 v[38:41], v[150:153], v[200:203], v[38:41]
	v_mfma_f32_16x16x32_bf16 v[30:33], v[150:153], v[208:211], v[30:33]
	v_mfma_f32_16x16x32_bf16 v[26:29], v[168:171], v[208:211], v[26:29]
	v_mfma_f32_16x16x32_bf16 v[18:21], v[168:171], v[216:219], v[18:21]
	v_mfma_f32_16x16x32_bf16 v[22:25], v[150:153], v[216:219], v[22:25]
	v_mfma_f32_16x16x32_bf16 v[46:49], v[164:167], v[196:199], v[46:49]
	v_mfma_f32_16x16x32_bf16 v[42:45], v[172:175], v[196:199], v[42:45]
	v_mfma_f32_16x16x32_bf16 v[34:37], v[172:175], v[204:207], v[34:37]
	v_mfma_f32_16x16x32_bf16 v[38:41], v[164:167], v[204:207], v[38:41]
	v_mfma_f32_16x16x32_bf16 v[30:33], v[164:167], v[212:215], v[30:33]
	v_mfma_f32_16x16x32_bf16 v[26:29], v[172:175], v[212:215], v[26:29]
	v_mfma_f32_16x16x32_bf16 v[18:21], v[172:175], v[220:223], v[18:21]
	v_mfma_f32_16x16x32_bf16 v[22:25], v[164:167], v[220:223], v[22:25]
	v_mfma_f32_16x16x32_bf16 v[14:17], v[176:179], v[192:195], v[14:17]
	v_mfma_f32_16x16x32_bf16 v[10:13], v[184:187], v[192:195], v[10:13]
	v_mfma_f32_16x16x32_bf16 v[2:5], v[184:187], v[200:203], v[2:5]
	v_mfma_f32_16x16x32_bf16 v[6:9], v[176:179], v[200:203], v[6:9]
	v_mfma_f32_16x16x32_bf16 v[114:117], v[176:179], v[208:211], v[114:117]
	v_mfma_f32_16x16x32_bf16 v[118:121], v[184:187], v[208:211], v[118:121]
	v_mfma_f32_16x16x32_bf16 v[126:129], v[184:187], v[216:219], v[126:129]
	v_mfma_f32_16x16x32_bf16 v[122:125], v[176:179], v[216:219], v[122:125]
	v_mfma_f32_16x16x32_bf16 v[14:17], v[180:183], v[196:199], v[14:17]
	v_mfma_f32_16x16x32_bf16 v[10:13], v[188:191], v[196:199], v[10:13]
	v_mfma_f32_16x16x32_bf16 v[2:5], v[188:191], v[204:207], v[2:5]
	v_mfma_f32_16x16x32_bf16 v[6:9], v[180:183], v[204:207], v[6:9]
	v_mfma_f32_16x16x32_bf16 v[114:117], v[180:183], v[212:215], v[114:117]
	v_mfma_f32_16x16x32_bf16 v[118:121], v[188:191], v[212:215], v[118:121]
	v_mfma_f32_16x16x32_bf16 v[126:129], v[188:191], v[220:223], v[126:129]
	v_mfma_f32_16x16x32_bf16 v[122:125], v[180:183], v[220:223], v[122:125]
	s_barrier
	s_add_i32 s59, s59, 2
	s_add_u32 s74, s74, 0x100
	s_addc_u32 s75, s75, 0
	s_cmp_gt_u32 s59, 13
	s_cbranch_scc0 .LBB0_538
	s_branch .Lmy_kexit_2
.LBB0_538:
	v_add_u32_e32 v154, s88, v159
	ds_read_b128 v[150:153], v154
	ds_read_b128 v[164:167], v154 offset:1024
	ds_read_b128 v[168:171], v154 offset:2048
	ds_read_b128 v[172:175], v154 offset:3072
	v_add_u32_e32 v154, s89, v159
	s_add_u32 s69, s38, s74
	ds_read_b128 v[176:179], v154
	ds_read_b128 v[180:183], v154 offset:1024
	ds_read_b128 v[184:187], v154 offset:2048
	ds_read_b128 v[188:191], v154 offset:3072
	s_addc_u32 s76, s39, s75
	s_add_u32 s69, s69, 0x100
	s_addc_u32 s76, s76, 0
	s_add_u32 s91, s54, s74
	s_addc_u32 s77, s55, s75
	s_cmpk_eq_i32 s74, 0x700
	s_cselect_b32 s79, s56, s76
	s_cselect_b32 s78, s57, s69
	s_cselect_b32 s77, s41, s77
	s_cselect_b32 s76, s58, s91
	v_lshl_add_u64 v[154:155], v[146:147], 0, s[74:75]
	s_add_i32 m0, s15, 0xc000
	ds_read_b128 v[192:195], v162
	ds_read_b128 v[196:199], v162 offset:1024
	ds_read_b128 v[200:203], v162 offset:2048
	ds_read_b128 v[204:207], v162 offset:3072
	ds_read_b128 v[208:211], v162 offset:4096
	ds_read_b128 v[212:215], v162 offset:5120
	ds_read_b128 v[216:219], v162 offset:6144
	ds_read_b128 v[220:223], v162 offset:7168
	global_load_lds_dwordx4 v[154:155], off
	v_lshl_add_u64 v[154:155], v[148:149], 0, s[74:75]
	s_add_i32 m0, s15, 0xe000
	s_nop 0
	global_load_lds_dwordx4 v[154:155], off
	s_waitcnt vmcnt(8)
	s_waitcnt lgkmcnt(0)
	s_barrier
; #define PG8_STAGEA(bufoff, gbase) PG8_STAGE_(bufoff, gbase, voffA)
; #define PG8_STAGEB(bufoff, gbase) PG8_STAGE_(bufoff, gbase, voffB)
; #define PG8_LDA(dst, b, h) do { _Pragma("unroll") for (int m = 0; m < 4; ++m) _Pragma("unroll") for (int k = 0; k < 2; ++k) dst[m][k] = *(const LAS bf16x8*)(lds + PG8_SA(b, h) + aoff + m * 2048 + k * 1024); } while (0)
; #define PG8_LDB(dst, b, h) do { _Pragma("unroll") for (int n = 0; n < 2; ++n) _Pragma("unroll") for (int k = 0; k < 2; ++k) dst[n][k] = *(const LAS bf16x8*)(lds + PG8_SB(b, h) + boff + n * 2048 + k * 1024); } while (0)
; #define PG8_MMA(ai, bj, At, Bt_) do { __builtin_amdgcn_s_setprio(1); _Pragma("unroll") for (int m = 0; m < 4; ++m) _Pragma("unroll") for (int n = 0; n < 2; ++n) _Pragma("unroll") for (int k = 0; k < 2; ++k) \
;         acc[ai][bj][m][n] = __builtin_amdgcn_mfma_f32_16x16x32_bf16(Bt_[n][k], At[m][k], acc[ai][bj][m][n], 0, 0, 0); __builtin_amdgcn_s_setprio(0); } while (0)
; #define PG8_WAIT_V(n) asm volatile("s_waitcnt vmcnt(" #n ")" ::: "memory")
; #define PG8_WAIT_L(n) asm volatile("s_waitcnt lgkmcnt(" #n ")" ::: "memory")
; #define PG8_BAR __builtin_amdgcn_s_barrier()
; #define PG8_SCHED __builtin_amdgcn_sched_barrier(0)
; template <int EK, int SK = -1>
; __device__ __forceinline__ void gemm_phase(LAS unsigned char* lds, const bf16_t* A, const bf16_t* Bt, int nM, int N, int K, const EpiArgs& E) {
;     ...
;             PG8_LDB(B0, 0, 0); PG8_LDB(B1, 0, 1); PG8_SCHED; PG8_LDA(At, 0, 0); PG8_STAGEA(PG8_SA(1, 1), a1 + hstep);
;             PG8_WAIT_V(8); PG8_WAIT_L(0); PG8_BAR; PG8_MMA(0, 0, At, B0); PG8_MMA(0, 1, At, B1); PG8_BAR; PG8_SCHED;
;             PG8_LDA(At, 0, 1); PG8_STAGEB(PG8_SB(0, 0), b2); PG8_STAGEB(PG8_SB(0, 1), b2 + hstep); PG8_STAGEA(PG8_SA(0, 0), a2);
;             PG8_WAIT_V(8); PG8_WAIT_L(0); PG8_BAR; PG8_MMA(1, 0, At, B0); PG8_MMA(1, 1, At, B1); PG8_BAR; PG8_SCHED;
	s_waitcnt lgkmcnt(0)
	v_mfma_f32_16x16x32_bf16 v[110:113], v[150:153], v[192:195], v[110:113]
	v_mfma_f32_16x16x32_bf16 v[106:109], v[168:171], v[192:195], v[106:109]
	v_mfma_f32_16x16x32_bf16 v[98:101], v[168:171], v[200:203], v[98:101]
	v_mfma_f32_16x16x32_bf16 v[102:105], v[150:153], v[200:203], v[102:105]
	v_mfma_f32_16x16x32_bf16 v[94:97], v[150:153], v[208:211], v[94:97]
	v_mfma_f32_16x16x32_bf16 v[90:93], v[168:171], v[208:211], v[90:93]
	v_mfma_f32_16x16x32_bf16 v[82:85], v[168:171], v[216:219], v[82:85]
	v_mfma_f32_16x16x32_bf16 v[86:89], v[150:153], v[216:219], v[86:89]
	v_mfma_f32_16x16x32_bf16 v[110:113], v[164:167], v[196:199], v[110:113]
	v_mfma_f32_16x16x32_bf16 v[106:109], v[172:175], v[196:199], v[106:109]
	v_mfma_f32_16x16x32_bf16 v[98:101], v[172:175], v[204:207], v[98:101]
	v_mfma_f32_16x16x32_bf16 v[102:105], v[164:167], v[204:207], v[102:105]
	v_mfma_f32_16x16x32_bf16 v[94:97], v[164:167], v[212:215], v[94:97]
	v_mfma_f32_16x16x32_bf16 v[90:93], v[172:175], v[212:215], v[90:93]
	v_mfma_f32_16x16x32_bf16 v[82:85], v[172:175], v[220:223], v[82:85]
	v_mfma_f32_16x16x32_bf16 v[86:89], v[164:167], v[220:223], v[86:89]
	v_mfma_f32_16x16x32_bf16 v[78:81], v[176:179], v[192:195], v[78:81]
	v_mfma_f32_16x16x32_bf16 v[74:77], v[184:187], v[192:195], v[74:77]
	v_mfma_f32_16x16x32_bf16 v[66:69], v[184:187], v[200:203], v[66:69]
	v_mfma_f32_16x16x32_bf16 v[70:73], v[176:179], v[200:203], v[70:73]
	v_mfma_f32_16x16x32_bf16 v[62:65], v[176:179], v[208:211], v[62:65]
	v_mfma_f32_16x16x32_bf16 v[58:61], v[184:187], v[208:211], v[58:61]
	v_mfma_f32_16x16x32_bf16 v[50:53], v[184:187], v[216:219], v[50:53]
	v_mfma_f32_16x16x32_bf16 v[54:57], v[176:179], v[216:219], v[54:57]
	v_mfma_f32_16x16x32_bf16 v[78:81], v[180:183], v[196:199], v[78:81]
	v_mfma_f32_16x16x32_bf16 v[74:77], v[188:191], v[196:199], v[74:77]
	v_mfma_f32_16x16x32_bf16 v[66:69], v[188:191], v[204:207], v[66:69]
	v_mfma_f32_16x16x32_bf16 v[70:73], v[180:183], v[204:207], v[70:73]
	v_mfma_f32_16x16x32_bf16 v[62:65], v[180:183], v[212:215], v[62:65]
	v_mfma_f32_16x16x32_bf16 v[58:61], v[188:191], v[212:215], v[58:61]
	v_mfma_f32_16x16x32_bf16 v[50:53], v[188:191], v[220:223], v[50:53]
	v_mfma_f32_16x16x32_bf16 v[54:57], v[180:183], v[220:223], v[54:57]
	s_barrier
	s_add_i32 s69, s88, s83
	v_lshl_add_u64 v[154:155], s[76:77], 0, v[132:133]
	s_mov_b32 m0, s69
	ds_read_b128 v[192:195], v162 offset:16384
	ds_read_b128 v[196:199], v162 offset:17408
	ds_read_b128 v[200:203], v162 offset:18432
	ds_read_b128 v[204:207], v162 offset:19456
	ds_read_b128 v[208:211], v162 offset:20480
	ds_read_b128 v[212:215], v162 offset:21504
	ds_read_b128 v[216:219], v162 offset:22528
	ds_read_b128 v[220:223], v162 offset:23552
	global_load_lds_dwordx4 v[154:155], off
	s_add_i32 m0, s69, 0x2000
	s_add_u32 s92, s76, 0x40000
	v_lshl_add_u64 v[224:225], s[76:77], 0, v[136:137]
	s_addc_u32 s93, s77, 0
	s_add_i32 s69, s89, s83
	global_load_lds_dwordx4 v[224:225], off
	v_lshl_add_u64 v[226:227], s[92:93], 0, v[132:133]
	s_mov_b32 m0, s69
	v_lshl_add_u64 v[228:229], s[78:79], 0, v[134:135]
	global_load_lds_dwordx4 v[226:227], off
	v_lshl_add_u64 v[226:227], s[92:93], 0, v[136:137]
	s_add_i32 m0, s69, 0x2000
	s_nop 0
	global_load_lds_dwordx4 v[226:227], off
	v_lshl_add_u64 v[226:227], s[78:79], 0, v[130:131]
	s_mov_b32 m0, s15
	s_nop 0
	global_load_lds_dwordx4 v[226:227], off
	s_mov_b32 m0, s17
	s_nop 0
	global_load_lds_dwordx4 v[228:229], off
	s_waitcnt vmcnt(8)
	s_waitcnt lgkmcnt(0)
	s_barrier
	s_waitcnt lgkmcnt(0)
	v_mfma_f32_16x16x32_bf16 v[46:49], v[150:153], v[192:195], v[46:49]
	v_mfma_f32_16x16x32_bf16 v[42:45], v[168:171], v[192:195], v[42:45]
	v_mfma_f32_16x16x32_bf16 v[34:37], v[168:171], v[200:203], v[34:37]
	v_mfma_f32_16x16x32_bf16 v[38:41], v[150:153], v[200:203], v[38:41]
	v_mfma_f32_16x16x32_bf16 v[30:33], v[150:153], v[208:211], v[30:33]
	v_mfma_f32_16x16x32_bf16 v[26:29], v[168:171], v[208:211], v[26:29]
	v_mfma_f32_16x16x32_bf16 v[18:21], v[168:171], v[216:219], v[18:21]
	v_mfma_f32_16x16x32_bf16 v[22:25], v[150:153], v[216:219], v[22:25]
	v_mfma_f32_16x16x32_bf16 v[46:49], v[164:167], v[196:199], v[46:49]
	v_mfma_f32_16x16x32_bf16 v[42:45], v[172:175], v[196:199], v[42:45]
	v_mfma_f32_16x16x32_bf16 v[34:37], v[172:175], v[204:207], v[34:37]
	v_mfma_f32_16x16x32_bf16 v[38:41], v[164:167], v[204:207], v[38:41]
	v_mfma_f32_16x16x32_bf16 v[30:33], v[164:167], v[212:215], v[30:33]
	v_mfma_f32_16x16x32_bf16 v[26:29], v[172:175], v[212:215], v[26:29]
	v_mfma_f32_16x16x32_bf16 v[18:21], v[172:175], v[220:223], v[18:21]
	v_mfma_f32_16x16x32_bf16 v[22:25], v[164:167], v[220:223], v[22:25]
	v_mfma_f32_16x16x32_bf16 v[14:17], v[176:179], v[192:195], v[14:17]
	v_mfma_f32_16x16x32_bf16 v[10:13], v[184:187], v[192:195], v[10:13]
	v_mfma_f32_16x16x32_bf16 v[2:5], v[184:187], v[200:203], v[2:5]
	v_mfma_f32_16x16x32_bf16 v[6:9], v[176:179], v[200:203], v[6:9]
	v_mfma_f32_16x16x32_bf16 v[114:117], v[176:179], v[208:211], v[114:117]
	v_mfma_f32_16x16x32_bf16 v[118:121], v[184:187], v[208:211], v[118:121]
	v_mfma_f32_16x16x32_bf16 v[126:129], v[184:187], v[216:219], v[126:129]
	v_mfma_f32_16x16x32_bf16 v[122:125], v[176:179], v[216:219], v[122:125]
	v_mfma_f32_16x16x32_bf16 v[14:17], v[180:183], v[196:199], v[14:17]
	v_mfma_f32_16x16x32_bf16 v[10:13], v[188:191], v[196:199], v[10:13]
	v_mfma_f32_16x16x32_bf16 v[2:5], v[188:191], v[204:207], v[2:5]
	v_mfma_f32_16x16x32_bf16 v[6:9], v[180:183], v[204:207], v[6:9]
	v_mfma_f32_16x16x32_bf16 v[114:117], v[180:183], v[212:215], v[114:117]
	v_mfma_f32_16x16x32_bf16 v[118:121], v[188:191], v[212:215], v[118:121]
	v_mfma_f32_16x16x32_bf16 v[126:129], v[188:191], v[220:223], v[126:129]
	v_mfma_f32_16x16x32_bf16 v[122:125], v[180:183], v[220:223], v[122:125]
	s_barrier
; #define PG8_STAGEA(bufoff, gbase) PG8_STAGE_(bufoff, gbase, voffA)
; #define PG8_STAGEB(bufoff, gbase) PG8_STAGE_(bufoff, gbase, voffB)
; #define PG8_LDA(dst, b, h) do { _Pragma("unroll") for (int m = 0; m < 4; ++m) _Pragma("unroll") for (int k = 0; k < 2; ++k) dst[m][k] = *(const LAS bf16x8*)(lds + PG8_SA(b, h) + aoff + m * 2048 + k * 1024); } while (0)
; #define PG8_LDB(dst, b, h) do { _Pragma("unroll") for (int n = 0; n < 2; ++n) _Pragma("unroll") for (int k = 0; k < 2; ++k) dst[n][k] = *(const LAS bf16x8*)(lds + PG8_SB(b, h) + boff + n * 2048 + k * 1024); } while (0)
; #define PG8_MMA(ai, bj, At, Bt_) do { __builtin_amdgcn_s_setprio(1); _Pragma("unroll") for (int m = 0; m < 4; ++m) _Pragma("unroll") for (int n = 0; n < 2; ++n) _Pragma("unroll") for (int k = 0; k < 2; ++k) \
;         acc[ai][bj][m][n] = __builtin_amdgcn_mfma_f32_16x16x32_bf16(Bt_[n][k], At[m][k], acc[ai][bj][m][n], 0, 0, 0); __builtin_amdgcn_s_setprio(0); } while (0)
; #define PG8_WAIT_V(n) asm volatile("s_waitcnt vmcnt(" #n ")" ::: "memory")
; #define PG8_WAIT_L(n) asm volatile("s_waitcnt lgkmcnt(" #n ")" ::: "memory")
; #define PG8_BAR __builtin_amdgcn_s_barrier()
; #define PG8_SCHED __builtin_amdgcn_sched_barrier(0)
; template <int EK, int SK = -1>
; __device__ __forceinline__ void gemm_phase(LAS unsigned char* lds, const bf16_t* A, const bf16_t* Bt, int nM, int N, int K, const EpiArgs& E) {
;     ...
;             PG8_LDB(B0, 1, 0); PG8_LDB(B1, 1, 1); PG8_SCHED; PG8_LDA(At, 1, 0); PG8_STAGEA(PG8_SA(0, 1), a2 + hstep);
;             PG8_WAIT_V(8); PG8_WAIT_L(0); PG8_BAR; PG8_MMA(0, 0, At, B0); PG8_MMA(0, 1, At, B1); PG8_BAR; PG8_SCHED;
;             PG8_LDA(At, 1, 1); PG8_STAGEB(PG8_SB(1, 0), b3); PG8_STAGEB(PG8_SB(1, 1), b3 + hstep); PG8_STAGEA(PG8_SA(1, 0), a3);
;             PG8_WAIT_V(8); PG8_WAIT_L(0); PG8_BAR; PG8_MMA(1, 0, At, B0); PG8_MMA(1, 1, At, B1); PG8_BAR; PG8_SCHED;
;         }
	s_add_i32 s69, 0, 0x18000
	v_add_u32_e32 v163, s69, v159
	s_add_i32 s91, 0, 0x1c000
	ds_read_b128 v[150:153], v163
	ds_read_b128 v[164:167], v163 offset:1024
	ds_read_b128 v[168:171], v163 offset:2048
	ds_read_b128 v[172:175], v163 offset:3072
	v_add_u32_e32 v163, s91, v159
	ds_read_b128 v[176:179], v163
	ds_read_b128 v[180:183], v163 offset:1024
	ds_read_b128 v[184:187], v163 offset:2048
	ds_read_b128 v[188:191], v163 offset:3072
	s_add_u32 s78, s78, 0x40000
	s_addc_u32 s79, s79, 0
	s_mov_b32 m0, s84
	v_lshl_add_u64 v[230:231], s[78:79], 0, v[130:131]
	ds_read_b128 v[192:195], v162 offset:32768
	ds_read_b128 v[196:199], v162 offset:33792
	ds_read_b128 v[200:203], v162 offset:34816
	ds_read_b128 v[204:207], v162 offset:35840
	ds_read_b128 v[208:211], v162 offset:36864
	ds_read_b128 v[212:215], v162 offset:37888
	ds_read_b128 v[216:219], v162 offset:38912
	ds_read_b128 v[220:223], v162 offset:39936
	global_load_lds_dwordx4 v[230:231], off
	v_lshl_add_u64 v[230:231], s[78:79], 0, v[134:135]
	s_mov_b32 m0, s85
	s_nop 0
	global_load_lds_dwordx4 v[230:231], off
	s_waitcnt vmcnt(8)
	s_waitcnt lgkmcnt(0)
	s_barrier
	s_waitcnt lgkmcnt(0)
	v_mfma_f32_16x16x32_bf16 v[110:113], v[150:153], v[192:195], v[110:113]
	v_mfma_f32_16x16x32_bf16 v[106:109], v[168:171], v[192:195], v[106:109]
	v_mfma_f32_16x16x32_bf16 v[98:101], v[168:171], v[200:203], v[98:101]
	v_mfma_f32_16x16x32_bf16 v[102:105], v[150:153], v[200:203], v[102:105]
	v_mfma_f32_16x16x32_bf16 v[94:97], v[150:153], v[208:211], v[94:97]
	v_mfma_f32_16x16x32_bf16 v[90:93], v[168:171], v[208:211], v[90:93]
	v_mfma_f32_16x16x32_bf16 v[82:85], v[168:171], v[216:219], v[82:85]
	v_mfma_f32_16x16x32_bf16 v[86:89], v[150:153], v[216:219], v[86:89]
	v_mfma_f32_16x16x32_bf16 v[110:113], v[164:167], v[196:199], v[110:113]
	v_mfma_f32_16x16x32_bf16 v[106:109], v[172:175], v[196:199], v[106:109]
	v_mfma_f32_16x16x32_bf16 v[98:101], v[172:175], v[204:207], v[98:101]
	v_mfma_f32_16x16x32_bf16 v[102:105], v[164:167], v[204:207], v[102:105]
	v_mfma_f32_16x16x32_bf16 v[94:97], v[164:167], v[212:215], v[94:97]
	v_mfma_f32_16x16x32_bf16 v[90:93], v[172:175], v[212:215], v[90:93]
	v_mfma_f32_16x16x32_bf16 v[82:85], v[172:175], v[220:223], v[82:85]
	v_mfma_f32_16x16x32_bf16 v[86:89], v[164:167], v[220:223], v[86:89]
	v_mfma_f32_16x16x32_bf16 v[78:81], v[176:179], v[192:195], v[78:81]
	v_mfma_f32_16x16x32_bf16 v[74:77], v[184:187], v[192:195], v[74:77]
	v_mfma_f32_16x16x32_bf16 v[66:69], v[184:187], v[200:203], v[66:69]
	v_mfma_f32_16x16x32_bf16 v[70:73], v[176:179], v[200:203], v[70:73]
	v_mfma_f32_16x16x32_bf16 v[62:65], v[176:179], v[208:211], v[62:65]
	v_mfma_f32_16x16x32_bf16 v[58:61], v[184:187], v[208:211], v[58:61]
	v_mfma_f32_16x16x32_bf16 v[50:53], v[184:187], v[216:219], v[50:53]
	v_mfma_f32_16x16x32_bf16 v[54:57], v[176:179], v[216:219], v[54:57]
	v_mfma_f32_16x16x32_bf16 v[78:81], v[180:183], v[196:199], v[78:81]
	v_mfma_f32_16x16x32_bf16 v[74:77], v[188:191], v[196:199], v[74:77]
	v_mfma_f32_16x16x32_bf16 v[66:69], v[188:191], v[204:207], v[66:69]
	v_mfma_f32_16x16x32_bf16 v[70:73], v[180:183], v[204:207], v[70:73]
	v_mfma_f32_16x16x32_bf16 v[62:65], v[180:183], v[212:215], v[62:65]
	v_mfma_f32_16x16x32_bf16 v[58:61], v[188:191], v[212:215], v[58:61]
	v_mfma_f32_16x16x32_bf16 v[50:53], v[188:191], v[220:223], v[50:53]
	v_mfma_f32_16x16x32_bf16 v[54:57], v[180:183], v[220:223], v[54:57]
	s_barrier
	s_add_i32 s69, s69, s83
	v_lshl_add_u64 v[154:155], v[154:155], 0, s[10:11]
	s_mov_b32 m0, s69
	ds_read_b128 v[192:195], v162 offset:49152
	ds_read_b128 v[196:199], v162 offset:50176
	ds_read_b128 v[200:203], v162 offset:51200
	ds_read_b128 v[204:207], v162 offset:52224
	ds_read_b128 v[208:211], v162 offset:53248
	ds_read_b128 v[212:215], v162 offset:54272
	ds_read_b128 v[216:219], v162 offset:55296
	ds_read_b128 v[220:223], v162 offset:56320
	global_load_lds_dwordx4 v[154:155], off
	s_add_i32 m0, s69, 0x2000
	s_add_u32 s76, s76, 0x40080
	v_lshl_add_u64 v[154:155], v[224:225], 0, s[10:11]
	s_addc_u32 s77, s77, 0
	s_add_i32 s69, s91, s83
	global_load_lds_dwordx4 v[154:155], off
	v_lshl_add_u64 v[154:155], s[76:77], 0, v[132:133]
	s_mov_b32 m0, s69
	s_nop 0
	global_load_lds_dwordx4 v[154:155], off
	v_lshl_add_u64 v[154:155], s[76:77], 0, v[136:137]
	s_add_i32 m0, s69, 0x2000
	s_nop 0
	global_load_lds_dwordx4 v[154:155], off
	v_lshl_add_u64 v[154:155], v[226:227], 0, s[10:11]
	s_mov_b32 m0, s86
	s_nop 0
	global_load_lds_dwordx4 v[154:155], off
	v_lshl_add_u64 v[154:155], v[228:229], 0, s[10:11]
	s_mov_b32 m0, s87
	s_nop 0
	global_load_lds_dwordx4 v[154:155], off
	s_waitcnt vmcnt(8)
	s_waitcnt lgkmcnt(0)
	s_barrier
	s_waitcnt lgkmcnt(0)
	v_mfma_f32_16x16x32_bf16 v[46:49], v[150:153], v[192:195], v[46:49]
	v_mfma_f32_16x16x32_bf16 v[42:45], v[168:171], v[192:195], v[42:45]
	v_mfma_f32_16x16x32_bf16 v[34:37], v[168:171], v[200:203], v[34:37]
	v_mfma_f32_16x16x32_bf16 v[38:41], v[150:153], v[200:203], v[38:41]
	v_mfma_f32_16x16x32_bf16 v[30:33], v[150:153], v[208:211], v[30:33]
	v_mfma_f32_16x16x32_bf16 v[26:29], v[168:171], v[208:211], v[26:29]
	v_mfma_f32_16x16x32_bf16 v[18:21], v[168:171], v[216:219], v[18:21]
	v_mfma_f32_16x16x32_bf16 v[22:25], v[150:153], v[216:219], v[22:25]
	v_mfma_f32_16x16x32_bf16 v[46:49], v[164:167], v[196:199], v[46:49]
	v_mfma_f32_16x16x32_bf16 v[42:45], v[172:175], v[196:199], v[42:45]
	v_mfma_f32_16x16x32_bf16 v[34:37], v[172:175], v[204:207], v[34:37]
	v_mfma_f32_16x16x32_bf16 v[38:41], v[164:167], v[204:207], v[38:41]
	v_mfma_f32_16x16x32_bf16 v[30:33], v[164:167], v[212:215], v[30:33]
	v_mfma_f32_16x16x32_bf16 v[26:29], v[172:175], v[212:215], v[26:29]
	v_mfma_f32_16x16x32_bf16 v[18:21], v[172:175], v[220:223], v[18:21]
	v_mfma_f32_16x16x32_bf16 v[22:25], v[164:167], v[220:223], v[22:25]
	v_mfma_f32_16x16x32_bf16 v[14:17], v[176:179], v[192:195], v[14:17]
	v_mfma_f32_16x16x32_bf16 v[10:13], v[184:187], v[192:195], v[10:13]
	v_mfma_f32_16x16x32_bf16 v[2:5], v[184:187], v[200:203], v[2:5]
	v_mfma_f32_16x16x32_bf16 v[6:9], v[176:179], v[200:203], v[6:9]
	v_mfma_f32_16x16x32_bf16 v[114:117], v[176:179], v[208:211], v[114:117]
	v_mfma_f32_16x16x32_bf16 v[118:121], v[184:187], v[208:211], v[118:121]
	v_mfma_f32_16x16x32_bf16 v[126:129], v[184:187], v[216:219], v[126:129]
	v_mfma_f32_16x16x32_bf16 v[122:125], v[176:179], v[216:219], v[122:125]
	v_mfma_f32_16x16x32_bf16 v[14:17], v[180:183], v[196:199], v[14:17]
	v_mfma_f32_16x16x32_bf16 v[10:13], v[188:191], v[196:199], v[10:13]
	v_mfma_f32_16x16x32_bf16 v[2:5], v[188:191], v[204:207], v[2:5]
	v_mfma_f32_16x16x32_bf16 v[6:9], v[180:183], v[204:207], v[6:9]
	v_mfma_f32_16x16x32_bf16 v[114:117], v[180:183], v[212:215], v[114:117]
	v_mfma_f32_16x16x32_bf16 v[118:121], v[188:191], v[212:215], v[118:121]
	v_mfma_f32_16x16x32_bf16 v[126:129], v[188:191], v[220:223], v[126:129]
	v_mfma_f32_16x16x32_bf16 v[122:125], v[180:183], v[220:223], v[122:125]
	s_barrier
	s_add_i32 s59, s59, 2
	s_add_u32 s74, s74, 0x100
	s_addc_u32 s75, s75, 0
	s_cmp_gt_u32 s59, 13
	s_cbranch_scc0 .LBB0_538

; #define PG8_STAGEA(bufoff, gbase) PG8_STAGE_(bufoff, gbase, voffA)
; #define PG8_STAGEB(bufoff, gbase) PG8_STAGE_(bufoff, gbase, voffB)
; #define PG8_LDA(dst, b, h) do { _Pragma("unroll") for (int m = 0; m < 4; ++m) _Pragma("unroll") for (int k = 0; k < 2; ++k) dst[m][k] = *(const LAS bf16x8*)(lds + PG8_SA(b, h) + aoff + m * 2048 + k * 1024); } while (0)
; #define PG8_LDB(dst, b, h) do { _Pragma("unroll") for (int n = 0; n < 2; ++n) _Pragma("unroll") for (int k = 0; k < 2; ++k) dst[n][k] = *(const LAS bf16x8*)(lds + PG8_SB(b, h) + boff + n * 2048 + k * 1024); } while (0)
; #define PG8_MMA(ai, bj, At, Bt_) do { __builtin_amdgcn_s_setprio(1); _Pragma("unroll") for (int m = 0; m < 4; ++m) _Pragma("unroll") for (int n = 0; n < 2; ++n) _Pragma("unroll") for (int k = 0; k < 2; ++k) \
;         acc[ai][bj][m][n] = __builtin_amdgcn_mfma_f32_16x16x32_bf16(Bt_[n][k], At[m][k], acc[ai][bj][m][n], 0, 0, 0); __builtin_amdgcn_s_setprio(0); } while (0)
; #define PG8_WAIT_V(n) asm volatile("s_waitcnt vmcnt(" #n ")" ::: "memory")
; #define PG8_WAIT_L(n) asm volatile("s_waitcnt lgkmcnt(" #n ")" ::: "memory")
; #define PG8_BAR __builtin_amdgcn_s_barrier()
; #define PG8_SCHED __builtin_amdgcn_sched_barrier(0)
; template <int EK, int SK = -1>
; __device__ __forceinline__ void gemm_phase(LAS unsigned char* lds, const bf16_t* A, const bf16_t* Bt, int nM, int N, int K, const EpiArgs& E) {
;     ...
;         const bool has_next = S.next(ui + 1, nxt);
;         const char* nA = has_next ? (const char*)A + (size_t)nxt.pm * tstep : cA; const char* nB = has_next ? (const char*)Bt + (size_t)nxt.pn * tstep : cB;
;         for (int t = 0; t < nt; t += 2) {
;             const bool last = (t == nt - 2);
;             const char* a1 = cA + (size_t)(t + 1) * kstep;
;             const char* a2 = last ? nA : cA + (size_t)(t + 2) * kstep; const char* b2 = last ? nB : cB + (size_t)(t + 2) * kstep;
;             const char* a3 = a2 + kstep; const char* b3 = b2 + kstep;
;             PG8_LDB(B0, 0, 0); PG8_LDB(B1, 0, 1); PG8_SCHED; PG8_LDA(At, 0, 0); PG8_STAGEA(PG8_SA(1, 1), a1 + hstep);
;             PG8_WAIT_V(8); PG8_WAIT_L(0); PG8_BAR; PG8_MMA(0, 0, At, B0); PG8_MMA(0, 1, At, B1); PG8_BAR; PG8_SCHED;
;             PG8_LDA(At, 0, 1); PG8_STAGEB(PG8_SB(0, 0), b2); PG8_STAGEB(PG8_SB(0, 1), b2 + hstep); PG8_STAGEA(PG8_SA(0, 0), a2);
.LBB0_792:
	s_add_u32 s77, s38, 0x100
	s_addc_u32 s78, s39, 0
	v_lshl_add_u64 v[146:147], s[14:15], 0, v[138:139]
	v_lshl_add_u64 v[148:149], s[14:15], 0, v[140:141]
	s_mov_b32 s20, -2
	s_mov_b64 s[38:39], 0
	v_add_u32_e32 v150, s71, v152
	ds_read_b128 v[156:159], v150
	ds_read_b128 v[160:163], v150 offset:1024
	ds_read_b128 v[164:167], v150 offset:2048
	ds_read_b128 v[168:171], v150 offset:3072
	v_add_u32_e32 v150, s72, v152
	s_add_u32 s40, s14, s38
	ds_read_b128 v[172:175], v150
	ds_read_b128 v[176:179], v150 offset:1024
	ds_read_b128 v[180:183], v150 offset:2048
	ds_read_b128 v[184:187], v150 offset:3072
	s_addc_u32 s41, s15, s39
	s_add_u32 s40, s40, 0x100
	s_addc_u32 s41, s41, 0
	s_add_u32 s79, s77, s38
	s_addc_u32 s80, s78, s39
	s_cmpk_eq_i32 s38, 0x1500
	s_cselect_b32 s43, s37, s41
	s_cselect_b32 s42, s36, s40
	s_cselect_b32 s41, s11, s80
	s_cselect_b32 s40, s10, s79
	v_lshl_add_u64 v[150:151], v[146:147], 0, s[38:39]
	s_add_i32 m0, s55, 0xc000
	ds_read_b128 v[188:191], v154
	ds_read_b128 v[192:195], v154 offset:1024
	ds_read_b128 v[196:199], v154 offset:2048
	ds_read_b128 v[200:203], v154 offset:3072
	ds_read_b128 v[204:207], v154 offset:4096
	ds_read_b128 v[208:211], v154 offset:5120
	ds_read_b128 v[212:215], v154 offset:6144
	ds_read_b128 v[216:219], v154 offset:7168
	global_load_lds_dwordx4 v[150:151], off
	v_lshl_add_u64 v[150:151], v[148:149], 0, s[38:39]
	s_add_i32 m0, s55, 0xe000
	s_nop 0
	global_load_lds_dwordx4 v[150:151], off
	s_waitcnt vmcnt(8)
	s_waitcnt lgkmcnt(0)
	s_barrier
	s_waitcnt lgkmcnt(0)
	v_mfma_f32_16x16x32_bf16 v[126:129], v[156:159], v[188:191], 0
	v_mfma_f32_16x16x32_bf16 v[122:125], v[164:167], v[188:191], 0
	v_mfma_f32_16x16x32_bf16 v[114:117], v[164:167], v[196:199], 0
	v_mfma_f32_16x16x32_bf16 v[118:121], v[156:159], v[196:199], 0
	v_mfma_f32_16x16x32_bf16 v[110:113], v[156:159], v[204:207], 0
	v_mfma_f32_16x16x32_bf16 v[106:109], v[164:167], v[204:207], 0
	v_mfma_f32_16x16x32_bf16 v[98:101], v[164:167], v[212:215], 0
	v_mfma_f32_16x16x32_bf16 v[102:105], v[156:159], v[212:215], 0
	v_mfma_f32_16x16x32_bf16 v[126:129], v[160:163], v[192:195], v[126:129]
	v_mfma_f32_16x16x32_bf16 v[122:125], v[168:171], v[192:195], v[122:125]
	v_mfma_f32_16x16x32_bf16 v[114:117], v[168:171], v[200:203], v[114:117]
	v_mfma_f32_16x16x32_bf16 v[118:121], v[160:163], v[200:203], v[118:121]
	v_mfma_f32_16x16x32_bf16 v[110:113], v[160:163], v[208:211], v[110:113]
	v_mfma_f32_16x16x32_bf16 v[106:109], v[168:171], v[208:211], v[106:109]
	v_mfma_f32_16x16x32_bf16 v[98:101], v[168:171], v[216:219], v[98:101]
	v_mfma_f32_16x16x32_bf16 v[102:105], v[160:163], v[216:219], v[102:105]
	v_mfma_f32_16x16x32_bf16 v[94:97], v[172:175], v[188:191], 0
	v_mfma_f32_16x16x32_bf16 v[90:93], v[180:183], v[188:191], 0
	v_mfma_f32_16x16x32_bf16 v[82:85], v[180:183], v[196:199], 0
	v_mfma_f32_16x16x32_bf16 v[86:89], v[172:175], v[196:199], 0
	v_mfma_f32_16x16x32_bf16 v[78:81], v[172:175], v[204:207], 0
	v_mfma_f32_16x16x32_bf16 v[74:77], v[180:183], v[204:207], 0
	v_mfma_f32_16x16x32_bf16 v[66:69], v[180:183], v[212:215], 0
	v_mfma_f32_16x16x32_bf16 v[70:73], v[172:175], v[212:215], 0
	v_mfma_f32_16x16x32_bf16 v[94:97], v[176:179], v[192:195], v[94:97]
	v_mfma_f32_16x16x32_bf16 v[90:93], v[184:187], v[192:195], v[90:93]
	v_mfma_f32_16x16x32_bf16 v[82:85], v[184:187], v[200:203], v[82:85]
	v_mfma_f32_16x16x32_bf16 v[86:89], v[176:179], v[200:203], v[86:89]
	v_mfma_f32_16x16x32_bf16 v[78:81], v[176:179], v[208:211], v[78:81]
	v_mfma_f32_16x16x32_bf16 v[74:77], v[184:187], v[208:211], v[74:77]
	v_mfma_f32_16x16x32_bf16 v[66:69], v[184:187], v[216:219], v[66:69]
	v_mfma_f32_16x16x32_bf16 v[70:73], v[176:179], v[216:219], v[70:73]
	s_barrier
	s_add_i32 s79, s71, s54
	v_lshl_add_u64 v[150:151], s[40:41], 0, v[132:133]
	s_mov_b32 m0, s79
	ds_read_b128 v[188:191], v154 offset:16384
	ds_read_b128 v[192:195], v154 offset:17408
	ds_read_b128 v[196:199], v154 offset:18432
	ds_read_b128 v[200:203], v154 offset:19456
	ds_read_b128 v[204:207], v154 offset:20480
	ds_read_b128 v[208:211], v154 offset:21504
	ds_read_b128 v[212:215], v154 offset:22528
	ds_read_b128 v[216:219], v154 offset:23552
	global_load_lds_dwordx4 v[150:151], off
	s_add_i32 m0, s79, 0x2000
	s_add_u32 s80, s40, 0xb0000
	v_lshl_add_u64 v[220:221], s[40:41], 0, v[136:137]
	s_addc_u32 s81, s41, 0
	s_add_i32 s79, s72, s54
	global_load_lds_dwordx4 v[220:221], off
	v_lshl_add_u64 v[222:223], s[80:81], 0, v[132:133]
	s_mov_b32 m0, s79
	v_lshl_add_u64 v[224:225], s[42:43], 0, v[134:135]
	global_load_lds_dwordx4 v[222:223], off
	v_lshl_add_u64 v[222:223], s[80:81], 0, v[136:137]
	s_add_i32 m0, s79, 0x2000
	s_nop 0
	global_load_lds_dwordx4 v[222:223], off
	v_lshl_add_u64 v[222:223], s[42:43], 0, v[130:131]
	s_mov_b32 m0, s55
	s_nop 0
	global_load_lds_dwordx4 v[222:223], off
	s_mov_b32 m0, s56
	s_nop 0
	global_load_lds_dwordx4 v[224:225], off
	s_waitcnt vmcnt(8)
	s_waitcnt lgkmcnt(0)
	s_barrier
; #define PG8_STAGEA(bufoff, gbase) PG8_STAGE_(bufoff, gbase, voffA)
; #define PG8_LDA(dst, b, h) do { _Pragma("unroll") for (int m = 0; m < 4; ++m) _Pragma("unroll") for (int k = 0; k < 2; ++k) dst[m][k] = *(const LAS bf16x8*)(lds + PG8_SA(b, h) + aoff + m * 2048 + k * 1024); } while (0)
; #define PG8_LDB(dst, b, h) do { _Pragma("unroll") for (int n = 0; n < 2; ++n) _Pragma("unroll") for (int k = 0; k < 2; ++k) dst[n][k] = *(const LAS bf16x8*)(lds + PG8_SB(b, h) + boff + n * 2048 + k * 1024); } while (0)
; #define PG8_MMA(ai, bj, At, Bt_) do { __builtin_amdgcn_s_setprio(1); _Pragma("unroll") for (int m = 0; m < 4; ++m) _Pragma("unroll") for (int n = 0; n < 2; ++n) _Pragma("unroll") for (int k = 0; k < 2; ++k) \
;         acc[ai][bj][m][n] = __builtin_amdgcn_mfma_f32_16x16x32_bf16(Bt_[n][k], At[m][k], acc[ai][bj][m][n], 0, 0, 0); __builtin_amdgcn_s_setprio(0); } while (0)
; #define PG8_WAIT_V(n) asm volatile("s_waitcnt vmcnt(" #n ")" ::: "memory")
; #define PG8_WAIT_L(n) asm volatile("s_waitcnt lgkmcnt(" #n ")" ::: "memory")
; #define PG8_BAR __builtin_amdgcn_s_barrier()
; #define PG8_SCHED __builtin_amdgcn_sched_barrier(0)
; template <int EK, int SK = -1>
; __device__ __forceinline__ void gemm_phase(LAS unsigned char* lds, const bf16_t* A, const bf16_t* Bt, int nM, int N, int K, const EpiArgs& E) {
;     ...
;             PG8_WAIT_V(8); PG8_WAIT_L(0); PG8_BAR; PG8_MMA(1, 0, At, B0); PG8_MMA(1, 1, At, B1); PG8_BAR; PG8_SCHED;
;             PG8_LDB(B0, 1, 0); PG8_LDB(B1, 1, 1); PG8_SCHED; PG8_LDA(At, 1, 0); PG8_STAGEA(PG8_SA(0, 1), a2 + hstep);
;             PG8_WAIT_V(8); PG8_WAIT_L(0); PG8_BAR; PG8_MMA(0, 0, At, B0); PG8_MMA(0, 1, At, B1); PG8_BAR; PG8_SCHED;
	s_waitcnt lgkmcnt(0)
	v_mfma_f32_16x16x32_bf16 v[62:65], v[156:159], v[188:191], 0
	v_mfma_f32_16x16x32_bf16 v[58:61], v[164:167], v[188:191], 0
	v_mfma_f32_16x16x32_bf16 v[50:53], v[164:167], v[196:199], 0
	v_mfma_f32_16x16x32_bf16 v[54:57], v[156:159], v[196:199], 0
	v_mfma_f32_16x16x32_bf16 v[46:49], v[156:159], v[204:207], 0
	v_mfma_f32_16x16x32_bf16 v[42:45], v[164:167], v[204:207], 0
	v_mfma_f32_16x16x32_bf16 v[34:37], v[164:167], v[212:215], 0
	v_mfma_f32_16x16x32_bf16 v[38:41], v[156:159], v[212:215], 0
	v_mfma_f32_16x16x32_bf16 v[62:65], v[160:163], v[192:195], v[62:65]
	v_mfma_f32_16x16x32_bf16 v[58:61], v[168:171], v[192:195], v[58:61]
	v_mfma_f32_16x16x32_bf16 v[50:53], v[168:171], v[200:203], v[50:53]
	v_mfma_f32_16x16x32_bf16 v[54:57], v[160:163], v[200:203], v[54:57]
	v_mfma_f32_16x16x32_bf16 v[46:49], v[160:163], v[208:211], v[46:49]
	v_mfma_f32_16x16x32_bf16 v[42:45], v[168:171], v[208:211], v[42:45]
	v_mfma_f32_16x16x32_bf16 v[34:37], v[168:171], v[216:219], v[34:37]
	v_mfma_f32_16x16x32_bf16 v[38:41], v[160:163], v[216:219], v[38:41]
	v_mfma_f32_16x16x32_bf16 v[30:33], v[172:175], v[188:191], 0
	v_mfma_f32_16x16x32_bf16 v[26:29], v[180:183], v[188:191], 0
	v_mfma_f32_16x16x32_bf16 v[18:21], v[180:183], v[196:199], 0
	v_mfma_f32_16x16x32_bf16 v[22:25], v[172:175], v[196:199], 0
	v_mfma_f32_16x16x32_bf16 v[14:17], v[172:175], v[204:207], 0
	v_mfma_f32_16x16x32_bf16 v[10:13], v[180:183], v[204:207], 0
	v_mfma_f32_16x16x32_bf16 v[2:5], v[180:183], v[212:215], 0
	v_mfma_f32_16x16x32_bf16 v[6:9], v[172:175], v[212:215], 0
	v_mfma_f32_16x16x32_bf16 v[30:33], v[176:179], v[192:195], v[30:33]
	v_mfma_f32_16x16x32_bf16 v[26:29], v[184:187], v[192:195], v[26:29]
	v_mfma_f32_16x16x32_bf16 v[18:21], v[184:187], v[200:203], v[18:21]
	v_mfma_f32_16x16x32_bf16 v[22:25], v[176:179], v[200:203], v[22:25]
	v_mfma_f32_16x16x32_bf16 v[14:17], v[176:179], v[208:211], v[14:17]
	v_mfma_f32_16x16x32_bf16 v[10:13], v[184:187], v[208:211], v[10:13]
	v_mfma_f32_16x16x32_bf16 v[2:5], v[184:187], v[216:219], v[2:5]
	v_mfma_f32_16x16x32_bf16 v[6:9], v[176:179], v[216:219], v[6:9]
	s_barrier
	s_add_i32 s79, 0, 0x18000
	s_add_i32 s80, 0, 0x1c000
	v_add_u32_e32 v168, s79, v152
	v_add_u32_e32 v184, s80, v152
	ds_read_b128 v[156:159], v168
	ds_read_b128 v[160:163], v168 offset:1024
	ds_read_b128 v[164:167], v168 offset:2048
	ds_read_b128 v[168:171], v168 offset:3072
	ds_read_b128 v[172:175], v184
	ds_read_b128 v[176:179], v184 offset:1024
	ds_read_b128 v[180:183], v184 offset:2048
	ds_read_b128 v[184:187], v184 offset:3072
	s_add_u32 s42, s42, 0xb0000
	s_addc_u32 s43, s43, 0
	s_mov_b32 m0, s57
	v_lshl_add_u64 v[226:227], s[42:43], 0, v[130:131]
	ds_read_b128 v[188:191], v154 offset:32768
	ds_read_b128 v[192:195], v154 offset:33792
	ds_read_b128 v[196:199], v154 offset:34816
	ds_read_b128 v[200:203], v154 offset:35840
	ds_read_b128 v[204:207], v154 offset:36864
	ds_read_b128 v[208:211], v154 offset:37888
	ds_read_b128 v[212:215], v154 offset:38912
	ds_read_b128 v[216:219], v154 offset:39936
	global_load_lds_dwordx4 v[226:227], off
	v_lshl_add_u64 v[226:227], s[42:43], 0, v[134:135]
	s_mov_b32 m0, s58
	s_nop 0
	global_load_lds_dwordx4 v[226:227], off
	s_waitcnt vmcnt(8)
	s_waitcnt lgkmcnt(0)
	s_barrier
	s_waitcnt lgkmcnt(0)
	v_mfma_f32_16x16x32_bf16 v[126:129], v[156:159], v[188:191], v[126:129]
	v_mfma_f32_16x16x32_bf16 v[122:125], v[164:167], v[188:191], v[122:125]
	v_mfma_f32_16x16x32_bf16 v[114:117], v[164:167], v[196:199], v[114:117]
	v_mfma_f32_16x16x32_bf16 v[118:121], v[156:159], v[196:199], v[118:121]
	v_mfma_f32_16x16x32_bf16 v[110:113], v[156:159], v[204:207], v[110:113]
	v_mfma_f32_16x16x32_bf16 v[106:109], v[164:167], v[204:207], v[106:109]
	v_mfma_f32_16x16x32_bf16 v[98:101], v[164:167], v[212:215], v[98:101]
	v_mfma_f32_16x16x32_bf16 v[102:105], v[156:159], v[212:215], v[102:105]
	v_mfma_f32_16x16x32_bf16 v[126:129], v[160:163], v[192:195], v[126:129]
	v_mfma_f32_16x16x32_bf16 v[122:125], v[168:171], v[192:195], v[122:125]
	v_mfma_f32_16x16x32_bf16 v[114:117], v[168:171], v[200:203], v[114:117]
	v_mfma_f32_16x16x32_bf16 v[118:121], v[160:163], v[200:203], v[118:121]
	v_mfma_f32_16x16x32_bf16 v[110:113], v[160:163], v[208:211], v[110:113]
	v_mfma_f32_16x16x32_bf16 v[106:109], v[168:171], v[208:211], v[106:109]
	v_mfma_f32_16x16x32_bf16 v[98:101], v[168:171], v[216:219], v[98:101]
	v_mfma_f32_16x16x32_bf16 v[102:105], v[160:163], v[216:219], v[102:105]
	v_mfma_f32_16x16x32_bf16 v[94:97], v[172:175], v[188:191], v[94:97]
	v_mfma_f32_16x16x32_bf16 v[90:93], v[180:183], v[188:191], v[90:93]
	v_mfma_f32_16x16x32_bf16 v[82:85], v[180:183], v[196:199], v[82:85]
	v_mfma_f32_16x16x32_bf16 v[86:89], v[172:175], v[196:199], v[86:89]
	v_mfma_f32_16x16x32_bf16 v[78:81], v[172:175], v[204:207], v[78:81]
	v_mfma_f32_16x16x32_bf16 v[74:77], v[180:183], v[204:207], v[74:77]
	v_mfma_f32_16x16x32_bf16 v[66:69], v[180:183], v[212:215], v[66:69]
	v_mfma_f32_16x16x32_bf16 v[70:73], v[172:175], v[212:215], v[70:73]
	v_mfma_f32_16x16x32_bf16 v[94:97], v[176:179], v[192:195], v[94:97]
	v_mfma_f32_16x16x32_bf16 v[90:93], v[184:187], v[192:195], v[90:93]
	v_mfma_f32_16x16x32_bf16 v[82:85], v[184:187], v[200:203], v[82:85]
	v_mfma_f32_16x16x32_bf16 v[86:89], v[176:179], v[200:203], v[86:89]
	v_mfma_f32_16x16x32_bf16 v[78:81], v[176:179], v[208:211], v[78:81]
	v_mfma_f32_16x16x32_bf16 v[74:77], v[184:187], v[208:211], v[74:77]
	v_mfma_f32_16x16x32_bf16 v[66:69], v[184:187], v[216:219], v[66:69]
	v_mfma_f32_16x16x32_bf16 v[70:73], v[176:179], v[216:219], v[70:73]
	s_barrier
; #define PG8_STAGEA(bufoff, gbase) PG8_STAGE_(bufoff, gbase, voffA)
; #define PG8_STAGEB(bufoff, gbase) PG8_STAGE_(bufoff, gbase, voffB)
; #define PG8_LDA(dst, b, h) do { _Pragma("unroll") for (int m = 0; m < 4; ++m) _Pragma("unroll") for (int k = 0; k < 2; ++k) dst[m][k] = *(const LAS bf16x8*)(lds + PG8_SA(b, h) + aoff + m * 2048 + k * 1024); } while (0)
; #define PG8_LDB(dst, b, h) do { _Pragma("unroll") for (int n = 0; n < 2; ++n) _Pragma("unroll") for (int k = 0; k < 2; ++k) dst[n][k] = *(const LAS bf16x8*)(lds + PG8_SB(b, h) + boff + n * 2048 + k * 1024); } while (0)
; #define PG8_MMA(ai, bj, At, Bt_) do { __builtin_amdgcn_s_setprio(1); _Pragma("unroll") for (int m = 0; m < 4; ++m) _Pragma("unroll") for (int n = 0; n < 2; ++n) _Pragma("unroll") for (int k = 0; k < 2; ++k) \
;         acc[ai][bj][m][n] = __builtin_amdgcn_mfma_f32_16x16x32_bf16(Bt_[n][k], At[m][k], acc[ai][bj][m][n], 0, 0, 0); __builtin_amdgcn_s_setprio(0); } while (0)
; #define PG8_WAIT_V(n) asm volatile("s_waitcnt vmcnt(" #n ")" ::: "memory")
; #define PG8_WAIT_L(n) asm volatile("s_waitcnt lgkmcnt(" #n ")" ::: "memory")
; #define PG8_BAR __builtin_amdgcn_s_barrier()
; #define PG8_SCHED __builtin_amdgcn_sched_barrier(0)
; template <int EK, int SK = -1>
; __device__ __forceinline__ void gemm_phase(LAS unsigned char* lds, const bf16_t* A, const bf16_t* Bt, int nM, int N, int K, const EpiArgs& E) {
;     ...
;             PG8_LDB(B0, 0, 0); PG8_LDB(B1, 0, 1); PG8_SCHED; PG8_LDA(At, 0, 0); PG8_STAGEA(PG8_SA(1, 1), a1 + hstep);
;             PG8_WAIT_V(8); PG8_WAIT_L(0); PG8_BAR; PG8_MMA(0, 0, At, B0); PG8_MMA(0, 1, At, B1); PG8_BAR; PG8_SCHED;
;     ...
;             PG8_LDA(At, 1, 1); PG8_STAGEB(PG8_SB(1, 0), b3); PG8_STAGEB(PG8_SB(1, 1), b3 + hstep); PG8_STAGEA(PG8_SA(1, 0), a3);
;             PG8_WAIT_V(8); PG8_WAIT_L(0); PG8_BAR; PG8_MMA(1, 0, At, B0); PG8_MMA(1, 1, At, B1); PG8_BAR; PG8_SCHED;
;         }
	s_add_i32 s42, s79, s54
	v_lshl_add_u64 v[150:151], v[150:151], 0, s[22:23]
	s_mov_b32 m0, s42
	ds_read_b128 v[188:191], v154 offset:49152
	ds_read_b128 v[192:195], v154 offset:50176
	ds_read_b128 v[196:199], v154 offset:51200
	ds_read_b128 v[200:203], v154 offset:52224
	ds_read_b128 v[204:207], v154 offset:53248
	ds_read_b128 v[208:211], v154 offset:54272
	ds_read_b128 v[212:215], v154 offset:55296
	ds_read_b128 v[216:219], v154 offset:56320
	global_load_lds_dwordx4 v[150:151], off
	s_add_i32 m0, s42, 0x2000
	s_add_u32 s40, s40, 0xb0080
	v_lshl_add_u64 v[150:151], v[220:221], 0, s[22:23]
	s_addc_u32 s41, s41, 0
	s_add_i32 s42, s80, s54
	global_load_lds_dwordx4 v[150:151], off
	v_lshl_add_u64 v[150:151], s[40:41], 0, v[132:133]
	s_mov_b32 m0, s42
	s_nop 0
	global_load_lds_dwordx4 v[150:151], off
	v_lshl_add_u64 v[150:151], s[40:41], 0, v[136:137]
	s_add_i32 m0, s42, 0x2000
	s_nop 0
	global_load_lds_dwordx4 v[150:151], off
	v_lshl_add_u64 v[150:151], v[222:223], 0, s[22:23]
	s_mov_b32 m0, s69
	s_nop 0
	global_load_lds_dwordx4 v[150:151], off
	v_lshl_add_u64 v[150:151], v[224:225], 0, s[22:23]
	s_mov_b32 m0, s70
	s_nop 0
	global_load_lds_dwordx4 v[150:151], off
	s_waitcnt vmcnt(8)
	s_waitcnt lgkmcnt(0)
	s_barrier
	s_waitcnt lgkmcnt(0)
	v_mfma_f32_16x16x32_bf16 v[62:65], v[156:159], v[188:191], v[62:65]
	v_mfma_f32_16x16x32_bf16 v[58:61], v[164:167], v[188:191], v[58:61]
	v_mfma_f32_16x16x32_bf16 v[50:53], v[164:167], v[196:199], v[50:53]
	v_mfma_f32_16x16x32_bf16 v[54:57], v[156:159], v[196:199], v[54:57]
	v_mfma_f32_16x16x32_bf16 v[46:49], v[156:159], v[204:207], v[46:49]
	v_mfma_f32_16x16x32_bf16 v[42:45], v[164:167], v[204:207], v[42:45]
	v_mfma_f32_16x16x32_bf16 v[34:37], v[164:167], v[212:215], v[34:37]
	v_mfma_f32_16x16x32_bf16 v[38:41], v[156:159], v[212:215], v[38:41]
	v_mfma_f32_16x16x32_bf16 v[62:65], v[160:163], v[192:195], v[62:65]
	v_mfma_f32_16x16x32_bf16 v[58:61], v[168:171], v[192:195], v[58:61]
	v_mfma_f32_16x16x32_bf16 v[50:53], v[168:171], v[200:203], v[50:53]
	v_mfma_f32_16x16x32_bf16 v[54:57], v[160:163], v[200:203], v[54:57]
	v_mfma_f32_16x16x32_bf16 v[46:49], v[160:163], v[208:211], v[46:49]
	v_mfma_f32_16x16x32_bf16 v[42:45], v[168:171], v[208:211], v[42:45]
	v_mfma_f32_16x16x32_bf16 v[34:37], v[168:171], v[216:219], v[34:37]
	v_mfma_f32_16x16x32_bf16 v[38:41], v[160:163], v[216:219], v[38:41]
	v_mfma_f32_16x16x32_bf16 v[30:33], v[172:175], v[188:191], v[30:33]
	v_mfma_f32_16x16x32_bf16 v[26:29], v[180:183], v[188:191], v[26:29]
	v_mfma_f32_16x16x32_bf16 v[18:21], v[180:183], v[196:199], v[18:21]
	v_mfma_f32_16x16x32_bf16 v[22:25], v[172:175], v[196:199], v[22:25]
	v_mfma_f32_16x16x32_bf16 v[14:17], v[172:175], v[204:207], v[14:17]
	v_mfma_f32_16x16x32_bf16 v[10:13], v[180:183], v[204:207], v[10:13]
	v_mfma_f32_16x16x32_bf16 v[2:5], v[180:183], v[212:215], v[2:5]
	v_mfma_f32_16x16x32_bf16 v[6:9], v[172:175], v[212:215], v[6:9]
	v_mfma_f32_16x16x32_bf16 v[30:33], v[176:179], v[192:195], v[30:33]
	v_mfma_f32_16x16x32_bf16 v[26:29], v[184:187], v[192:195], v[26:29]
	v_mfma_f32_16x16x32_bf16 v[18:21], v[184:187], v[200:203], v[18:21]
	v_mfma_f32_16x16x32_bf16 v[22:25], v[176:179], v[200:203], v[22:25]
	v_mfma_f32_16x16x32_bf16 v[14:17], v[176:179], v[208:211], v[14:17]
	v_mfma_f32_16x16x32_bf16 v[10:13], v[184:187], v[208:211], v[10:13]
	v_mfma_f32_16x16x32_bf16 v[2:5], v[184:187], v[216:219], v[2:5]
	v_mfma_f32_16x16x32_bf16 v[6:9], v[176:179], v[216:219], v[6:9]
	s_barrier
	s_add_i32 s20, s20, 2
	s_add_u32 s38, s38, 0x100
	s_addc_u32 s39, s39, 0
	s_cmp_gt_u32 s20, 41
	s_cbranch_scc0 .LBB0_793
	s_branch .Lmy_kexit_3
.LBB0_793:
	v_add_u32_e32 v150, s71, v152
	ds_read_b128 v[156:159], v150
	ds_read_b128 v[160:163], v150 offset:1024
	ds_read_b128 v[164:167], v150 offset:2048
	ds_read_b128 v[168:171], v150 offset:3072
	v_add_u32_e32 v150, s72, v152
	s_add_u32 s40, s14, s38
	ds_read_b128 v[172:175], v150
	ds_read_b128 v[176:179], v150 offset:1024
	ds_read_b128 v[180:183], v150 offset:2048
	ds_read_b128 v[184:187], v150 offset:3072
	s_addc_u32 s41, s15, s39
	s_add_u32 s40, s40, 0x100
	s_addc_u32 s41, s41, 0
	s_add_u32 s79, s77, s38
	s_addc_u32 s80, s78, s39
	s_cmpk_eq_i32 s38, 0x1500
	s_cselect_b32 s43, s37, s41
	s_cselect_b32 s42, s36, s40
	s_cselect_b32 s41, s11, s80
	s_cselect_b32 s40, s10, s79
	v_lshl_add_u64 v[150:151], v[146:147], 0, s[38:39]
	s_add_i32 m0, s55, 0xc000
	ds_read_b128 v[188:191], v154
	ds_read_b128 v[192:195], v154 offset:1024
	ds_read_b128 v[196:199], v154 offset:2048
	ds_read_b128 v[200:203], v154 offset:3072
	ds_read_b128 v[204:207], v154 offset:4096
	ds_read_b128 v[208:211], v154 offset:5120
	ds_read_b128 v[212:215], v154 offset:6144
	ds_read_b128 v[216:219], v154 offset:7168
	global_load_lds_dwordx4 v[150:151], off
	v_lshl_add_u64 v[150:151], v[148:149], 0, s[38:39]
	s_add_i32 m0, s55, 0xe000
	s_nop 0
	global_load_lds_dwordx4 v[150:151], off
	s_waitcnt vmcnt(8)
	s_waitcnt lgkmcnt(0)
	s_barrier
; #define PG8_STAGEA(bufoff, gbase) PG8_STAGE_(bufoff, gbase, voffA)
; #define PG8_STAGEB(bufoff, gbase) PG8_STAGE_(bufoff, gbase, voffB)
; #define PG8_LDA(dst, b, h) do { _Pragma("unroll") for (int m = 0; m < 4; ++m) _Pragma("unroll") for (int k = 0; k < 2; ++k) dst[m][k] = *(const LAS bf16x8*)(lds + PG8_SA(b, h) + aoff + m * 2048 + k * 1024); } while (0)
; #define PG8_LDB(dst, b, h) do { _Pragma("unroll") for (int n = 0; n < 2; ++n) _Pragma("unroll") for (int k = 0; k < 2; ++k) dst[n][k] = *(const LAS bf16x8*)(lds + PG8_SB(b, h) + boff + n * 2048 + k * 1024); } while (0)
; #define PG8_MMA(ai, bj, At, Bt_) do { __builtin_amdgcn_s_setprio(1); _Pragma("unroll") for (int m = 0; m < 4; ++m) _Pragma("unroll") for (int n = 0; n < 2; ++n) _Pragma("unroll") for (int k = 0; k < 2; ++k) \
;         acc[ai][bj][m][n] = __builtin_amdgcn_mfma_f32_16x16x32_bf16(Bt_[n][k], At[m][k], acc[ai][bj][m][n], 0, 0, 0); __builtin_amdgcn_s_setprio(0); } while (0)
; #define PG8_WAIT_V(n) asm volatile("s_waitcnt vmcnt(" #n ")" ::: "memory")
; #define PG8_WAIT_L(n) asm volatile("s_waitcnt lgkmcnt(" #n ")" ::: "memory")
; #define PG8_BAR __builtin_amdgcn_s_barrier()
; #define PG8_SCHED __builtin_amdgcn_sched_barrier(0)
; template <int EK, int SK = -1>
; __device__ __forceinline__ void gemm_phase(LAS unsigned char* lds, const bf16_t* A, const bf16_t* Bt, int nM, int N, int K, const EpiArgs& E) {
;     ...
;             PG8_WAIT_V(8); PG8_WAIT_L(0); PG8_BAR; PG8_MMA(0, 0, At, B0); PG8_MMA(0, 1, At, B1); PG8_BAR; PG8_SCHED;
;             PG8_LDA(At, 0, 1); PG8_STAGEB(PG8_SB(0, 0), b2); PG8_STAGEB(PG8_SB(0, 1), b2 + hstep); PG8_STAGEA(PG8_SA(0, 0), a2);
;             PG8_WAIT_V(8); PG8_WAIT_L(0); PG8_BAR; PG8_MMA(1, 0, At, B0); PG8_MMA(1, 1, At, B1); PG8_BAR; PG8_SCHED;
;             PG8_LDB(B0, 1, 0); PG8_LDB(B1, 1, 1); PG8_SCHED; PG8_LDA(At, 1, 0); PG8_STAGEA(PG8_SA(0, 1), a2 + hstep);
;             PG8_WAIT_V(8); PG8_WAIT_L(0); PG8_BAR; PG8_MMA(0, 0, At, B0); PG8_MMA(0, 1, At, B1); PG8_BAR; PG8_SCHED;
	s_waitcnt lgkmcnt(0)
	v_mfma_f32_16x16x32_bf16 v[126:129], v[156:159], v[188:191], v[126:129]
	v_mfma_f32_16x16x32_bf16 v[122:125], v[164:167], v[188:191], v[122:125]
	v_mfma_f32_16x16x32_bf16 v[114:117], v[164:167], v[196:199], v[114:117]
	v_mfma_f32_16x16x32_bf16 v[118:121], v[156:159], v[196:199], v[118:121]
	v_mfma_f32_16x16x32_bf16 v[110:113], v[156:159], v[204:207], v[110:113]
	v_mfma_f32_16x16x32_bf16 v[106:109], v[164:167], v[204:207], v[106:109]
	v_mfma_f32_16x16x32_bf16 v[98:101], v[164:167], v[212:215], v[98:101]
	v_mfma_f32_16x16x32_bf16 v[102:105], v[156:159], v[212:215], v[102:105]
	v_mfma_f32_16x16x32_bf16 v[126:129], v[160:163], v[192:195], v[126:129]
	v_mfma_f32_16x16x32_bf16 v[122:125], v[168:171], v[192:195], v[122:125]
	v_mfma_f32_16x16x32_bf16 v[114:117], v[168:171], v[200:203], v[114:117]
	v_mfma_f32_16x16x32_bf16 v[118:121], v[160:163], v[200:203], v[118:121]
	v_mfma_f32_16x16x32_bf16 v[110:113], v[160:163], v[208:211], v[110:113]
	v_mfma_f32_16x16x32_bf16 v[106:109], v[168:171], v[208:211], v[106:109]
	v_mfma_f32_16x16x32_bf16 v[98:101], v[168:171], v[216:219], v[98:101]
	v_mfma_f32_16x16x32_bf16 v[102:105], v[160:163], v[216:219], v[102:105]
	v_mfma_f32_16x16x32_bf16 v[94:97], v[172:175], v[188:191], v[94:97]
	v_mfma_f32_16x16x32_bf16 v[90:93], v[180:183], v[188:191], v[90:93]
	v_mfma_f32_16x16x32_bf16 v[82:85], v[180:183], v[196:199], v[82:85]
	v_mfma_f32_16x16x32_bf16 v[86:89], v[172:175], v[196:199], v[86:89]
	v_mfma_f32_16x16x32_bf16 v[78:81], v[172:175], v[204:207], v[78:81]
	v_mfma_f32_16x16x32_bf16 v[74:77], v[180:183], v[204:207], v[74:77]
	v_mfma_f32_16x16x32_bf16 v[66:69], v[180:183], v[212:215], v[66:69]
	v_mfma_f32_16x16x32_bf16 v[70:73], v[172:175], v[212:215], v[70:73]
	v_mfma_f32_16x16x32_bf16 v[94:97], v[176:179], v[192:195], v[94:97]
	v_mfma_f32_16x16x32_bf16 v[90:93], v[184:187], v[192:195], v[90:93]
	v_mfma_f32_16x16x32_bf16 v[82:85], v[184:187], v[200:203], v[82:85]
	v_mfma_f32_16x16x32_bf16 v[86:89], v[176:179], v[200:203], v[86:89]
	v_mfma_f32_16x16x32_bf16 v[78:81], v[176:179], v[208:211], v[78:81]
	v_mfma_f32_16x16x32_bf16 v[74:77], v[184:187], v[208:211], v[74:77]
	v_mfma_f32_16x16x32_bf16 v[66:69], v[184:187], v[216:219], v[66:69]
	v_mfma_f32_16x16x32_bf16 v[70:73], v[176:179], v[216:219], v[70:73]
	s_barrier
	s_add_i32 s79, s71, s54
	v_lshl_add_u64 v[150:151], s[40:41], 0, v[132:133]
	s_mov_b32 m0, s79
	ds_read_b128 v[188:191], v154 offset:16384
	ds_read_b128 v[192:195], v154 offset:17408
	ds_read_b128 v[196:199], v154 offset:18432
	ds_read_b128 v[200:203], v154 offset:19456
	ds_read_b128 v[204:207], v154 offset:20480
	ds_read_b128 v[208:211], v154 offset:21504
	ds_read_b128 v[212:215], v154 offset:22528
	ds_read_b128 v[216:219], v154 offset:23552
	global_load_lds_dwordx4 v[150:151], off
	s_add_i32 m0, s79, 0x2000
	s_add_u32 s80, s40, 0xb0000
	v_lshl_add_u64 v[220:221], s[40:41], 0, v[136:137]
	s_addc_u32 s81, s41, 0
	s_add_i32 s79, s72, s54
	global_load_lds_dwordx4 v[220:221], off
	v_lshl_add_u64 v[222:223], s[80:81], 0, v[132:133]
	s_mov_b32 m0, s79
	v_lshl_add_u64 v[224:225], s[42:43], 0, v[134:135]
	global_load_lds_dwordx4 v[222:223], off
	v_lshl_add_u64 v[222:223], s[80:81], 0, v[136:137]
	s_add_i32 m0, s79, 0x2000
	s_nop 0
	global_load_lds_dwordx4 v[222:223], off
	v_lshl_add_u64 v[222:223], s[42:43], 0, v[130:131]
	s_mov_b32 m0, s55
	s_nop 0
	global_load_lds_dwordx4 v[222:223], off
	s_mov_b32 m0, s56
	s_nop 0
	global_load_lds_dwordx4 v[224:225], off
	s_waitcnt vmcnt(8)
	s_waitcnt lgkmcnt(0)
	s_barrier
	s_waitcnt lgkmcnt(0)
	v_mfma_f32_16x16x32_bf16 v[62:65], v[156:159], v[188:191], v[62:65]
	v_mfma_f32_16x16x32_bf16 v[58:61], v[164:167], v[188:191], v[58:61]
	v_mfma_f32_16x16x32_bf16 v[50:53], v[164:167], v[196:199], v[50:53]
	v_mfma_f32_16x16x32_bf16 v[54:57], v[156:159], v[196:199], v[54:57]
	v_mfma_f32_16x16x32_bf16 v[46:49], v[156:159], v[204:207], v[46:49]
	v_mfma_f32_16x16x32_bf16 v[42:45], v[164:167], v[204:207], v[42:45]
	v_mfma_f32_16x16x32_bf16 v[34:37], v[164:167], v[212:215], v[34:37]
	v_mfma_f32_16x16x32_bf16 v[38:41], v[156:159], v[212:215], v[38:41]
	v_mfma_f32_16x16x32_bf16 v[62:65], v[160:163], v[192:195], v[62:65]
	v_mfma_f32_16x16x32_bf16 v[58:61], v[168:171], v[192:195], v[58:61]
	v_mfma_f32_16x16x32_bf16 v[50:53], v[168:171], v[200:203], v[50:53]
	v_mfma_f32_16x16x32_bf16 v[54:57], v[160:163], v[200:203], v[54:57]
	v_mfma_f32_16x16x32_bf16 v[46:49], v[160:163], v[208:211], v[46:49]
	v_mfma_f32_16x16x32_bf16 v[42:45], v[168:171], v[208:211], v[42:45]
	v_mfma_f32_16x16x32_bf16 v[34:37], v[168:171], v[216:219], v[34:37]
	v_mfma_f32_16x16x32_bf16 v[38:41], v[160:163], v[216:219], v[38:41]
	v_mfma_f32_16x16x32_bf16 v[30:33], v[172:175], v[188:191], v[30:33]
	v_mfma_f32_16x16x32_bf16 v[26:29], v[180:183], v[188:191], v[26:29]
	v_mfma_f32_16x16x32_bf16 v[18:21], v[180:183], v[196:199], v[18:21]
	v_mfma_f32_16x16x32_bf16 v[22:25], v[172:175], v[196:199], v[22:25]
	v_mfma_f32_16x16x32_bf16 v[14:17], v[172:175], v[204:207], v[14:17]
	v_mfma_f32_16x16x32_bf16 v[10:13], v[180:183], v[204:207], v[10:13]
	v_mfma_f32_16x16x32_bf16 v[2:5], v[180:183], v[212:215], v[2:5]
	v_mfma_f32_16x16x32_bf16 v[6:9], v[172:175], v[212:215], v[6:9]
	v_mfma_f32_16x16x32_bf16 v[30:33], v[176:179], v[192:195], v[30:33]
	v_mfma_f32_16x16x32_bf16 v[26:29], v[184:187], v[192:195], v[26:29]
	v_mfma_f32_16x16x32_bf16 v[18:21], v[184:187], v[200:203], v[18:21]
	v_mfma_f32_16x16x32_bf16 v[22:25], v[176:179], v[200:203], v[22:25]
	v_mfma_f32_16x16x32_bf16 v[14:17], v[176:179], v[208:211], v[14:17]
	v_mfma_f32_16x16x32_bf16 v[10:13], v[184:187], v[208:211], v[10:13]
	v_mfma_f32_16x16x32_bf16 v[2:5], v[184:187], v[216:219], v[2:5]
	v_mfma_f32_16x16x32_bf16 v[6:9], v[176:179], v[216:219], v[6:9]
	s_barrier
; #define PG8_STAGEA(bufoff, gbase) PG8_STAGE_(bufoff, gbase, voffA)
; #define PG8_STAGEB(bufoff, gbase) PG8_STAGE_(bufoff, gbase, voffB)
; #define PG8_LDA(dst, b, h) do { _Pragma("unroll") for (int m = 0; m < 4; ++m) _Pragma("unroll") for (int k = 0; k < 2; ++k) dst[m][k] = *(const LAS bf16x8*)(lds + PG8_SA(b, h) + aoff + m * 2048 + k * 1024); } while (0)
; #define PG8_LDB(dst, b, h) do { _Pragma("unroll") for (int n = 0; n < 2; ++n) _Pragma("unroll") for (int k = 0; k < 2; ++k) dst[n][k] = *(const LAS bf16x8*)(lds + PG8_SB(b, h) + boff + n * 2048 + k * 1024); } while (0)
; #define PG8_MMA(ai, bj, At, Bt_) do { __builtin_amdgcn_s_setprio(1); _Pragma("unroll") for (int m = 0; m < 4; ++m) _Pragma("unroll") for (int n = 0; n < 2; ++n) _Pragma("unroll") for (int k = 0; k < 2; ++k) \
;         acc[ai][bj][m][n] = __builtin_amdgcn_mfma_f32_16x16x32_bf16(Bt_[n][k], At[m][k], acc[ai][bj][m][n], 0, 0, 0); __builtin_amdgcn_s_setprio(0); } while (0)
; #define PG8_WAIT_V(n) asm volatile("s_waitcnt vmcnt(" #n ")" ::: "memory")
; #define PG8_WAIT_L(n) asm volatile("s_waitcnt lgkmcnt(" #n ")" ::: "memory")
; #define PG8_BAR __builtin_amdgcn_s_barrier()
; #define PG8_SCHED __builtin_amdgcn_sched_barrier(0)
; template <int EK, int SK = -1>
; __device__ __forceinline__ void gemm_phase(LAS unsigned char* lds, const bf16_t* A, const bf16_t* Bt, int nM, int N, int K, const EpiArgs& E) {
;     ...
;             PG8_LDB(B0, 1, 0); PG8_LDB(B1, 1, 1); PG8_SCHED; PG8_LDA(At, 1, 0); PG8_STAGEA(PG8_SA(0, 1), a2 + hstep);
;             PG8_WAIT_V(8); PG8_WAIT_L(0); PG8_BAR; PG8_MMA(0, 0, At, B0); PG8_MMA(0, 1, At, B1); PG8_BAR; PG8_SCHED;
;             PG8_LDA(At, 1, 1); PG8_STAGEB(PG8_SB(1, 0), b3); PG8_STAGEB(PG8_SB(1, 1), b3 + hstep); PG8_STAGEA(PG8_SA(1, 0), a3);
;             PG8_WAIT_V(8); PG8_WAIT_L(0); PG8_BAR; PG8_MMA(1, 0, At, B0); PG8_MMA(1, 1, At, B1); PG8_BAR; PG8_SCHED;
;         }
	s_add_i32 s79, 0, 0x18000
	s_add_i32 s80, 0, 0x1c000
	v_add_u32_e32 v168, s79, v152
	v_add_u32_e32 v184, s80, v152
	ds_read_b128 v[156:159], v168
	ds_read_b128 v[160:163], v168 offset:1024
	ds_read_b128 v[164:167], v168 offset:2048
	ds_read_b128 v[168:171], v168 offset:3072
	ds_read_b128 v[172:175], v184
	ds_read_b128 v[176:179], v184 offset:1024
	ds_read_b128 v[180:183], v184 offset:2048
	ds_read_b128 v[184:187], v184 offset:3072
	s_add_u32 s42, s42, 0xb0000
	s_addc_u32 s43, s43, 0
	s_mov_b32 m0, s57
	v_lshl_add_u64 v[226:227], s[42:43], 0, v[130:131]
	ds_read_b128 v[188:191], v154 offset:32768
	ds_read_b128 v[192:195], v154 offset:33792
	ds_read_b128 v[196:199], v154 offset:34816
	ds_read_b128 v[200:203], v154 offset:35840
	ds_read_b128 v[204:207], v154 offset:36864
	ds_read_b128 v[208:211], v154 offset:37888
	ds_read_b128 v[212:215], v154 offset:38912
	ds_read_b128 v[216:219], v154 offset:39936
	global_load_lds_dwordx4 v[226:227], off
	v_lshl_add_u64 v[226:227], s[42:43], 0, v[134:135]
	s_mov_b32 m0, s58
	s_nop 0
	global_load_lds_dwordx4 v[226:227], off
	s_waitcnt vmcnt(8)
	s_waitcnt lgkmcnt(0)
	s_barrier
	s_waitcnt lgkmcnt(0)
	v_mfma_f32_16x16x32_bf16 v[126:129], v[156:159], v[188:191], v[126:129]
	v_mfma_f32_16x16x32_bf16 v[122:125], v[164:167], v[188:191], v[122:125]
	v_mfma_f32_16x16x32_bf16 v[114:117], v[164:167], v[196:199], v[114:117]
	v_mfma_f32_16x16x32_bf16 v[118:121], v[156:159], v[196:199], v[118:121]
	v_mfma_f32_16x16x32_bf16 v[110:113], v[156:159], v[204:207], v[110:113]
	v_mfma_f32_16x16x32_bf16 v[106:109], v[164:167], v[204:207], v[106:109]
	v_mfma_f32_16x16x32_bf16 v[98:101], v[164:167], v[212:215], v[98:101]
	v_mfma_f32_16x16x32_bf16 v[102:105], v[156:159], v[212:215], v[102:105]
	v_mfma_f32_16x16x32_bf16 v[126:129], v[160:163], v[192:195], v[126:129]
	v_mfma_f32_16x16x32_bf16 v[122:125], v[168:171], v[192:195], v[122:125]
	v_mfma_f32_16x16x32_bf16 v[114:117], v[168:171], v[200:203], v[114:117]
	v_mfma_f32_16x16x32_bf16 v[118:121], v[160:163], v[200:203], v[118:121]
	v_mfma_f32_16x16x32_bf16 v[110:113], v[160:163], v[208:211], v[110:113]
	v_mfma_f32_16x16x32_bf16 v[106:109], v[168:171], v[208:211], v[106:109]
	v_mfma_f32_16x16x32_bf16 v[98:101], v[168:171], v[216:219], v[98:101]
	v_mfma_f32_16x16x32_bf16 v[102:105], v[160:163], v[216:219], v[102:105]
	v_mfma_f32_16x16x32_bf16 v[94:97], v[172:175], v[188:191], v[94:97]
	v_mfma_f32_16x16x32_bf16 v[90:93], v[180:183], v[188:191], v[90:93]
	v_mfma_f32_16x16x32_bf16 v[82:85], v[180:183], v[196:199], v[82:85]
	v_mfma_f32_16x16x32_bf16 v[86:89], v[172:175], v[196:199], v[86:89]
	v_mfma_f32_16x16x32_bf16 v[78:81], v[172:175], v[204:207], v[78:81]
	v_mfma_f32_16x16x32_bf16 v[74:77], v[180:183], v[204:207], v[74:77]
	v_mfma_f32_16x16x32_bf16 v[66:69], v[180:183], v[212:215], v[66:69]
	v_mfma_f32_16x16x32_bf16 v[70:73], v[172:175], v[212:215], v[70:73]
	v_mfma_f32_16x16x32_bf16 v[94:97], v[176:179], v[192:195], v[94:97]
	v_mfma_f32_16x16x32_bf16 v[90:93], v[184:187], v[192:195], v[90:93]
	v_mfma_f32_16x16x32_bf16 v[82:85], v[184:187], v[200:203], v[82:85]
	v_mfma_f32_16x16x32_bf16 v[86:89], v[176:179], v[200:203], v[86:89]
	v_mfma_f32_16x16x32_bf16 v[78:81], v[176:179], v[208:211], v[78:81]
	v_mfma_f32_16x16x32_bf16 v[74:77], v[184:187], v[208:211], v[74:77]
	v_mfma_f32_16x16x32_bf16 v[66:69], v[184:187], v[216:219], v[66:69]
	v_mfma_f32_16x16x32_bf16 v[70:73], v[176:179], v[216:219], v[70:73]
	s_barrier
	s_add_i32 s42, s79, s54
	v_lshl_add_u64 v[150:151], v[150:151], 0, s[22:23]
	s_mov_b32 m0, s42
	ds_read_b128 v[188:191], v154 offset:49152
	ds_read_b128 v[192:195], v154 offset:50176
	ds_read_b128 v[196:199], v154 offset:51200
	ds_read_b128 v[200:203], v154 offset:52224
	ds_read_b128 v[204:207], v154 offset:53248
	ds_read_b128 v[208:211], v154 offset:54272
	ds_read_b128 v[212:215], v154 offset:55296
	ds_read_b128 v[216:219], v154 offset:56320
	global_load_lds_dwordx4 v[150:151], off
	s_add_i32 m0, s42, 0x2000
	s_add_u32 s40, s40, 0xb0080
	v_lshl_add_u64 v[150:151], v[220:221], 0, s[22:23]
	s_addc_u32 s41, s41, 0
	s_add_i32 s42, s80, s54
	global_load_lds_dwordx4 v[150:151], off
	v_lshl_add_u64 v[150:151], s[40:41], 0, v[132:133]
	s_mov_b32 m0, s42
	s_nop 0
	global_load_lds_dwordx4 v[150:151], off
	v_lshl_add_u64 v[150:151], s[40:41], 0, v[136:137]
	s_add_i32 m0, s42, 0x2000
	s_nop 0
	global_load_lds_dwordx4 v[150:151], off
	v_lshl_add_u64 v[150:151], v[222:223], 0, s[22:23]
	s_mov_b32 m0, s69
	s_nop 0
	global_load_lds_dwordx4 v[150:151], off
	v_lshl_add_u64 v[150:151], v[224:225], 0, s[22:23]
	s_mov_b32 m0, s70
	s_nop 0
	global_load_lds_dwordx4 v[150:151], off
	s_waitcnt vmcnt(8)
	s_waitcnt lgkmcnt(0)
	s_barrier
	s_waitcnt lgkmcnt(0)
	v_mfma_f32_16x16x32_bf16 v[62:65], v[156:159], v[188:191], v[62:65]
	v_mfma_f32_16x16x32_bf16 v[58:61], v[164:167], v[188:191], v[58:61]
	v_mfma_f32_16x16x32_bf16 v[50:53], v[164:167], v[196:199], v[50:53]
	v_mfma_f32_16x16x32_bf16 v[54:57], v[156:159], v[196:199], v[54:57]
	v_mfma_f32_16x16x32_bf16 v[46:49], v[156:159], v[204:207], v[46:49]
	v_mfma_f32_16x16x32_bf16 v[42:45], v[164:167], v[204:207], v[42:45]
	v_mfma_f32_16x16x32_bf16 v[34:37], v[164:167], v[212:215], v[34:37]
	v_mfma_f32_16x16x32_bf16 v[38:41], v[156:159], v[212:215], v[38:41]
	v_mfma_f32_16x16x32_bf16 v[62:65], v[160:163], v[192:195], v[62:65]
	v_mfma_f32_16x16x32_bf16 v[58:61], v[168:171], v[192:195], v[58:61]
	v_mfma_f32_16x16x32_bf16 v[50:53], v[168:171], v[200:203], v[50:53]
	v_mfma_f32_16x16x32_bf16 v[54:57], v[160:163], v[200:203], v[54:57]
	v_mfma_f32_16x16x32_bf16 v[46:49], v[160:163], v[208:211], v[46:49]
	v_mfma_f32_16x16x32_bf16 v[42:45], v[168:171], v[208:211], v[42:45]
	v_mfma_f32_16x16x32_bf16 v[34:37], v[168:171], v[216:219], v[34:37]
	v_mfma_f32_16x16x32_bf16 v[38:41], v[160:163], v[216:219], v[38:41]
	v_mfma_f32_16x16x32_bf16 v[30:33], v[172:175], v[188:191], v[30:33]
	v_mfma_f32_16x16x32_bf16 v[26:29], v[180:183], v[188:191], v[26:29]
	v_mfma_f32_16x16x32_bf16 v[18:21], v[180:183], v[196:199], v[18:21]
	v_mfma_f32_16x16x32_bf16 v[22:25], v[172:175], v[196:199], v[22:25]
	v_mfma_f32_16x16x32_bf16 v[14:17], v[172:175], v[204:207], v[14:17]
	v_mfma_f32_16x16x32_bf16 v[10:13], v[180:183], v[204:207], v[10:13]
	v_mfma_f32_16x16x32_bf16 v[2:5], v[180:183], v[212:215], v[2:5]
	v_mfma_f32_16x16x32_bf16 v[6:9], v[172:175], v[212:215], v[6:9]
	v_mfma_f32_16x16x32_bf16 v[30:33], v[176:179], v[192:195], v[30:33]
	v_mfma_f32_16x16x32_bf16 v[26:29], v[184:187], v[192:195], v[26:29]
	v_mfma_f32_16x16x32_bf16 v[18:21], v[184:187], v[200:203], v[18:21]
	v_mfma_f32_16x16x32_bf16 v[22:25], v[176:179], v[200:203], v[22:25]
	v_mfma_f32_16x16x32_bf16 v[14:17], v[176:179], v[208:211], v[14:17]
	v_mfma_f32_16x16x32_bf16 v[10:13], v[184:187], v[208:211], v[10:13]
	v_mfma_f32_16x16x32_bf16 v[2:5], v[184:187], v[216:219], v[2:5]
	v_mfma_f32_16x16x32_bf16 v[6:9], v[176:179], v[216:219], v[6:9]
	s_barrier
	s_add_i32 s20, s20, 2
	s_add_u32 s38, s38, 0x100
	s_addc_u32 s39, s39, 0
	s_cmp_gt_u32 s20, 41
	s_cbranch_scc0 .LBB0_793

; #define PG8_STAGEA(bufoff, gbase) PG8_STAGE_(bufoff, gbase, voffA)
; #define PG8_STAGEB(bufoff, gbase) PG8_STAGE_(bufoff, gbase, voffB)
; #define PG8_LDA(dst, b, h) do { _Pragma("unroll") for (int m = 0; m < 4; ++m) _Pragma("unroll") for (int k = 0; k < 2; ++k) dst[m][k] = *(const LAS bf16x8*)(lds + PG8_SA(b, h) + aoff + m * 2048 + k * 1024); } while (0)
; #define PG8_LDB(dst, b, h) do { _Pragma("unroll") for (int n = 0; n < 2; ++n) _Pragma("unroll") for (int k = 0; k < 2; ++k) dst[n][k] = *(const LAS bf16x8*)(lds + PG8_SB(b, h) + boff + n * 2048 + k * 1024); } while (0)
; #define PG8_MMA(ai, bj, At, Bt_) do { __builtin_amdgcn_s_setprio(1); _Pragma("unroll") for (int m = 0; m < 4; ++m) _Pragma("unroll") for (int n = 0; n < 2; ++n) _Pragma("unroll") for (int k = 0; k < 2; ++k) \
;         acc[ai][bj][m][n] = __builtin_amdgcn_mfma_f32_16x16x32_bf16(Bt_[n][k], At[m][k], acc[ai][bj][m][n], 0, 0, 0); __builtin_amdgcn_s_setprio(0); } while (0)
; #define PG8_WAIT_V(n) asm volatile("s_waitcnt vmcnt(" #n ")" ::: "memory")
; #define PG8_WAIT_L(n) asm volatile("s_waitcnt lgkmcnt(" #n ")" ::: "memory")
; #define PG8_BAR __builtin_amdgcn_s_barrier()
; #define PG8_SCHED __builtin_amdgcn_sched_barrier(0)
; template <int EK, int SK = -1>
; __device__ __forceinline__ void gemm_phase(LAS unsigned char* lds, const bf16_t* A, const bf16_t* Bt, int nM, int N, int K, const EpiArgs& E) {
;     ...
;         const bool has_next = S.next(ui + 1, nxt);
;         const char* nA = has_next ? (const char*)A + (size_t)nxt.pm * tstep : cA; const char* nB = has_next ? (const char*)Bt + (size_t)nxt.pn * tstep : cB;
;         for (int t = 0; t < nt; t += 2) {
;             const bool last = (t == nt - 2);
;             const char* a1 = cA + (size_t)(t + 1) * kstep;
;             const char* a2 = last ? nA : cA + (size_t)(t + 2) * kstep; const char* b2 = last ? nB : cB + (size_t)(t + 2) * kstep;
;             const char* a3 = a2 + kstep; const char* b3 = b2 + kstep;
;             PG8_LDB(B0, 0, 0); PG8_LDB(B1, 0, 1); PG8_SCHED; PG8_LDA(At, 0, 0); PG8_STAGEA(PG8_SA(1, 1), a1 + hstep);
;             PG8_WAIT_V(8); PG8_WAIT_L(0); PG8_BAR; PG8_MMA(0, 0, At, B0); PG8_MMA(0, 1, At, B1); PG8_BAR; PG8_SCHED;
;             PG8_LDA(At, 0, 1); PG8_STAGEB(PG8_SB(0, 0), b2); PG8_STAGEB(PG8_SB(0, 1), b2 + hstep); PG8_STAGEA(PG8_SA(0, 0), a2);
.LBB0_928:
	s_add_u32 s86, s76, 0x100
	s_addc_u32 s87, s77, 0
	s_ashr_i32 s71, s70, 31
	s_lshl_b64 s[10:11], s[70:71], 19
	s_add_u32 s74, s62, s10
	s_addc_u32 s75, s63, s11
	s_and_b64 s[10:11], s[8:9], exec
	s_cselect_b32 s14, s75, s37
	s_cselect_b32 s71, s74, s36
	s_ashr_i32 s69, s68, 31
	s_lshl_b64 s[10:11], s[68:69], 19
	s_add_u32 s72, s43, s10
	s_addc_u32 s73, s45, s11
	s_and_b64 s[10:11], s[8:9], exec
	s_cselect_b32 s69, s73, s77
	s_cselect_b32 s88, s72, s76
	s_waitcnt lgkmcnt(0)
	v_lshl_add_u64 v[146:147], s[36:37], 0, v[138:139]
	v_lshl_add_u64 v[148:149], s[36:37], 0, v[140:141]
	s_mov_b32 s89, -2
	s_mov_b64 s[10:11], 0
	v_add_u32_e32 v158, s82, v160
	ds_read_b128 v[150:153], v158
	ds_read_b128 v[154:157], v158 offset:1024
	ds_read_b128 v[166:169], v158 offset:2048
	ds_read_b128 v[170:173], v158 offset:3072
	v_add_u32_e32 v158, s83, v160
	s_add_u32 s76, s36, s10
	ds_read_b128 v[174:177], v158
	ds_read_b128 v[178:181], v158 offset:1024
	ds_read_b128 v[182:185], v158 offset:2048
	ds_read_b128 v[186:189], v158 offset:3072
	s_addc_u32 s77, s37, s11
	s_add_u32 s76, s76, 0x100
	s_addc_u32 s77, s77, 0
	s_add_u32 s90, s86, s10
	s_addc_u32 s91, s87, s11
	s_cmpk_eq_i32 s10, 0x700
	s_cselect_b32 s79, s14, s77
	s_cselect_b32 s78, s71, s76
	s_cselect_b32 s77, s69, s91
	s_cselect_b32 s76, s88, s90
	v_lshl_add_u64 v[158:159], v[146:147], 0, s[10:11]
	s_add_i32 m0, s23, 0xc000
	ds_read_b128 v[190:193], v163
	ds_read_b128 v[194:197], v163 offset:1024
	ds_read_b128 v[198:201], v163 offset:2048
	ds_read_b128 v[202:205], v163 offset:3072
	ds_read_b128 v[206:209], v163 offset:4096
	ds_read_b128 v[210:213], v163 offset:5120
	ds_read_b128 v[214:217], v163 offset:6144
	ds_read_b128 v[218:221], v163 offset:7168
	global_load_lds_dwordx4 v[158:159], off
	v_lshl_add_u64 v[158:159], v[148:149], 0, s[10:11]
	s_add_i32 m0, s23, 0xe000
	s_nop 0
	global_load_lds_dwordx4 v[158:159], off
	s_waitcnt vmcnt(8)
	s_waitcnt lgkmcnt(0)
	s_barrier
	s_waitcnt lgkmcnt(0)
	v_mfma_f32_16x16x32_bf16 v[110:113], v[150:153], v[190:193], 0
	v_mfma_f32_16x16x32_bf16 v[106:109], v[166:169], v[190:193], 0
	v_mfma_f32_16x16x32_bf16 v[98:101], v[166:169], v[198:201], 0
	v_mfma_f32_16x16x32_bf16 v[102:105], v[150:153], v[198:201], 0
	v_mfma_f32_16x16x32_bf16 v[94:97], v[150:153], v[206:209], 0
	v_mfma_f32_16x16x32_bf16 v[90:93], v[166:169], v[206:209], 0
	v_mfma_f32_16x16x32_bf16 v[82:85], v[166:169], v[214:217], 0
	v_mfma_f32_16x16x32_bf16 v[86:89], v[150:153], v[214:217], 0
	v_mfma_f32_16x16x32_bf16 v[110:113], v[154:157], v[194:197], v[110:113]
	v_mfma_f32_16x16x32_bf16 v[106:109], v[170:173], v[194:197], v[106:109]
	v_mfma_f32_16x16x32_bf16 v[98:101], v[170:173], v[202:205], v[98:101]
	v_mfma_f32_16x16x32_bf16 v[102:105], v[154:157], v[202:205], v[102:105]
	v_mfma_f32_16x16x32_bf16 v[94:97], v[154:157], v[210:213], v[94:97]
	v_mfma_f32_16x16x32_bf16 v[90:93], v[170:173], v[210:213], v[90:93]
	v_mfma_f32_16x16x32_bf16 v[82:85], v[170:173], v[218:221], v[82:85]
	v_mfma_f32_16x16x32_bf16 v[86:89], v[154:157], v[218:221], v[86:89]
	v_mfma_f32_16x16x32_bf16 v[78:81], v[174:177], v[190:193], 0
	v_mfma_f32_16x16x32_bf16 v[74:77], v[182:185], v[190:193], 0
	v_mfma_f32_16x16x32_bf16 v[66:69], v[182:185], v[198:201], 0
	v_mfma_f32_16x16x32_bf16 v[70:73], v[174:177], v[198:201], 0
	v_mfma_f32_16x16x32_bf16 v[62:65], v[174:177], v[206:209], 0
	v_mfma_f32_16x16x32_bf16 v[58:61], v[182:185], v[206:209], 0
	v_mfma_f32_16x16x32_bf16 v[50:53], v[182:185], v[214:217], 0
	v_mfma_f32_16x16x32_bf16 v[54:57], v[174:177], v[214:217], 0
	v_mfma_f32_16x16x32_bf16 v[78:81], v[178:181], v[194:197], v[78:81]
	v_mfma_f32_16x16x32_bf16 v[74:77], v[186:189], v[194:197], v[74:77]
	v_mfma_f32_16x16x32_bf16 v[66:69], v[186:189], v[202:205], v[66:69]
	v_mfma_f32_16x16x32_bf16 v[70:73], v[178:181], v[202:205], v[70:73]
	v_mfma_f32_16x16x32_bf16 v[62:65], v[178:181], v[210:213], v[62:65]
	v_mfma_f32_16x16x32_bf16 v[58:61], v[186:189], v[210:213], v[58:61]
	v_mfma_f32_16x16x32_bf16 v[50:53], v[186:189], v[218:221], v[50:53]
	v_mfma_f32_16x16x32_bf16 v[54:57], v[178:181], v[218:221], v[54:57]
	s_barrier
	s_add_i32 s90, s82, s53
	v_lshl_add_u64 v[158:159], s[76:77], 0, v[132:133]
	s_mov_b32 m0, s90
	ds_read_b128 v[190:193], v163 offset:16384
	ds_read_b128 v[194:197], v163 offset:17408
	ds_read_b128 v[198:201], v163 offset:18432
	ds_read_b128 v[202:205], v163 offset:19456
	ds_read_b128 v[206:209], v163 offset:20480
	ds_read_b128 v[210:213], v163 offset:21504
	ds_read_b128 v[214:217], v163 offset:22528
	ds_read_b128 v[218:221], v163 offset:23552
	global_load_lds_dwordx4 v[158:159], off
	s_add_i32 m0, s90, 0x2000
	s_add_u32 s90, s76, 0x40000
	v_lshl_add_u64 v[222:223], s[76:77], 0, v[136:137]
	s_addc_u32 s91, s77, 0
	s_add_i32 s92, s83, s53
	global_load_lds_dwordx4 v[222:223], off
	v_lshl_add_u64 v[224:225], s[90:91], 0, v[132:133]
	s_mov_b32 m0, s92
	v_lshl_add_u64 v[226:227], s[78:79], 0, v[134:135]
	global_load_lds_dwordx4 v[224:225], off
	v_lshl_add_u64 v[224:225], s[90:91], 0, v[136:137]
	s_add_i32 m0, s92, 0x2000
	s_nop 0
	global_load_lds_dwordx4 v[224:225], off
	v_lshl_add_u64 v[224:225], s[78:79], 0, v[130:131]
	s_mov_b32 m0, s23
	s_nop 0
	global_load_lds_dwordx4 v[224:225], off
	s_mov_b32 m0, s27
	s_nop 0
	global_load_lds_dwordx4 v[226:227], off
	s_waitcnt vmcnt(8)
	s_waitcnt lgkmcnt(0)
	s_barrier
; #define PG8_STAGEA(bufoff, gbase) PG8_STAGE_(bufoff, gbase, voffA)
; #define PG8_LDA(dst, b, h) do { _Pragma("unroll") for (int m = 0; m < 4; ++m) _Pragma("unroll") for (int k = 0; k < 2; ++k) dst[m][k] = *(const LAS bf16x8*)(lds + PG8_SA(b, h) + aoff + m * 2048 + k * 1024); } while (0)
; #define PG8_LDB(dst, b, h) do { _Pragma("unroll") for (int n = 0; n < 2; ++n) _Pragma("unroll") for (int k = 0; k < 2; ++k) dst[n][k] = *(const LAS bf16x8*)(lds + PG8_SB(b, h) + boff + n * 2048 + k * 1024); } while (0)
; #define PG8_MMA(ai, bj, At, Bt_) do { __builtin_amdgcn_s_setprio(1); _Pragma("unroll") for (int m = 0; m < 4; ++m) _Pragma("unroll") for (int n = 0; n < 2; ++n) _Pragma("unroll") for (int k = 0; k < 2; ++k) \
;         acc[ai][bj][m][n] = __builtin_amdgcn_mfma_f32_16x16x32_bf16(Bt_[n][k], At[m][k], acc[ai][bj][m][n], 0, 0, 0); __builtin_amdgcn_s_setprio(0); } while (0)
; #define PG8_WAIT_V(n) asm volatile("s_waitcnt vmcnt(" #n ")" ::: "memory")
; #define PG8_WAIT_L(n) asm volatile("s_waitcnt lgkmcnt(" #n ")" ::: "memory")
; #define PG8_BAR __builtin_amdgcn_s_barrier()
; #define PG8_SCHED __builtin_amdgcn_sched_barrier(0)
; template <int EK, int SK = -1>
; __device__ __forceinline__ void gemm_phase(LAS unsigned char* lds, const bf16_t* A, const bf16_t* Bt, int nM, int N, int K, const EpiArgs& E) {
;     ...
;             PG8_WAIT_V(8); PG8_WAIT_L(0); PG8_BAR; PG8_MMA(1, 0, At, B0); PG8_MMA(1, 1, At, B1); PG8_BAR; PG8_SCHED;
;             PG8_LDB(B0, 1, 0); PG8_LDB(B1, 1, 1); PG8_SCHED; PG8_LDA(At, 1, 0); PG8_STAGEA(PG8_SA(0, 1), a2 + hstep);
;             PG8_WAIT_V(8); PG8_WAIT_L(0); PG8_BAR; PG8_MMA(0, 0, At, B0); PG8_MMA(0, 1, At, B1); PG8_BAR; PG8_SCHED;
	s_waitcnt lgkmcnt(0)
	v_mfma_f32_16x16x32_bf16 v[46:49], v[150:153], v[190:193], 0
	v_mfma_f32_16x16x32_bf16 v[42:45], v[166:169], v[190:193], 0
	v_mfma_f32_16x16x32_bf16 v[34:37], v[166:169], v[198:201], 0
	v_mfma_f32_16x16x32_bf16 v[38:41], v[150:153], v[198:201], 0
	v_mfma_f32_16x16x32_bf16 v[30:33], v[150:153], v[206:209], 0
	v_mfma_f32_16x16x32_bf16 v[26:29], v[166:169], v[206:209], 0
	v_mfma_f32_16x16x32_bf16 v[18:21], v[166:169], v[214:217], 0
	v_mfma_f32_16x16x32_bf16 v[22:25], v[150:153], v[214:217], 0
	v_mfma_f32_16x16x32_bf16 v[46:49], v[154:157], v[194:197], v[46:49]
	v_mfma_f32_16x16x32_bf16 v[42:45], v[170:173], v[194:197], v[42:45]
	v_mfma_f32_16x16x32_bf16 v[34:37], v[170:173], v[202:205], v[34:37]
	v_mfma_f32_16x16x32_bf16 v[38:41], v[154:157], v[202:205], v[38:41]
	v_mfma_f32_16x16x32_bf16 v[30:33], v[154:157], v[210:213], v[30:33]
	v_mfma_f32_16x16x32_bf16 v[26:29], v[170:173], v[210:213], v[26:29]
	v_mfma_f32_16x16x32_bf16 v[18:21], v[170:173], v[218:221], v[18:21]
	v_mfma_f32_16x16x32_bf16 v[22:25], v[154:157], v[218:221], v[22:25]
	v_mfma_f32_16x16x32_bf16 v[14:17], v[174:177], v[190:193], 0
	v_mfma_f32_16x16x32_bf16 v[10:13], v[182:185], v[190:193], 0
	v_mfma_f32_16x16x32_bf16 v[2:5], v[182:185], v[198:201], 0
	v_mfma_f32_16x16x32_bf16 v[6:9], v[174:177], v[198:201], 0
	v_mfma_f32_16x16x32_bf16 v[114:117], v[174:177], v[206:209], 0
	v_mfma_f32_16x16x32_bf16 v[118:121], v[182:185], v[206:209], 0
	v_mfma_f32_16x16x32_bf16 v[126:129], v[182:185], v[214:217], 0
	v_mfma_f32_16x16x32_bf16 v[122:125], v[174:177], v[214:217], 0
	v_mfma_f32_16x16x32_bf16 v[14:17], v[178:181], v[194:197], v[14:17]
	v_mfma_f32_16x16x32_bf16 v[10:13], v[186:189], v[194:197], v[10:13]
	v_mfma_f32_16x16x32_bf16 v[2:5], v[186:189], v[202:205], v[2:5]
	v_mfma_f32_16x16x32_bf16 v[6:9], v[178:181], v[202:205], v[6:9]
	v_mfma_f32_16x16x32_bf16 v[114:117], v[178:181], v[210:213], v[114:117]
	v_mfma_f32_16x16x32_bf16 v[118:121], v[186:189], v[210:213], v[118:121]
	v_mfma_f32_16x16x32_bf16 v[126:129], v[186:189], v[218:221], v[126:129]
	v_mfma_f32_16x16x32_bf16 v[122:125], v[178:181], v[218:221], v[122:125]
	s_barrier
	s_add_i32 s90, 0, 0x18000
	v_add_u32_e32 v165, s90, v160
	s_add_i32 s91, 0, 0x1c000
	ds_read_b128 v[150:153], v165
	ds_read_b128 v[154:157], v165 offset:1024
	ds_read_b128 v[166:169], v165 offset:2048
	ds_read_b128 v[170:173], v165 offset:3072
	v_add_u32_e32 v165, s91, v160
	ds_read_b128 v[174:177], v165
	ds_read_b128 v[178:181], v165 offset:1024
	ds_read_b128 v[182:185], v165 offset:2048
	ds_read_b128 v[186:189], v165 offset:3072
	s_add_u32 s78, s78, 0x40000
	s_addc_u32 s79, s79, 0
	s_mov_b32 m0, s55
	v_lshl_add_u64 v[228:229], s[78:79], 0, v[130:131]
	ds_read_b128 v[190:193], v163 offset:32768
	ds_read_b128 v[194:197], v163 offset:33792
	ds_read_b128 v[198:201], v163 offset:34816
	ds_read_b128 v[202:205], v163 offset:35840
	ds_read_b128 v[206:209], v163 offset:36864
	ds_read_b128 v[210:213], v163 offset:37888
	ds_read_b128 v[214:217], v163 offset:38912
	ds_read_b128 v[218:221], v163 offset:39936
	global_load_lds_dwordx4 v[228:229], off
	v_lshl_add_u64 v[228:229], s[78:79], 0, v[134:135]
	s_mov_b32 m0, s57
	s_nop 0
	global_load_lds_dwordx4 v[228:229], off
	s_waitcnt vmcnt(8)
	s_waitcnt lgkmcnt(0)
	s_barrier
	s_waitcnt lgkmcnt(0)
	v_mfma_f32_16x16x32_bf16 v[110:113], v[150:153], v[190:193], v[110:113]
	v_mfma_f32_16x16x32_bf16 v[106:109], v[166:169], v[190:193], v[106:109]
	v_mfma_f32_16x16x32_bf16 v[98:101], v[166:169], v[198:201], v[98:101]
	v_mfma_f32_16x16x32_bf16 v[102:105], v[150:153], v[198:201], v[102:105]
	v_mfma_f32_16x16x32_bf16 v[94:97], v[150:153], v[206:209], v[94:97]
	v_mfma_f32_16x16x32_bf16 v[90:93], v[166:169], v[206:209], v[90:93]
	v_mfma_f32_16x16x32_bf16 v[82:85], v[166:169], v[214:217], v[82:85]
	v_mfma_f32_16x16x32_bf16 v[86:89], v[150:153], v[214:217], v[86:89]
	v_mfma_f32_16x16x32_bf16 v[110:113], v[154:157], v[194:197], v[110:113]
	v_mfma_f32_16x16x32_bf16 v[106:109], v[170:173], v[194:197], v[106:109]
	v_mfma_f32_16x16x32_bf16 v[98:101], v[170:173], v[202:205], v[98:101]
	v_mfma_f32_16x16x32_bf16 v[102:105], v[154:157], v[202:205], v[102:105]
	v_mfma_f32_16x16x32_bf16 v[94:97], v[154:157], v[210:213], v[94:97]
	v_mfma_f32_16x16x32_bf16 v[90:93], v[170:173], v[210:213], v[90:93]
	v_mfma_f32_16x16x32_bf16 v[82:85], v[170:173], v[218:221], v[82:85]
	v_mfma_f32_16x16x32_bf16 v[86:89], v[154:157], v[218:221], v[86:89]
	v_mfma_f32_16x16x32_bf16 v[78:81], v[174:177], v[190:193], v[78:81]
	v_mfma_f32_16x16x32_bf16 v[74:77], v[182:185], v[190:193], v[74:77]
	v_mfma_f32_16x16x32_bf16 v[66:69], v[182:185], v[198:201], v[66:69]
	v_mfma_f32_16x16x32_bf16 v[70:73], v[174:177], v[198:201], v[70:73]
	v_mfma_f32_16x16x32_bf16 v[62:65], v[174:177], v[206:209], v[62:65]
	v_mfma_f32_16x16x32_bf16 v[58:61], v[182:185], v[206:209], v[58:61]
	v_mfma_f32_16x16x32_bf16 v[50:53], v[182:185], v[214:217], v[50:53]
	v_mfma_f32_16x16x32_bf16 v[54:57], v[174:177], v[214:217], v[54:57]
	v_mfma_f32_16x16x32_bf16 v[78:81], v[178:181], v[194:197], v[78:81]
	v_mfma_f32_16x16x32_bf16 v[74:77], v[186:189], v[194:197], v[74:77]
	v_mfma_f32_16x16x32_bf16 v[66:69], v[186:189], v[202:205], v[66:69]
	v_mfma_f32_16x16x32_bf16 v[70:73], v[178:181], v[202:205], v[70:73]
	v_mfma_f32_16x16x32_bf16 v[62:65], v[178:181], v[210:213], v[62:65]
	v_mfma_f32_16x16x32_bf16 v[58:61], v[186:189], v[210:213], v[58:61]
	v_mfma_f32_16x16x32_bf16 v[50:53], v[186:189], v[218:221], v[50:53]
	v_mfma_f32_16x16x32_bf16 v[54:57], v[178:181], v[218:221], v[54:57]
	s_barrier
; #define PG8_STAGEA(bufoff, gbase) PG8_STAGE_(bufoff, gbase, voffA)
; #define PG8_STAGEB(bufoff, gbase) PG8_STAGE_(bufoff, gbase, voffB)
; #define PG8_LDA(dst, b, h) do { _Pragma("unroll") for (int m = 0; m < 4; ++m) _Pragma("unroll") for (int k = 0; k < 2; ++k) dst[m][k] = *(const LAS bf16x8*)(lds + PG8_SA(b, h) + aoff + m * 2048 + k * 1024); } while (0)
; #define PG8_LDB(dst, b, h) do { _Pragma("unroll") for (int n = 0; n < 2; ++n) _Pragma("unroll") for (int k = 0; k < 2; ++k) dst[n][k] = *(const LAS bf16x8*)(lds + PG8_SB(b, h) + boff + n * 2048 + k * 1024); } while (0)
; #define PG8_MMA(ai, bj, At, Bt_) do { __builtin_amdgcn_s_setprio(1); _Pragma("unroll") for (int m = 0; m < 4; ++m) _Pragma("unroll") for (int n = 0; n < 2; ++n) _Pragma("unroll") for (int k = 0; k < 2; ++k) \
;         acc[ai][bj][m][n] = __builtin_amdgcn_mfma_f32_16x16x32_bf16(Bt_[n][k], At[m][k], acc[ai][bj][m][n], 0, 0, 0); __builtin_amdgcn_s_setprio(0); } while (0)
; #define PG8_WAIT_V(n) asm volatile("s_waitcnt vmcnt(" #n ")" ::: "memory")
; #define PG8_WAIT_L(n) asm volatile("s_waitcnt lgkmcnt(" #n ")" ::: "memory")
; #define PG8_BAR __builtin_amdgcn_s_barrier()
; #define PG8_SCHED __builtin_amdgcn_sched_barrier(0)
; template <int EK, int SK = -1>
; __device__ __forceinline__ void gemm_phase(LAS unsigned char* lds, const bf16_t* A, const bf16_t* Bt, int nM, int N, int K, const EpiArgs& E) {
;     ...
;             PG8_LDB(B0, 0, 0); PG8_LDB(B1, 0, 1); PG8_SCHED; PG8_LDA(At, 0, 0); PG8_STAGEA(PG8_SA(1, 1), a1 + hstep);
;             PG8_WAIT_V(8); PG8_WAIT_L(0); PG8_BAR; PG8_MMA(0, 0, At, B0); PG8_MMA(0, 1, At, B1); PG8_BAR; PG8_SCHED;
;     ...
;             PG8_LDA(At, 1, 1); PG8_STAGEB(PG8_SB(1, 0), b3); PG8_STAGEB(PG8_SB(1, 1), b3 + hstep); PG8_STAGEA(PG8_SA(1, 0), a3);
;             PG8_WAIT_V(8); PG8_WAIT_L(0); PG8_BAR; PG8_MMA(1, 0, At, B0); PG8_MMA(1, 1, At, B1); PG8_BAR; PG8_SCHED;
;         }
	s_add_i32 s78, s90, s53
	v_lshl_add_u64 v[158:159], v[158:159], 0, s[16:17]
	s_mov_b32 m0, s78
	ds_read_b128 v[190:193], v163 offset:49152
	ds_read_b128 v[194:197], v163 offset:50176
	ds_read_b128 v[198:201], v163 offset:51200
	ds_read_b128 v[202:205], v163 offset:52224
	ds_read_b128 v[206:209], v163 offset:53248
	ds_read_b128 v[210:213], v163 offset:54272
	ds_read_b128 v[214:217], v163 offset:55296
	ds_read_b128 v[218:221], v163 offset:56320
	global_load_lds_dwordx4 v[158:159], off
	s_add_i32 m0, s78, 0x2000
	s_add_u32 s76, s76, 0x40080
	v_lshl_add_u64 v[158:159], v[222:223], 0, s[16:17]
	s_addc_u32 s77, s77, 0
	s_add_i32 s78, s91, s53
	global_load_lds_dwordx4 v[158:159], off
	v_lshl_add_u64 v[158:159], s[76:77], 0, v[132:133]
	s_mov_b32 m0, s78
	s_nop 0
	global_load_lds_dwordx4 v[158:159], off
	v_lshl_add_u64 v[158:159], s[76:77], 0, v[136:137]
	s_add_i32 m0, s78, 0x2000
	s_nop 0
	global_load_lds_dwordx4 v[158:159], off
	v_lshl_add_u64 v[158:159], v[224:225], 0, s[16:17]
	s_mov_b32 m0, s80
	s_nop 0
	global_load_lds_dwordx4 v[158:159], off
	v_lshl_add_u64 v[158:159], v[226:227], 0, s[16:17]
	s_mov_b32 m0, s81
	s_nop 0
	global_load_lds_dwordx4 v[158:159], off
	s_waitcnt vmcnt(8)
	s_waitcnt lgkmcnt(0)
	s_barrier
	s_waitcnt lgkmcnt(0)
	v_mfma_f32_16x16x32_bf16 v[46:49], v[150:153], v[190:193], v[46:49]
	v_mfma_f32_16x16x32_bf16 v[42:45], v[166:169], v[190:193], v[42:45]
	v_mfma_f32_16x16x32_bf16 v[34:37], v[166:169], v[198:201], v[34:37]
	v_mfma_f32_16x16x32_bf16 v[38:41], v[150:153], v[198:201], v[38:41]
	v_mfma_f32_16x16x32_bf16 v[30:33], v[150:153], v[206:209], v[30:33]
	v_mfma_f32_16x16x32_bf16 v[26:29], v[166:169], v[206:209], v[26:29]
	v_mfma_f32_16x16x32_bf16 v[18:21], v[166:169], v[214:217], v[18:21]
	v_mfma_f32_16x16x32_bf16 v[22:25], v[150:153], v[214:217], v[22:25]
	v_mfma_f32_16x16x32_bf16 v[46:49], v[154:157], v[194:197], v[46:49]
	v_mfma_f32_16x16x32_bf16 v[42:45], v[170:173], v[194:197], v[42:45]
	v_mfma_f32_16x16x32_bf16 v[34:37], v[170:173], v[202:205], v[34:37]
	v_mfma_f32_16x16x32_bf16 v[38:41], v[154:157], v[202:205], v[38:41]
	v_mfma_f32_16x16x32_bf16 v[30:33], v[154:157], v[210:213], v[30:33]
	v_mfma_f32_16x16x32_bf16 v[26:29], v[170:173], v[210:213], v[26:29]
	v_mfma_f32_16x16x32_bf16 v[18:21], v[170:173], v[218:221], v[18:21]
	v_mfma_f32_16x16x32_bf16 v[22:25], v[154:157], v[218:221], v[22:25]
	v_mfma_f32_16x16x32_bf16 v[14:17], v[174:177], v[190:193], v[14:17]
	v_mfma_f32_16x16x32_bf16 v[10:13], v[182:185], v[190:193], v[10:13]
	v_mfma_f32_16x16x32_bf16 v[2:5], v[182:185], v[198:201], v[2:5]
	v_mfma_f32_16x16x32_bf16 v[6:9], v[174:177], v[198:201], v[6:9]
	v_mfma_f32_16x16x32_bf16 v[114:117], v[174:177], v[206:209], v[114:117]
	v_mfma_f32_16x16x32_bf16 v[118:121], v[182:185], v[206:209], v[118:121]
	v_mfma_f32_16x16x32_bf16 v[126:129], v[182:185], v[214:217], v[126:129]
	v_mfma_f32_16x16x32_bf16 v[122:125], v[174:177], v[214:217], v[122:125]
	v_mfma_f32_16x16x32_bf16 v[14:17], v[178:181], v[194:197], v[14:17]
	v_mfma_f32_16x16x32_bf16 v[10:13], v[186:189], v[194:197], v[10:13]
	v_mfma_f32_16x16x32_bf16 v[2:5], v[186:189], v[202:205], v[2:5]
	v_mfma_f32_16x16x32_bf16 v[6:9], v[178:181], v[202:205], v[6:9]
	v_mfma_f32_16x16x32_bf16 v[114:117], v[178:181], v[210:213], v[114:117]
	v_mfma_f32_16x16x32_bf16 v[118:121], v[186:189], v[210:213], v[118:121]
	v_mfma_f32_16x16x32_bf16 v[126:129], v[186:189], v[218:221], v[126:129]
	v_mfma_f32_16x16x32_bf16 v[122:125], v[178:181], v[218:221], v[122:125]
	s_barrier
	s_add_i32 s89, s89, 2
	s_add_u32 s10, s10, 0x100
	s_addc_u32 s11, s11, 0
	s_cmp_gt_u32 s89, 13
	s_cbranch_scc0 .LBB0_929
	s_branch .Lmy_kexit_4
.LBB0_929:
	v_add_u32_e32 v158, s82, v160
	ds_read_b128 v[150:153], v158
	ds_read_b128 v[154:157], v158 offset:1024
	ds_read_b128 v[166:169], v158 offset:2048
	ds_read_b128 v[170:173], v158 offset:3072
	v_add_u32_e32 v158, s83, v160
	s_add_u32 s76, s36, s10
	ds_read_b128 v[174:177], v158
	ds_read_b128 v[178:181], v158 offset:1024
	ds_read_b128 v[182:185], v158 offset:2048
	ds_read_b128 v[186:189], v158 offset:3072
	s_addc_u32 s77, s37, s11
	s_add_u32 s76, s76, 0x100
	s_addc_u32 s77, s77, 0
	s_add_u32 s90, s86, s10
	s_addc_u32 s91, s87, s11
	s_cmpk_eq_i32 s10, 0x700
	s_cselect_b32 s79, s14, s77
	s_cselect_b32 s78, s71, s76
	s_cselect_b32 s77, s69, s91
	s_cselect_b32 s76, s88, s90
	v_lshl_add_u64 v[158:159], v[146:147], 0, s[10:11]
	s_add_i32 m0, s23, 0xc000
	ds_read_b128 v[190:193], v163
	ds_read_b128 v[194:197], v163 offset:1024
	ds_read_b128 v[198:201], v163 offset:2048
	ds_read_b128 v[202:205], v163 offset:3072
	ds_read_b128 v[206:209], v163 offset:4096
	ds_read_b128 v[210:213], v163 offset:5120
	ds_read_b128 v[214:217], v163 offset:6144
	ds_read_b128 v[218:221], v163 offset:7168
	global_load_lds_dwordx4 v[158:159], off
	v_lshl_add_u64 v[158:159], v[148:149], 0, s[10:11]
	s_add_i32 m0, s23, 0xe000
	s_nop 0
	global_load_lds_dwordx4 v[158:159], off
	s_waitcnt vmcnt(8)
	s_waitcnt lgkmcnt(0)
	s_barrier
; #define PG8_STAGEA(bufoff, gbase) PG8_STAGE_(bufoff, gbase, voffA)
; #define PG8_STAGEB(bufoff, gbase) PG8_STAGE_(bufoff, gbase, voffB)
; #define PG8_LDA(dst, b, h) do { _Pragma("unroll") for (int m = 0; m < 4; ++m) _Pragma("unroll") for (int k = 0; k < 2; ++k) dst[m][k] = *(const LAS bf16x8*)(lds + PG8_SA(b, h) + aoff + m * 2048 + k * 1024); } while (0)
; #define PG8_LDB(dst, b, h) do { _Pragma("unroll") for (int n = 0; n < 2; ++n) _Pragma("unroll") for (int k = 0; k < 2; ++k) dst[n][k] = *(const LAS bf16x8*)(lds + PG8_SB(b, h) + boff + n * 2048 + k * 1024); } while (0)
; #define PG8_MMA(ai, bj, At, Bt_) do { __builtin_amdgcn_s_setprio(1); _Pragma("unroll") for (int m = 0; m < 4; ++m) _Pragma("unroll") for (int n = 0; n < 2; ++n) _Pragma("unroll") for (int k = 0; k < 2; ++k) \
;         acc[ai][bj][m][n] = __builtin_amdgcn_mfma_f32_16x16x32_bf16(Bt_[n][k], At[m][k], acc[ai][bj][m][n], 0, 0, 0); __builtin_amdgcn_s_setprio(0); } while (0)
; #define PG8_WAIT_V(n) asm volatile("s_waitcnt vmcnt(" #n ")" ::: "memory")
; #define PG8_WAIT_L(n) asm volatile("s_waitcnt lgkmcnt(" #n ")" ::: "memory")
; #define PG8_BAR __builtin_amdgcn_s_barrier()
; #define PG8_SCHED __builtin_amdgcn_sched_barrier(0)
; template <int EK, int SK = -1>
; __device__ __forceinline__ void gemm_phase(LAS unsigned char* lds, const bf16_t* A, const bf16_t* Bt, int nM, int N, int K, const EpiArgs& E) {
;     ...
;             PG8_WAIT_V(8); PG8_WAIT_L(0); PG8_BAR; PG8_MMA(0, 0, At, B0); PG8_MMA(0, 1, At, B1); PG8_BAR; PG8_SCHED;
;             PG8_LDA(At, 0, 1); PG8_STAGEB(PG8_SB(0, 0), b2); PG8_STAGEB(PG8_SB(0, 1), b2 + hstep); PG8_STAGEA(PG8_SA(0, 0), a2);
;             PG8_WAIT_V(8); PG8_WAIT_L(0); PG8_BAR; PG8_MMA(1, 0, At, B0); PG8_MMA(1, 1, At, B1); PG8_BAR; PG8_SCHED;
;             PG8_LDB(B0, 1, 0); PG8_LDB(B1, 1, 1); PG8_SCHED; PG8_LDA(At, 1, 0); PG8_STAGEA(PG8_SA(0, 1), a2 + hstep);
;             PG8_WAIT_V(8); PG8_WAIT_L(0); PG8_BAR; PG8_MMA(0, 0, At, B0); PG8_MMA(0, 1, At, B1); PG8_BAR; PG8_SCHED;
	s_waitcnt lgkmcnt(0)
	v_mfma_f32_16x16x32_bf16 v[110:113], v[150:153], v[190:193], v[110:113]
	v_mfma_f32_16x16x32_bf16 v[106:109], v[166:169], v[190:193], v[106:109]
	v_mfma_f32_16x16x32_bf16 v[98:101], v[166:169], v[198:201], v[98:101]
	v_mfma_f32_16x16x32_bf16 v[102:105], v[150:153], v[198:201], v[102:105]
	v_mfma_f32_16x16x32_bf16 v[94:97], v[150:153], v[206:209], v[94:97]
	v_mfma_f32_16x16x32_bf16 v[90:93], v[166:169], v[206:209], v[90:93]
	v_mfma_f32_16x16x32_bf16 v[82:85], v[166:169], v[214:217], v[82:85]
	v_mfma_f32_16x16x32_bf16 v[86:89], v[150:153], v[214:217], v[86:89]
	v_mfma_f32_16x16x32_bf16 v[110:113], v[154:157], v[194:197], v[110:113]
	v_mfma_f32_16x16x32_bf16 v[106:109], v[170:173], v[194:197], v[106:109]
	v_mfma_f32_16x16x32_bf16 v[98:101], v[170:173], v[202:205], v[98:101]
	v_mfma_f32_16x16x32_bf16 v[102:105], v[154:157], v[202:205], v[102:105]
	v_mfma_f32_16x16x32_bf16 v[94:97], v[154:157], v[210:213], v[94:97]
	v_mfma_f32_16x16x32_bf16 v[90:93], v[170:173], v[210:213], v[90:93]
	v_mfma_f32_16x16x32_bf16 v[82:85], v[170:173], v[218:221], v[82:85]
	v_mfma_f32_16x16x32_bf16 v[86:89], v[154:157], v[218:221], v[86:89]
	v_mfma_f32_16x16x32_bf16 v[78:81], v[174:177], v[190:193], v[78:81]
	v_mfma_f32_16x16x32_bf16 v[74:77], v[182:185], v[190:193], v[74:77]
	v_mfma_f32_16x16x32_bf16 v[66:69], v[182:185], v[198:201], v[66:69]
	v_mfma_f32_16x16x32_bf16 v[70:73], v[174:177], v[198:201], v[70:73]
	v_mfma_f32_16x16x32_bf16 v[62:65], v[174:177], v[206:209], v[62:65]
	v_mfma_f32_16x16x32_bf16 v[58:61], v[182:185], v[206:209], v[58:61]
	v_mfma_f32_16x16x32_bf16 v[50:53], v[182:185], v[214:217], v[50:53]
	v_mfma_f32_16x16x32_bf16 v[54:57], v[174:177], v[214:217], v[54:57]
	v_mfma_f32_16x16x32_bf16 v[78:81], v[178:181], v[194:197], v[78:81]
	v_mfma_f32_16x16x32_bf16 v[74:77], v[186:189], v[194:197], v[74:77]
	v_mfma_f32_16x16x32_bf16 v[66:69], v[186:189], v[202:205], v[66:69]
	v_mfma_f32_16x16x32_bf16 v[70:73], v[178:181], v[202:205], v[70:73]
	v_mfma_f32_16x16x32_bf16 v[62:65], v[178:181], v[210:213], v[62:65]
	v_mfma_f32_16x16x32_bf16 v[58:61], v[186:189], v[210:213], v[58:61]
	v_mfma_f32_16x16x32_bf16 v[50:53], v[186:189], v[218:221], v[50:53]
	v_mfma_f32_16x16x32_bf16 v[54:57], v[178:181], v[218:221], v[54:57]
	s_barrier
	s_add_i32 s90, s82, s53
	v_lshl_add_u64 v[158:159], s[76:77], 0, v[132:133]
	s_mov_b32 m0, s90
	ds_read_b128 v[190:193], v163 offset:16384
	ds_read_b128 v[194:197], v163 offset:17408
	ds_read_b128 v[198:201], v163 offset:18432
	ds_read_b128 v[202:205], v163 offset:19456
	ds_read_b128 v[206:209], v163 offset:20480
	ds_read_b128 v[210:213], v163 offset:21504
	ds_read_b128 v[214:217], v163 offset:22528
	ds_read_b128 v[218:221], v163 offset:23552
	global_load_lds_dwordx4 v[158:159], off
	s_add_i32 m0, s90, 0x2000
	s_add_u32 s90, s76, 0x40000
	v_lshl_add_u64 v[222:223], s[76:77], 0, v[136:137]
	s_addc_u32 s91, s77, 0
	s_add_i32 s92, s83, s53
	global_load_lds_dwordx4 v[222:223], off
	v_lshl_add_u64 v[224:225], s[90:91], 0, v[132:133]
	s_mov_b32 m0, s92
	v_lshl_add_u64 v[226:227], s[78:79], 0, v[134:135]
	global_load_lds_dwordx4 v[224:225], off
	v_lshl_add_u64 v[224:225], s[90:91], 0, v[136:137]
	s_add_i32 m0, s92, 0x2000
	s_nop 0
	global_load_lds_dwordx4 v[224:225], off
	v_lshl_add_u64 v[224:225], s[78:79], 0, v[130:131]
	s_mov_b32 m0, s23
	s_nop 0
	global_load_lds_dwordx4 v[224:225], off
	s_mov_b32 m0, s27
	s_nop 0
	global_load_lds_dwordx4 v[226:227], off
	s_waitcnt vmcnt(8)
	s_waitcnt lgkmcnt(0)
	s_barrier
	s_waitcnt lgkmcnt(0)
	v_mfma_f32_16x16x32_bf16 v[46:49], v[150:153], v[190:193], v[46:49]
	v_mfma_f32_16x16x32_bf16 v[42:45], v[166:169], v[190:193], v[42:45]
	v_mfma_f32_16x16x32_bf16 v[34:37], v[166:169], v[198:201], v[34:37]
	v_mfma_f32_16x16x32_bf16 v[38:41], v[150:153], v[198:201], v[38:41]
	v_mfma_f32_16x16x32_bf16 v[30:33], v[150:153], v[206:209], v[30:33]
	v_mfma_f32_16x16x32_bf16 v[26:29], v[166:169], v[206:209], v[26:29]
	v_mfma_f32_16x16x32_bf16 v[18:21], v[166:169], v[214:217], v[18:21]
	v_mfma_f32_16x16x32_bf16 v[22:25], v[150:153], v[214:217], v[22:25]
	v_mfma_f32_16x16x32_bf16 v[46:49], v[154:157], v[194:197], v[46:49]
	v_mfma_f32_16x16x32_bf16 v[42:45], v[170:173], v[194:197], v[42:45]
	v_mfma_f32_16x16x32_bf16 v[34:37], v[170:173], v[202:205], v[34:37]
	v_mfma_f32_16x16x32_bf16 v[38:41], v[154:157], v[202:205], v[38:41]
	v_mfma_f32_16x16x32_bf16 v[30:33], v[154:157], v[210:213], v[30:33]
	v_mfma_f32_16x16x32_bf16 v[26:29], v[170:173], v[210:213], v[26:29]
	v_mfma_f32_16x16x32_bf16 v[18:21], v[170:173], v[218:221], v[18:21]
	v_mfma_f32_16x16x32_bf16 v[22:25], v[154:157], v[218:221], v[22:25]
	v_mfma_f32_16x16x32_bf16 v[14:17], v[174:177], v[190:193], v[14:17]
	v_mfma_f32_16x16x32_bf16 v[10:13], v[182:185], v[190:193], v[10:13]
	v_mfma_f32_16x16x32_bf16 v[2:5], v[182:185], v[198:201], v[2:5]
	v_mfma_f32_16x16x32_bf16 v[6:9], v[174:177], v[198:201], v[6:9]
	v_mfma_f32_16x16x32_bf16 v[114:117], v[174:177], v[206:209], v[114:117]
	v_mfma_f32_16x16x32_bf16 v[118:121], v[182:185], v[206:209], v[118:121]
	v_mfma_f32_16x16x32_bf16 v[126:129], v[182:185], v[214:217], v[126:129]
	v_mfma_f32_16x16x32_bf16 v[122:125], v[174:177], v[214:217], v[122:125]
	v_mfma_f32_16x16x32_bf16 v[14:17], v[178:181], v[194:197], v[14:17]
	v_mfma_f32_16x16x32_bf16 v[10:13], v[186:189], v[194:197], v[10:13]
	v_mfma_f32_16x16x32_bf16 v[2:5], v[186:189], v[202:205], v[2:5]
	v_mfma_f32_16x16x32_bf16 v[6:9], v[178:181], v[202:205], v[6:9]
	v_mfma_f32_16x16x32_bf16 v[114:117], v[178:181], v[210:213], v[114:117]
	v_mfma_f32_16x16x32_bf16 v[118:121], v[186:189], v[210:213], v[118:121]
	v_mfma_f32_16x16x32_bf16 v[126:129], v[186:189], v[218:221], v[126:129]
	v_mfma_f32_16x16x32_bf16 v[122:125], v[178:181], v[218:221], v[122:125]
	s_barrier
; #define PG8_STAGEA(bufoff, gbase) PG8_STAGE_(bufoff, gbase, voffA)
; #define PG8_STAGEB(bufoff, gbase) PG8_STAGE_(bufoff, gbase, voffB)
; #define PG8_LDA(dst, b, h) do { _Pragma("unroll") for (int m = 0; m < 4; ++m) _Pragma("unroll") for (int k = 0; k < 2; ++k) dst[m][k] = *(const LAS bf16x8*)(lds + PG8_SA(b, h) + aoff + m * 2048 + k * 1024); } while (0)
; #define PG8_LDB(dst, b, h) do { _Pragma("unroll") for (int n = 0; n < 2; ++n) _Pragma("unroll") for (int k = 0; k < 2; ++k) dst[n][k] = *(const LAS bf16x8*)(lds + PG8_SB(b, h) + boff + n * 2048 + k * 1024); } while (0)
; #define PG8_MMA(ai, bj, At, Bt_) do { __builtin_amdgcn_s_setprio(1); _Pragma("unroll") for (int m = 0; m < 4; ++m) _Pragma("unroll") for (int n = 0; n < 2; ++n) _Pragma("unroll") for (int k = 0; k < 2; ++k) \
;         acc[ai][bj][m][n] = __builtin_amdgcn_mfma_f32_16x16x32_bf16(Bt_[n][k], At[m][k], acc[ai][bj][m][n], 0, 0, 0); __builtin_amdgcn_s_setprio(0); } while (0)
; #define PG8_WAIT_V(n) asm volatile("s_waitcnt vmcnt(" #n ")" ::: "memory")
; #define PG8_WAIT_L(n) asm volatile("s_waitcnt lgkmcnt(" #n ")" ::: "memory")
; #define PG8_BAR __builtin_amdgcn_s_barrier()
; #define PG8_SCHED __builtin_amdgcn_sched_barrier(0)
; template <int EK, int SK = -1>
; __device__ __forceinline__ void gemm_phase(LAS unsigned char* lds, const bf16_t* A, const bf16_t* Bt, int nM, int N, int K, const EpiArgs& E) {
;     ...
;             PG8_LDB(B0, 1, 0); PG8_LDB(B1, 1, 1); PG8_SCHED; PG8_LDA(At, 1, 0); PG8_STAGEA(PG8_SA(0, 1), a2 + hstep);
;             PG8_WAIT_V(8); PG8_WAIT_L(0); PG8_BAR; PG8_MMA(0, 0, At, B0); PG8_MMA(0, 1, At, B1); PG8_BAR; PG8_SCHED;
;             PG8_LDA(At, 1, 1); PG8_STAGEB(PG8_SB(1, 0), b3); PG8_STAGEB(PG8_SB(1, 1), b3 + hstep); PG8_STAGEA(PG8_SA(1, 0), a3);
;             PG8_WAIT_V(8); PG8_WAIT_L(0); PG8_BAR; PG8_MMA(1, 0, At, B0); PG8_MMA(1, 1, At, B1); PG8_BAR; PG8_SCHED;
;         }
	s_add_i32 s90, 0, 0x18000
	v_add_u32_e32 v165, s90, v160
	s_add_i32 s91, 0, 0x1c000
	ds_read_b128 v[150:153], v165
	ds_read_b128 v[154:157], v165 offset:1024
	ds_read_b128 v[166:169], v165 offset:2048
	ds_read_b128 v[170:173], v165 offset:3072
	v_add_u32_e32 v165, s91, v160
	ds_read_b128 v[174:177], v165
	ds_read_b128 v[178:181], v165 offset:1024
	ds_read_b128 v[182:185], v165 offset:2048
	ds_read_b128 v[186:189], v165 offset:3072
	s_add_u32 s78, s78, 0x40000
	s_addc_u32 s79, s79, 0
	s_mov_b32 m0, s55
	v_lshl_add_u64 v[228:229], s[78:79], 0, v[130:131]
	ds_read_b128 v[190:193], v163 offset:32768
	ds_read_b128 v[194:197], v163 offset:33792
	ds_read_b128 v[198:201], v163 offset:34816
	ds_read_b128 v[202:205], v163 offset:35840
	ds_read_b128 v[206:209], v163 offset:36864
	ds_read_b128 v[210:213], v163 offset:37888
	ds_read_b128 v[214:217], v163 offset:38912
	ds_read_b128 v[218:221], v163 offset:39936
	global_load_lds_dwordx4 v[228:229], off
	v_lshl_add_u64 v[228:229], s[78:79], 0, v[134:135]
	s_mov_b32 m0, s57
	s_nop 0
	global_load_lds_dwordx4 v[228:229], off
	s_waitcnt vmcnt(8)
	s_waitcnt lgkmcnt(0)
	s_barrier
	s_waitcnt lgkmcnt(0)
	v_mfma_f32_16x16x32_bf16 v[110:113], v[150:153], v[190:193], v[110:113]
	v_mfma_f32_16x16x32_bf16 v[106:109], v[166:169], v[190:193], v[106:109]
	v_mfma_f32_16x16x32_bf16 v[98:101], v[166:169], v[198:201], v[98:101]
	v_mfma_f32_16x16x32_bf16 v[102:105], v[150:153], v[198:201], v[102:105]
	v_mfma_f32_16x16x32_bf16 v[94:97], v[150:153], v[206:209], v[94:97]
	v_mfma_f32_16x16x32_bf16 v[90:93], v[166:169], v[206:209], v[90:93]
	v_mfma_f32_16x16x32_bf16 v[82:85], v[166:169], v[214:217], v[82:85]
	v_mfma_f32_16x16x32_bf16 v[86:89], v[150:153], v[214:217], v[86:89]
	v_mfma_f32_16x16x32_bf16 v[110:113], v[154:157], v[194:197], v[110:113]
	v_mfma_f32_16x16x32_bf16 v[106:109], v[170:173], v[194:197], v[106:109]
	v_mfma_f32_16x16x32_bf16 v[98:101], v[170:173], v[202:205], v[98:101]
	v_mfma_f32_16x16x32_bf16 v[102:105], v[154:157], v[202:205], v[102:105]
	v_mfma_f32_16x16x32_bf16 v[94:97], v[154:157], v[210:213], v[94:97]
	v_mfma_f32_16x16x32_bf16 v[90:93], v[170:173], v[210:213], v[90:93]
	v_mfma_f32_16x16x32_bf16 v[82:85], v[170:173], v[218:221], v[82:85]
	v_mfma_f32_16x16x32_bf16 v[86:89], v[154:157], v[218:221], v[86:89]
	v_mfma_f32_16x16x32_bf16 v[78:81], v[174:177], v[190:193], v[78:81]
	v_mfma_f32_16x16x32_bf16 v[74:77], v[182:185], v[190:193], v[74:77]
	v_mfma_f32_16x16x32_bf16 v[66:69], v[182:185], v[198:201], v[66:69]
	v_mfma_f32_16x16x32_bf16 v[70:73], v[174:177], v[198:201], v[70:73]
	v_mfma_f32_16x16x32_bf16 v[62:65], v[174:177], v[206:209], v[62:65]
	v_mfma_f32_16x16x32_bf16 v[58:61], v[182:185], v[206:209], v[58:61]
	v_mfma_f32_16x16x32_bf16 v[50:53], v[182:185], v[214:217], v[50:53]
	v_mfma_f32_16x16x32_bf16 v[54:57], v[174:177], v[214:217], v[54:57]
	v_mfma_f32_16x16x32_bf16 v[78:81], v[178:181], v[194:197], v[78:81]
	v_mfma_f32_16x16x32_bf16 v[74:77], v[186:189], v[194:197], v[74:77]
	v_mfma_f32_16x16x32_bf16 v[66:69], v[186:189], v[202:205], v[66:69]
	v_mfma_f32_16x16x32_bf16 v[70:73], v[178:181], v[202:205], v[70:73]
	v_mfma_f32_16x16x32_bf16 v[62:65], v[178:181], v[210:213], v[62:65]
	v_mfma_f32_16x16x32_bf16 v[58:61], v[186:189], v[210:213], v[58:61]
	v_mfma_f32_16x16x32_bf16 v[50:53], v[186:189], v[218:221], v[50:53]
	v_mfma_f32_16x16x32_bf16 v[54:57], v[178:181], v[218:221], v[54:57]
	s_barrier
	s_add_i32 s78, s90, s53
	v_lshl_add_u64 v[158:159], v[158:159], 0, s[16:17]
	s_mov_b32 m0, s78
	ds_read_b128 v[190:193], v163 offset:49152
	ds_read_b128 v[194:197], v163 offset:50176
	ds_read_b128 v[198:201], v163 offset:51200
	ds_read_b128 v[202:205], v163 offset:52224
	ds_read_b128 v[206:209], v163 offset:53248
	ds_read_b128 v[210:213], v163 offset:54272
	ds_read_b128 v[214:217], v163 offset:55296
	ds_read_b128 v[218:221], v163 offset:56320
	global_load_lds_dwordx4 v[158:159], off
	s_add_i32 m0, s78, 0x2000
	s_add_u32 s76, s76, 0x40080
	v_lshl_add_u64 v[158:159], v[222:223], 0, s[16:17]
	s_addc_u32 s77, s77, 0
	s_add_i32 s78, s91, s53
	global_load_lds_dwordx4 v[158:159], off
	v_lshl_add_u64 v[158:159], s[76:77], 0, v[132:133]
	s_mov_b32 m0, s78
	s_nop 0
	global_load_lds_dwordx4 v[158:159], off
	v_lshl_add_u64 v[158:159], s[76:77], 0, v[136:137]
	s_add_i32 m0, s78, 0x2000
	s_nop 0
	global_load_lds_dwordx4 v[158:159], off
	v_lshl_add_u64 v[158:159], v[224:225], 0, s[16:17]
	s_mov_b32 m0, s80
	s_nop 0
	global_load_lds_dwordx4 v[158:159], off
	v_lshl_add_u64 v[158:159], v[226:227], 0, s[16:17]
	s_mov_b32 m0, s81
	s_nop 0
	global_load_lds_dwordx4 v[158:159], off
	s_waitcnt vmcnt(8)
	s_waitcnt lgkmcnt(0)
	s_barrier
	s_waitcnt lgkmcnt(0)
	v_mfma_f32_16x16x32_bf16 v[46:49], v[150:153], v[190:193], v[46:49]
	v_mfma_f32_16x16x32_bf16 v[42:45], v[166:169], v[190:193], v[42:45]
	v_mfma_f32_16x16x32_bf16 v[34:37], v[166:169], v[198:201], v[34:37]
	v_mfma_f32_16x16x32_bf16 v[38:41], v[150:153], v[198:201], v[38:41]
	v_mfma_f32_16x16x32_bf16 v[30:33], v[150:153], v[206:209], v[30:33]
	v_mfma_f32_16x16x32_bf16 v[26:29], v[166:169], v[206:209], v[26:29]
	v_mfma_f32_16x16x32_bf16 v[18:21], v[166:169], v[214:217], v[18:21]
	v_mfma_f32_16x16x32_bf16 v[22:25], v[150:153], v[214:217], v[22:25]
	v_mfma_f32_16x16x32_bf16 v[46:49], v[154:157], v[194:197], v[46:49]
	v_mfma_f32_16x16x32_bf16 v[42:45], v[170:173], v[194:197], v[42:45]
	v_mfma_f32_16x16x32_bf16 v[34:37], v[170:173], v[202:205], v[34:37]
	v_mfma_f32_16x16x32_bf16 v[38:41], v[154:157], v[202:205], v[38:41]
	v_mfma_f32_16x16x32_bf16 v[30:33], v[154:157], v[210:213], v[30:33]
	v_mfma_f32_16x16x32_bf16 v[26:29], v[170:173], v[210:213], v[26:29]
	v_mfma_f32_16x16x32_bf16 v[18:21], v[170:173], v[218:221], v[18:21]
	v_mfma_f32_16x16x32_bf16 v[22:25], v[154:157], v[218:221], v[22:25]
	v_mfma_f32_16x16x32_bf16 v[14:17], v[174:177], v[190:193], v[14:17]
	v_mfma_f32_16x16x32_bf16 v[10:13], v[182:185], v[190:193], v[10:13]
	v_mfma_f32_16x16x32_bf16 v[2:5], v[182:185], v[198:201], v[2:5]
	v_mfma_f32_16x16x32_bf16 v[6:9], v[174:177], v[198:201], v[6:9]
	v_mfma_f32_16x16x32_bf16 v[114:117], v[174:177], v[206:209], v[114:117]
	v_mfma_f32_16x16x32_bf16 v[118:121], v[182:185], v[206:209], v[118:121]
	v_mfma_f32_16x16x32_bf16 v[126:129], v[182:185], v[214:217], v[126:129]
	v_mfma_f32_16x16x32_bf16 v[122:125], v[174:177], v[214:217], v[122:125]
	v_mfma_f32_16x16x32_bf16 v[14:17], v[178:181], v[194:197], v[14:17]
	v_mfma_f32_16x16x32_bf16 v[10:13], v[186:189], v[194:197], v[10:13]
	v_mfma_f32_16x16x32_bf16 v[2:5], v[186:189], v[202:205], v[2:5]
	v_mfma_f32_16x16x32_bf16 v[6:9], v[178:181], v[202:205], v[6:9]
	v_mfma_f32_16x16x32_bf16 v[114:117], v[178:181], v[210:213], v[114:117]
	v_mfma_f32_16x16x32_bf16 v[118:121], v[186:189], v[210:213], v[118:121]
	v_mfma_f32_16x16x32_bf16 v[126:129], v[186:189], v[218:221], v[126:129]
	v_mfma_f32_16x16x32_bf16 v[122:125], v[178:181], v[218:221], v[122:125]
	s_barrier
	s_add_i32 s89, s89, 2
	s_add_u32 s10, s10, 0x100
	s_addc_u32 s11, s11, 0
	s_cmp_gt_u32 s89, 13
	s_cbranch_scc0 .LBB0_929

; #define PG8_STAGEA(bufoff, gbase) PG8_STAGE_(bufoff, gbase, voffA)
; #define PG8_STAGEB(bufoff, gbase) PG8_STAGE_(bufoff, gbase, voffB)
; #define PG8_LDA(dst, b, h) do { _Pragma("unroll") for (int m = 0; m < 4; ++m) _Pragma("unroll") for (int k = 0; k < 2; ++k) dst[m][k] = *(const LAS bf16x8*)(lds + PG8_SA(b, h) + aoff + m * 2048 + k * 1024); } while (0)
; #define PG8_LDB(dst, b, h) do { _Pragma("unroll") for (int n = 0; n < 2; ++n) _Pragma("unroll") for (int k = 0; k < 2; ++k) dst[n][k] = *(const LAS bf16x8*)(lds + PG8_SB(b, h) + boff + n * 2048 + k * 1024); } while (0)
; #define PG8_MMA(ai, bj, At, Bt_) do { __builtin_amdgcn_s_setprio(1); _Pragma("unroll") for (int m = 0; m < 4; ++m) _Pragma("unroll") for (int n = 0; n < 2; ++n) _Pragma("unroll") for (int k = 0; k < 2; ++k) \
;         acc[ai][bj][m][n] = __builtin_amdgcn_mfma_f32_16x16x32_bf16(Bt_[n][k], At[m][k], acc[ai][bj][m][n], 0, 0, 0); __builtin_amdgcn_s_setprio(0); } while (0)
; #define PG8_WAIT_V(n) asm volatile("s_waitcnt vmcnt(" #n ")" ::: "memory")
; #define PG8_WAIT_L(n) asm volatile("s_waitcnt lgkmcnt(" #n ")" ::: "memory")
; #define PG8_BAR __builtin_amdgcn_s_barrier()
; #define PG8_SCHED __builtin_amdgcn_sched_barrier(0)
; template <int EK, int SK = -1>
; __device__ __forceinline__ void gemm_phase(LAS unsigned char* lds, const bf16_t* A, const bf16_t* Bt, int nM, int N, int K, const EpiArgs& E) {
;     ...
;         const bool has_next = S.next(ui + 1, nxt);
;         const char* nA = has_next ? (const char*)A + (size_t)nxt.pm * tstep : cA; const char* nB = has_next ? (const char*)Bt + (size_t)nxt.pn * tstep : cB;
;         for (int t = 0; t < nt; t += 2) {
;             const bool last = (t == nt - 2);
;             const char* a1 = cA + (size_t)(t + 1) * kstep;
;             const char* a2 = last ? nA : cA + (size_t)(t + 2) * kstep; const char* b2 = last ? nB : cB + (size_t)(t + 2) * kstep;
;             const char* a3 = a2 + kstep; const char* b3 = b2 + kstep;
;             PG8_LDB(B0, 0, 0); PG8_LDB(B1, 0, 1); PG8_SCHED; PG8_LDA(At, 0, 0); PG8_STAGEA(PG8_SA(1, 1), a1 + hstep);
;             PG8_WAIT_V(8); PG8_WAIT_L(0); PG8_BAR; PG8_MMA(0, 0, At, B0); PG8_MMA(0, 1, At, B1); PG8_BAR; PG8_SCHED;
;             PG8_LDA(At, 0, 1); PG8_STAGEB(PG8_SB(0, 0), b2); PG8_STAGEB(PG8_SB(0, 1), b2 + hstep); PG8_STAGEA(PG8_SA(0, 0), a2);
.LBB0_1119:
	s_add_u32 s73, s46, 0x100
	s_addc_u32 s74, s47, 0
	s_ashr_i32 s41, s40, 31
	s_lshl_b64 s[42:43], s[40:41], 19
	s_add_u32 s44, s66, s42
	s_addc_u32 s45, s67, s43
	s_and_b64 s[42:43], s[8:9], exec
	s_cselect_b32 s22, s45, s19
	s_cselect_b32 s41, s44, s18
	s_ashr_i32 s39, s38, 31
	s_lshl_b64 s[42:43], s[38:39], 19
	s_add_u32 s42, s52, s42
	s_addc_u32 s43, s53, s43
	s_and_b64 s[48:49], s[8:9], exec
	s_cselect_b32 s39, s43, s47
	s_cselect_b32 s75, s42, s46
	v_lshl_add_u64 v[146:147], s[18:19], 0, v[138:139]
	v_lshl_add_u64 v[148:149], s[18:19], 0, v[140:141]
	s_mov_b32 s76, -2
	s_mov_b64 s[46:47], 0
	v_add_u32_e32 v150, s69, v152
	ds_read_b128 v[156:159], v150
	ds_read_b128 v[160:163], v150 offset:1024
	ds_read_b128 v[164:167], v150 offset:2048
	ds_read_b128 v[168:171], v150 offset:3072
	v_add_u32_e32 v150, s70, v152
	s_add_u32 s48, s18, s46
	ds_read_b128 v[172:175], v150
	ds_read_b128 v[176:179], v150 offset:1024
	ds_read_b128 v[180:183], v150 offset:2048
	ds_read_b128 v[184:187], v150 offset:3072
	s_addc_u32 s49, s19, s47
	s_add_u32 s48, s48, 0x100
	s_addc_u32 s49, s49, 0
	s_add_u32 s77, s73, s46
	s_addc_u32 s78, s74, s47
	s_cmpk_eq_i32 s46, 0x700
	s_cselect_b32 s51, s22, s49
	s_cselect_b32 s50, s41, s48
	s_cselect_b32 s49, s39, s78
	s_cselect_b32 s48, s75, s77
	v_lshl_add_u64 v[150:151], v[146:147], 0, s[46:47]
	s_add_i32 m0, s15, 0xc000
	ds_read_b128 v[188:191], v154
	ds_read_b128 v[192:195], v154 offset:1024
	ds_read_b128 v[196:199], v154 offset:2048
	ds_read_b128 v[200:203], v154 offset:3072
	ds_read_b128 v[204:207], v154 offset:4096
	ds_read_b128 v[208:211], v154 offset:5120
	ds_read_b128 v[212:215], v154 offset:6144
	ds_read_b128 v[216:219], v154 offset:7168
	global_load_lds_dwordx4 v[150:151], off
	v_lshl_add_u64 v[150:151], v[148:149], 0, s[46:47]
	s_add_i32 m0, s15, 0xe000
	s_nop 0
	global_load_lds_dwordx4 v[150:151], off
	s_waitcnt vmcnt(8)
	s_waitcnt lgkmcnt(0)
	s_barrier
	s_waitcnt lgkmcnt(0)
	v_mfma_f32_16x16x32_bf16 v[126:129], v[156:159], v[188:191], 0
	v_mfma_f32_16x16x32_bf16 v[122:125], v[164:167], v[188:191], 0
	v_mfma_f32_16x16x32_bf16 v[114:117], v[164:167], v[196:199], 0
	v_mfma_f32_16x16x32_bf16 v[118:121], v[156:159], v[196:199], 0
	v_mfma_f32_16x16x32_bf16 v[110:113], v[156:159], v[204:207], 0
	v_mfma_f32_16x16x32_bf16 v[106:109], v[164:167], v[204:207], 0
	v_mfma_f32_16x16x32_bf16 v[98:101], v[164:167], v[212:215], 0
	v_mfma_f32_16x16x32_bf16 v[102:105], v[156:159], v[212:215], 0
	v_mfma_f32_16x16x32_bf16 v[126:129], v[160:163], v[192:195], v[126:129]
	v_mfma_f32_16x16x32_bf16 v[122:125], v[168:171], v[192:195], v[122:125]
	v_mfma_f32_16x16x32_bf16 v[114:117], v[168:171], v[200:203], v[114:117]
	v_mfma_f32_16x16x32_bf16 v[118:121], v[160:163], v[200:203], v[118:121]
	v_mfma_f32_16x16x32_bf16 v[110:113], v[160:163], v[208:211], v[110:113]
	v_mfma_f32_16x16x32_bf16 v[106:109], v[168:171], v[208:211], v[106:109]
	v_mfma_f32_16x16x32_bf16 v[98:101], v[168:171], v[216:219], v[98:101]
	v_mfma_f32_16x16x32_bf16 v[102:105], v[160:163], v[216:219], v[102:105]
	v_mfma_f32_16x16x32_bf16 v[94:97], v[172:175], v[188:191], 0
	v_mfma_f32_16x16x32_bf16 v[90:93], v[180:183], v[188:191], 0
	v_mfma_f32_16x16x32_bf16 v[82:85], v[180:183], v[196:199], 0
	v_mfma_f32_16x16x32_bf16 v[86:89], v[172:175], v[196:199], 0
	v_mfma_f32_16x16x32_bf16 v[78:81], v[172:175], v[204:207], 0
	v_mfma_f32_16x16x32_bf16 v[74:77], v[180:183], v[204:207], 0
	v_mfma_f32_16x16x32_bf16 v[66:69], v[180:183], v[212:215], 0
	v_mfma_f32_16x16x32_bf16 v[70:73], v[172:175], v[212:215], 0
	v_mfma_f32_16x16x32_bf16 v[94:97], v[176:179], v[192:195], v[94:97]
	v_mfma_f32_16x16x32_bf16 v[90:93], v[184:187], v[192:195], v[90:93]
	v_mfma_f32_16x16x32_bf16 v[82:85], v[184:187], v[200:203], v[82:85]
	v_mfma_f32_16x16x32_bf16 v[86:89], v[176:179], v[200:203], v[86:89]
	v_mfma_f32_16x16x32_bf16 v[78:81], v[176:179], v[208:211], v[78:81]
	v_mfma_f32_16x16x32_bf16 v[74:77], v[184:187], v[208:211], v[74:77]
	v_mfma_f32_16x16x32_bf16 v[66:69], v[184:187], v[216:219], v[66:69]
	v_mfma_f32_16x16x32_bf16 v[70:73], v[176:179], v[216:219], v[70:73]
	s_barrier
	s_add_i32 s77, s69, s54
	v_lshl_add_u64 v[150:151], s[48:49], 0, v[132:133]
	s_mov_b32 m0, s77
	ds_read_b128 v[188:191], v154 offset:16384
	ds_read_b128 v[192:195], v154 offset:17408
	ds_read_b128 v[196:199], v154 offset:18432
	ds_read_b128 v[200:203], v154 offset:19456
	ds_read_b128 v[204:207], v154 offset:20480
	ds_read_b128 v[208:211], v154 offset:21504
	ds_read_b128 v[212:215], v154 offset:22528
	ds_read_b128 v[216:219], v154 offset:23552
	global_load_lds_dwordx4 v[150:151], off
	s_add_i32 m0, s77, 0x2000
	s_add_u32 s78, s48, 0x40000
	v_lshl_add_u64 v[220:221], s[48:49], 0, v[136:137]
	s_addc_u32 s79, s49, 0
	s_add_i32 s77, s70, s54
	global_load_lds_dwordx4 v[220:221], off
	v_lshl_add_u64 v[222:223], s[78:79], 0, v[132:133]
	s_mov_b32 m0, s77
	v_lshl_add_u64 v[224:225], s[50:51], 0, v[134:135]
	global_load_lds_dwordx4 v[222:223], off
	v_lshl_add_u64 v[222:223], s[78:79], 0, v[136:137]
	s_add_i32 m0, s77, 0x2000
	s_nop 0
	global_load_lds_dwordx4 v[222:223], off
	v_lshl_add_u64 v[222:223], s[50:51], 0, v[130:131]
	s_mov_b32 m0, s15
	s_nop 0
	global_load_lds_dwordx4 v[222:223], off
	s_mov_b32 m0, s17
	s_nop 0
	global_load_lds_dwordx4 v[224:225], off
	s_waitcnt vmcnt(8)
	s_waitcnt lgkmcnt(0)
	s_barrier
; #define PG8_STAGEA(bufoff, gbase) PG8_STAGE_(bufoff, gbase, voffA)
; #define PG8_LDA(dst, b, h) do { _Pragma("unroll") for (int m = 0; m < 4; ++m) _Pragma("unroll") for (int k = 0; k < 2; ++k) dst[m][k] = *(const LAS bf16x8*)(lds + PG8_SA(b, h) + aoff + m * 2048 + k * 1024); } while (0)
; #define PG8_LDB(dst, b, h) do { _Pragma("unroll") for (int n = 0; n < 2; ++n) _Pragma("unroll") for (int k = 0; k < 2; ++k) dst[n][k] = *(const LAS bf16x8*)(lds + PG8_SB(b, h) + boff + n * 2048 + k * 1024); } while (0)
; #define PG8_MMA(ai, bj, At, Bt_) do { __builtin_amdgcn_s_setprio(1); _Pragma("unroll") for (int m = 0; m < 4; ++m) _Pragma("unroll") for (int n = 0; n < 2; ++n) _Pragma("unroll") for (int k = 0; k < 2; ++k) \
;         acc[ai][bj][m][n] = __builtin_amdgcn_mfma_f32_16x16x32_bf16(Bt_[n][k], At[m][k], acc[ai][bj][m][n], 0, 0, 0); __builtin_amdgcn_s_setprio(0); } while (0)
; #define PG8_WAIT_V(n) asm volatile("s_waitcnt vmcnt(" #n ")" ::: "memory")
; #define PG8_WAIT_L(n) asm volatile("s_waitcnt lgkmcnt(" #n ")" ::: "memory")
; #define PG8_BAR __builtin_amdgcn_s_barrier()
; #define PG8_SCHED __builtin_amdgcn_sched_barrier(0)
; template <int EK, int SK = -1>
; __device__ __forceinline__ void gemm_phase(LAS unsigned char* lds, const bf16_t* A, const bf16_t* Bt, int nM, int N, int K, const EpiArgs& E) {
;     ...
;             PG8_WAIT_V(8); PG8_WAIT_L(0); PG8_BAR; PG8_MMA(1, 0, At, B0); PG8_MMA(1, 1, At, B1); PG8_BAR; PG8_SCHED;
;             PG8_LDB(B0, 1, 0); PG8_LDB(B1, 1, 1); PG8_SCHED; PG8_LDA(At, 1, 0); PG8_STAGEA(PG8_SA(0, 1), a2 + hstep);
;             PG8_WAIT_V(8); PG8_WAIT_L(0); PG8_BAR; PG8_MMA(0, 0, At, B0); PG8_MMA(0, 1, At, B1); PG8_BAR; PG8_SCHED;
	s_waitcnt lgkmcnt(0)
	v_mfma_f32_16x16x32_bf16 v[62:65], v[156:159], v[188:191], 0
	v_mfma_f32_16x16x32_bf16 v[58:61], v[164:167], v[188:191], 0
	v_mfma_f32_16x16x32_bf16 v[50:53], v[164:167], v[196:199], 0
	v_mfma_f32_16x16x32_bf16 v[54:57], v[156:159], v[196:199], 0
	v_mfma_f32_16x16x32_bf16 v[46:49], v[156:159], v[204:207], 0
	v_mfma_f32_16x16x32_bf16 v[42:45], v[164:167], v[204:207], 0
	v_mfma_f32_16x16x32_bf16 v[34:37], v[164:167], v[212:215], 0
	v_mfma_f32_16x16x32_bf16 v[38:41], v[156:159], v[212:215], 0
	v_mfma_f32_16x16x32_bf16 v[62:65], v[160:163], v[192:195], v[62:65]
	v_mfma_f32_16x16x32_bf16 v[58:61], v[168:171], v[192:195], v[58:61]
	v_mfma_f32_16x16x32_bf16 v[50:53], v[168:171], v[200:203], v[50:53]
	v_mfma_f32_16x16x32_bf16 v[54:57], v[160:163], v[200:203], v[54:57]
	v_mfma_f32_16x16x32_bf16 v[46:49], v[160:163], v[208:211], v[46:49]
	v_mfma_f32_16x16x32_bf16 v[42:45], v[168:171], v[208:211], v[42:45]
	v_mfma_f32_16x16x32_bf16 v[34:37], v[168:171], v[216:219], v[34:37]
	v_mfma_f32_16x16x32_bf16 v[38:41], v[160:163], v[216:219], v[38:41]
	v_mfma_f32_16x16x32_bf16 v[30:33], v[172:175], v[188:191], 0
	v_mfma_f32_16x16x32_bf16 v[26:29], v[180:183], v[188:191], 0
	v_mfma_f32_16x16x32_bf16 v[18:21], v[180:183], v[196:199], 0
	v_mfma_f32_16x16x32_bf16 v[22:25], v[172:175], v[196:199], 0
	v_mfma_f32_16x16x32_bf16 v[14:17], v[172:175], v[204:207], 0
	v_mfma_f32_16x16x32_bf16 v[10:13], v[180:183], v[204:207], 0
	v_mfma_f32_16x16x32_bf16 v[2:5], v[180:183], v[212:215], 0
	v_mfma_f32_16x16x32_bf16 v[6:9], v[172:175], v[212:215], 0
	v_mfma_f32_16x16x32_bf16 v[30:33], v[176:179], v[192:195], v[30:33]
	v_mfma_f32_16x16x32_bf16 v[26:29], v[184:187], v[192:195], v[26:29]
	v_mfma_f32_16x16x32_bf16 v[18:21], v[184:187], v[200:203], v[18:21]
	v_mfma_f32_16x16x32_bf16 v[22:25], v[176:179], v[200:203], v[22:25]
	v_mfma_f32_16x16x32_bf16 v[14:17], v[176:179], v[208:211], v[14:17]
	v_mfma_f32_16x16x32_bf16 v[10:13], v[184:187], v[208:211], v[10:13]
	v_mfma_f32_16x16x32_bf16 v[2:5], v[184:187], v[216:219], v[2:5]
	v_mfma_f32_16x16x32_bf16 v[6:9], v[176:179], v[216:219], v[6:9]
	s_barrier
	s_add_i32 s77, 0, 0x18000
	s_add_i32 s78, 0, 0x1c000
	v_add_u32_e32 v168, s77, v152
	v_add_u32_e32 v184, s78, v152
	ds_read_b128 v[156:159], v168
	ds_read_b128 v[160:163], v168 offset:1024
	ds_read_b128 v[164:167], v168 offset:2048
	ds_read_b128 v[168:171], v168 offset:3072
	ds_read_b128 v[172:175], v184
	ds_read_b128 v[176:179], v184 offset:1024
	ds_read_b128 v[180:183], v184 offset:2048
	ds_read_b128 v[184:187], v184 offset:3072
	s_add_u32 s50, s50, 0x40000
	s_addc_u32 s51, s51, 0
	s_mov_b32 m0, s55
	v_lshl_add_u64 v[226:227], s[50:51], 0, v[130:131]
	ds_read_b128 v[188:191], v154 offset:32768
	ds_read_b128 v[192:195], v154 offset:33792
	ds_read_b128 v[196:199], v154 offset:34816
	ds_read_b128 v[200:203], v154 offset:35840
	ds_read_b128 v[204:207], v154 offset:36864
	ds_read_b128 v[208:211], v154 offset:37888
	ds_read_b128 v[212:215], v154 offset:38912
	ds_read_b128 v[216:219], v154 offset:39936
	global_load_lds_dwordx4 v[226:227], off
	v_lshl_add_u64 v[226:227], s[50:51], 0, v[134:135]
	s_mov_b32 m0, s56
	s_nop 0
	global_load_lds_dwordx4 v[226:227], off
	s_waitcnt vmcnt(8)
	s_waitcnt lgkmcnt(0)
	s_barrier
	s_waitcnt lgkmcnt(0)
	v_mfma_f32_16x16x32_bf16 v[126:129], v[156:159], v[188:191], v[126:129]
	v_mfma_f32_16x16x32_bf16 v[122:125], v[164:167], v[188:191], v[122:125]
	v_mfma_f32_16x16x32_bf16 v[114:117], v[164:167], v[196:199], v[114:117]
	v_mfma_f32_16x16x32_bf16 v[118:121], v[156:159], v[196:199], v[118:121]
	v_mfma_f32_16x16x32_bf16 v[110:113], v[156:159], v[204:207], v[110:113]
	v_mfma_f32_16x16x32_bf16 v[106:109], v[164:167], v[204:207], v[106:109]
	v_mfma_f32_16x16x32_bf16 v[98:101], v[164:167], v[212:215], v[98:101]
	v_mfma_f32_16x16x32_bf16 v[102:105], v[156:159], v[212:215], v[102:105]
	v_mfma_f32_16x16x32_bf16 v[126:129], v[160:163], v[192:195], v[126:129]
	v_mfma_f32_16x16x32_bf16 v[122:125], v[168:171], v[192:195], v[122:125]
	v_mfma_f32_16x16x32_bf16 v[114:117], v[168:171], v[200:203], v[114:117]
	v_mfma_f32_16x16x32_bf16 v[118:121], v[160:163], v[200:203], v[118:121]
	v_mfma_f32_16x16x32_bf16 v[110:113], v[160:163], v[208:211], v[110:113]
	v_mfma_f32_16x16x32_bf16 v[106:109], v[168:171], v[208:211], v[106:109]
	v_mfma_f32_16x16x32_bf16 v[98:101], v[168:171], v[216:219], v[98:101]
	v_mfma_f32_16x16x32_bf16 v[102:105], v[160:163], v[216:219], v[102:105]
	v_mfma_f32_16x16x32_bf16 v[94:97], v[172:175], v[188:191], v[94:97]
	v_mfma_f32_16x16x32_bf16 v[90:93], v[180:183], v[188:191], v[90:93]
	v_mfma_f32_16x16x32_bf16 v[82:85], v[180:183], v[196:199], v[82:85]
	v_mfma_f32_16x16x32_bf16 v[86:89], v[172:175], v[196:199], v[86:89]
	v_mfma_f32_16x16x32_bf16 v[78:81], v[172:175], v[204:207], v[78:81]
	v_mfma_f32_16x16x32_bf16 v[74:77], v[180:183], v[204:207], v[74:77]
	v_mfma_f32_16x16x32_bf16 v[66:69], v[180:183], v[212:215], v[66:69]
	v_mfma_f32_16x16x32_bf16 v[70:73], v[172:175], v[212:215], v[70:73]
	v_mfma_f32_16x16x32_bf16 v[94:97], v[176:179], v[192:195], v[94:97]
	v_mfma_f32_16x16x32_bf16 v[90:93], v[184:187], v[192:195], v[90:93]
	v_mfma_f32_16x16x32_bf16 v[82:85], v[184:187], v[200:203], v[82:85]
	v_mfma_f32_16x16x32_bf16 v[86:89], v[176:179], v[200:203], v[86:89]
	v_mfma_f32_16x16x32_bf16 v[78:81], v[176:179], v[208:211], v[78:81]
	v_mfma_f32_16x16x32_bf16 v[74:77], v[184:187], v[208:211], v[74:77]
	v_mfma_f32_16x16x32_bf16 v[66:69], v[184:187], v[216:219], v[66:69]
	v_mfma_f32_16x16x32_bf16 v[70:73], v[176:179], v[216:219], v[70:73]
	s_barrier
; #define PG8_STAGEA(bufoff, gbase) PG8_STAGE_(bufoff, gbase, voffA)
; #define PG8_STAGEB(bufoff, gbase) PG8_STAGE_(bufoff, gbase, voffB)
; #define PG8_LDA(dst, b, h) do { _Pragma("unroll") for (int m = 0; m < 4; ++m) _Pragma("unroll") for (int k = 0; k < 2; ++k) dst[m][k] = *(const LAS bf16x8*)(lds + PG8_SA(b, h) + aoff + m * 2048 + k * 1024); } while (0)
; #define PG8_LDB(dst, b, h) do { _Pragma("unroll") for (int n = 0; n < 2; ++n) _Pragma("unroll") for (int k = 0; k < 2; ++k) dst[n][k] = *(const LAS bf16x8*)(lds + PG8_SB(b, h) + boff + n * 2048 + k * 1024); } while (0)
; #define PG8_MMA(ai, bj, At, Bt_) do { __builtin_amdgcn_s_setprio(1); _Pragma("unroll") for (int m = 0; m < 4; ++m) _Pragma("unroll") for (int n = 0; n < 2; ++n) _Pragma("unroll") for (int k = 0; k < 2; ++k) \
;         acc[ai][bj][m][n] = __builtin_amdgcn_mfma_f32_16x16x32_bf16(Bt_[n][k], At[m][k], acc[ai][bj][m][n], 0, 0, 0); __builtin_amdgcn_s_setprio(0); } while (0)
; #define PG8_WAIT_V(n) asm volatile("s_waitcnt vmcnt(" #n ")" ::: "memory")
; #define PG8_WAIT_L(n) asm volatile("s_waitcnt lgkmcnt(" #n ")" ::: "memory")
; #define PG8_BAR __builtin_amdgcn_s_barrier()
; #define PG8_SCHED __builtin_amdgcn_sched_barrier(0)
; template <int EK, int SK = -1>
; __device__ __forceinline__ void gemm_phase(LAS unsigned char* lds, const bf16_t* A, const bf16_t* Bt, int nM, int N, int K, const EpiArgs& E) {
;     ...
;             PG8_LDB(B0, 0, 0); PG8_LDB(B1, 0, 1); PG8_SCHED; PG8_LDA(At, 0, 0); PG8_STAGEA(PG8_SA(1, 1), a1 + hstep);
;             PG8_WAIT_V(8); PG8_WAIT_L(0); PG8_BAR; PG8_MMA(0, 0, At, B0); PG8_MMA(0, 1, At, B1); PG8_BAR; PG8_SCHED;
;     ...
;             PG8_LDA(At, 1, 1); PG8_STAGEB(PG8_SB(1, 0), b3); PG8_STAGEB(PG8_SB(1, 1), b3 + hstep); PG8_STAGEA(PG8_SA(1, 0), a3);
;             PG8_WAIT_V(8); PG8_WAIT_L(0); PG8_BAR; PG8_MMA(1, 0, At, B0); PG8_MMA(1, 1, At, B1); PG8_BAR; PG8_SCHED;
;         }
	s_add_i32 s50, s77, s54
	v_lshl_add_u64 v[150:151], v[150:151], 0, s[26:27]
	s_mov_b32 m0, s50
	ds_read_b128 v[188:191], v154 offset:49152
	ds_read_b128 v[192:195], v154 offset:50176
	ds_read_b128 v[196:199], v154 offset:51200
	ds_read_b128 v[200:203], v154 offset:52224
	ds_read_b128 v[204:207], v154 offset:53248
	ds_read_b128 v[208:211], v154 offset:54272
	ds_read_b128 v[212:215], v154 offset:55296
	ds_read_b128 v[216:219], v154 offset:56320
	global_load_lds_dwordx4 v[150:151], off
	s_add_i32 m0, s50, 0x2000
	s_add_u32 s48, s48, 0x40080
	v_lshl_add_u64 v[150:151], v[220:221], 0, s[26:27]
	s_addc_u32 s49, s49, 0
	s_add_i32 s50, s78, s54
	global_load_lds_dwordx4 v[150:151], off
	v_lshl_add_u64 v[150:151], s[48:49], 0, v[132:133]
	s_mov_b32 m0, s50
	s_nop 0
	global_load_lds_dwordx4 v[150:151], off
	v_lshl_add_u64 v[150:151], s[48:49], 0, v[136:137]
	s_add_i32 m0, s50, 0x2000
	s_nop 0
	global_load_lds_dwordx4 v[150:151], off
	v_lshl_add_u64 v[150:151], v[222:223], 0, s[26:27]
	s_mov_b32 m0, s59
	s_nop 0
	global_load_lds_dwordx4 v[150:151], off
	v_lshl_add_u64 v[150:151], v[224:225], 0, s[26:27]
	s_mov_b32 m0, s68
	s_nop 0
	global_load_lds_dwordx4 v[150:151], off
	s_waitcnt vmcnt(8)
	s_waitcnt lgkmcnt(0)
	s_barrier
	s_waitcnt lgkmcnt(0)
	v_mfma_f32_16x16x32_bf16 v[62:65], v[156:159], v[188:191], v[62:65]
	v_mfma_f32_16x16x32_bf16 v[58:61], v[164:167], v[188:191], v[58:61]
	v_mfma_f32_16x16x32_bf16 v[50:53], v[164:167], v[196:199], v[50:53]
	v_mfma_f32_16x16x32_bf16 v[54:57], v[156:159], v[196:199], v[54:57]
	v_mfma_f32_16x16x32_bf16 v[46:49], v[156:159], v[204:207], v[46:49]
	v_mfma_f32_16x16x32_bf16 v[42:45], v[164:167], v[204:207], v[42:45]
	v_mfma_f32_16x16x32_bf16 v[34:37], v[164:167], v[212:215], v[34:37]
	v_mfma_f32_16x16x32_bf16 v[38:41], v[156:159], v[212:215], v[38:41]
	v_mfma_f32_16x16x32_bf16 v[62:65], v[160:163], v[192:195], v[62:65]
	v_mfma_f32_16x16x32_bf16 v[58:61], v[168:171], v[192:195], v[58:61]
	v_mfma_f32_16x16x32_bf16 v[50:53], v[168:171], v[200:203], v[50:53]
	v_mfma_f32_16x16x32_bf16 v[54:57], v[160:163], v[200:203], v[54:57]
	v_mfma_f32_16x16x32_bf16 v[46:49], v[160:163], v[208:211], v[46:49]
	v_mfma_f32_16x16x32_bf16 v[42:45], v[168:171], v[208:211], v[42:45]
	v_mfma_f32_16x16x32_bf16 v[34:37], v[168:171], v[216:219], v[34:37]
	v_mfma_f32_16x16x32_bf16 v[38:41], v[160:163], v[216:219], v[38:41]
	v_mfma_f32_16x16x32_bf16 v[30:33], v[172:175], v[188:191], v[30:33]
	v_mfma_f32_16x16x32_bf16 v[26:29], v[180:183], v[188:191], v[26:29]
	v_mfma_f32_16x16x32_bf16 v[18:21], v[180:183], v[196:199], v[18:21]
	v_mfma_f32_16x16x32_bf16 v[22:25], v[172:175], v[196:199], v[22:25]
	v_mfma_f32_16x16x32_bf16 v[14:17], v[172:175], v[204:207], v[14:17]
	v_mfma_f32_16x16x32_bf16 v[10:13], v[180:183], v[204:207], v[10:13]
	v_mfma_f32_16x16x32_bf16 v[2:5], v[180:183], v[212:215], v[2:5]
	v_mfma_f32_16x16x32_bf16 v[6:9], v[172:175], v[212:215], v[6:9]
	v_mfma_f32_16x16x32_bf16 v[30:33], v[176:179], v[192:195], v[30:33]
	v_mfma_f32_16x16x32_bf16 v[26:29], v[184:187], v[192:195], v[26:29]
	v_mfma_f32_16x16x32_bf16 v[18:21], v[184:187], v[200:203], v[18:21]
	v_mfma_f32_16x16x32_bf16 v[22:25], v[176:179], v[200:203], v[22:25]
	v_mfma_f32_16x16x32_bf16 v[14:17], v[176:179], v[208:211], v[14:17]
	v_mfma_f32_16x16x32_bf16 v[10:13], v[184:187], v[208:211], v[10:13]
	v_mfma_f32_16x16x32_bf16 v[2:5], v[184:187], v[216:219], v[2:5]
	v_mfma_f32_16x16x32_bf16 v[6:9], v[176:179], v[216:219], v[6:9]
	s_barrier
	s_add_i32 s76, s76, 2
	s_add_u32 s46, s46, 0x100
	s_addc_u32 s47, s47, 0
	s_cmp_gt_u32 s76, 13
	s_cbranch_scc0 .LBB0_1120
	s_branch .Lmy_kexit_5
.LBB0_1120:
	v_add_u32_e32 v150, s69, v152
	ds_read_b128 v[156:159], v150
	ds_read_b128 v[160:163], v150 offset:1024
	ds_read_b128 v[164:167], v150 offset:2048
	ds_read_b128 v[168:171], v150 offset:3072
	v_add_u32_e32 v150, s70, v152
	s_add_u32 s48, s18, s46
	ds_read_b128 v[172:175], v150
	ds_read_b128 v[176:179], v150 offset:1024
	ds_read_b128 v[180:183], v150 offset:2048
	ds_read_b128 v[184:187], v150 offset:3072
	s_addc_u32 s49, s19, s47
	s_add_u32 s48, s48, 0x100
	s_addc_u32 s49, s49, 0
	s_add_u32 s77, s73, s46
	s_addc_u32 s78, s74, s47
	s_cmpk_eq_i32 s46, 0x700
	s_cselect_b32 s51, s22, s49
	s_cselect_b32 s50, s41, s48
	s_cselect_b32 s49, s39, s78
	s_cselect_b32 s48, s75, s77
	v_lshl_add_u64 v[150:151], v[146:147], 0, s[46:47]
	s_add_i32 m0, s15, 0xc000
	ds_read_b128 v[188:191], v154
	ds_read_b128 v[192:195], v154 offset:1024
	ds_read_b128 v[196:199], v154 offset:2048
	ds_read_b128 v[200:203], v154 offset:3072
	ds_read_b128 v[204:207], v154 offset:4096
	ds_read_b128 v[208:211], v154 offset:5120
	ds_read_b128 v[212:215], v154 offset:6144
	ds_read_b128 v[216:219], v154 offset:7168
	global_load_lds_dwordx4 v[150:151], off
	v_lshl_add_u64 v[150:151], v[148:149], 0, s[46:47]
	s_add_i32 m0, s15, 0xe000
	s_nop 0
	global_load_lds_dwordx4 v[150:151], off
	s_waitcnt vmcnt(8)
	s_waitcnt lgkmcnt(0)
	s_barrier
; #define PG8_STAGEA(bufoff, gbase) PG8_STAGE_(bufoff, gbase, voffA)
; #define PG8_STAGEB(bufoff, gbase) PG8_STAGE_(bufoff, gbase, voffB)
; #define PG8_LDA(dst, b, h) do { _Pragma("unroll") for (int m = 0; m < 4; ++m) _Pragma("unroll") for (int k = 0; k < 2; ++k) dst[m][k] = *(const LAS bf16x8*)(lds + PG8_SA(b, h) + aoff + m * 2048 + k * 1024); } while (0)
; #define PG8_LDB(dst, b, h) do { _Pragma("unroll") for (int n = 0; n < 2; ++n) _Pragma("unroll") for (int k = 0; k < 2; ++k) dst[n][k] = *(const LAS bf16x8*)(lds + PG8_SB(b, h) + boff + n * 2048 + k * 1024); } while (0)
; #define PG8_MMA(ai, bj, At, Bt_) do { __builtin_amdgcn_s_setprio(1); _Pragma("unroll") for (int m = 0; m < 4; ++m) _Pragma("unroll") for (int n = 0; n < 2; ++n) _Pragma("unroll") for (int k = 0; k < 2; ++k) \
;         acc[ai][bj][m][n] = __builtin_amdgcn_mfma_f32_16x16x32_bf16(Bt_[n][k], At[m][k], acc[ai][bj][m][n], 0, 0, 0); __builtin_amdgcn_s_setprio(0); } while (0)
; #define PG8_WAIT_V(n) asm volatile("s_waitcnt vmcnt(" #n ")" ::: "memory")
; #define PG8_WAIT_L(n) asm volatile("s_waitcnt lgkmcnt(" #n ")" ::: "memory")
; #define PG8_BAR __builtin_amdgcn_s_barrier()
; #define PG8_SCHED __builtin_amdgcn_sched_barrier(0)
; template <int EK, int SK = -1>
; __device__ __forceinline__ void gemm_phase(LAS unsigned char* lds, const bf16_t* A, const bf16_t* Bt, int nM, int N, int K, const EpiArgs& E) {
;     ...
;             PG8_WAIT_V(8); PG8_WAIT_L(0); PG8_BAR; PG8_MMA(0, 0, At, B0); PG8_MMA(0, 1, At, B1); PG8_BAR; PG8_SCHED;
;             PG8_LDA(At, 0, 1); PG8_STAGEB(PG8_SB(0, 0), b2); PG8_STAGEB(PG8_SB(0, 1), b2 + hstep); PG8_STAGEA(PG8_SA(0, 0), a2);
;             PG8_WAIT_V(8); PG8_WAIT_L(0); PG8_BAR; PG8_MMA(1, 0, At, B0); PG8_MMA(1, 1, At, B1); PG8_BAR; PG8_SCHED;
;             PG8_LDB(B0, 1, 0); PG8_LDB(B1, 1, 1); PG8_SCHED; PG8_LDA(At, 1, 0); PG8_STAGEA(PG8_SA(0, 1), a2 + hstep);
;             PG8_WAIT_V(8); PG8_WAIT_L(0); PG8_BAR; PG8_MMA(0, 0, At, B0); PG8_MMA(0, 1, At, B1); PG8_BAR; PG8_SCHED;
	s_waitcnt lgkmcnt(0)
	v_mfma_f32_16x16x32_bf16 v[126:129], v[156:159], v[188:191], v[126:129]
	v_mfma_f32_16x16x32_bf16 v[122:125], v[164:167], v[188:191], v[122:125]
	v_mfma_f32_16x16x32_bf16 v[114:117], v[164:167], v[196:199], v[114:117]
	v_mfma_f32_16x16x32_bf16 v[118:121], v[156:159], v[196:199], v[118:121]
	v_mfma_f32_16x16x32_bf16 v[110:113], v[156:159], v[204:207], v[110:113]
	v_mfma_f32_16x16x32_bf16 v[106:109], v[164:167], v[204:207], v[106:109]
	v_mfma_f32_16x16x32_bf16 v[98:101], v[164:167], v[212:215], v[98:101]
	v_mfma_f32_16x16x32_bf16 v[102:105], v[156:159], v[212:215], v[102:105]
	v_mfma_f32_16x16x32_bf16 v[126:129], v[160:163], v[192:195], v[126:129]
	v_mfma_f32_16x16x32_bf16 v[122:125], v[168:171], v[192:195], v[122:125]
	v_mfma_f32_16x16x32_bf16 v[114:117], v[168:171], v[200:203], v[114:117]
	v_mfma_f32_16x16x32_bf16 v[118:121], v[160:163], v[200:203], v[118:121]
	v_mfma_f32_16x16x32_bf16 v[110:113], v[160:163], v[208:211], v[110:113]
	v_mfma_f32_16x16x32_bf16 v[106:109], v[168:171], v[208:211], v[106:109]
	v_mfma_f32_16x16x32_bf16 v[98:101], v[168:171], v[216:219], v[98:101]
	v_mfma_f32_16x16x32_bf16 v[102:105], v[160:163], v[216:219], v[102:105]
	v_mfma_f32_16x16x32_bf16 v[94:97], v[172:175], v[188:191], v[94:97]
	v_mfma_f32_16x16x32_bf16 v[90:93], v[180:183], v[188:191], v[90:93]
	v_mfma_f32_16x16x32_bf16 v[82:85], v[180:183], v[196:199], v[82:85]
	v_mfma_f32_16x16x32_bf16 v[86:89], v[172:175], v[196:199], v[86:89]
	v_mfma_f32_16x16x32_bf16 v[78:81], v[172:175], v[204:207], v[78:81]
	v_mfma_f32_16x16x32_bf16 v[74:77], v[180:183], v[204:207], v[74:77]
	v_mfma_f32_16x16x32_bf16 v[66:69], v[180:183], v[212:215], v[66:69]
	v_mfma_f32_16x16x32_bf16 v[70:73], v[172:175], v[212:215], v[70:73]
	v_mfma_f32_16x16x32_bf16 v[94:97], v[176:179], v[192:195], v[94:97]
	v_mfma_f32_16x16x32_bf16 v[90:93], v[184:187], v[192:195], v[90:93]
	v_mfma_f32_16x16x32_bf16 v[82:85], v[184:187], v[200:203], v[82:85]
	v_mfma_f32_16x16x32_bf16 v[86:89], v[176:179], v[200:203], v[86:89]
	v_mfma_f32_16x16x32_bf16 v[78:81], v[176:179], v[208:211], v[78:81]
	v_mfma_f32_16x16x32_bf16 v[74:77], v[184:187], v[208:211], v[74:77]
	v_mfma_f32_16x16x32_bf16 v[66:69], v[184:187], v[216:219], v[66:69]
	v_mfma_f32_16x16x32_bf16 v[70:73], v[176:179], v[216:219], v[70:73]
	s_barrier
	s_add_i32 s77, s69, s54
	v_lshl_add_u64 v[150:151], s[48:49], 0, v[132:133]
	s_mov_b32 m0, s77
	ds_read_b128 v[188:191], v154 offset:16384
	ds_read_b128 v[192:195], v154 offset:17408
	ds_read_b128 v[196:199], v154 offset:18432
	ds_read_b128 v[200:203], v154 offset:19456
	ds_read_b128 v[204:207], v154 offset:20480
	ds_read_b128 v[208:211], v154 offset:21504
	ds_read_b128 v[212:215], v154 offset:22528
	ds_read_b128 v[216:219], v154 offset:23552
	global_load_lds_dwordx4 v[150:151], off
	s_add_i32 m0, s77, 0x2000
	s_add_u32 s78, s48, 0x40000
	v_lshl_add_u64 v[220:221], s[48:49], 0, v[136:137]
	s_addc_u32 s79, s49, 0
	s_add_i32 s77, s70, s54
	global_load_lds_dwordx4 v[220:221], off
	v_lshl_add_u64 v[222:223], s[78:79], 0, v[132:133]
	s_mov_b32 m0, s77
	v_lshl_add_u64 v[224:225], s[50:51], 0, v[134:135]
	global_load_lds_dwordx4 v[222:223], off
	v_lshl_add_u64 v[222:223], s[78:79], 0, v[136:137]
	s_add_i32 m0, s77, 0x2000
	s_nop 0
	global_load_lds_dwordx4 v[222:223], off
	v_lshl_add_u64 v[222:223], s[50:51], 0, v[130:131]
	s_mov_b32 m0, s15
	s_nop 0
	global_load_lds_dwordx4 v[222:223], off
	s_mov_b32 m0, s17
	s_nop 0
	global_load_lds_dwordx4 v[224:225], off
	s_waitcnt vmcnt(8)
	s_waitcnt lgkmcnt(0)
	s_barrier
	s_waitcnt lgkmcnt(0)
	v_mfma_f32_16x16x32_bf16 v[62:65], v[156:159], v[188:191], v[62:65]
	v_mfma_f32_16x16x32_bf16 v[58:61], v[164:167], v[188:191], v[58:61]
	v_mfma_f32_16x16x32_bf16 v[50:53], v[164:167], v[196:199], v[50:53]
	v_mfma_f32_16x16x32_bf16 v[54:57], v[156:159], v[196:199], v[54:57]
	v_mfma_f32_16x16x32_bf16 v[46:49], v[156:159], v[204:207], v[46:49]
	v_mfma_f32_16x16x32_bf16 v[42:45], v[164:167], v[204:207], v[42:45]
	v_mfma_f32_16x16x32_bf16 v[34:37], v[164:167], v[212:215], v[34:37]
	v_mfma_f32_16x16x32_bf16 v[38:41], v[156:159], v[212:215], v[38:41]
	v_mfma_f32_16x16x32_bf16 v[62:65], v[160:163], v[192:195], v[62:65]
	v_mfma_f32_16x16x32_bf16 v[58:61], v[168:171], v[192:195], v[58:61]
	v_mfma_f32_16x16x32_bf16 v[50:53], v[168:171], v[200:203], v[50:53]
	v_mfma_f32_16x16x32_bf16 v[54:57], v[160:163], v[200:203], v[54:57]
	v_mfma_f32_16x16x32_bf16 v[46:49], v[160:163], v[208:211], v[46:49]
	v_mfma_f32_16x16x32_bf16 v[42:45], v[168:171], v[208:211], v[42:45]
	v_mfma_f32_16x16x32_bf16 v[34:37], v[168:171], v[216:219], v[34:37]
	v_mfma_f32_16x16x32_bf16 v[38:41], v[160:163], v[216:219], v[38:41]
	v_mfma_f32_16x16x32_bf16 v[30:33], v[172:175], v[188:191], v[30:33]
	v_mfma_f32_16x16x32_bf16 v[26:29], v[180:183], v[188:191], v[26:29]
	v_mfma_f32_16x16x32_bf16 v[18:21], v[180:183], v[196:199], v[18:21]
	v_mfma_f32_16x16x32_bf16 v[22:25], v[172:175], v[196:199], v[22:25]
	v_mfma_f32_16x16x32_bf16 v[14:17], v[172:175], v[204:207], v[14:17]
	v_mfma_f32_16x16x32_bf16 v[10:13], v[180:183], v[204:207], v[10:13]
	v_mfma_f32_16x16x32_bf16 v[2:5], v[180:183], v[212:215], v[2:5]
	v_mfma_f32_16x16x32_bf16 v[6:9], v[172:175], v[212:215], v[6:9]
	v_mfma_f32_16x16x32_bf16 v[30:33], v[176:179], v[192:195], v[30:33]
	v_mfma_f32_16x16x32_bf16 v[26:29], v[184:187], v[192:195], v[26:29]
	v_mfma_f32_16x16x32_bf16 v[18:21], v[184:187], v[200:203], v[18:21]
	v_mfma_f32_16x16x32_bf16 v[22:25], v[176:179], v[200:203], v[22:25]
	v_mfma_f32_16x16x32_bf16 v[14:17], v[176:179], v[208:211], v[14:17]
	v_mfma_f32_16x16x32_bf16 v[10:13], v[184:187], v[208:211], v[10:13]
	v_mfma_f32_16x16x32_bf16 v[2:5], v[184:187], v[216:219], v[2:5]
	v_mfma_f32_16x16x32_bf16 v[6:9], v[176:179], v[216:219], v[6:9]
	s_barrier
; #define PG8_STAGEA(bufoff, gbase) PG8_STAGE_(bufoff, gbase, voffA)
; #define PG8_STAGEB(bufoff, gbase) PG8_STAGE_(bufoff, gbase, voffB)
; #define PG8_LDA(dst, b, h) do { _Pragma("unroll") for (int m = 0; m < 4; ++m) _Pragma("unroll") for (int k = 0; k < 2; ++k) dst[m][k] = *(const LAS bf16x8*)(lds + PG8_SA(b, h) + aoff + m * 2048 + k * 1024); } while (0)
; #define PG8_LDB(dst, b, h) do { _Pragma("unroll") for (int n = 0; n < 2; ++n) _Pragma("unroll") for (int k = 0; k < 2; ++k) dst[n][k] = *(const LAS bf16x8*)(lds + PG8_SB(b, h) + boff + n * 2048 + k * 1024); } while (0)
; #define PG8_MMA(ai, bj, At, Bt_) do { __builtin_amdgcn_s_setprio(1); _Pragma("unroll") for (int m = 0; m < 4; ++m) _Pragma("unroll") for (int n = 0; n < 2; ++n) _Pragma("unroll") for (int k = 0; k < 2; ++k) \
;         acc[ai][bj][m][n] = __builtin_amdgcn_mfma_f32_16x16x32_bf16(Bt_[n][k], At[m][k], acc[ai][bj][m][n], 0, 0, 0); __builtin_amdgcn_s_setprio(0); } while (0)
; #define PG8_WAIT_V(n) asm volatile("s_waitcnt vmcnt(" #n ")" ::: "memory")
; #define PG8_WAIT_L(n) asm volatile("s_waitcnt lgkmcnt(" #n ")" ::: "memory")
; #define PG8_BAR __builtin_amdgcn_s_barrier()
; #define PG8_SCHED __builtin_amdgcn_sched_barrier(0)
; template <int EK, int SK = -1>
; __device__ __forceinline__ void gemm_phase(LAS unsigned char* lds, const bf16_t* A, const bf16_t* Bt, int nM, int N, int K, const EpiArgs& E) {
;     ...
;             PG8_LDB(B0, 1, 0); PG8_LDB(B1, 1, 1); PG8_SCHED; PG8_LDA(At, 1, 0); PG8_STAGEA(PG8_SA(0, 1), a2 + hstep);
;             PG8_WAIT_V(8); PG8_WAIT_L(0); PG8_BAR; PG8_MMA(0, 0, At, B0); PG8_MMA(0, 1, At, B1); PG8_BAR; PG8_SCHED;
;             PG8_LDA(At, 1, 1); PG8_STAGEB(PG8_SB(1, 0), b3); PG8_STAGEB(PG8_SB(1, 1), b3 + hstep); PG8_STAGEA(PG8_SA(1, 0), a3);
;             PG8_WAIT_V(8); PG8_WAIT_L(0); PG8_BAR; PG8_MMA(1, 0, At, B0); PG8_MMA(1, 1, At, B1); PG8_BAR; PG8_SCHED;
;         }
	s_add_i32 s77, 0, 0x18000
	s_add_i32 s78, 0, 0x1c000
	v_add_u32_e32 v168, s77, v152
	v_add_u32_e32 v184, s78, v152
	ds_read_b128 v[156:159], v168
	ds_read_b128 v[160:163], v168 offset:1024
	ds_read_b128 v[164:167], v168 offset:2048
	ds_read_b128 v[168:171], v168 offset:3072
	ds_read_b128 v[172:175], v184
	ds_read_b128 v[176:179], v184 offset:1024
	ds_read_b128 v[180:183], v184 offset:2048
	ds_read_b128 v[184:187], v184 offset:3072
	s_add_u32 s50, s50, 0x40000
	s_addc_u32 s51, s51, 0
	s_mov_b32 m0, s55
	v_lshl_add_u64 v[226:227], s[50:51], 0, v[130:131]
	ds_read_b128 v[188:191], v154 offset:32768
	ds_read_b128 v[192:195], v154 offset:33792
	ds_read_b128 v[196:199], v154 offset:34816
	ds_read_b128 v[200:203], v154 offset:35840
	ds_read_b128 v[204:207], v154 offset:36864
	ds_read_b128 v[208:211], v154 offset:37888
	ds_read_b128 v[212:215], v154 offset:38912
	ds_read_b128 v[216:219], v154 offset:39936
	global_load_lds_dwordx4 v[226:227], off
	v_lshl_add_u64 v[226:227], s[50:51], 0, v[134:135]
	s_mov_b32 m0, s56
	s_nop 0
	global_load_lds_dwordx4 v[226:227], off
	s_waitcnt vmcnt(8)
	s_waitcnt lgkmcnt(0)
	s_barrier
	s_waitcnt lgkmcnt(0)
	v_mfma_f32_16x16x32_bf16 v[126:129], v[156:159], v[188:191], v[126:129]
	v_mfma_f32_16x16x32_bf16 v[122:125], v[164:167], v[188:191], v[122:125]
	v_mfma_f32_16x16x32_bf16 v[114:117], v[164:167], v[196:199], v[114:117]
	v_mfma_f32_16x16x32_bf16 v[118:121], v[156:159], v[196:199], v[118:121]
	v_mfma_f32_16x16x32_bf16 v[110:113], v[156:159], v[204:207], v[110:113]
	v_mfma_f32_16x16x32_bf16 v[106:109], v[164:167], v[204:207], v[106:109]
	v_mfma_f32_16x16x32_bf16 v[98:101], v[164:167], v[212:215], v[98:101]
	v_mfma_f32_16x16x32_bf16 v[102:105], v[156:159], v[212:215], v[102:105]
	v_mfma_f32_16x16x32_bf16 v[126:129], v[160:163], v[192:195], v[126:129]
	v_mfma_f32_16x16x32_bf16 v[122:125], v[168:171], v[192:195], v[122:125]
	v_mfma_f32_16x16x32_bf16 v[114:117], v[168:171], v[200:203], v[114:117]
	v_mfma_f32_16x16x32_bf16 v[118:121], v[160:163], v[200:203], v[118:121]
	v_mfma_f32_16x16x32_bf16 v[110:113], v[160:163], v[208:211], v[110:113]
	v_mfma_f32_16x16x32_bf16 v[106:109], v[168:171], v[208:211], v[106:109]
	v_mfma_f32_16x16x32_bf16 v[98:101], v[168:171], v[216:219], v[98:101]
	v_mfma_f32_16x16x32_bf16 v[102:105], v[160:163], v[216:219], v[102:105]
	v_mfma_f32_16x16x32_bf16 v[94:97], v[172:175], v[188:191], v[94:97]
	v_mfma_f32_16x16x32_bf16 v[90:93], v[180:183], v[188:191], v[90:93]
	v_mfma_f32_16x16x32_bf16 v[82:85], v[180:183], v[196:199], v[82:85]
	v_mfma_f32_16x16x32_bf16 v[86:89], v[172:175], v[196:199], v[86:89]
	v_mfma_f32_16x16x32_bf16 v[78:81], v[172:175], v[204:207], v[78:81]
	v_mfma_f32_16x16x32_bf16 v[74:77], v[180:183], v[204:207], v[74:77]
	v_mfma_f32_16x16x32_bf16 v[66:69], v[180:183], v[212:215], v[66:69]
	v_mfma_f32_16x16x32_bf16 v[70:73], v[172:175], v[212:215], v[70:73]
	v_mfma_f32_16x16x32_bf16 v[94:97], v[176:179], v[192:195], v[94:97]
	v_mfma_f32_16x16x32_bf16 v[90:93], v[184:187], v[192:195], v[90:93]
	v_mfma_f32_16x16x32_bf16 v[82:85], v[184:187], v[200:203], v[82:85]
	v_mfma_f32_16x16x32_bf16 v[86:89], v[176:179], v[200:203], v[86:89]
	v_mfma_f32_16x16x32_bf16 v[78:81], v[176:179], v[208:211], v[78:81]
	v_mfma_f32_16x16x32_bf16 v[74:77], v[184:187], v[208:211], v[74:77]
	v_mfma_f32_16x16x32_bf16 v[66:69], v[184:187], v[216:219], v[66:69]
	v_mfma_f32_16x16x32_bf16 v[70:73], v[176:179], v[216:219], v[70:73]
	s_barrier
	s_add_i32 s50, s77, s54
	v_lshl_add_u64 v[150:151], v[150:151], 0, s[26:27]
	s_mov_b32 m0, s50
	ds_read_b128 v[188:191], v154 offset:49152
	ds_read_b128 v[192:195], v154 offset:50176
	ds_read_b128 v[196:199], v154 offset:51200
	ds_read_b128 v[200:203], v154 offset:52224
	ds_read_b128 v[204:207], v154 offset:53248
	ds_read_b128 v[208:211], v154 offset:54272
	ds_read_b128 v[212:215], v154 offset:55296
	ds_read_b128 v[216:219], v154 offset:56320
	global_load_lds_dwordx4 v[150:151], off
	s_add_i32 m0, s50, 0x2000
	s_add_u32 s48, s48, 0x40080
	v_lshl_add_u64 v[150:151], v[220:221], 0, s[26:27]
	s_addc_u32 s49, s49, 0
	s_add_i32 s50, s78, s54
	global_load_lds_dwordx4 v[150:151], off
	v_lshl_add_u64 v[150:151], s[48:49], 0, v[132:133]
	s_mov_b32 m0, s50
	s_nop 0
	global_load_lds_dwordx4 v[150:151], off
	v_lshl_add_u64 v[150:151], s[48:49], 0, v[136:137]
	s_add_i32 m0, s50, 0x2000
	s_nop 0
	global_load_lds_dwordx4 v[150:151], off
	v_lshl_add_u64 v[150:151], v[222:223], 0, s[26:27]
	s_mov_b32 m0, s59
	s_nop 0
	global_load_lds_dwordx4 v[150:151], off
	v_lshl_add_u64 v[150:151], v[224:225], 0, s[26:27]
	s_mov_b32 m0, s68
	s_nop 0
	global_load_lds_dwordx4 v[150:151], off
	s_waitcnt vmcnt(8)
	s_waitcnt lgkmcnt(0)
	s_barrier
	s_waitcnt lgkmcnt(0)
	v_mfma_f32_16x16x32_bf16 v[62:65], v[156:159], v[188:191], v[62:65]
	v_mfma_f32_16x16x32_bf16 v[58:61], v[164:167], v[188:191], v[58:61]
	v_mfma_f32_16x16x32_bf16 v[50:53], v[164:167], v[196:199], v[50:53]
	v_mfma_f32_16x16x32_bf16 v[54:57], v[156:159], v[196:199], v[54:57]
	v_mfma_f32_16x16x32_bf16 v[46:49], v[156:159], v[204:207], v[46:49]
	v_mfma_f32_16x16x32_bf16 v[42:45], v[164:167], v[204:207], v[42:45]
	v_mfma_f32_16x16x32_bf16 v[34:37], v[164:167], v[212:215], v[34:37]
	v_mfma_f32_16x16x32_bf16 v[38:41], v[156:159], v[212:215], v[38:41]
	v_mfma_f32_16x16x32_bf16 v[62:65], v[160:163], v[192:195], v[62:65]
	v_mfma_f32_16x16x32_bf16 v[58:61], v[168:171], v[192:195], v[58:61]
	v_mfma_f32_16x16x32_bf16 v[50:53], v[168:171], v[200:203], v[50:53]
	v_mfma_f32_16x16x32_bf16 v[54:57], v[160:163], v[200:203], v[54:57]
	v_mfma_f32_16x16x32_bf16 v[46:49], v[160:163], v[208:211], v[46:49]
	v_mfma_f32_16x16x32_bf16 v[42:45], v[168:171], v[208:211], v[42:45]
	v_mfma_f32_16x16x32_bf16 v[34:37], v[168:171], v[216:219], v[34:37]
	v_mfma_f32_16x16x32_bf16 v[38:41], v[160:163], v[216:219], v[38:41]
	v_mfma_f32_16x16x32_bf16 v[30:33], v[172:175], v[188:191], v[30:33]
	v_mfma_f32_16x16x32_bf16 v[26:29], v[180:183], v[188:191], v[26:29]
	v_mfma_f32_16x16x32_bf16 v[18:21], v[180:183], v[196:199], v[18:21]
	v_mfma_f32_16x16x32_bf16 v[22:25], v[172:175], v[196:199], v[22:25]
	v_mfma_f32_16x16x32_bf16 v[14:17], v[172:175], v[204:207], v[14:17]
	v_mfma_f32_16x16x32_bf16 v[10:13], v[180:183], v[204:207], v[10:13]
	v_mfma_f32_16x16x32_bf16 v[2:5], v[180:183], v[212:215], v[2:5]
	v_mfma_f32_16x16x32_bf16 v[6:9], v[172:175], v[212:215], v[6:9]
	v_mfma_f32_16x16x32_bf16 v[30:33], v[176:179], v[192:195], v[30:33]
	v_mfma_f32_16x16x32_bf16 v[26:29], v[184:187], v[192:195], v[26:29]
	v_mfma_f32_16x16x32_bf16 v[18:21], v[184:187], v[200:203], v[18:21]
	v_mfma_f32_16x16x32_bf16 v[22:25], v[176:179], v[200:203], v[22:25]
	v_mfma_f32_16x16x32_bf16 v[14:17], v[176:179], v[208:211], v[14:17]
	v_mfma_f32_16x16x32_bf16 v[10:13], v[184:187], v[208:211], v[10:13]
	v_mfma_f32_16x16x32_bf16 v[2:5], v[184:187], v[216:219], v[2:5]
	v_mfma_f32_16x16x32_bf16 v[6:9], v[176:179], v[216:219], v[6:9]
	s_barrier
	s_add_i32 s76, s76, 2
	s_add_u32 s46, s46, 0x100
	s_addc_u32 s47, s47, 0
	s_cmp_gt_u32 s76, 13
	s_cbranch_scc0 .LBB0_1120

; #define PG8_STAGEA(bufoff, gbase) PG8_STAGE_(bufoff, gbase, voffA)
; #define PG8_STAGEB(bufoff, gbase) PG8_STAGE_(bufoff, gbase, voffB)
; #define PG8_LDA(dst, b, h) do { _Pragma("unroll") for (int m = 0; m < 4; ++m) _Pragma("unroll") for (int k = 0; k < 2; ++k) dst[m][k] = *(const LAS bf16x8*)(lds + PG8_SA(b, h) + aoff + m * 2048 + k * 1024); } while (0)
; #define PG8_LDB(dst, b, h) do { _Pragma("unroll") for (int n = 0; n < 2; ++n) _Pragma("unroll") for (int k = 0; k < 2; ++k) dst[n][k] = *(const LAS bf16x8*)(lds + PG8_SB(b, h) + boff + n * 2048 + k * 1024); } while (0)
; #define PG8_MMA(ai, bj, At, Bt_) do { __builtin_amdgcn_s_setprio(1); _Pragma("unroll") for (int m = 0; m < 4; ++m) _Pragma("unroll") for (int n = 0; n < 2; ++n) _Pragma("unroll") for (int k = 0; k < 2; ++k) \
;         acc[ai][bj][m][n] = __builtin_amdgcn_mfma_f32_16x16x32_bf16(Bt_[n][k], At[m][k], acc[ai][bj][m][n], 0, 0, 0); __builtin_amdgcn_s_setprio(0); } while (0)
; #define PG8_WAIT_V(n) asm volatile("s_waitcnt vmcnt(" #n ")" ::: "memory")
; #define PG8_WAIT_L(n) asm volatile("s_waitcnt lgkmcnt(" #n ")" ::: "memory")
; #define PG8_BAR __builtin_amdgcn_s_barrier()
; template <int EK, int SK = -1>
; __device__ __forceinline__ void gemm_phase(LAS unsigned char* lds, const bf16_t* A, const bf16_t* Bt, int nM, int N, int K, const EpiArgs& E) {
;     ...
;         const bool has_next = S.next(ui + 1, nxt);
;         const char* nA = has_next ? (const char*)A + (size_t)nxt.pm * tstep : cA; const char* nB = has_next ? (const char*)Bt + (size_t)nxt.pn * tstep : cB;
;         for (int t = 0; t < nt; t += 2) {
;             const bool last = (t == nt - 2);
;             const char* a1 = cA + (size_t)(t + 1) * kstep;
;             const char* a2 = last ? nA : cA + (size_t)(t + 2) * kstep; const char* b2 = last ? nB : cB + (size_t)(t + 2) * kstep;
;             const char* a3 = a2 + kstep; const char* b3 = b2 + kstep;
;             PG8_LDB(B0, 0, 0); PG8_LDB(B1, 0, 1); PG8_SCHED; PG8_LDA(At, 0, 0); PG8_STAGEA(PG8_SA(1, 1), a1 + hstep);
;             PG8_WAIT_V(8); PG8_WAIT_L(0); PG8_BAR; PG8_MMA(0, 0, At, B0); PG8_MMA(0, 1, At, B1); PG8_BAR; PG8_SCHED;
;             PG8_LDA(At, 0, 1); PG8_STAGEB(PG8_SB(0, 0), b2); PG8_STAGEB(PG8_SB(0, 1), b2 + hstep); PG8_STAGEA(PG8_SA(0, 0), a2);
;             PG8_WAIT_V(8); PG8_WAIT_L(0); PG8_BAR; PG8_MMA(1, 0, At, B0); PG8_MMA(1, 1, At, B1); PG8_BAR; PG8_SCHED;
.LBB0_1244:
	s_add_u32 s59, s40, 0x100
	s_addc_u32 s66, s41, 0
	s_ashr_i32 s27, s26, 31
	s_lshl_b64 s[36:37], s[26:27], 19
	s_add_u32 s38, s62, s36
	s_addc_u32 s39, s63, s37
	s_and_b64 s[36:37], s[6:7], exec
	s_cselect_b32 s27, s39, s21
	s_cselect_b32 s67, s38, s20
	s_ashr_i32 s23, s22, 31
	s_lshl_b64 s[36:37], s[22:23], 19
	s_add_u32 s36, s47, s36
	s_addc_u32 s37, s48, s37
	s_and_b64 s[42:43], s[6:7], exec
	s_cselect_b32 s23, s37, s41
	s_cselect_b32 s68, s36, s40
	v_lshl_add_u64 v[146:147], s[20:21], 0, v[138:139]
	v_lshl_add_u64 v[148:149], s[20:21], 0, v[140:141]
	s_mov_b32 s69, -2
	s_mov_b64 s[40:41], 0
	v_add_u32_e32 v154, s54, v156
	ds_read_b128 v[150:153], v154
	ds_read_b128 v[160:163], v154 offset:1024
	ds_read_b128 v[164:167], v154 offset:2048
	ds_read_b128 v[168:171], v154 offset:3072
	v_add_u32_e32 v154, s55, v156
	s_add_u32 s42, s20, s40
	ds_read_b128 v[172:175], v154
	ds_read_b128 v[176:179], v154 offset:1024
	ds_read_b128 v[180:183], v154 offset:2048
	ds_read_b128 v[184:187], v154 offset:3072
	s_addc_u32 s43, s21, s41
	s_add_u32 s42, s42, 0x100
	s_addc_u32 s43, s43, 0
	s_add_u32 s70, s59, s40
	s_addc_u32 s71, s66, s41
	s_cmpk_eq_i32 s40, 0x700
	s_cselect_b32 s45, s27, s43
	s_cselect_b32 s44, s67, s42
	s_cselect_b32 s43, s23, s71
	s_cselect_b32 s42, s68, s70
	v_lshl_add_u64 v[154:155], v[146:147], 0, s[40:41]
	s_add_i32 m0, s17, 0xc000
	ds_read_b128 v[188:191], v159
	ds_read_b128 v[192:195], v159 offset:1024
	ds_read_b128 v[196:199], v159 offset:2048
	ds_read_b128 v[200:203], v159 offset:3072
	ds_read_b128 v[204:207], v159 offset:4096
	ds_read_b128 v[208:211], v159 offset:5120
	ds_read_b128 v[212:215], v159 offset:6144
	ds_read_b128 v[216:219], v159 offset:7168
	global_load_lds_dwordx4 v[154:155], off
	v_lshl_add_u64 v[154:155], v[148:149], 0, s[40:41]
	s_add_i32 m0, s17, 0xe000
	s_nop 0
	global_load_lds_dwordx4 v[154:155], off
	s_waitcnt vmcnt(8)
	s_waitcnt lgkmcnt(0)
	s_barrier
	s_waitcnt lgkmcnt(0)
	v_mfma_f32_16x16x32_bf16 v[110:113], v[150:153], v[188:191], 0
	v_mfma_f32_16x16x32_bf16 v[106:109], v[164:167], v[188:191], 0
	v_mfma_f32_16x16x32_bf16 v[98:101], v[164:167], v[196:199], 0
	v_mfma_f32_16x16x32_bf16 v[102:105], v[150:153], v[196:199], 0
	v_mfma_f32_16x16x32_bf16 v[94:97], v[150:153], v[204:207], 0
	v_mfma_f32_16x16x32_bf16 v[90:93], v[164:167], v[204:207], 0
	v_mfma_f32_16x16x32_bf16 v[82:85], v[164:167], v[212:215], 0
	v_mfma_f32_16x16x32_bf16 v[86:89], v[150:153], v[212:215], 0
	v_mfma_f32_16x16x32_bf16 v[110:113], v[160:163], v[192:195], v[110:113]
	v_mfma_f32_16x16x32_bf16 v[106:109], v[168:171], v[192:195], v[106:109]
	v_mfma_f32_16x16x32_bf16 v[98:101], v[168:171], v[200:203], v[98:101]
	v_mfma_f32_16x16x32_bf16 v[102:105], v[160:163], v[200:203], v[102:105]
	v_mfma_f32_16x16x32_bf16 v[94:97], v[160:163], v[208:211], v[94:97]
	v_mfma_f32_16x16x32_bf16 v[90:93], v[168:171], v[208:211], v[90:93]
	v_mfma_f32_16x16x32_bf16 v[82:85], v[168:171], v[216:219], v[82:85]
	v_mfma_f32_16x16x32_bf16 v[86:89], v[160:163], v[216:219], v[86:89]
	v_mfma_f32_16x16x32_bf16 v[78:81], v[172:175], v[188:191], 0
	v_mfma_f32_16x16x32_bf16 v[74:77], v[180:183], v[188:191], 0
	v_mfma_f32_16x16x32_bf16 v[66:69], v[180:183], v[196:199], 0
	v_mfma_f32_16x16x32_bf16 v[70:73], v[172:175], v[196:199], 0
	v_mfma_f32_16x16x32_bf16 v[62:65], v[172:175], v[204:207], 0
	v_mfma_f32_16x16x32_bf16 v[58:61], v[180:183], v[204:207], 0
	v_mfma_f32_16x16x32_bf16 v[50:53], v[180:183], v[212:215], 0
	v_mfma_f32_16x16x32_bf16 v[54:57], v[172:175], v[212:215], 0
	v_mfma_f32_16x16x32_bf16 v[78:81], v[176:179], v[192:195], v[78:81]
	v_mfma_f32_16x16x32_bf16 v[74:77], v[184:187], v[192:195], v[74:77]
	v_mfma_f32_16x16x32_bf16 v[66:69], v[184:187], v[200:203], v[66:69]
	v_mfma_f32_16x16x32_bf16 v[70:73], v[176:179], v[200:203], v[70:73]
	v_mfma_f32_16x16x32_bf16 v[62:65], v[176:179], v[208:211], v[62:65]
	v_mfma_f32_16x16x32_bf16 v[58:61], v[184:187], v[208:211], v[58:61]
	v_mfma_f32_16x16x32_bf16 v[50:53], v[184:187], v[216:219], v[50:53]
	v_mfma_f32_16x16x32_bf16 v[54:57], v[176:179], v[216:219], v[54:57]
	s_barrier
	s_add_i32 s70, s54, s49
	v_lshl_add_u64 v[154:155], s[42:43], 0, v[132:133]
	s_mov_b32 m0, s70
	ds_read_b128 v[188:191], v159 offset:16384
	ds_read_b128 v[192:195], v159 offset:17408
	ds_read_b128 v[196:199], v159 offset:18432
	ds_read_b128 v[200:203], v159 offset:19456
	ds_read_b128 v[204:207], v159 offset:20480
	ds_read_b128 v[208:211], v159 offset:21504
	ds_read_b128 v[212:215], v159 offset:22528
	ds_read_b128 v[216:219], v159 offset:23552
	global_load_lds_dwordx4 v[154:155], off
	s_add_i32 m0, s70, 0x2000
	s_add_u32 s70, s42, 0x40000
	v_lshl_add_u64 v[220:221], s[42:43], 0, v[136:137]
	s_addc_u32 s71, s43, 0
	s_add_i32 s72, s55, s49
	global_load_lds_dwordx4 v[220:221], off
	v_lshl_add_u64 v[222:223], s[70:71], 0, v[132:133]
	s_mov_b32 m0, s72
	v_lshl_add_u64 v[224:225], s[44:45], 0, v[134:135]
	global_load_lds_dwordx4 v[222:223], off
	v_lshl_add_u64 v[222:223], s[70:71], 0, v[136:137]
	s_add_i32 m0, s72, 0x2000
	s_nop 0
	global_load_lds_dwordx4 v[222:223], off
	v_lshl_add_u64 v[222:223], s[44:45], 0, v[130:131]
	s_mov_b32 m0, s17
	s_nop 0
	global_load_lds_dwordx4 v[222:223], off
	s_mov_b32 m0, s19
	s_nop 0
	global_load_lds_dwordx4 v[224:225], off
	s_waitcnt vmcnt(8)
	s_waitcnt lgkmcnt(0)
	s_barrier
; #define PG8_STAGEA(bufoff, gbase) PG8_STAGE_(bufoff, gbase, voffA)
; #define PG8_LDA(dst, b, h) do { _Pragma("unroll") for (int m = 0; m < 4; ++m) _Pragma("unroll") for (int k = 0; k < 2; ++k) dst[m][k] = *(const LAS bf16x8*)(lds + PG8_SA(b, h) + aoff + m * 2048 + k * 1024); } while (0)
; #define PG8_LDB(dst, b, h) do { _Pragma("unroll") for (int n = 0; n < 2; ++n) _Pragma("unroll") for (int k = 0; k < 2; ++k) dst[n][k] = *(const LAS bf16x8*)(lds + PG8_SB(b, h) + boff + n * 2048 + k * 1024); } while (0)
; #define PG8_MMA(ai, bj, At, Bt_) do { __builtin_amdgcn_s_setprio(1); _Pragma("unroll") for (int m = 0; m < 4; ++m) _Pragma("unroll") for (int n = 0; n < 2; ++n) _Pragma("unroll") for (int k = 0; k < 2; ++k) \
;         acc[ai][bj][m][n] = __builtin_amdgcn_mfma_f32_16x16x32_bf16(Bt_[n][k], At[m][k], acc[ai][bj][m][n], 0, 0, 0); __builtin_amdgcn_s_setprio(0); } while (0)
; #define PG8_WAIT_V(n) asm volatile("s_waitcnt vmcnt(" #n ")" ::: "memory")
; #define PG8_WAIT_L(n) asm volatile("s_waitcnt lgkmcnt(" #n ")" ::: "memory")
; #define PG8_BAR __builtin_amdgcn_s_barrier()
; #define PG8_SCHED __builtin_amdgcn_sched_barrier(0)
; template <int EK, int SK = -1>
; __device__ __forceinline__ void gemm_phase(LAS unsigned char* lds, const bf16_t* A, const bf16_t* Bt, int nM, int N, int K, const EpiArgs& E) {
;     ...
;             PG8_WAIT_V(8); PG8_WAIT_L(0); PG8_BAR; PG8_MMA(1, 0, At, B0); PG8_MMA(1, 1, At, B1); PG8_BAR; PG8_SCHED;
;             PG8_LDB(B0, 1, 0); PG8_LDB(B1, 1, 1); PG8_SCHED; PG8_LDA(At, 1, 0); PG8_STAGEA(PG8_SA(0, 1), a2 + hstep);
;             PG8_WAIT_V(8); PG8_WAIT_L(0); PG8_BAR; PG8_MMA(0, 0, At, B0); PG8_MMA(0, 1, At, B1); PG8_BAR; PG8_SCHED;
	s_waitcnt lgkmcnt(0)
	v_mfma_f32_16x16x32_bf16 v[46:49], v[150:153], v[188:191], 0
	v_mfma_f32_16x16x32_bf16 v[42:45], v[164:167], v[188:191], 0
	v_mfma_f32_16x16x32_bf16 v[34:37], v[164:167], v[196:199], 0
	v_mfma_f32_16x16x32_bf16 v[38:41], v[150:153], v[196:199], 0
	v_mfma_f32_16x16x32_bf16 v[30:33], v[150:153], v[204:207], 0
	v_mfma_f32_16x16x32_bf16 v[26:29], v[164:167], v[204:207], 0
	v_mfma_f32_16x16x32_bf16 v[18:21], v[164:167], v[212:215], 0
	v_mfma_f32_16x16x32_bf16 v[22:25], v[150:153], v[212:215], 0
	v_mfma_f32_16x16x32_bf16 v[46:49], v[160:163], v[192:195], v[46:49]
	v_mfma_f32_16x16x32_bf16 v[42:45], v[168:171], v[192:195], v[42:45]
	v_mfma_f32_16x16x32_bf16 v[34:37], v[168:171], v[200:203], v[34:37]
	v_mfma_f32_16x16x32_bf16 v[38:41], v[160:163], v[200:203], v[38:41]
	v_mfma_f32_16x16x32_bf16 v[30:33], v[160:163], v[208:211], v[30:33]
	v_mfma_f32_16x16x32_bf16 v[26:29], v[168:171], v[208:211], v[26:29]
	v_mfma_f32_16x16x32_bf16 v[18:21], v[168:171], v[216:219], v[18:21]
	v_mfma_f32_16x16x32_bf16 v[22:25], v[160:163], v[216:219], v[22:25]
	v_mfma_f32_16x16x32_bf16 v[14:17], v[172:175], v[188:191], 0
	v_mfma_f32_16x16x32_bf16 v[10:13], v[180:183], v[188:191], 0
	v_mfma_f32_16x16x32_bf16 v[2:5], v[180:183], v[196:199], 0
	v_mfma_f32_16x16x32_bf16 v[6:9], v[172:175], v[196:199], 0
	v_mfma_f32_16x16x32_bf16 v[114:117], v[172:175], v[204:207], 0
	v_mfma_f32_16x16x32_bf16 v[118:121], v[180:183], v[204:207], 0
	v_mfma_f32_16x16x32_bf16 v[126:129], v[180:183], v[212:215], 0
	v_mfma_f32_16x16x32_bf16 v[122:125], v[172:175], v[212:215], 0
	v_mfma_f32_16x16x32_bf16 v[14:17], v[176:179], v[192:195], v[14:17]
	v_mfma_f32_16x16x32_bf16 v[10:13], v[184:187], v[192:195], v[10:13]
	v_mfma_f32_16x16x32_bf16 v[2:5], v[184:187], v[200:203], v[2:5]
	v_mfma_f32_16x16x32_bf16 v[6:9], v[176:179], v[200:203], v[6:9]
	v_mfma_f32_16x16x32_bf16 v[114:117], v[176:179], v[208:211], v[114:117]
	v_mfma_f32_16x16x32_bf16 v[118:121], v[184:187], v[208:211], v[118:121]
	v_mfma_f32_16x16x32_bf16 v[126:129], v[184:187], v[216:219], v[126:129]
	v_mfma_f32_16x16x32_bf16 v[122:125], v[176:179], v[216:219], v[122:125]
	s_barrier
	s_add_i32 s70, 0, 0x18000
	s_add_i32 s71, 0, 0x1c000
	v_add_u32_e32 v168, s70, v156
	v_add_u32_e32 v184, s71, v156
	ds_read_b128 v[150:153], v168
	ds_read_b128 v[160:163], v168 offset:1024
	ds_read_b128 v[164:167], v168 offset:2048
	ds_read_b128 v[168:171], v168 offset:3072
	ds_read_b128 v[172:175], v184
	ds_read_b128 v[176:179], v184 offset:1024
	ds_read_b128 v[180:183], v184 offset:2048
	ds_read_b128 v[184:187], v184 offset:3072
	s_add_u32 s44, s44, 0x40000
	s_addc_u32 s45, s45, 0
	s_mov_b32 m0, s50
	v_lshl_add_u64 v[226:227], s[44:45], 0, v[130:131]
	ds_read_b128 v[188:191], v159 offset:32768
	ds_read_b128 v[192:195], v159 offset:33792
	ds_read_b128 v[196:199], v159 offset:34816
	ds_read_b128 v[200:203], v159 offset:35840
	ds_read_b128 v[204:207], v159 offset:36864
	ds_read_b128 v[208:211], v159 offset:37888
	ds_read_b128 v[212:215], v159 offset:38912
	ds_read_b128 v[216:219], v159 offset:39936
	global_load_lds_dwordx4 v[226:227], off
	v_lshl_add_u64 v[226:227], s[44:45], 0, v[134:135]
	s_mov_b32 m0, s51
	s_nop 0
	global_load_lds_dwordx4 v[226:227], off
	s_waitcnt vmcnt(8)
	s_waitcnt lgkmcnt(0)
	s_barrier
	s_waitcnt lgkmcnt(0)
	v_mfma_f32_16x16x32_bf16 v[110:113], v[150:153], v[188:191], v[110:113]
	v_mfma_f32_16x16x32_bf16 v[106:109], v[164:167], v[188:191], v[106:109]
	v_mfma_f32_16x16x32_bf16 v[98:101], v[164:167], v[196:199], v[98:101]
	v_mfma_f32_16x16x32_bf16 v[102:105], v[150:153], v[196:199], v[102:105]
	v_mfma_f32_16x16x32_bf16 v[94:97], v[150:153], v[204:207], v[94:97]
	v_mfma_f32_16x16x32_bf16 v[90:93], v[164:167], v[204:207], v[90:93]
	v_mfma_f32_16x16x32_bf16 v[82:85], v[164:167], v[212:215], v[82:85]
	v_mfma_f32_16x16x32_bf16 v[86:89], v[150:153], v[212:215], v[86:89]
	v_mfma_f32_16x16x32_bf16 v[110:113], v[160:163], v[192:195], v[110:113]
	v_mfma_f32_16x16x32_bf16 v[106:109], v[168:171], v[192:195], v[106:109]
	v_mfma_f32_16x16x32_bf16 v[98:101], v[168:171], v[200:203], v[98:101]
	v_mfma_f32_16x16x32_bf16 v[102:105], v[160:163], v[200:203], v[102:105]
	v_mfma_f32_16x16x32_bf16 v[94:97], v[160:163], v[208:211], v[94:97]
	v_mfma_f32_16x16x32_bf16 v[90:93], v[168:171], v[208:211], v[90:93]
	v_mfma_f32_16x16x32_bf16 v[82:85], v[168:171], v[216:219], v[82:85]
	v_mfma_f32_16x16x32_bf16 v[86:89], v[160:163], v[216:219], v[86:89]
	v_mfma_f32_16x16x32_bf16 v[78:81], v[172:175], v[188:191], v[78:81]
	v_mfma_f32_16x16x32_bf16 v[74:77], v[180:183], v[188:191], v[74:77]
	v_mfma_f32_16x16x32_bf16 v[66:69], v[180:183], v[196:199], v[66:69]
	v_mfma_f32_16x16x32_bf16 v[70:73], v[172:175], v[196:199], v[70:73]
	v_mfma_f32_16x16x32_bf16 v[62:65], v[172:175], v[204:207], v[62:65]
	v_mfma_f32_16x16x32_bf16 v[58:61], v[180:183], v[204:207], v[58:61]
	v_mfma_f32_16x16x32_bf16 v[50:53], v[180:183], v[212:215], v[50:53]
	v_mfma_f32_16x16x32_bf16 v[54:57], v[172:175], v[212:215], v[54:57]
	v_mfma_f32_16x16x32_bf16 v[78:81], v[176:179], v[192:195], v[78:81]
	v_mfma_f32_16x16x32_bf16 v[74:77], v[184:187], v[192:195], v[74:77]
	v_mfma_f32_16x16x32_bf16 v[66:69], v[184:187], v[200:203], v[66:69]
	v_mfma_f32_16x16x32_bf16 v[70:73], v[176:179], v[200:203], v[70:73]
	v_mfma_f32_16x16x32_bf16 v[62:65], v[176:179], v[208:211], v[62:65]
	v_mfma_f32_16x16x32_bf16 v[58:61], v[184:187], v[208:211], v[58:61]
	v_mfma_f32_16x16x32_bf16 v[50:53], v[184:187], v[216:219], v[50:53]
	v_mfma_f32_16x16x32_bf16 v[54:57], v[176:179], v[216:219], v[54:57]
	s_barrier
; #define PG8_STAGEA(bufoff, gbase) PG8_STAGE_(bufoff, gbase, voffA)
; #define PG8_STAGEB(bufoff, gbase) PG8_STAGE_(bufoff, gbase, voffB)
; #define PG8_LDA(dst, b, h) do { _Pragma("unroll") for (int m = 0; m < 4; ++m) _Pragma("unroll") for (int k = 0; k < 2; ++k) dst[m][k] = *(const LAS bf16x8*)(lds + PG8_SA(b, h) + aoff + m * 2048 + k * 1024); } while (0)
; #define PG8_LDB(dst, b, h) do { _Pragma("unroll") for (int n = 0; n < 2; ++n) _Pragma("unroll") for (int k = 0; k < 2; ++k) dst[n][k] = *(const LAS bf16x8*)(lds + PG8_SB(b, h) + boff + n * 2048 + k * 1024); } while (0)
; #define PG8_WAIT_V(n) asm volatile("s_waitcnt vmcnt(" #n ")" ::: "memory")
; #define PG8_WAIT_L(n) asm volatile("s_waitcnt lgkmcnt(" #n ")" ::: "memory")
; #define PG8_BAR __builtin_amdgcn_s_barrier()
; #define PG8_SCHED __builtin_amdgcn_sched_barrier(0)
; template <int EK, int SK = -1>
; __device__ __forceinline__ void gemm_phase(LAS unsigned char* lds, const bf16_t* A, const bf16_t* Bt, int nM, int N, int K, const EpiArgs& E) {
;     ...
;         for (int t = 0; t < nt; t += 2) {
;             const bool last = (t == nt - 2);
;             const char* a1 = cA + (size_t)(t + 1) * kstep;
;             const char* a2 = last ? nA : cA + (size_t)(t + 2) * kstep; const char* b2 = last ? nB : cB + (size_t)(t + 2) * kstep;
;             const char* a3 = a2 + kstep; const char* b3 = b2 + kstep;
;             PG8_LDB(B0, 0, 0); PG8_LDB(B1, 0, 1); PG8_SCHED; PG8_LDA(At, 0, 0); PG8_STAGEA(PG8_SA(1, 1), a1 + hstep);
;             PG8_WAIT_V(8); PG8_WAIT_L(0); PG8_BAR; PG8_MMA(0, 0, At, B0); PG8_MMA(0, 1, At, B1); PG8_BAR; PG8_SCHED;
;             PG8_LDA(At, 0, 1); PG8_STAGEB(PG8_SB(0, 0), b2); PG8_STAGEB(PG8_SB(0, 1), b2 + hstep); PG8_STAGEA(PG8_SA(0, 0), a2);
;             PG8_WAIT_V(8); PG8_WAIT_L(0); PG8_BAR; PG8_MMA(1, 0, At, B0); PG8_MMA(1, 1, At, B1); PG8_BAR; PG8_SCHED;
;             PG8_LDB(B0, 1, 0); PG8_LDB(B1, 1, 1); PG8_SCHED; PG8_LDA(At, 1, 0); PG8_STAGEA(PG8_SA(0, 1), a2 + hstep);
;             PG8_WAIT_V(8); PG8_WAIT_L(0); PG8_BAR; PG8_MMA(0, 0, At, B0); PG8_MMA(0, 1, At, B1); PG8_BAR; PG8_SCHED;
;             PG8_LDA(At, 1, 1); PG8_STAGEB(PG8_SB(1, 0), b3); PG8_STAGEB(PG8_SB(1, 1), b3 + hstep); PG8_STAGEA(PG8_SA(1, 0), a3);
;             PG8_WAIT_V(8); PG8_WAIT_L(0); PG8_BAR; PG8_MMA(1, 0, At, B0); PG8_MMA(1, 1, At, B1); PG8_BAR; PG8_SCHED;
	s_add_i32 s44, s70, s49
	v_lshl_add_u64 v[154:155], v[154:155], 0, s[10:11]
	s_mov_b32 m0, s44
	ds_read_b128 v[188:191], v159 offset:49152
	ds_read_b128 v[192:195], v159 offset:50176
	ds_read_b128 v[196:199], v159 offset:51200
	ds_read_b128 v[200:203], v159 offset:52224
	ds_read_b128 v[204:207], v159 offset:53248
	ds_read_b128 v[208:211], v159 offset:54272
	ds_read_b128 v[212:215], v159 offset:55296
	ds_read_b128 v[216:219], v159 offset:56320
	global_load_lds_dwordx4 v[154:155], off
	s_add_i32 m0, s44, 0x2000
	s_add_u32 s42, s42, 0x40080
	v_lshl_add_u64 v[154:155], v[220:221], 0, s[10:11]
	s_addc_u32 s43, s43, 0
	s_add_i32 s44, s71, s49
	global_load_lds_dwordx4 v[154:155], off
	v_lshl_add_u64 v[154:155], s[42:43], 0, v[132:133]
	s_mov_b32 m0, s44
	s_nop 0
	global_load_lds_dwordx4 v[154:155], off
	v_lshl_add_u64 v[154:155], s[42:43], 0, v[136:137]
	s_add_i32 m0, s44, 0x2000
	s_nop 0
	global_load_lds_dwordx4 v[154:155], off
	v_lshl_add_u64 v[154:155], v[222:223], 0, s[10:11]
	s_mov_b32 m0, s52
	s_nop 0
	global_load_lds_dwordx4 v[154:155], off
	v_lshl_add_u64 v[154:155], v[224:225], 0, s[10:11]
	s_mov_b32 m0, s53
	s_nop 0
	global_load_lds_dwordx4 v[154:155], off
	s_waitcnt vmcnt(8)
	s_waitcnt lgkmcnt(0)
	s_barrier
	s_waitcnt lgkmcnt(0)
	v_mfma_f32_16x16x32_bf16 v[46:49], v[150:153], v[188:191], v[46:49]
	v_mfma_f32_16x16x32_bf16 v[42:45], v[164:167], v[188:191], v[42:45]
	v_mfma_f32_16x16x32_bf16 v[34:37], v[164:167], v[196:199], v[34:37]
	v_mfma_f32_16x16x32_bf16 v[38:41], v[150:153], v[196:199], v[38:41]
	v_mfma_f32_16x16x32_bf16 v[30:33], v[150:153], v[204:207], v[30:33]
	v_mfma_f32_16x16x32_bf16 v[26:29], v[164:167], v[204:207], v[26:29]
	v_mfma_f32_16x16x32_bf16 v[18:21], v[164:167], v[212:215], v[18:21]
	v_mfma_f32_16x16x32_bf16 v[22:25], v[150:153], v[212:215], v[22:25]
	v_mfma_f32_16x16x32_bf16 v[46:49], v[160:163], v[192:195], v[46:49]
	v_mfma_f32_16x16x32_bf16 v[42:45], v[168:171], v[192:195], v[42:45]
	v_mfma_f32_16x16x32_bf16 v[34:37], v[168:171], v[200:203], v[34:37]
	v_mfma_f32_16x16x32_bf16 v[38:41], v[160:163], v[200:203], v[38:41]
	v_mfma_f32_16x16x32_bf16 v[30:33], v[160:163], v[208:211], v[30:33]
	v_mfma_f32_16x16x32_bf16 v[26:29], v[168:171], v[208:211], v[26:29]
	v_mfma_f32_16x16x32_bf16 v[18:21], v[168:171], v[216:219], v[18:21]
	v_mfma_f32_16x16x32_bf16 v[22:25], v[160:163], v[216:219], v[22:25]
	v_mfma_f32_16x16x32_bf16 v[14:17], v[172:175], v[188:191], v[14:17]
	v_mfma_f32_16x16x32_bf16 v[10:13], v[180:183], v[188:191], v[10:13]
	v_mfma_f32_16x16x32_bf16 v[2:5], v[180:183], v[196:199], v[2:5]
	v_mfma_f32_16x16x32_bf16 v[6:9], v[172:175], v[196:199], v[6:9]
	v_mfma_f32_16x16x32_bf16 v[114:117], v[172:175], v[204:207], v[114:117]
	v_mfma_f32_16x16x32_bf16 v[118:121], v[180:183], v[204:207], v[118:121]
	v_mfma_f32_16x16x32_bf16 v[126:129], v[180:183], v[212:215], v[126:129]
	v_mfma_f32_16x16x32_bf16 v[122:125], v[172:175], v[212:215], v[122:125]
	v_mfma_f32_16x16x32_bf16 v[14:17], v[176:179], v[192:195], v[14:17]
	v_mfma_f32_16x16x32_bf16 v[10:13], v[184:187], v[192:195], v[10:13]
	v_mfma_f32_16x16x32_bf16 v[2:5], v[184:187], v[200:203], v[2:5]
	v_mfma_f32_16x16x32_bf16 v[6:9], v[176:179], v[200:203], v[6:9]
	v_mfma_f32_16x16x32_bf16 v[114:117], v[176:179], v[208:211], v[114:117]
	v_mfma_f32_16x16x32_bf16 v[118:121], v[184:187], v[208:211], v[118:121]
	v_mfma_f32_16x16x32_bf16 v[126:129], v[184:187], v[216:219], v[126:129]
	v_mfma_f32_16x16x32_bf16 v[122:125], v[176:179], v[216:219], v[122:125]
	s_barrier
	s_add_i32 s69, s69, 2
	s_add_u32 s40, s40, 0x100
	s_addc_u32 s41, s41, 0
	s_cmp_gt_u32 s69, 13
	s_cbranch_scc0 .LBB0_1245
	s_branch .Lmy_kexit_6
.LBB0_1245:
	v_add_u32_e32 v154, s54, v156
	ds_read_b128 v[150:153], v154
	ds_read_b128 v[160:163], v154 offset:1024
	ds_read_b128 v[164:167], v154 offset:2048
	ds_read_b128 v[168:171], v154 offset:3072
	v_add_u32_e32 v154, s55, v156
	s_add_u32 s42, s20, s40
	ds_read_b128 v[172:175], v154
	ds_read_b128 v[176:179], v154 offset:1024
	ds_read_b128 v[180:183], v154 offset:2048
	ds_read_b128 v[184:187], v154 offset:3072
	s_addc_u32 s43, s21, s41
	s_add_u32 s42, s42, 0x100
	s_addc_u32 s43, s43, 0
	s_add_u32 s70, s59, s40
	s_addc_u32 s71, s66, s41
	s_cmpk_eq_i32 s40, 0x700
	s_cselect_b32 s45, s27, s43
	s_cselect_b32 s44, s67, s42
	s_cselect_b32 s43, s23, s71
	s_cselect_b32 s42, s68, s70
	v_lshl_add_u64 v[154:155], v[146:147], 0, s[40:41]
	s_add_i32 m0, s17, 0xc000
	ds_read_b128 v[188:191], v159
	ds_read_b128 v[192:195], v159 offset:1024
	ds_read_b128 v[196:199], v159 offset:2048
	ds_read_b128 v[200:203], v159 offset:3072
	ds_read_b128 v[204:207], v159 offset:4096
	ds_read_b128 v[208:211], v159 offset:5120
	ds_read_b128 v[212:215], v159 offset:6144
	ds_read_b128 v[216:219], v159 offset:7168
	global_load_lds_dwordx4 v[154:155], off
	v_lshl_add_u64 v[154:155], v[148:149], 0, s[40:41]
	s_add_i32 m0, s17, 0xe000
	s_nop 0
	global_load_lds_dwordx4 v[154:155], off
	s_waitcnt vmcnt(8)
	s_waitcnt lgkmcnt(0)
	s_barrier
; #define PG8_STAGEA(bufoff, gbase) PG8_STAGE_(bufoff, gbase, voffA)
; #define PG8_STAGEB(bufoff, gbase) PG8_STAGE_(bufoff, gbase, voffB)
; #define PG8_LDA(dst, b, h) do { _Pragma("unroll") for (int m = 0; m < 4; ++m) _Pragma("unroll") for (int k = 0; k < 2; ++k) dst[m][k] = *(const LAS bf16x8*)(lds + PG8_SA(b, h) + aoff + m * 2048 + k * 1024); } while (0)
; #define PG8_MMA(ai, bj, At, Bt_) do { __builtin_amdgcn_s_setprio(1); _Pragma("unroll") for (int m = 0; m < 4; ++m) _Pragma("unroll") for (int n = 0; n < 2; ++n) _Pragma("unroll") for (int k = 0; k < 2; ++k) \
;         acc[ai][bj][m][n] = __builtin_amdgcn_mfma_f32_16x16x32_bf16(Bt_[n][k], At[m][k], acc[ai][bj][m][n], 0, 0, 0); __builtin_amdgcn_s_setprio(0); } while (0)
; #define PG8_WAIT_V(n) asm volatile("s_waitcnt vmcnt(" #n ")" ::: "memory")
; #define PG8_WAIT_L(n) asm volatile("s_waitcnt lgkmcnt(" #n ")" ::: "memory")
; #define PG8_BAR __builtin_amdgcn_s_barrier()
; #define PG8_SCHED __builtin_amdgcn_sched_barrier(0)
; template <int EK, int SK = -1>
; __device__ __forceinline__ void gemm_phase(LAS unsigned char* lds, const bf16_t* A, const bf16_t* Bt, int nM, int N, int K, const EpiArgs& E) {
;     ...
;             PG8_WAIT_V(8); PG8_WAIT_L(0); PG8_BAR; PG8_MMA(0, 0, At, B0); PG8_MMA(0, 1, At, B1); PG8_BAR; PG8_SCHED;
;             PG8_LDA(At, 0, 1); PG8_STAGEB(PG8_SB(0, 0), b2); PG8_STAGEB(PG8_SB(0, 1), b2 + hstep); PG8_STAGEA(PG8_SA(0, 0), a2);
;             PG8_WAIT_V(8); PG8_WAIT_L(0); PG8_BAR; PG8_MMA(1, 0, At, B0); PG8_MMA(1, 1, At, B1); PG8_BAR; PG8_SCHED;
	s_waitcnt lgkmcnt(0)
	v_mfma_f32_16x16x32_bf16 v[110:113], v[150:153], v[188:191], v[110:113]
	v_mfma_f32_16x16x32_bf16 v[106:109], v[164:167], v[188:191], v[106:109]
	v_mfma_f32_16x16x32_bf16 v[98:101], v[164:167], v[196:199], v[98:101]
	v_mfma_f32_16x16x32_bf16 v[102:105], v[150:153], v[196:199], v[102:105]
	v_mfma_f32_16x16x32_bf16 v[94:97], v[150:153], v[204:207], v[94:97]
	v_mfma_f32_16x16x32_bf16 v[90:93], v[164:167], v[204:207], v[90:93]
	v_mfma_f32_16x16x32_bf16 v[82:85], v[164:167], v[212:215], v[82:85]
	v_mfma_f32_16x16x32_bf16 v[86:89], v[150:153], v[212:215], v[86:89]
	v_mfma_f32_16x16x32_bf16 v[110:113], v[160:163], v[192:195], v[110:113]
	v_mfma_f32_16x16x32_bf16 v[106:109], v[168:171], v[192:195], v[106:109]
	v_mfma_f32_16x16x32_bf16 v[98:101], v[168:171], v[200:203], v[98:101]
	v_mfma_f32_16x16x32_bf16 v[102:105], v[160:163], v[200:203], v[102:105]
	v_mfma_f32_16x16x32_bf16 v[94:97], v[160:163], v[208:211], v[94:97]
	v_mfma_f32_16x16x32_bf16 v[90:93], v[168:171], v[208:211], v[90:93]
	v_mfma_f32_16x16x32_bf16 v[82:85], v[168:171], v[216:219], v[82:85]
	v_mfma_f32_16x16x32_bf16 v[86:89], v[160:163], v[216:219], v[86:89]
	v_mfma_f32_16x16x32_bf16 v[78:81], v[172:175], v[188:191], v[78:81]
	v_mfma_f32_16x16x32_bf16 v[74:77], v[180:183], v[188:191], v[74:77]
	v_mfma_f32_16x16x32_bf16 v[66:69], v[180:183], v[196:199], v[66:69]
	v_mfma_f32_16x16x32_bf16 v[70:73], v[172:175], v[196:199], v[70:73]
	v_mfma_f32_16x16x32_bf16 v[62:65], v[172:175], v[204:207], v[62:65]
	v_mfma_f32_16x16x32_bf16 v[58:61], v[180:183], v[204:207], v[58:61]
	v_mfma_f32_16x16x32_bf16 v[50:53], v[180:183], v[212:215], v[50:53]
	v_mfma_f32_16x16x32_bf16 v[54:57], v[172:175], v[212:215], v[54:57]
	v_mfma_f32_16x16x32_bf16 v[78:81], v[176:179], v[192:195], v[78:81]
	v_mfma_f32_16x16x32_bf16 v[74:77], v[184:187], v[192:195], v[74:77]
	v_mfma_f32_16x16x32_bf16 v[66:69], v[184:187], v[200:203], v[66:69]
	v_mfma_f32_16x16x32_bf16 v[70:73], v[176:179], v[200:203], v[70:73]
	v_mfma_f32_16x16x32_bf16 v[62:65], v[176:179], v[208:211], v[62:65]
	v_mfma_f32_16x16x32_bf16 v[58:61], v[184:187], v[208:211], v[58:61]
	v_mfma_f32_16x16x32_bf16 v[50:53], v[184:187], v[216:219], v[50:53]
	v_mfma_f32_16x16x32_bf16 v[54:57], v[176:179], v[216:219], v[54:57]
	s_barrier
	s_add_i32 s70, s54, s49
	v_lshl_add_u64 v[154:155], s[42:43], 0, v[132:133]
	s_mov_b32 m0, s70
	ds_read_b128 v[188:191], v159 offset:16384
	ds_read_b128 v[192:195], v159 offset:17408
	ds_read_b128 v[196:199], v159 offset:18432
	ds_read_b128 v[200:203], v159 offset:19456
	ds_read_b128 v[204:207], v159 offset:20480
	ds_read_b128 v[208:211], v159 offset:21504
	ds_read_b128 v[212:215], v159 offset:22528
	ds_read_b128 v[216:219], v159 offset:23552
	global_load_lds_dwordx4 v[154:155], off
	s_add_i32 m0, s70, 0x2000
	s_add_u32 s70, s42, 0x40000
	v_lshl_add_u64 v[220:221], s[42:43], 0, v[136:137]
	s_addc_u32 s71, s43, 0
	s_add_i32 s72, s55, s49
	global_load_lds_dwordx4 v[220:221], off
	v_lshl_add_u64 v[222:223], s[70:71], 0, v[132:133]
	s_mov_b32 m0, s72
	v_lshl_add_u64 v[224:225], s[44:45], 0, v[134:135]
	global_load_lds_dwordx4 v[222:223], off
	v_lshl_add_u64 v[222:223], s[70:71], 0, v[136:137]
	s_add_i32 m0, s72, 0x2000
	s_nop 0
	global_load_lds_dwordx4 v[222:223], off
	v_lshl_add_u64 v[222:223], s[44:45], 0, v[130:131]
	s_mov_b32 m0, s17
	s_nop 0
	global_load_lds_dwordx4 v[222:223], off
	s_mov_b32 m0, s19
	s_nop 0
	global_load_lds_dwordx4 v[224:225], off
	s_waitcnt vmcnt(8)
	s_waitcnt lgkmcnt(0)
	s_barrier
	s_waitcnt lgkmcnt(0)
	v_mfma_f32_16x16x32_bf16 v[46:49], v[150:153], v[188:191], v[46:49]
	v_mfma_f32_16x16x32_bf16 v[42:45], v[164:167], v[188:191], v[42:45]
	v_mfma_f32_16x16x32_bf16 v[34:37], v[164:167], v[196:199], v[34:37]
	v_mfma_f32_16x16x32_bf16 v[38:41], v[150:153], v[196:199], v[38:41]
	v_mfma_f32_16x16x32_bf16 v[30:33], v[150:153], v[204:207], v[30:33]
	v_mfma_f32_16x16x32_bf16 v[26:29], v[164:167], v[204:207], v[26:29]
	v_mfma_f32_16x16x32_bf16 v[18:21], v[164:167], v[212:215], v[18:21]
	v_mfma_f32_16x16x32_bf16 v[22:25], v[150:153], v[212:215], v[22:25]
	v_mfma_f32_16x16x32_bf16 v[46:49], v[160:163], v[192:195], v[46:49]
	v_mfma_f32_16x16x32_bf16 v[42:45], v[168:171], v[192:195], v[42:45]
	v_mfma_f32_16x16x32_bf16 v[34:37], v[168:171], v[200:203], v[34:37]
	v_mfma_f32_16x16x32_bf16 v[38:41], v[160:163], v[200:203], v[38:41]
	v_mfma_f32_16x16x32_bf16 v[30:33], v[160:163], v[208:211], v[30:33]
	v_mfma_f32_16x16x32_bf16 v[26:29], v[168:171], v[208:211], v[26:29]
	v_mfma_f32_16x16x32_bf16 v[18:21], v[168:171], v[216:219], v[18:21]
	v_mfma_f32_16x16x32_bf16 v[22:25], v[160:163], v[216:219], v[22:25]
	v_mfma_f32_16x16x32_bf16 v[14:17], v[172:175], v[188:191], v[14:17]
	v_mfma_f32_16x16x32_bf16 v[10:13], v[180:183], v[188:191], v[10:13]
	v_mfma_f32_16x16x32_bf16 v[2:5], v[180:183], v[196:199], v[2:5]
	v_mfma_f32_16x16x32_bf16 v[6:9], v[172:175], v[196:199], v[6:9]
	v_mfma_f32_16x16x32_bf16 v[114:117], v[172:175], v[204:207], v[114:117]
	v_mfma_f32_16x16x32_bf16 v[118:121], v[180:183], v[204:207], v[118:121]
	v_mfma_f32_16x16x32_bf16 v[126:129], v[180:183], v[212:215], v[126:129]
	v_mfma_f32_16x16x32_bf16 v[122:125], v[172:175], v[212:215], v[122:125]
	v_mfma_f32_16x16x32_bf16 v[14:17], v[176:179], v[192:195], v[14:17]
	v_mfma_f32_16x16x32_bf16 v[10:13], v[184:187], v[192:195], v[10:13]
	v_mfma_f32_16x16x32_bf16 v[2:5], v[184:187], v[200:203], v[2:5]
	v_mfma_f32_16x16x32_bf16 v[6:9], v[176:179], v[200:203], v[6:9]
	v_mfma_f32_16x16x32_bf16 v[114:117], v[176:179], v[208:211], v[114:117]
	v_mfma_f32_16x16x32_bf16 v[118:121], v[184:187], v[208:211], v[118:121]
	v_mfma_f32_16x16x32_bf16 v[126:129], v[184:187], v[216:219], v[126:129]
	v_mfma_f32_16x16x32_bf16 v[122:125], v[176:179], v[216:219], v[122:125]
	s_barrier
; #define PG8_STAGEA(bufoff, gbase) PG8_STAGE_(bufoff, gbase, voffA)
; #define PG8_STAGEB(bufoff, gbase) PG8_STAGE_(bufoff, gbase, voffB)
; #define PG8_LDA(dst, b, h) do { _Pragma("unroll") for (int m = 0; m < 4; ++m) _Pragma("unroll") for (int k = 0; k < 2; ++k) dst[m][k] = *(const LAS bf16x8*)(lds + PG8_SA(b, h) + aoff + m * 2048 + k * 1024); } while (0)
; #define PG8_LDB(dst, b, h) do { _Pragma("unroll") for (int n = 0; n < 2; ++n) _Pragma("unroll") for (int k = 0; k < 2; ++k) dst[n][k] = *(const LAS bf16x8*)(lds + PG8_SB(b, h) + boff + n * 2048 + k * 1024); } while (0)
; #define PG8_MMA(ai, bj, At, Bt_) do { __builtin_amdgcn_s_setprio(1); _Pragma("unroll") for (int m = 0; m < 4; ++m) _Pragma("unroll") for (int n = 0; n < 2; ++n) _Pragma("unroll") for (int k = 0; k < 2; ++k) \
;         acc[ai][bj][m][n] = __builtin_amdgcn_mfma_f32_16x16x32_bf16(Bt_[n][k], At[m][k], acc[ai][bj][m][n], 0, 0, 0); __builtin_amdgcn_s_setprio(0); } while (0)
; #define PG8_WAIT_V(n) asm volatile("s_waitcnt vmcnt(" #n ")" ::: "memory")
; #define PG8_WAIT_L(n) asm volatile("s_waitcnt lgkmcnt(" #n ")" ::: "memory")
; #define PG8_BAR __builtin_amdgcn_s_barrier()
; #define PG8_SCHED __builtin_amdgcn_sched_barrier(0)
; template <int EK, int SK = -1>
; __device__ __forceinline__ void gemm_phase(LAS unsigned char* lds, const bf16_t* A, const bf16_t* Bt, int nM, int N, int K, const EpiArgs& E) {
;     ...
;             PG8_LDB(B0, 1, 0); PG8_LDB(B1, 1, 1); PG8_SCHED; PG8_LDA(At, 1, 0); PG8_STAGEA(PG8_SA(0, 1), a2 + hstep);
;             PG8_WAIT_V(8); PG8_WAIT_L(0); PG8_BAR; PG8_MMA(0, 0, At, B0); PG8_MMA(0, 1, At, B1); PG8_BAR; PG8_SCHED;
;             PG8_LDA(At, 1, 1); PG8_STAGEB(PG8_SB(1, 0), b3); PG8_STAGEB(PG8_SB(1, 1), b3 + hstep); PG8_STAGEA(PG8_SA(1, 0), a3);
;             PG8_WAIT_V(8); PG8_WAIT_L(0); PG8_BAR; PG8_MMA(1, 0, At, B0); PG8_MMA(1, 1, At, B1); PG8_BAR; PG8_SCHED;
;         }
	s_add_i32 s70, 0, 0x18000
	s_add_i32 s71, 0, 0x1c000
	v_add_u32_e32 v168, s70, v156
	v_add_u32_e32 v184, s71, v156
	ds_read_b128 v[150:153], v168
	ds_read_b128 v[160:163], v168 offset:1024
	ds_read_b128 v[164:167], v168 offset:2048
	ds_read_b128 v[168:171], v168 offset:3072
	ds_read_b128 v[172:175], v184
	ds_read_b128 v[176:179], v184 offset:1024
	ds_read_b128 v[180:183], v184 offset:2048
	ds_read_b128 v[184:187], v184 offset:3072
	s_add_u32 s44, s44, 0x40000
	s_addc_u32 s45, s45, 0
	s_mov_b32 m0, s50
	v_lshl_add_u64 v[226:227], s[44:45], 0, v[130:131]
	ds_read_b128 v[188:191], v159 offset:32768
	ds_read_b128 v[192:195], v159 offset:33792
	ds_read_b128 v[196:199], v159 offset:34816
	ds_read_b128 v[200:203], v159 offset:35840
	ds_read_b128 v[204:207], v159 offset:36864
	ds_read_b128 v[208:211], v159 offset:37888
	ds_read_b128 v[212:215], v159 offset:38912
	ds_read_b128 v[216:219], v159 offset:39936
	global_load_lds_dwordx4 v[226:227], off
	v_lshl_add_u64 v[226:227], s[44:45], 0, v[134:135]
	s_mov_b32 m0, s51
	s_nop 0
	global_load_lds_dwordx4 v[226:227], off
	s_waitcnt vmcnt(8)
	s_waitcnt lgkmcnt(0)
	s_barrier
	s_waitcnt lgkmcnt(0)
	v_mfma_f32_16x16x32_bf16 v[110:113], v[150:153], v[188:191], v[110:113]
	v_mfma_f32_16x16x32_bf16 v[106:109], v[164:167], v[188:191], v[106:109]
	v_mfma_f32_16x16x32_bf16 v[98:101], v[164:167], v[196:199], v[98:101]
	v_mfma_f32_16x16x32_bf16 v[102:105], v[150:153], v[196:199], v[102:105]
	v_mfma_f32_16x16x32_bf16 v[94:97], v[150:153], v[204:207], v[94:97]
	v_mfma_f32_16x16x32_bf16 v[90:93], v[164:167], v[204:207], v[90:93]
	v_mfma_f32_16x16x32_bf16 v[82:85], v[164:167], v[212:215], v[82:85]
	v_mfma_f32_16x16x32_bf16 v[86:89], v[150:153], v[212:215], v[86:89]
	v_mfma_f32_16x16x32_bf16 v[110:113], v[160:163], v[192:195], v[110:113]
	v_mfma_f32_16x16x32_bf16 v[106:109], v[168:171], v[192:195], v[106:109]
	v_mfma_f32_16x16x32_bf16 v[98:101], v[168:171], v[200:203], v[98:101]
	v_mfma_f32_16x16x32_bf16 v[102:105], v[160:163], v[200:203], v[102:105]
	v_mfma_f32_16x16x32_bf16 v[94:97], v[160:163], v[208:211], v[94:97]
	v_mfma_f32_16x16x32_bf16 v[90:93], v[168:171], v[208:211], v[90:93]
	v_mfma_f32_16x16x32_bf16 v[82:85], v[168:171], v[216:219], v[82:85]
	v_mfma_f32_16x16x32_bf16 v[86:89], v[160:163], v[216:219], v[86:89]
	v_mfma_f32_16x16x32_bf16 v[78:81], v[172:175], v[188:191], v[78:81]
	v_mfma_f32_16x16x32_bf16 v[74:77], v[180:183], v[188:191], v[74:77]
	v_mfma_f32_16x16x32_bf16 v[66:69], v[180:183], v[196:199], v[66:69]
	v_mfma_f32_16x16x32_bf16 v[70:73], v[172:175], v[196:199], v[70:73]
	v_mfma_f32_16x16x32_bf16 v[62:65], v[172:175], v[204:207], v[62:65]
	v_mfma_f32_16x16x32_bf16 v[58:61], v[180:183], v[204:207], v[58:61]
	v_mfma_f32_16x16x32_bf16 v[50:53], v[180:183], v[212:215], v[50:53]
	v_mfma_f32_16x16x32_bf16 v[54:57], v[172:175], v[212:215], v[54:57]
	v_mfma_f32_16x16x32_bf16 v[78:81], v[176:179], v[192:195], v[78:81]
	v_mfma_f32_16x16x32_bf16 v[74:77], v[184:187], v[192:195], v[74:77]
	v_mfma_f32_16x16x32_bf16 v[66:69], v[184:187], v[200:203], v[66:69]
	v_mfma_f32_16x16x32_bf16 v[70:73], v[176:179], v[200:203], v[70:73]
	v_mfma_f32_16x16x32_bf16 v[62:65], v[176:179], v[208:211], v[62:65]
	v_mfma_f32_16x16x32_bf16 v[58:61], v[184:187], v[208:211], v[58:61]
	v_mfma_f32_16x16x32_bf16 v[50:53], v[184:187], v[216:219], v[50:53]
	v_mfma_f32_16x16x32_bf16 v[54:57], v[176:179], v[216:219], v[54:57]
	s_barrier
	s_add_i32 s44, s70, s49
	v_lshl_add_u64 v[154:155], v[154:155], 0, s[10:11]
	s_mov_b32 m0, s44
	ds_read_b128 v[188:191], v159 offset:49152
	ds_read_b128 v[192:195], v159 offset:50176
	ds_read_b128 v[196:199], v159 offset:51200
	ds_read_b128 v[200:203], v159 offset:52224
	ds_read_b128 v[204:207], v159 offset:53248
	ds_read_b128 v[208:211], v159 offset:54272
	ds_read_b128 v[212:215], v159 offset:55296
	ds_read_b128 v[216:219], v159 offset:56320
	global_load_lds_dwordx4 v[154:155], off
	s_add_i32 m0, s44, 0x2000
	s_add_u32 s42, s42, 0x40080
	v_lshl_add_u64 v[154:155], v[220:221], 0, s[10:11]
	s_addc_u32 s43, s43, 0
	s_add_i32 s44, s71, s49
	global_load_lds_dwordx4 v[154:155], off
	v_lshl_add_u64 v[154:155], s[42:43], 0, v[132:133]
	s_mov_b32 m0, s44
	s_nop 0
	global_load_lds_dwordx4 v[154:155], off
	v_lshl_add_u64 v[154:155], s[42:43], 0, v[136:137]
	s_add_i32 m0, s44, 0x2000
	s_nop 0
	global_load_lds_dwordx4 v[154:155], off
	v_lshl_add_u64 v[154:155], v[222:223], 0, s[10:11]
	s_mov_b32 m0, s52
	s_nop 0
	global_load_lds_dwordx4 v[154:155], off
	v_lshl_add_u64 v[154:155], v[224:225], 0, s[10:11]
	s_mov_b32 m0, s53
	s_nop 0
	global_load_lds_dwordx4 v[154:155], off
	s_waitcnt vmcnt(8)
	s_waitcnt lgkmcnt(0)
	s_barrier
	s_waitcnt lgkmcnt(0)
	v_mfma_f32_16x16x32_bf16 v[46:49], v[150:153], v[188:191], v[46:49]
	v_mfma_f32_16x16x32_bf16 v[42:45], v[164:167], v[188:191], v[42:45]
	v_mfma_f32_16x16x32_bf16 v[34:37], v[164:167], v[196:199], v[34:37]
	v_mfma_f32_16x16x32_bf16 v[38:41], v[150:153], v[196:199], v[38:41]
	v_mfma_f32_16x16x32_bf16 v[30:33], v[150:153], v[204:207], v[30:33]
	v_mfma_f32_16x16x32_bf16 v[26:29], v[164:167], v[204:207], v[26:29]
	v_mfma_f32_16x16x32_bf16 v[18:21], v[164:167], v[212:215], v[18:21]
	v_mfma_f32_16x16x32_bf16 v[22:25], v[150:153], v[212:215], v[22:25]
	v_mfma_f32_16x16x32_bf16 v[46:49], v[160:163], v[192:195], v[46:49]
	v_mfma_f32_16x16x32_bf16 v[42:45], v[168:171], v[192:195], v[42:45]
	v_mfma_f32_16x16x32_bf16 v[34:37], v[168:171], v[200:203], v[34:37]
	v_mfma_f32_16x16x32_bf16 v[38:41], v[160:163], v[200:203], v[38:41]
	v_mfma_f32_16x16x32_bf16 v[30:33], v[160:163], v[208:211], v[30:33]
	v_mfma_f32_16x16x32_bf16 v[26:29], v[168:171], v[208:211], v[26:29]
	v_mfma_f32_16x16x32_bf16 v[18:21], v[168:171], v[216:219], v[18:21]
	v_mfma_f32_16x16x32_bf16 v[22:25], v[160:163], v[216:219], v[22:25]
	v_mfma_f32_16x16x32_bf16 v[14:17], v[172:175], v[188:191], v[14:17]
	v_mfma_f32_16x16x32_bf16 v[10:13], v[180:183], v[188:191], v[10:13]
	v_mfma_f32_16x16x32_bf16 v[2:5], v[180:183], v[196:199], v[2:5]
	v_mfma_f32_16x16x32_bf16 v[6:9], v[172:175], v[196:199], v[6:9]
	v_mfma_f32_16x16x32_bf16 v[114:117], v[172:175], v[204:207], v[114:117]
	v_mfma_f32_16x16x32_bf16 v[118:121], v[180:183], v[204:207], v[118:121]
	v_mfma_f32_16x16x32_bf16 v[126:129], v[180:183], v[212:215], v[126:129]
	v_mfma_f32_16x16x32_bf16 v[122:125], v[172:175], v[212:215], v[122:125]
	v_mfma_f32_16x16x32_bf16 v[14:17], v[176:179], v[192:195], v[14:17]
	v_mfma_f32_16x16x32_bf16 v[10:13], v[184:187], v[192:195], v[10:13]
	v_mfma_f32_16x16x32_bf16 v[2:5], v[184:187], v[200:203], v[2:5]
	v_mfma_f32_16x16x32_bf16 v[6:9], v[176:179], v[200:203], v[6:9]
	v_mfma_f32_16x16x32_bf16 v[114:117], v[176:179], v[208:211], v[114:117]
	v_mfma_f32_16x16x32_bf16 v[118:121], v[184:187], v[208:211], v[118:121]
	v_mfma_f32_16x16x32_bf16 v[126:129], v[184:187], v[216:219], v[126:129]
	v_mfma_f32_16x16x32_bf16 v[122:125], v[176:179], v[216:219], v[122:125]
	s_barrier
	s_add_i32 s69, s69, 2
	s_add_u32 s40, s40, 0x100
	s_addc_u32 s41, s41, 0
	s_cmp_gt_u32 s69, 13
	s_cbranch_scc0 .LBB0_1245

; #define PG8_STAGEA(bufoff, gbase) PG8_STAGE_(bufoff, gbase, voffA)
; #define PG8_STAGEB(bufoff, gbase) PG8_STAGE_(bufoff, gbase, voffB)
; #define PG8_LDA(dst, b, h) do { _Pragma("unroll") for (int m = 0; m < 4; ++m) _Pragma("unroll") for (int k = 0; k < 2; ++k) dst[m][k] = *(const LAS bf16x8*)(lds + PG8_SA(b, h) + aoff + m * 2048 + k * 1024); } while (0)
; #define PG8_LDB(dst, b, h) do { _Pragma("unroll") for (int n = 0; n < 2; ++n) _Pragma("unroll") for (int k = 0; k < 2; ++k) dst[n][k] = *(const LAS bf16x8*)(lds + PG8_SB(b, h) + boff + n * 2048 + k * 1024); } while (0)
; #define PG8_MMA(ai, bj, At, Bt_) do { __builtin_amdgcn_s_setprio(1); _Pragma("unroll") for (int m = 0; m < 4; ++m) _Pragma("unroll") for (int n = 0; n < 2; ++n) _Pragma("unroll") for (int k = 0; k < 2; ++k) \
;         acc[ai][bj][m][n] = __builtin_amdgcn_mfma_f32_16x16x32_bf16(Bt_[n][k], At[m][k], acc[ai][bj][m][n], 0, 0, 0); __builtin_amdgcn_s_setprio(0); } while (0)
; #define PG8_WAIT_V(n) asm volatile("s_waitcnt vmcnt(" #n ")" ::: "memory")
; #define PG8_WAIT_L(n) asm volatile("s_waitcnt lgkmcnt(" #n ")" ::: "memory")
; #define PG8_BAR __builtin_amdgcn_s_barrier()
; #define PG8_SCHED __builtin_amdgcn_sched_barrier(0)
; template <int EK, int SK = -1>
; __device__ __forceinline__ void gemm_phase(LAS unsigned char* lds, const bf16_t* A, const bf16_t* Bt, int nM, int N, int K, const EpiArgs& E) {
;     ...
;         const bool has_next = S.next(ui + 1, nxt);
;         const char* nA = has_next ? (const char*)A + (size_t)nxt.pm * tstep : cA; const char* nB = has_next ? (const char*)Bt + (size_t)nxt.pn * tstep : cB;
;         for (int t = 0; t < nt; t += 2) {
;             const bool last = (t == nt - 2);
;             const char* a1 = cA + (size_t)(t + 1) * kstep;
;             const char* a2 = last ? nA : cA + (size_t)(t + 2) * kstep; const char* b2 = last ? nB : cB + (size_t)(t + 2) * kstep;
;             const char* a3 = a2 + kstep; const char* b3 = b2 + kstep;
;             PG8_LDB(B0, 0, 0); PG8_LDB(B1, 0, 1); PG8_SCHED; PG8_LDA(At, 0, 0); PG8_STAGEA(PG8_SA(1, 1), a1 + hstep);
;             PG8_WAIT_V(8); PG8_WAIT_L(0); PG8_BAR; PG8_MMA(0, 0, At, B0); PG8_MMA(0, 1, At, B1); PG8_BAR; PG8_SCHED;
;             PG8_LDA(At, 0, 1); PG8_STAGEB(PG8_SB(0, 0), b2); PG8_STAGEB(PG8_SB(0, 1), b2 + hstep); PG8_STAGEA(PG8_SA(0, 0), a2);
.LBB0_1337:
	s_add_u32 s73, s42, 0x100
	s_addc_u32 s74, s43, 0
	s_waitcnt lgkmcnt(0)
	v_lshl_add_u64 v[146:147], s[20:21], 0, v[138:139]
	v_lshl_add_u64 v[148:149], s[20:21], 0, v[140:141]
	s_mov_b32 s26, -2
	s_mov_b64 s[42:43], 0
	v_add_u32_e32 v150, s67, v152
	ds_read_b128 v[156:159], v150
	ds_read_b128 v[160:163], v150 offset:1024
	ds_read_b128 v[164:167], v150 offset:2048
	ds_read_b128 v[168:171], v150 offset:3072
	v_add_u32_e32 v150, s68, v152
	s_add_u32 s44, s20, s42
	ds_read_b128 v[172:175], v150
	ds_read_b128 v[176:179], v150 offset:1024
	ds_read_b128 v[180:183], v150 offset:2048
	ds_read_b128 v[184:187], v150 offset:3072
	s_addc_u32 s45, s21, s43
	s_add_u32 s44, s44, 0x100
	s_addc_u32 s45, s45, 0
	s_add_u32 s75, s73, s42
	s_addc_u32 s76, s74, s43
	s_cmpk_eq_i32 s42, 0x1500
	s_cselect_b32 s47, s41, s45
	s_cselect_b32 s46, s40, s44
	s_cselect_b32 s45, s9, s76
	s_cselect_b32 s44, s8, s75
	v_lshl_add_u64 v[150:151], v[146:147], 0, s[42:43]
	s_add_i32 m0, s53, 0xc000
	ds_read_b128 v[188:191], v154
	ds_read_b128 v[192:195], v154 offset:1024
	ds_read_b128 v[196:199], v154 offset:2048
	ds_read_b128 v[200:203], v154 offset:3072
	ds_read_b128 v[204:207], v154 offset:4096
	ds_read_b128 v[208:211], v154 offset:5120
	ds_read_b128 v[212:215], v154 offset:6144
	ds_read_b128 v[216:219], v154 offset:7168
	global_load_lds_dwordx4 v[150:151], off
	v_lshl_add_u64 v[150:151], v[148:149], 0, s[42:43]
	s_add_i32 m0, s53, 0xe000
	s_nop 0
	global_load_lds_dwordx4 v[150:151], off
	s_waitcnt vmcnt(8)
	s_waitcnt lgkmcnt(0)
	s_barrier
	s_waitcnt lgkmcnt(0)
	v_mfma_f32_16x16x32_bf16 v[126:129], v[156:159], v[188:191], 0
	v_mfma_f32_16x16x32_bf16 v[122:125], v[164:167], v[188:191], 0
	v_mfma_f32_16x16x32_bf16 v[114:117], v[164:167], v[196:199], 0
	v_mfma_f32_16x16x32_bf16 v[118:121], v[156:159], v[196:199], 0
	v_mfma_f32_16x16x32_bf16 v[110:113], v[156:159], v[204:207], 0
	v_mfma_f32_16x16x32_bf16 v[106:109], v[164:167], v[204:207], 0
	v_mfma_f32_16x16x32_bf16 v[98:101], v[164:167], v[212:215], 0
	v_mfma_f32_16x16x32_bf16 v[102:105], v[156:159], v[212:215], 0
	v_mfma_f32_16x16x32_bf16 v[126:129], v[160:163], v[192:195], v[126:129]
	v_mfma_f32_16x16x32_bf16 v[122:125], v[168:171], v[192:195], v[122:125]
	v_mfma_f32_16x16x32_bf16 v[114:117], v[168:171], v[200:203], v[114:117]
	v_mfma_f32_16x16x32_bf16 v[118:121], v[160:163], v[200:203], v[118:121]
	v_mfma_f32_16x16x32_bf16 v[110:113], v[160:163], v[208:211], v[110:113]
	v_mfma_f32_16x16x32_bf16 v[106:109], v[168:171], v[208:211], v[106:109]
	v_mfma_f32_16x16x32_bf16 v[98:101], v[168:171], v[216:219], v[98:101]
	v_mfma_f32_16x16x32_bf16 v[102:105], v[160:163], v[216:219], v[102:105]
	v_mfma_f32_16x16x32_bf16 v[94:97], v[172:175], v[188:191], 0
	v_mfma_f32_16x16x32_bf16 v[90:93], v[180:183], v[188:191], 0
	v_mfma_f32_16x16x32_bf16 v[82:85], v[180:183], v[196:199], 0
	v_mfma_f32_16x16x32_bf16 v[86:89], v[172:175], v[196:199], 0
	v_mfma_f32_16x16x32_bf16 v[78:81], v[172:175], v[204:207], 0
	v_mfma_f32_16x16x32_bf16 v[74:77], v[180:183], v[204:207], 0
	v_mfma_f32_16x16x32_bf16 v[66:69], v[180:183], v[212:215], 0
	v_mfma_f32_16x16x32_bf16 v[70:73], v[172:175], v[212:215], 0
	v_mfma_f32_16x16x32_bf16 v[94:97], v[176:179], v[192:195], v[94:97]
	v_mfma_f32_16x16x32_bf16 v[90:93], v[184:187], v[192:195], v[90:93]
	v_mfma_f32_16x16x32_bf16 v[82:85], v[184:187], v[200:203], v[82:85]
	v_mfma_f32_16x16x32_bf16 v[86:89], v[176:179], v[200:203], v[86:89]
	v_mfma_f32_16x16x32_bf16 v[78:81], v[176:179], v[208:211], v[78:81]
	v_mfma_f32_16x16x32_bf16 v[74:77], v[184:187], v[208:211], v[74:77]
	v_mfma_f32_16x16x32_bf16 v[66:69], v[184:187], v[216:219], v[66:69]
	v_mfma_f32_16x16x32_bf16 v[70:73], v[176:179], v[216:219], v[70:73]
	s_barrier
	s_add_i32 s75, s67, s52
	v_lshl_add_u64 v[150:151], s[44:45], 0, v[132:133]
	s_mov_b32 m0, s75
	ds_read_b128 v[188:191], v154 offset:16384
	ds_read_b128 v[192:195], v154 offset:17408
	ds_read_b128 v[196:199], v154 offset:18432
	ds_read_b128 v[200:203], v154 offset:19456
	ds_read_b128 v[204:207], v154 offset:20480
	ds_read_b128 v[208:211], v154 offset:21504
	ds_read_b128 v[212:215], v154 offset:22528
	ds_read_b128 v[216:219], v154 offset:23552
	global_load_lds_dwordx4 v[150:151], off
	s_add_i32 m0, s75, 0x2000
	s_add_u32 s76, s44, 0xb0000
	v_lshl_add_u64 v[220:221], s[44:45], 0, v[136:137]
	s_addc_u32 s77, s45, 0
	s_add_i32 s75, s68, s52
	global_load_lds_dwordx4 v[220:221], off
	v_lshl_add_u64 v[222:223], s[76:77], 0, v[132:133]
	s_mov_b32 m0, s75
	v_lshl_add_u64 v[224:225], s[46:47], 0, v[134:135]
	global_load_lds_dwordx4 v[222:223], off
	v_lshl_add_u64 v[222:223], s[76:77], 0, v[136:137]
	s_add_i32 m0, s75, 0x2000
	s_nop 0
	global_load_lds_dwordx4 v[222:223], off
	v_lshl_add_u64 v[222:223], s[46:47], 0, v[130:131]
	s_mov_b32 m0, s53
	s_nop 0
	global_load_lds_dwordx4 v[222:223], off
	s_mov_b32 m0, s54
	s_nop 0
	global_load_lds_dwordx4 v[224:225], off
	s_waitcnt vmcnt(8)
	s_waitcnt lgkmcnt(0)
	s_barrier
; #define PG8_STAGEA(bufoff, gbase) PG8_STAGE_(bufoff, gbase, voffA)
; #define PG8_LDA(dst, b, h) do { _Pragma("unroll") for (int m = 0; m < 4; ++m) _Pragma("unroll") for (int k = 0; k < 2; ++k) dst[m][k] = *(const LAS bf16x8*)(lds + PG8_SA(b, h) + aoff + m * 2048 + k * 1024); } while (0)
; #define PG8_LDB(dst, b, h) do { _Pragma("unroll") for (int n = 0; n < 2; ++n) _Pragma("unroll") for (int k = 0; k < 2; ++k) dst[n][k] = *(const LAS bf16x8*)(lds + PG8_SB(b, h) + boff + n * 2048 + k * 1024); } while (0)
; #define PG8_MMA(ai, bj, At, Bt_) do { __builtin_amdgcn_s_setprio(1); _Pragma("unroll") for (int m = 0; m < 4; ++m) _Pragma("unroll") for (int n = 0; n < 2; ++n) _Pragma("unroll") for (int k = 0; k < 2; ++k) \
;         acc[ai][bj][m][n] = __builtin_amdgcn_mfma_f32_16x16x32_bf16(Bt_[n][k], At[m][k], acc[ai][bj][m][n], 0, 0, 0); __builtin_amdgcn_s_setprio(0); } while (0)
; #define PG8_WAIT_V(n) asm volatile("s_waitcnt vmcnt(" #n ")" ::: "memory")
; #define PG8_WAIT_L(n) asm volatile("s_waitcnt lgkmcnt(" #n ")" ::: "memory")
; #define PG8_BAR __builtin_amdgcn_s_barrier()
; #define PG8_SCHED __builtin_amdgcn_sched_barrier(0)
; template <int EK, int SK = -1>
; __device__ __forceinline__ void gemm_phase(LAS unsigned char* lds, const bf16_t* A, const bf16_t* Bt, int nM, int N, int K, const EpiArgs& E) {
;     ...
;             PG8_WAIT_V(8); PG8_WAIT_L(0); PG8_BAR; PG8_MMA(1, 0, At, B0); PG8_MMA(1, 1, At, B1); PG8_BAR; PG8_SCHED;
;             PG8_LDB(B0, 1, 0); PG8_LDB(B1, 1, 1); PG8_SCHED; PG8_LDA(At, 1, 0); PG8_STAGEA(PG8_SA(0, 1), a2 + hstep);
;             PG8_WAIT_V(8); PG8_WAIT_L(0); PG8_BAR; PG8_MMA(0, 0, At, B0); PG8_MMA(0, 1, At, B1); PG8_BAR; PG8_SCHED;
	s_waitcnt lgkmcnt(0)
	v_mfma_f32_16x16x32_bf16 v[62:65], v[156:159], v[188:191], 0
	v_mfma_f32_16x16x32_bf16 v[58:61], v[164:167], v[188:191], 0
	v_mfma_f32_16x16x32_bf16 v[50:53], v[164:167], v[196:199], 0
	v_mfma_f32_16x16x32_bf16 v[54:57], v[156:159], v[196:199], 0
	v_mfma_f32_16x16x32_bf16 v[46:49], v[156:159], v[204:207], 0
	v_mfma_f32_16x16x32_bf16 v[42:45], v[164:167], v[204:207], 0
	v_mfma_f32_16x16x32_bf16 v[34:37], v[164:167], v[212:215], 0
	v_mfma_f32_16x16x32_bf16 v[38:41], v[156:159], v[212:215], 0
	v_mfma_f32_16x16x32_bf16 v[62:65], v[160:163], v[192:195], v[62:65]
	v_mfma_f32_16x16x32_bf16 v[58:61], v[168:171], v[192:195], v[58:61]
	v_mfma_f32_16x16x32_bf16 v[50:53], v[168:171], v[200:203], v[50:53]
	v_mfma_f32_16x16x32_bf16 v[54:57], v[160:163], v[200:203], v[54:57]
	v_mfma_f32_16x16x32_bf16 v[46:49], v[160:163], v[208:211], v[46:49]
	v_mfma_f32_16x16x32_bf16 v[42:45], v[168:171], v[208:211], v[42:45]
	v_mfma_f32_16x16x32_bf16 v[34:37], v[168:171], v[216:219], v[34:37]
	v_mfma_f32_16x16x32_bf16 v[38:41], v[160:163], v[216:219], v[38:41]
	v_mfma_f32_16x16x32_bf16 v[30:33], v[172:175], v[188:191], 0
	v_mfma_f32_16x16x32_bf16 v[26:29], v[180:183], v[188:191], 0
	v_mfma_f32_16x16x32_bf16 v[18:21], v[180:183], v[196:199], 0
	v_mfma_f32_16x16x32_bf16 v[22:25], v[172:175], v[196:199], 0
	v_mfma_f32_16x16x32_bf16 v[14:17], v[172:175], v[204:207], 0
	v_mfma_f32_16x16x32_bf16 v[10:13], v[180:183], v[204:207], 0
	v_mfma_f32_16x16x32_bf16 v[2:5], v[180:183], v[212:215], 0
	v_mfma_f32_16x16x32_bf16 v[6:9], v[172:175], v[212:215], 0
	v_mfma_f32_16x16x32_bf16 v[30:33], v[176:179], v[192:195], v[30:33]
	v_mfma_f32_16x16x32_bf16 v[26:29], v[184:187], v[192:195], v[26:29]
	v_mfma_f32_16x16x32_bf16 v[18:21], v[184:187], v[200:203], v[18:21]
	v_mfma_f32_16x16x32_bf16 v[22:25], v[176:179], v[200:203], v[22:25]
	v_mfma_f32_16x16x32_bf16 v[14:17], v[176:179], v[208:211], v[14:17]
	v_mfma_f32_16x16x32_bf16 v[10:13], v[184:187], v[208:211], v[10:13]
	v_mfma_f32_16x16x32_bf16 v[2:5], v[184:187], v[216:219], v[2:5]
	v_mfma_f32_16x16x32_bf16 v[6:9], v[176:179], v[216:219], v[6:9]
	s_barrier
	s_add_i32 s75, 0, 0x18000
	s_add_i32 s76, 0, 0x1c000
	v_add_u32_e32 v168, s75, v152
	v_add_u32_e32 v184, s76, v152
	ds_read_b128 v[156:159], v168
	ds_read_b128 v[160:163], v168 offset:1024
	ds_read_b128 v[164:167], v168 offset:2048
	ds_read_b128 v[168:171], v168 offset:3072
	ds_read_b128 v[172:175], v184
	ds_read_b128 v[176:179], v184 offset:1024
	ds_read_b128 v[180:183], v184 offset:2048
	ds_read_b128 v[184:187], v184 offset:3072
	s_add_u32 s46, s46, 0xb0000
	s_addc_u32 s47, s47, 0
	s_mov_b32 m0, s55
	v_lshl_add_u64 v[226:227], s[46:47], 0, v[130:131]
	ds_read_b128 v[188:191], v154 offset:32768
	ds_read_b128 v[192:195], v154 offset:33792
	ds_read_b128 v[196:199], v154 offset:34816
	ds_read_b128 v[200:203], v154 offset:35840
	ds_read_b128 v[204:207], v154 offset:36864
	ds_read_b128 v[208:211], v154 offset:37888
	ds_read_b128 v[212:215], v154 offset:38912
	ds_read_b128 v[216:219], v154 offset:39936
	global_load_lds_dwordx4 v[226:227], off
	v_lshl_add_u64 v[226:227], s[46:47], 0, v[134:135]
	s_mov_b32 m0, s56
	s_nop 0
	global_load_lds_dwordx4 v[226:227], off
	s_waitcnt vmcnt(8)
	s_waitcnt lgkmcnt(0)
	s_barrier
	s_waitcnt lgkmcnt(0)
	v_mfma_f32_16x16x32_bf16 v[126:129], v[156:159], v[188:191], v[126:129]
	v_mfma_f32_16x16x32_bf16 v[122:125], v[164:167], v[188:191], v[122:125]
	v_mfma_f32_16x16x32_bf16 v[114:117], v[164:167], v[196:199], v[114:117]
	v_mfma_f32_16x16x32_bf16 v[118:121], v[156:159], v[196:199], v[118:121]
	v_mfma_f32_16x16x32_bf16 v[110:113], v[156:159], v[204:207], v[110:113]
	v_mfma_f32_16x16x32_bf16 v[106:109], v[164:167], v[204:207], v[106:109]
	v_mfma_f32_16x16x32_bf16 v[98:101], v[164:167], v[212:215], v[98:101]
	v_mfma_f32_16x16x32_bf16 v[102:105], v[156:159], v[212:215], v[102:105]
	v_mfma_f32_16x16x32_bf16 v[126:129], v[160:163], v[192:195], v[126:129]
	v_mfma_f32_16x16x32_bf16 v[122:125], v[168:171], v[192:195], v[122:125]
	v_mfma_f32_16x16x32_bf16 v[114:117], v[168:171], v[200:203], v[114:117]
	v_mfma_f32_16x16x32_bf16 v[118:121], v[160:163], v[200:203], v[118:121]
	v_mfma_f32_16x16x32_bf16 v[110:113], v[160:163], v[208:211], v[110:113]
	v_mfma_f32_16x16x32_bf16 v[106:109], v[168:171], v[208:211], v[106:109]
	v_mfma_f32_16x16x32_bf16 v[98:101], v[168:171], v[216:219], v[98:101]
	v_mfma_f32_16x16x32_bf16 v[102:105], v[160:163], v[216:219], v[102:105]
	v_mfma_f32_16x16x32_bf16 v[94:97], v[172:175], v[188:191], v[94:97]
	v_mfma_f32_16x16x32_bf16 v[90:93], v[180:183], v[188:191], v[90:93]
	v_mfma_f32_16x16x32_bf16 v[82:85], v[180:183], v[196:199], v[82:85]
	v_mfma_f32_16x16x32_bf16 v[86:89], v[172:175], v[196:199], v[86:89]
	v_mfma_f32_16x16x32_bf16 v[78:81], v[172:175], v[204:207], v[78:81]
	v_mfma_f32_16x16x32_bf16 v[74:77], v[180:183], v[204:207], v[74:77]
	v_mfma_f32_16x16x32_bf16 v[66:69], v[180:183], v[212:215], v[66:69]
	v_mfma_f32_16x16x32_bf16 v[70:73], v[172:175], v[212:215], v[70:73]
	v_mfma_f32_16x16x32_bf16 v[94:97], v[176:179], v[192:195], v[94:97]
	v_mfma_f32_16x16x32_bf16 v[90:93], v[184:187], v[192:195], v[90:93]
	v_mfma_f32_16x16x32_bf16 v[82:85], v[184:187], v[200:203], v[82:85]
	v_mfma_f32_16x16x32_bf16 v[86:89], v[176:179], v[200:203], v[86:89]
	v_mfma_f32_16x16x32_bf16 v[78:81], v[176:179], v[208:211], v[78:81]
	v_mfma_f32_16x16x32_bf16 v[74:77], v[184:187], v[208:211], v[74:77]
	v_mfma_f32_16x16x32_bf16 v[66:69], v[184:187], v[216:219], v[66:69]
	v_mfma_f32_16x16x32_bf16 v[70:73], v[176:179], v[216:219], v[70:73]
	s_barrier
; #define PG8_STAGEA(bufoff, gbase) PG8_STAGE_(bufoff, gbase, voffA)
; #define PG8_STAGEB(bufoff, gbase) PG8_STAGE_(bufoff, gbase, voffB)
; #define PG8_LDA(dst, b, h) do { _Pragma("unroll") for (int m = 0; m < 4; ++m) _Pragma("unroll") for (int k = 0; k < 2; ++k) dst[m][k] = *(const LAS bf16x8*)(lds + PG8_SA(b, h) + aoff + m * 2048 + k * 1024); } while (0)
; #define PG8_LDB(dst, b, h) do { _Pragma("unroll") for (int n = 0; n < 2; ++n) _Pragma("unroll") for (int k = 0; k < 2; ++k) dst[n][k] = *(const LAS bf16x8*)(lds + PG8_SB(b, h) + boff + n * 2048 + k * 1024); } while (0)
; #define PG8_WAIT_V(n) asm volatile("s_waitcnt vmcnt(" #n ")" ::: "memory")
; #define PG8_WAIT_L(n) asm volatile("s_waitcnt lgkmcnt(" #n ")" ::: "memory")
; #define PG8_BAR __builtin_amdgcn_s_barrier()
; #define PG8_SCHED __builtin_amdgcn_sched_barrier(0)
; template <int EK, int SK = -1>
; __device__ __forceinline__ void gemm_phase(LAS unsigned char* lds, const bf16_t* A, const bf16_t* Bt, int nM, int N, int K, const EpiArgs& E) {
;     ...
;         for (int t = 0; t < nt; t += 2) {
;             const bool last = (t == nt - 2);
;             const char* a1 = cA + (size_t)(t + 1) * kstep;
;             const char* a2 = last ? nA : cA + (size_t)(t + 2) * kstep; const char* b2 = last ? nB : cB + (size_t)(t + 2) * kstep;
;             const char* a3 = a2 + kstep; const char* b3 = b2 + kstep;
;             PG8_LDB(B0, 0, 0); PG8_LDB(B1, 0, 1); PG8_SCHED; PG8_LDA(At, 0, 0); PG8_STAGEA(PG8_SA(1, 1), a1 + hstep);
;             PG8_WAIT_V(8); PG8_WAIT_L(0); PG8_BAR; PG8_MMA(0, 0, At, B0); PG8_MMA(0, 1, At, B1); PG8_BAR; PG8_SCHED;
;             PG8_LDA(At, 0, 1); PG8_STAGEB(PG8_SB(0, 0), b2); PG8_STAGEB(PG8_SB(0, 1), b2 + hstep); PG8_STAGEA(PG8_SA(0, 0), a2);
;             PG8_WAIT_V(8); PG8_WAIT_L(0); PG8_BAR; PG8_MMA(1, 0, At, B0); PG8_MMA(1, 1, At, B1); PG8_BAR; PG8_SCHED;
;             PG8_LDB(B0, 1, 0); PG8_LDB(B1, 1, 1); PG8_SCHED; PG8_LDA(At, 1, 0); PG8_STAGEA(PG8_SA(0, 1), a2 + hstep);
;             PG8_WAIT_V(8); PG8_WAIT_L(0); PG8_BAR; PG8_MMA(0, 0, At, B0); PG8_MMA(0, 1, At, B1); PG8_BAR; PG8_SCHED;
;             PG8_LDA(At, 1, 1); PG8_STAGEB(PG8_SB(1, 0), b3); PG8_STAGEB(PG8_SB(1, 1), b3 + hstep); PG8_STAGEA(PG8_SA(1, 0), a3);
;             PG8_WAIT_V(8); PG8_WAIT_L(0); PG8_BAR; PG8_MMA(1, 0, At, B0); PG8_MMA(1, 1, At, B1); PG8_BAR; PG8_SCHED;
	s_add_i32 s46, s75, s52
	v_lshl_add_u64 v[150:151], v[150:151], 0, s[36:37]
	s_mov_b32 m0, s46
	ds_read_b128 v[188:191], v154 offset:49152
	ds_read_b128 v[192:195], v154 offset:50176
	ds_read_b128 v[196:199], v154 offset:51200
	ds_read_b128 v[200:203], v154 offset:52224
	ds_read_b128 v[204:207], v154 offset:53248
	ds_read_b128 v[208:211], v154 offset:54272
	ds_read_b128 v[212:215], v154 offset:55296
	ds_read_b128 v[216:219], v154 offset:56320
	global_load_lds_dwordx4 v[150:151], off
	s_add_i32 m0, s46, 0x2000
	s_add_u32 s44, s44, 0xb0080
	v_lshl_add_u64 v[150:151], v[220:221], 0, s[36:37]
	s_addc_u32 s45, s45, 0
	s_add_i32 s46, s76, s52
	global_load_lds_dwordx4 v[150:151], off
	v_lshl_add_u64 v[150:151], s[44:45], 0, v[132:133]
	s_mov_b32 m0, s46
	s_nop 0
	global_load_lds_dwordx4 v[150:151], off
	v_lshl_add_u64 v[150:151], s[44:45], 0, v[136:137]
	s_add_i32 m0, s46, 0x2000
	s_nop 0
	global_load_lds_dwordx4 v[150:151], off
	v_lshl_add_u64 v[150:151], v[222:223], 0, s[36:37]
	s_mov_b32 m0, s59
	s_nop 0
	global_load_lds_dwordx4 v[150:151], off
	v_lshl_add_u64 v[150:151], v[224:225], 0, s[36:37]
	s_mov_b32 m0, s66
	s_nop 0
	global_load_lds_dwordx4 v[150:151], off
	s_waitcnt vmcnt(8)
	s_waitcnt lgkmcnt(0)
	s_barrier
	s_waitcnt lgkmcnt(0)
	v_mfma_f32_16x16x32_bf16 v[62:65], v[156:159], v[188:191], v[62:65]
	v_mfma_f32_16x16x32_bf16 v[58:61], v[164:167], v[188:191], v[58:61]
	v_mfma_f32_16x16x32_bf16 v[50:53], v[164:167], v[196:199], v[50:53]
	v_mfma_f32_16x16x32_bf16 v[54:57], v[156:159], v[196:199], v[54:57]
	v_mfma_f32_16x16x32_bf16 v[46:49], v[156:159], v[204:207], v[46:49]
	v_mfma_f32_16x16x32_bf16 v[42:45], v[164:167], v[204:207], v[42:45]
	v_mfma_f32_16x16x32_bf16 v[34:37], v[164:167], v[212:215], v[34:37]
	v_mfma_f32_16x16x32_bf16 v[38:41], v[156:159], v[212:215], v[38:41]
	v_mfma_f32_16x16x32_bf16 v[62:65], v[160:163], v[192:195], v[62:65]
	v_mfma_f32_16x16x32_bf16 v[58:61], v[168:171], v[192:195], v[58:61]
	v_mfma_f32_16x16x32_bf16 v[50:53], v[168:171], v[200:203], v[50:53]
	v_mfma_f32_16x16x32_bf16 v[54:57], v[160:163], v[200:203], v[54:57]
	v_mfma_f32_16x16x32_bf16 v[46:49], v[160:163], v[208:211], v[46:49]
	v_mfma_f32_16x16x32_bf16 v[42:45], v[168:171], v[208:211], v[42:45]
	v_mfma_f32_16x16x32_bf16 v[34:37], v[168:171], v[216:219], v[34:37]
	v_mfma_f32_16x16x32_bf16 v[38:41], v[160:163], v[216:219], v[38:41]
	v_mfma_f32_16x16x32_bf16 v[30:33], v[172:175], v[188:191], v[30:33]
	v_mfma_f32_16x16x32_bf16 v[26:29], v[180:183], v[188:191], v[26:29]
	v_mfma_f32_16x16x32_bf16 v[18:21], v[180:183], v[196:199], v[18:21]
	v_mfma_f32_16x16x32_bf16 v[22:25], v[172:175], v[196:199], v[22:25]
	v_mfma_f32_16x16x32_bf16 v[14:17], v[172:175], v[204:207], v[14:17]
	v_mfma_f32_16x16x32_bf16 v[10:13], v[180:183], v[204:207], v[10:13]
	v_mfma_f32_16x16x32_bf16 v[2:5], v[180:183], v[212:215], v[2:5]
	v_mfma_f32_16x16x32_bf16 v[6:9], v[172:175], v[212:215], v[6:9]
	v_mfma_f32_16x16x32_bf16 v[30:33], v[176:179], v[192:195], v[30:33]
	v_mfma_f32_16x16x32_bf16 v[26:29], v[184:187], v[192:195], v[26:29]
	v_mfma_f32_16x16x32_bf16 v[18:21], v[184:187], v[200:203], v[18:21]
	v_mfma_f32_16x16x32_bf16 v[22:25], v[176:179], v[200:203], v[22:25]
	v_mfma_f32_16x16x32_bf16 v[14:17], v[176:179], v[208:211], v[14:17]
	v_mfma_f32_16x16x32_bf16 v[10:13], v[184:187], v[208:211], v[10:13]
	v_mfma_f32_16x16x32_bf16 v[2:5], v[184:187], v[216:219], v[2:5]
	v_mfma_f32_16x16x32_bf16 v[6:9], v[176:179], v[216:219], v[6:9]
	s_barrier
	s_add_i32 s26, s26, 2
	s_add_u32 s42, s42, 0x100
	s_addc_u32 s43, s43, 0
	s_cmp_gt_u32 s26, 41
	s_cbranch_scc0 .LBB0_1338
	s_branch .Lmy_kexit_7
.LBB0_1338:
	v_add_u32_e32 v150, s67, v152
	ds_read_b128 v[156:159], v150
	ds_read_b128 v[160:163], v150 offset:1024
	ds_read_b128 v[164:167], v150 offset:2048
	ds_read_b128 v[168:171], v150 offset:3072
	v_add_u32_e32 v150, s68, v152
	s_add_u32 s44, s20, s42
	ds_read_b128 v[172:175], v150
	ds_read_b128 v[176:179], v150 offset:1024
	ds_read_b128 v[180:183], v150 offset:2048
	ds_read_b128 v[184:187], v150 offset:3072
	s_addc_u32 s45, s21, s43
	s_add_u32 s44, s44, 0x100
	s_addc_u32 s45, s45, 0
	s_add_u32 s75, s73, s42
	s_addc_u32 s76, s74, s43
	s_cmpk_eq_i32 s42, 0x1500
	s_cselect_b32 s47, s41, s45
	s_cselect_b32 s46, s40, s44
	s_cselect_b32 s45, s9, s76
	s_cselect_b32 s44, s8, s75
	v_lshl_add_u64 v[150:151], v[146:147], 0, s[42:43]
	s_add_i32 m0, s53, 0xc000
	ds_read_b128 v[188:191], v154
	ds_read_b128 v[192:195], v154 offset:1024
	ds_read_b128 v[196:199], v154 offset:2048
	ds_read_b128 v[200:203], v154 offset:3072
	ds_read_b128 v[204:207], v154 offset:4096
	ds_read_b128 v[208:211], v154 offset:5120
	ds_read_b128 v[212:215], v154 offset:6144
	ds_read_b128 v[216:219], v154 offset:7168
	global_load_lds_dwordx4 v[150:151], off
	v_lshl_add_u64 v[150:151], v[148:149], 0, s[42:43]
	s_add_i32 m0, s53, 0xe000
	s_nop 0
	global_load_lds_dwordx4 v[150:151], off
	s_waitcnt vmcnt(8)
	s_waitcnt lgkmcnt(0)
	s_barrier
; #define PG8_STAGEA(bufoff, gbase) PG8_STAGE_(bufoff, gbase, voffA)
; #define PG8_STAGEB(bufoff, gbase) PG8_STAGE_(bufoff, gbase, voffB)
; #define PG8_LDA(dst, b, h) do { _Pragma("unroll") for (int m = 0; m < 4; ++m) _Pragma("unroll") for (int k = 0; k < 2; ++k) dst[m][k] = *(const LAS bf16x8*)(lds + PG8_SA(b, h) + aoff + m * 2048 + k * 1024); } while (0)
; #define PG8_MMA(ai, bj, At, Bt_) do { __builtin_amdgcn_s_setprio(1); _Pragma("unroll") for (int m = 0; m < 4; ++m) _Pragma("unroll") for (int n = 0; n < 2; ++n) _Pragma("unroll") for (int k = 0; k < 2; ++k) \
;         acc[ai][bj][m][n] = __builtin_amdgcn_mfma_f32_16x16x32_bf16(Bt_[n][k], At[m][k], acc[ai][bj][m][n], 0, 0, 0); __builtin_amdgcn_s_setprio(0); } while (0)
; #define PG8_WAIT_V(n) asm volatile("s_waitcnt vmcnt(" #n ")" ::: "memory")
; #define PG8_WAIT_L(n) asm volatile("s_waitcnt lgkmcnt(" #n ")" ::: "memory")
; #define PG8_BAR __builtin_amdgcn_s_barrier()
; #define PG8_SCHED __builtin_amdgcn_sched_barrier(0)
; template <int EK, int SK = -1>
; __device__ __forceinline__ void gemm_phase(LAS unsigned char* lds, const bf16_t* A, const bf16_t* Bt, int nM, int N, int K, const EpiArgs& E) {
;     ...
;             PG8_WAIT_V(8); PG8_WAIT_L(0); PG8_BAR; PG8_MMA(0, 0, At, B0); PG8_MMA(0, 1, At, B1); PG8_BAR; PG8_SCHED;
;             PG8_LDA(At, 0, 1); PG8_STAGEB(PG8_SB(0, 0), b2); PG8_STAGEB(PG8_SB(0, 1), b2 + hstep); PG8_STAGEA(PG8_SA(0, 0), a2);
;             PG8_WAIT_V(8); PG8_WAIT_L(0); PG8_BAR; PG8_MMA(1, 0, At, B0); PG8_MMA(1, 1, At, B1); PG8_BAR; PG8_SCHED;
	s_waitcnt lgkmcnt(0)
	v_mfma_f32_16x16x32_bf16 v[126:129], v[156:159], v[188:191], v[126:129]
	v_mfma_f32_16x16x32_bf16 v[122:125], v[164:167], v[188:191], v[122:125]
	v_mfma_f32_16x16x32_bf16 v[114:117], v[164:167], v[196:199], v[114:117]
	v_mfma_f32_16x16x32_bf16 v[118:121], v[156:159], v[196:199], v[118:121]
	v_mfma_f32_16x16x32_bf16 v[110:113], v[156:159], v[204:207], v[110:113]
	v_mfma_f32_16x16x32_bf16 v[106:109], v[164:167], v[204:207], v[106:109]
	v_mfma_f32_16x16x32_bf16 v[98:101], v[164:167], v[212:215], v[98:101]
	v_mfma_f32_16x16x32_bf16 v[102:105], v[156:159], v[212:215], v[102:105]
	v_mfma_f32_16x16x32_bf16 v[126:129], v[160:163], v[192:195], v[126:129]
	v_mfma_f32_16x16x32_bf16 v[122:125], v[168:171], v[192:195], v[122:125]
	v_mfma_f32_16x16x32_bf16 v[114:117], v[168:171], v[200:203], v[114:117]
	v_mfma_f32_16x16x32_bf16 v[118:121], v[160:163], v[200:203], v[118:121]
	v_mfma_f32_16x16x32_bf16 v[110:113], v[160:163], v[208:211], v[110:113]
	v_mfma_f32_16x16x32_bf16 v[106:109], v[168:171], v[208:211], v[106:109]
	v_mfma_f32_16x16x32_bf16 v[98:101], v[168:171], v[216:219], v[98:101]
	v_mfma_f32_16x16x32_bf16 v[102:105], v[160:163], v[216:219], v[102:105]
	v_mfma_f32_16x16x32_bf16 v[94:97], v[172:175], v[188:191], v[94:97]
	v_mfma_f32_16x16x32_bf16 v[90:93], v[180:183], v[188:191], v[90:93]
	v_mfma_f32_16x16x32_bf16 v[82:85], v[180:183], v[196:199], v[82:85]
	v_mfma_f32_16x16x32_bf16 v[86:89], v[172:175], v[196:199], v[86:89]
	v_mfma_f32_16x16x32_bf16 v[78:81], v[172:175], v[204:207], v[78:81]
	v_mfma_f32_16x16x32_bf16 v[74:77], v[180:183], v[204:207], v[74:77]
	v_mfma_f32_16x16x32_bf16 v[66:69], v[180:183], v[212:215], v[66:69]
	v_mfma_f32_16x16x32_bf16 v[70:73], v[172:175], v[212:215], v[70:73]
	v_mfma_f32_16x16x32_bf16 v[94:97], v[176:179], v[192:195], v[94:97]
	v_mfma_f32_16x16x32_bf16 v[90:93], v[184:187], v[192:195], v[90:93]
	v_mfma_f32_16x16x32_bf16 v[82:85], v[184:187], v[200:203], v[82:85]
	v_mfma_f32_16x16x32_bf16 v[86:89], v[176:179], v[200:203], v[86:89]
	v_mfma_f32_16x16x32_bf16 v[78:81], v[176:179], v[208:211], v[78:81]
	v_mfma_f32_16x16x32_bf16 v[74:77], v[184:187], v[208:211], v[74:77]
	v_mfma_f32_16x16x32_bf16 v[66:69], v[184:187], v[216:219], v[66:69]
	v_mfma_f32_16x16x32_bf16 v[70:73], v[176:179], v[216:219], v[70:73]
	s_barrier
	s_add_i32 s75, s67, s52
	v_lshl_add_u64 v[150:151], s[44:45], 0, v[132:133]
	s_mov_b32 m0, s75
	ds_read_b128 v[188:191], v154 offset:16384
	ds_read_b128 v[192:195], v154 offset:17408
	ds_read_b128 v[196:199], v154 offset:18432
	ds_read_b128 v[200:203], v154 offset:19456
	ds_read_b128 v[204:207], v154 offset:20480
	ds_read_b128 v[208:211], v154 offset:21504
	ds_read_b128 v[212:215], v154 offset:22528
	ds_read_b128 v[216:219], v154 offset:23552
	global_load_lds_dwordx4 v[150:151], off
	s_add_i32 m0, s75, 0x2000
	s_add_u32 s76, s44, 0xb0000
	v_lshl_add_u64 v[220:221], s[44:45], 0, v[136:137]
	s_addc_u32 s77, s45, 0
	s_add_i32 s75, s68, s52
	global_load_lds_dwordx4 v[220:221], off
	v_lshl_add_u64 v[222:223], s[76:77], 0, v[132:133]
	s_mov_b32 m0, s75
	v_lshl_add_u64 v[224:225], s[46:47], 0, v[134:135]
	global_load_lds_dwordx4 v[222:223], off
	v_lshl_add_u64 v[222:223], s[76:77], 0, v[136:137]
	s_add_i32 m0, s75, 0x2000
	s_nop 0
	global_load_lds_dwordx4 v[222:223], off
	v_lshl_add_u64 v[222:223], s[46:47], 0, v[130:131]
	s_mov_b32 m0, s53
	s_nop 0
	global_load_lds_dwordx4 v[222:223], off
	s_mov_b32 m0, s54
	s_nop 0
	global_load_lds_dwordx4 v[224:225], off
	s_waitcnt vmcnt(8)
	s_waitcnt lgkmcnt(0)
	s_barrier
	s_waitcnt lgkmcnt(0)
	v_mfma_f32_16x16x32_bf16 v[62:65], v[156:159], v[188:191], v[62:65]
	v_mfma_f32_16x16x32_bf16 v[58:61], v[164:167], v[188:191], v[58:61]
	v_mfma_f32_16x16x32_bf16 v[50:53], v[164:167], v[196:199], v[50:53]
	v_mfma_f32_16x16x32_bf16 v[54:57], v[156:159], v[196:199], v[54:57]
	v_mfma_f32_16x16x32_bf16 v[46:49], v[156:159], v[204:207], v[46:49]
	v_mfma_f32_16x16x32_bf16 v[42:45], v[164:167], v[204:207], v[42:45]
	v_mfma_f32_16x16x32_bf16 v[34:37], v[164:167], v[212:215], v[34:37]
	v_mfma_f32_16x16x32_bf16 v[38:41], v[156:159], v[212:215], v[38:41]
	v_mfma_f32_16x16x32_bf16 v[62:65], v[160:163], v[192:195], v[62:65]
	v_mfma_f32_16x16x32_bf16 v[58:61], v[168:171], v[192:195], v[58:61]
	v_mfma_f32_16x16x32_bf16 v[50:53], v[168:171], v[200:203], v[50:53]
	v_mfma_f32_16x16x32_bf16 v[54:57], v[160:163], v[200:203], v[54:57]
	v_mfma_f32_16x16x32_bf16 v[46:49], v[160:163], v[208:211], v[46:49]
	v_mfma_f32_16x16x32_bf16 v[42:45], v[168:171], v[208:211], v[42:45]
	v_mfma_f32_16x16x32_bf16 v[34:37], v[168:171], v[216:219], v[34:37]
	v_mfma_f32_16x16x32_bf16 v[38:41], v[160:163], v[216:219], v[38:41]
	v_mfma_f32_16x16x32_bf16 v[30:33], v[172:175], v[188:191], v[30:33]
	v_mfma_f32_16x16x32_bf16 v[26:29], v[180:183], v[188:191], v[26:29]
	v_mfma_f32_16x16x32_bf16 v[18:21], v[180:183], v[196:199], v[18:21]
	v_mfma_f32_16x16x32_bf16 v[22:25], v[172:175], v[196:199], v[22:25]
	v_mfma_f32_16x16x32_bf16 v[14:17], v[172:175], v[204:207], v[14:17]
	v_mfma_f32_16x16x32_bf16 v[10:13], v[180:183], v[204:207], v[10:13]
	v_mfma_f32_16x16x32_bf16 v[2:5], v[180:183], v[212:215], v[2:5]
	v_mfma_f32_16x16x32_bf16 v[6:9], v[172:175], v[212:215], v[6:9]
	v_mfma_f32_16x16x32_bf16 v[30:33], v[176:179], v[192:195], v[30:33]
	v_mfma_f32_16x16x32_bf16 v[26:29], v[184:187], v[192:195], v[26:29]
	v_mfma_f32_16x16x32_bf16 v[18:21], v[184:187], v[200:203], v[18:21]
	v_mfma_f32_16x16x32_bf16 v[22:25], v[176:179], v[200:203], v[22:25]
	v_mfma_f32_16x16x32_bf16 v[14:17], v[176:179], v[208:211], v[14:17]
	v_mfma_f32_16x16x32_bf16 v[10:13], v[184:187], v[208:211], v[10:13]
	v_mfma_f32_16x16x32_bf16 v[2:5], v[184:187], v[216:219], v[2:5]
	v_mfma_f32_16x16x32_bf16 v[6:9], v[176:179], v[216:219], v[6:9]
	s_barrier
; #define PG8_STAGEA(bufoff, gbase) PG8_STAGE_(bufoff, gbase, voffA)
; #define PG8_STAGEB(bufoff, gbase) PG8_STAGE_(bufoff, gbase, voffB)
; #define PG8_LDA(dst, b, h) do { _Pragma("unroll") for (int m = 0; m < 4; ++m) _Pragma("unroll") for (int k = 0; k < 2; ++k) dst[m][k] = *(const LAS bf16x8*)(lds + PG8_SA(b, h) + aoff + m * 2048 + k * 1024); } while (0)
; #define PG8_LDB(dst, b, h) do { _Pragma("unroll") for (int n = 0; n < 2; ++n) _Pragma("unroll") for (int k = 0; k < 2; ++k) dst[n][k] = *(const LAS bf16x8*)(lds + PG8_SB(b, h) + boff + n * 2048 + k * 1024); } while (0)
; #define PG8_MMA(ai, bj, At, Bt_) do { __builtin_amdgcn_s_setprio(1); _Pragma("unroll") for (int m = 0; m < 4; ++m) _Pragma("unroll") for (int n = 0; n < 2; ++n) _Pragma("unroll") for (int k = 0; k < 2; ++k) \
;         acc[ai][bj][m][n] = __builtin_amdgcn_mfma_f32_16x16x32_bf16(Bt_[n][k], At[m][k], acc[ai][bj][m][n], 0, 0, 0); __builtin_amdgcn_s_setprio(0); } while (0)
; #define PG8_WAIT_V(n) asm volatile("s_waitcnt vmcnt(" #n ")" ::: "memory")
; #define PG8_WAIT_L(n) asm volatile("s_waitcnt lgkmcnt(" #n ")" ::: "memory")
; #define PG8_BAR __builtin_amdgcn_s_barrier()
; #define PG8_SCHED __builtin_amdgcn_sched_barrier(0)
; template <int EK, int SK = -1>
; __device__ __forceinline__ void gemm_phase(LAS unsigned char* lds, const bf16_t* A, const bf16_t* Bt, int nM, int N, int K, const EpiArgs& E) {
;     ...
;             PG8_LDB(B0, 1, 0); PG8_LDB(B1, 1, 1); PG8_SCHED; PG8_LDA(At, 1, 0); PG8_STAGEA(PG8_SA(0, 1), a2 + hstep);
;             PG8_WAIT_V(8); PG8_WAIT_L(0); PG8_BAR; PG8_MMA(0, 0, At, B0); PG8_MMA(0, 1, At, B1); PG8_BAR; PG8_SCHED;
;             PG8_LDA(At, 1, 1); PG8_STAGEB(PG8_SB(1, 0), b3); PG8_STAGEB(PG8_SB(1, 1), b3 + hstep); PG8_STAGEA(PG8_SA(1, 0), a3);
;             PG8_WAIT_V(8); PG8_WAIT_L(0); PG8_BAR; PG8_MMA(1, 0, At, B0); PG8_MMA(1, 1, At, B1); PG8_BAR; PG8_SCHED;
;         }
	s_add_i32 s75, 0, 0x18000
	s_add_i32 s76, 0, 0x1c000
	v_add_u32_e32 v168, s75, v152
	v_add_u32_e32 v184, s76, v152
	ds_read_b128 v[156:159], v168
	ds_read_b128 v[160:163], v168 offset:1024
	ds_read_b128 v[164:167], v168 offset:2048
	ds_read_b128 v[168:171], v168 offset:3072
	ds_read_b128 v[172:175], v184
	ds_read_b128 v[176:179], v184 offset:1024
	ds_read_b128 v[180:183], v184 offset:2048
	ds_read_b128 v[184:187], v184 offset:3072
	s_add_u32 s46, s46, 0xb0000
	s_addc_u32 s47, s47, 0
	s_mov_b32 m0, s55
	v_lshl_add_u64 v[226:227], s[46:47], 0, v[130:131]
	ds_read_b128 v[188:191], v154 offset:32768
	ds_read_b128 v[192:195], v154 offset:33792
	ds_read_b128 v[196:199], v154 offset:34816
	ds_read_b128 v[200:203], v154 offset:35840
	ds_read_b128 v[204:207], v154 offset:36864
	ds_read_b128 v[208:211], v154 offset:37888
	ds_read_b128 v[212:215], v154 offset:38912
	ds_read_b128 v[216:219], v154 offset:39936
	global_load_lds_dwordx4 v[226:227], off
	v_lshl_add_u64 v[226:227], s[46:47], 0, v[134:135]
	s_mov_b32 m0, s56
	s_nop 0
	global_load_lds_dwordx4 v[226:227], off
	s_waitcnt vmcnt(8)
	s_waitcnt lgkmcnt(0)
	s_barrier
	s_waitcnt lgkmcnt(0)
	v_mfma_f32_16x16x32_bf16 v[126:129], v[156:159], v[188:191], v[126:129]
	v_mfma_f32_16x16x32_bf16 v[122:125], v[164:167], v[188:191], v[122:125]
	v_mfma_f32_16x16x32_bf16 v[114:117], v[164:167], v[196:199], v[114:117]
	v_mfma_f32_16x16x32_bf16 v[118:121], v[156:159], v[196:199], v[118:121]
	v_mfma_f32_16x16x32_bf16 v[110:113], v[156:159], v[204:207], v[110:113]
	v_mfma_f32_16x16x32_bf16 v[106:109], v[164:167], v[204:207], v[106:109]
	v_mfma_f32_16x16x32_bf16 v[98:101], v[164:167], v[212:215], v[98:101]
	v_mfma_f32_16x16x32_bf16 v[102:105], v[156:159], v[212:215], v[102:105]
	v_mfma_f32_16x16x32_bf16 v[126:129], v[160:163], v[192:195], v[126:129]
	v_mfma_f32_16x16x32_bf16 v[122:125], v[168:171], v[192:195], v[122:125]
	v_mfma_f32_16x16x32_bf16 v[114:117], v[168:171], v[200:203], v[114:117]
	v_mfma_f32_16x16x32_bf16 v[118:121], v[160:163], v[200:203], v[118:121]
	v_mfma_f32_16x16x32_bf16 v[110:113], v[160:163], v[208:211], v[110:113]
	v_mfma_f32_16x16x32_bf16 v[106:109], v[168:171], v[208:211], v[106:109]
	v_mfma_f32_16x16x32_bf16 v[98:101], v[168:171], v[216:219], v[98:101]
	v_mfma_f32_16x16x32_bf16 v[102:105], v[160:163], v[216:219], v[102:105]
	v_mfma_f32_16x16x32_bf16 v[94:97], v[172:175], v[188:191], v[94:97]
	v_mfma_f32_16x16x32_bf16 v[90:93], v[180:183], v[188:191], v[90:93]
	v_mfma_f32_16x16x32_bf16 v[82:85], v[180:183], v[196:199], v[82:85]
	v_mfma_f32_16x16x32_bf16 v[86:89], v[172:175], v[196:199], v[86:89]
	v_mfma_f32_16x16x32_bf16 v[78:81], v[172:175], v[204:207], v[78:81]
	v_mfma_f32_16x16x32_bf16 v[74:77], v[180:183], v[204:207], v[74:77]
	v_mfma_f32_16x16x32_bf16 v[66:69], v[180:183], v[212:215], v[66:69]
	v_mfma_f32_16x16x32_bf16 v[70:73], v[172:175], v[212:215], v[70:73]
	v_mfma_f32_16x16x32_bf16 v[94:97], v[176:179], v[192:195], v[94:97]
	v_mfma_f32_16x16x32_bf16 v[90:93], v[184:187], v[192:195], v[90:93]
	v_mfma_f32_16x16x32_bf16 v[82:85], v[184:187], v[200:203], v[82:85]
	v_mfma_f32_16x16x32_bf16 v[86:89], v[176:179], v[200:203], v[86:89]
	v_mfma_f32_16x16x32_bf16 v[78:81], v[176:179], v[208:211], v[78:81]
	v_mfma_f32_16x16x32_bf16 v[74:77], v[184:187], v[208:211], v[74:77]
	v_mfma_f32_16x16x32_bf16 v[66:69], v[184:187], v[216:219], v[66:69]
	v_mfma_f32_16x16x32_bf16 v[70:73], v[176:179], v[216:219], v[70:73]
	s_barrier
	s_add_i32 s46, s75, s52
	v_lshl_add_u64 v[150:151], v[150:151], 0, s[36:37]
	s_mov_b32 m0, s46
	ds_read_b128 v[188:191], v154 offset:49152
	ds_read_b128 v[192:195], v154 offset:50176
	ds_read_b128 v[196:199], v154 offset:51200
	ds_read_b128 v[200:203], v154 offset:52224
	ds_read_b128 v[204:207], v154 offset:53248
	ds_read_b128 v[208:211], v154 offset:54272
	ds_read_b128 v[212:215], v154 offset:55296
	ds_read_b128 v[216:219], v154 offset:56320
	global_load_lds_dwordx4 v[150:151], off
	s_add_i32 m0, s46, 0x2000
	s_add_u32 s44, s44, 0xb0080
	v_lshl_add_u64 v[150:151], v[220:221], 0, s[36:37]
	s_addc_u32 s45, s45, 0
	s_add_i32 s46, s76, s52
	global_load_lds_dwordx4 v[150:151], off
	v_lshl_add_u64 v[150:151], s[44:45], 0, v[132:133]
	s_mov_b32 m0, s46
	s_nop 0
	global_load_lds_dwordx4 v[150:151], off
	v_lshl_add_u64 v[150:151], s[44:45], 0, v[136:137]
	s_add_i32 m0, s46, 0x2000
	s_nop 0
	global_load_lds_dwordx4 v[150:151], off
	v_lshl_add_u64 v[150:151], v[222:223], 0, s[36:37]
	s_mov_b32 m0, s59
	s_nop 0
	global_load_lds_dwordx4 v[150:151], off
	v_lshl_add_u64 v[150:151], v[224:225], 0, s[36:37]
	s_mov_b32 m0, s66
	s_nop 0
	global_load_lds_dwordx4 v[150:151], off
	s_waitcnt vmcnt(8)
	s_waitcnt lgkmcnt(0)
	s_barrier
	s_waitcnt lgkmcnt(0)
	v_mfma_f32_16x16x32_bf16 v[62:65], v[156:159], v[188:191], v[62:65]
	v_mfma_f32_16x16x32_bf16 v[58:61], v[164:167], v[188:191], v[58:61]
	v_mfma_f32_16x16x32_bf16 v[50:53], v[164:167], v[196:199], v[50:53]
	v_mfma_f32_16x16x32_bf16 v[54:57], v[156:159], v[196:199], v[54:57]
	v_mfma_f32_16x16x32_bf16 v[46:49], v[156:159], v[204:207], v[46:49]
	v_mfma_f32_16x16x32_bf16 v[42:45], v[164:167], v[204:207], v[42:45]
	v_mfma_f32_16x16x32_bf16 v[34:37], v[164:167], v[212:215], v[34:37]
	v_mfma_f32_16x16x32_bf16 v[38:41], v[156:159], v[212:215], v[38:41]
	v_mfma_f32_16x16x32_bf16 v[62:65], v[160:163], v[192:195], v[62:65]
	v_mfma_f32_16x16x32_bf16 v[58:61], v[168:171], v[192:195], v[58:61]
	v_mfma_f32_16x16x32_bf16 v[50:53], v[168:171], v[200:203], v[50:53]
	v_mfma_f32_16x16x32_bf16 v[54:57], v[160:163], v[200:203], v[54:57]
	v_mfma_f32_16x16x32_bf16 v[46:49], v[160:163], v[208:211], v[46:49]
	v_mfma_f32_16x16x32_bf16 v[42:45], v[168:171], v[208:211], v[42:45]
	v_mfma_f32_16x16x32_bf16 v[34:37], v[168:171], v[216:219], v[34:37]
	v_mfma_f32_16x16x32_bf16 v[38:41], v[160:163], v[216:219], v[38:41]
	v_mfma_f32_16x16x32_bf16 v[30:33], v[172:175], v[188:191], v[30:33]
	v_mfma_f32_16x16x32_bf16 v[26:29], v[180:183], v[188:191], v[26:29]
	v_mfma_f32_16x16x32_bf16 v[18:21], v[180:183], v[196:199], v[18:21]
	v_mfma_f32_16x16x32_bf16 v[22:25], v[172:175], v[196:199], v[22:25]
	v_mfma_f32_16x16x32_bf16 v[14:17], v[172:175], v[204:207], v[14:17]
	v_mfma_f32_16x16x32_bf16 v[10:13], v[180:183], v[204:207], v[10:13]
	v_mfma_f32_16x16x32_bf16 v[2:5], v[180:183], v[212:215], v[2:5]
	v_mfma_f32_16x16x32_bf16 v[6:9], v[172:175], v[212:215], v[6:9]
	v_mfma_f32_16x16x32_bf16 v[30:33], v[176:179], v[192:195], v[30:33]
	v_mfma_f32_16x16x32_bf16 v[26:29], v[184:187], v[192:195], v[26:29]
	v_mfma_f32_16x16x32_bf16 v[18:21], v[184:187], v[200:203], v[18:21]
	v_mfma_f32_16x16x32_bf16 v[22:25], v[176:179], v[200:203], v[22:25]
	v_mfma_f32_16x16x32_bf16 v[14:17], v[176:179], v[208:211], v[14:17]
	v_mfma_f32_16x16x32_bf16 v[10:13], v[184:187], v[208:211], v[10:13]
	v_mfma_f32_16x16x32_bf16 v[2:5], v[184:187], v[216:219], v[2:5]
	v_mfma_f32_16x16x32_bf16 v[6:9], v[176:179], v[216:219], v[6:9]
	s_barrier
	s_add_i32 s26, s26, 2
	s_add_u32 s42, s42, 0x100
	s_addc_u32 s43, s43, 0
	s_cmp_gt_u32 s26, 41
	s_cbranch_scc0 .LBB0_1338

; #define PG8_STAGEA(bufoff, gbase) PG8_STAGE_(bufoff, gbase, voffA)
; #define PG8_STAGEB(bufoff, gbase) PG8_STAGE_(bufoff, gbase, voffB)
; #define PG8_LDA(dst, b, h) do { _Pragma("unroll") for (int m = 0; m < 4; ++m) _Pragma("unroll") for (int k = 0; k < 2; ++k) dst[m][k] = *(const LAS bf16x8*)(lds + PG8_SA(b, h) + aoff + m * 2048 + k * 1024); } while (0)
; #define PG8_LDB(dst, b, h) do { _Pragma("unroll") for (int n = 0; n < 2; ++n) _Pragma("unroll") for (int k = 0; k < 2; ++k) dst[n][k] = *(const LAS bf16x8*)(lds + PG8_SB(b, h) + boff + n * 2048 + k * 1024); } while (0)
; #define PG8_MMA(ai, bj, At, Bt_) do { __builtin_amdgcn_s_setprio(1); _Pragma("unroll") for (int m = 0; m < 4; ++m) _Pragma("unroll") for (int n = 0; n < 2; ++n) _Pragma("unroll") for (int k = 0; k < 2; ++k) \
;         acc[ai][bj][m][n] = __builtin_amdgcn_mfma_f32_16x16x32_bf16(Bt_[n][k], At[m][k], acc[ai][bj][m][n], 0, 0, 0); __builtin_amdgcn_s_setprio(0); } while (0)
; #define PG8_WAIT_V(n) asm volatile("s_waitcnt vmcnt(" #n ")" ::: "memory")
; #define PG8_WAIT_L(n) asm volatile("s_waitcnt lgkmcnt(" #n ")" ::: "memory")
; #define PG8_BAR __builtin_amdgcn_s_barrier()
; #define PG8_SCHED __builtin_amdgcn_sched_barrier(0)
; template <int EK, int SK = -1>
; __device__ __forceinline__ void gemm_phase(LAS unsigned char* lds, const bf16_t* A, const bf16_t* Bt, int nM, int N, int K, const EpiArgs& E) {
;     ...
;             PG8_LDB(B0, 0, 0); PG8_LDB(B1, 0, 1); PG8_SCHED; PG8_LDA(At, 0, 0); PG8_STAGEA(PG8_SA(1, 1), a1 + hstep);
;             PG8_WAIT_V(8); PG8_WAIT_L(0); PG8_BAR; PG8_MMA(0, 0, At, B0); PG8_MMA(0, 1, At, B1); PG8_BAR; PG8_SCHED;
;             PG8_LDA(At, 0, 1); PG8_STAGEB(PG8_SB(0, 0), b2); PG8_STAGEB(PG8_SB(0, 1), b2 + hstep); PG8_STAGEA(PG8_SA(0, 0), a2);
.LBB0_1401:
	v_add_u32_e32 v168, s66, v154
	v_add_u32_e32 v184, s67, v154
	s_add_u32 s42, s20, s40
	ds_read_b128 v[156:159], v168
	ds_read_b128 v[160:163], v168 offset:1024
	ds_read_b128 v[164:167], v168 offset:2048
	ds_read_b128 v[168:171], v168 offset:3072
	ds_read_b128 v[172:175], v184
	ds_read_b128 v[176:179], v184 offset:1024
	ds_read_b128 v[180:183], v184 offset:2048
	ds_read_b128 v[184:187], v184 offset:3072
	s_addc_u32 s43, s21, s41
	s_add_u32 s42, s42, 0x100
	s_addc_u32 s43, s43, 0
	s_add_u32 s73, s37, s40
	s_addc_u32 s74, s71, s41
	s_cmpk_eq_i32 s40, 0x1500
	s_cselect_b32 s45, s7, s43
	s_cselect_b32 s44, s6, s42
	s_cselect_b32 s43, s39, s74
	s_cselect_b32 s42, s38, s73
	v_lshl_add_u64 v[220:221], v[146:147], 0, s[40:41]
	s_add_i32 m0, s53, 0xc000
	ds_read_b128 v[188:191], v155
	ds_read_b128 v[192:195], v155 offset:1024
	ds_read_b128 v[196:199], v155 offset:2048
	ds_read_b128 v[200:203], v155 offset:3072
	ds_read_b128 v[204:207], v155 offset:4096
	ds_read_b128 v[208:211], v155 offset:5120
	ds_read_b128 v[212:215], v155 offset:6144
	ds_read_b128 v[216:219], v155 offset:7168
	global_load_lds_dwordx4 v[220:221], off
	v_lshl_add_u64 v[220:221], v[148:149], 0, s[40:41]
	s_add_i32 m0, s53, 0xe000
	s_nop 0
	global_load_lds_dwordx4 v[220:221], off
	s_waitcnt vmcnt(8)
	s_waitcnt lgkmcnt(0)
	s_barrier
	s_waitcnt lgkmcnt(0)
	v_mfma_f32_16x16x32_bf16 v[126:129], v[156:159], v[188:191], v[126:129]
	v_mfma_f32_16x16x32_bf16 v[122:125], v[164:167], v[188:191], v[122:125]
	v_mfma_f32_16x16x32_bf16 v[106:109], v[164:167], v[196:199], v[106:109]
	v_mfma_f32_16x16x32_bf16 v[110:113], v[156:159], v[196:199], v[110:113]
	v_mfma_f32_16x16x32_bf16 v[94:97], v[156:159], v[204:207], v[94:97]
	v_mfma_f32_16x16x32_bf16 v[90:93], v[164:167], v[204:207], v[90:93]
	v_mfma_f32_16x16x32_bf16 v[74:77], v[164:167], v[212:215], v[74:77]
	v_mfma_f32_16x16x32_bf16 v[78:81], v[156:159], v[212:215], v[78:81]
	v_mfma_f32_16x16x32_bf16 v[126:129], v[160:163], v[192:195], v[126:129]
	v_mfma_f32_16x16x32_bf16 v[122:125], v[168:171], v[192:195], v[122:125]
	v_mfma_f32_16x16x32_bf16 v[106:109], v[168:171], v[200:203], v[106:109]
	v_mfma_f32_16x16x32_bf16 v[110:113], v[160:163], v[200:203], v[110:113]
	v_mfma_f32_16x16x32_bf16 v[94:97], v[160:163], v[208:211], v[94:97]
	v_mfma_f32_16x16x32_bf16 v[90:93], v[168:171], v[208:211], v[90:93]
	v_mfma_f32_16x16x32_bf16 v[74:77], v[168:171], v[216:219], v[74:77]
	v_mfma_f32_16x16x32_bf16 v[78:81], v[160:163], v[216:219], v[78:81]
	v_mfma_f32_16x16x32_bf16 v[118:121], v[172:175], v[188:191], v[118:121]
	v_mfma_f32_16x16x32_bf16 v[114:117], v[180:183], v[188:191], v[114:117]
	v_mfma_f32_16x16x32_bf16 v[98:101], v[180:183], v[196:199], v[98:101]
	v_mfma_f32_16x16x32_bf16 v[102:105], v[172:175], v[196:199], v[102:105]
	v_mfma_f32_16x16x32_bf16 v[86:89], v[172:175], v[204:207], v[86:89]
	v_mfma_f32_16x16x32_bf16 v[82:85], v[180:183], v[204:207], v[82:85]
	v_mfma_f32_16x16x32_bf16 v[66:69], v[180:183], v[212:215], v[66:69]
	v_mfma_f32_16x16x32_bf16 v[70:73], v[172:175], v[212:215], v[70:73]
	v_mfma_f32_16x16x32_bf16 v[118:121], v[176:179], v[192:195], v[118:121]
	v_mfma_f32_16x16x32_bf16 v[114:117], v[184:187], v[192:195], v[114:117]
	v_mfma_f32_16x16x32_bf16 v[98:101], v[184:187], v[200:203], v[98:101]
	v_mfma_f32_16x16x32_bf16 v[102:105], v[176:179], v[200:203], v[102:105]
	v_mfma_f32_16x16x32_bf16 v[86:89], v[176:179], v[208:211], v[86:89]
	v_mfma_f32_16x16x32_bf16 v[82:85], v[184:187], v[208:211], v[82:85]
	v_mfma_f32_16x16x32_bf16 v[66:69], v[184:187], v[216:219], v[66:69]
	v_mfma_f32_16x16x32_bf16 v[70:73], v[176:179], v[216:219], v[70:73]
	s_barrier
	s_add_i32 s73, s66, s52
	v_lshl_add_u64 v[220:221], s[42:43], 0, v[132:133]
	s_mov_b32 m0, s73
	ds_read_b128 v[188:191], v155 offset:16384
	ds_read_b128 v[192:195], v155 offset:17408
	ds_read_b128 v[196:199], v155 offset:18432
	ds_read_b128 v[200:203], v155 offset:19456
	ds_read_b128 v[204:207], v155 offset:20480
	ds_read_b128 v[208:211], v155 offset:21504
	ds_read_b128 v[212:215], v155 offset:22528
	ds_read_b128 v[216:219], v155 offset:23552
	global_load_lds_dwordx4 v[220:221], off
	s_add_i32 m0, s73, 0x2000
	s_add_u32 s74, s42, 0xb0000
	v_lshl_add_u64 v[222:223], s[42:43], 0, v[136:137]
	s_addc_u32 s75, s43, 0
	s_add_i32 s73, s67, s52
	global_load_lds_dwordx4 v[222:223], off
	v_lshl_add_u64 v[224:225], s[74:75], 0, v[132:133]
	s_mov_b32 m0, s73
	v_lshl_add_u64 v[226:227], s[44:45], 0, v[134:135]
	global_load_lds_dwordx4 v[224:225], off
	v_lshl_add_u64 v[224:225], s[74:75], 0, v[136:137]
	s_add_i32 m0, s73, 0x2000
	s_nop 0
	global_load_lds_dwordx4 v[224:225], off
	v_lshl_add_u64 v[224:225], s[44:45], 0, v[130:131]
	s_mov_b32 m0, s53
	s_nop 0
	global_load_lds_dwordx4 v[224:225], off
	s_mov_b32 m0, s54
	s_nop 0
	global_load_lds_dwordx4 v[226:227], off
	s_waitcnt vmcnt(8)
	s_waitcnt lgkmcnt(0)
	s_barrier
; #define PG8_STAGEA(bufoff, gbase) PG8_STAGE_(bufoff, gbase, voffA)
; #define PG8_LDA(dst, b, h) do { _Pragma("unroll") for (int m = 0; m < 4; ++m) _Pragma("unroll") for (int k = 0; k < 2; ++k) dst[m][k] = *(const LAS bf16x8*)(lds + PG8_SA(b, h) + aoff + m * 2048 + k * 1024); } while (0)
; #define PG8_LDB(dst, b, h) do { _Pragma("unroll") for (int n = 0; n < 2; ++n) _Pragma("unroll") for (int k = 0; k < 2; ++k) dst[n][k] = *(const LAS bf16x8*)(lds + PG8_SB(b, h) + boff + n * 2048 + k * 1024); } while (0)
; #define PG8_MMA(ai, bj, At, Bt_) do { __builtin_amdgcn_s_setprio(1); _Pragma("unroll") for (int m = 0; m < 4; ++m) _Pragma("unroll") for (int n = 0; n < 2; ++n) _Pragma("unroll") for (int k = 0; k < 2; ++k) \
;         acc[ai][bj][m][n] = __builtin_amdgcn_mfma_f32_16x16x32_bf16(Bt_[n][k], At[m][k], acc[ai][bj][m][n], 0, 0, 0); __builtin_amdgcn_s_setprio(0); } while (0)
; #define PG8_WAIT_V(n) asm volatile("s_waitcnt vmcnt(" #n ")" ::: "memory")
; #define PG8_WAIT_L(n) asm volatile("s_waitcnt lgkmcnt(" #n ")" ::: "memory")
; #define PG8_BAR __builtin_amdgcn_s_barrier()
; #define PG8_SCHED __builtin_amdgcn_sched_barrier(0)
; template <int EK, int SK = -1>
; __device__ __forceinline__ void gemm_phase(LAS unsigned char* lds, const bf16_t* A, const bf16_t* Bt, int nM, int N, int K, const EpiArgs& E) {
;     ...
;             PG8_WAIT_V(8); PG8_WAIT_L(0); PG8_BAR; PG8_MMA(1, 0, At, B0); PG8_MMA(1, 1, At, B1); PG8_BAR; PG8_SCHED;
;             PG8_LDB(B0, 1, 0); PG8_LDB(B1, 1, 1); PG8_SCHED; PG8_LDA(At, 1, 0); PG8_STAGEA(PG8_SA(0, 1), a2 + hstep);
;             PG8_WAIT_V(8); PG8_WAIT_L(0); PG8_BAR; PG8_MMA(0, 0, At, B0); PG8_MMA(0, 1, At, B1); PG8_BAR; PG8_SCHED;
	s_waitcnt lgkmcnt(0)
	v_mfma_f32_16x16x32_bf16 v[62:65], v[156:159], v[188:191], v[62:65]
	v_mfma_f32_16x16x32_bf16 v[58:61], v[164:167], v[188:191], v[58:61]
	v_mfma_f32_16x16x32_bf16 v[42:45], v[164:167], v[196:199], v[42:45]
	v_mfma_f32_16x16x32_bf16 v[46:49], v[156:159], v[196:199], v[46:49]
	v_mfma_f32_16x16x32_bf16 v[30:33], v[156:159], v[204:207], v[30:33]
	v_mfma_f32_16x16x32_bf16 v[26:29], v[164:167], v[204:207], v[26:29]
	v_mfma_f32_16x16x32_bf16 v[10:13], v[164:167], v[212:215], v[10:13]
	v_mfma_f32_16x16x32_bf16 v[14:17], v[156:159], v[212:215], v[14:17]
	v_mfma_f32_16x16x32_bf16 v[62:65], v[160:163], v[192:195], v[62:65]
	v_mfma_f32_16x16x32_bf16 v[58:61], v[168:171], v[192:195], v[58:61]
	v_mfma_f32_16x16x32_bf16 v[42:45], v[168:171], v[200:203], v[42:45]
	v_mfma_f32_16x16x32_bf16 v[46:49], v[160:163], v[200:203], v[46:49]
	v_mfma_f32_16x16x32_bf16 v[30:33], v[160:163], v[208:211], v[30:33]
	v_mfma_f32_16x16x32_bf16 v[26:29], v[168:171], v[208:211], v[26:29]
	v_mfma_f32_16x16x32_bf16 v[10:13], v[168:171], v[216:219], v[10:13]
	v_mfma_f32_16x16x32_bf16 v[14:17], v[160:163], v[216:219], v[14:17]
	v_mfma_f32_16x16x32_bf16 v[54:57], v[172:175], v[188:191], v[54:57]
	v_mfma_f32_16x16x32_bf16 v[50:53], v[180:183], v[188:191], v[50:53]
	v_mfma_f32_16x16x32_bf16 v[34:37], v[180:183], v[196:199], v[34:37]
	v_mfma_f32_16x16x32_bf16 v[38:41], v[172:175], v[196:199], v[38:41]
	v_mfma_f32_16x16x32_bf16 v[22:25], v[172:175], v[204:207], v[22:25]
	v_mfma_f32_16x16x32_bf16 v[18:21], v[180:183], v[204:207], v[18:21]
	v_mfma_f32_16x16x32_bf16 v[2:5], v[180:183], v[212:215], v[2:5]
	v_mfma_f32_16x16x32_bf16 v[6:9], v[172:175], v[212:215], v[6:9]
	v_mfma_f32_16x16x32_bf16 v[54:57], v[176:179], v[192:195], v[54:57]
	v_mfma_f32_16x16x32_bf16 v[50:53], v[184:187], v[192:195], v[50:53]
	v_mfma_f32_16x16x32_bf16 v[34:37], v[184:187], v[200:203], v[34:37]
	v_mfma_f32_16x16x32_bf16 v[38:41], v[176:179], v[200:203], v[38:41]
	v_mfma_f32_16x16x32_bf16 v[22:25], v[176:179], v[208:211], v[22:25]
	v_mfma_f32_16x16x32_bf16 v[18:21], v[184:187], v[208:211], v[18:21]
	v_mfma_f32_16x16x32_bf16 v[2:5], v[184:187], v[216:219], v[2:5]
	v_mfma_f32_16x16x32_bf16 v[6:9], v[176:179], v[216:219], v[6:9]
	s_barrier
	s_add_i32 s73, 0, 0x18000
	s_add_i32 s74, 0, 0x1c000
	v_add_u32_e32 v168, s73, v154
	v_add_u32_e32 v184, s74, v154
	ds_read_b128 v[156:159], v168
	ds_read_b128 v[160:163], v168 offset:1024
	ds_read_b128 v[164:167], v168 offset:2048
	ds_read_b128 v[168:171], v168 offset:3072
	ds_read_b128 v[172:175], v184
	ds_read_b128 v[176:179], v184 offset:1024
	ds_read_b128 v[180:183], v184 offset:2048
	ds_read_b128 v[184:187], v184 offset:3072
	s_add_u32 s44, s44, 0xb0000
	s_addc_u32 s45, s45, 0
	s_mov_b32 m0, s55
	v_lshl_add_u64 v[228:229], s[44:45], 0, v[130:131]
	ds_read_b128 v[188:191], v155 offset:32768
	ds_read_b128 v[192:195], v155 offset:33792
	ds_read_b128 v[196:199], v155 offset:34816
	ds_read_b128 v[200:203], v155 offset:35840
	ds_read_b128 v[204:207], v155 offset:36864
	ds_read_b128 v[208:211], v155 offset:37888
	ds_read_b128 v[212:215], v155 offset:38912
	ds_read_b128 v[216:219], v155 offset:39936
	global_load_lds_dwordx4 v[228:229], off
	v_lshl_add_u64 v[228:229], s[44:45], 0, v[134:135]
	s_mov_b32 m0, s56
	s_nop 0
	global_load_lds_dwordx4 v[228:229], off
	s_waitcnt vmcnt(8)
	s_waitcnt lgkmcnt(0)
	s_barrier
	s_waitcnt lgkmcnt(0)
	v_mfma_f32_16x16x32_bf16 v[126:129], v[156:159], v[188:191], v[126:129]
	v_mfma_f32_16x16x32_bf16 v[122:125], v[164:167], v[188:191], v[122:125]
	v_mfma_f32_16x16x32_bf16 v[106:109], v[164:167], v[196:199], v[106:109]
	v_mfma_f32_16x16x32_bf16 v[110:113], v[156:159], v[196:199], v[110:113]
	v_mfma_f32_16x16x32_bf16 v[94:97], v[156:159], v[204:207], v[94:97]
	v_mfma_f32_16x16x32_bf16 v[90:93], v[164:167], v[204:207], v[90:93]
	v_mfma_f32_16x16x32_bf16 v[74:77], v[164:167], v[212:215], v[74:77]
	v_mfma_f32_16x16x32_bf16 v[78:81], v[156:159], v[212:215], v[78:81]
	v_mfma_f32_16x16x32_bf16 v[126:129], v[160:163], v[192:195], v[126:129]
	v_mfma_f32_16x16x32_bf16 v[122:125], v[168:171], v[192:195], v[122:125]
	v_mfma_f32_16x16x32_bf16 v[106:109], v[168:171], v[200:203], v[106:109]
	v_mfma_f32_16x16x32_bf16 v[110:113], v[160:163], v[200:203], v[110:113]
	v_mfma_f32_16x16x32_bf16 v[94:97], v[160:163], v[208:211], v[94:97]
	v_mfma_f32_16x16x32_bf16 v[90:93], v[168:171], v[208:211], v[90:93]
	v_mfma_f32_16x16x32_bf16 v[74:77], v[168:171], v[216:219], v[74:77]
	v_mfma_f32_16x16x32_bf16 v[78:81], v[160:163], v[216:219], v[78:81]
	v_mfma_f32_16x16x32_bf16 v[118:121], v[172:175], v[188:191], v[118:121]
	v_mfma_f32_16x16x32_bf16 v[114:117], v[180:183], v[188:191], v[114:117]
	v_mfma_f32_16x16x32_bf16 v[98:101], v[180:183], v[196:199], v[98:101]
	v_mfma_f32_16x16x32_bf16 v[102:105], v[172:175], v[196:199], v[102:105]
	v_mfma_f32_16x16x32_bf16 v[86:89], v[172:175], v[204:207], v[86:89]
	v_mfma_f32_16x16x32_bf16 v[82:85], v[180:183], v[204:207], v[82:85]
	v_mfma_f32_16x16x32_bf16 v[66:69], v[180:183], v[212:215], v[66:69]
	v_mfma_f32_16x16x32_bf16 v[70:73], v[172:175], v[212:215], v[70:73]
	v_mfma_f32_16x16x32_bf16 v[118:121], v[176:179], v[192:195], v[118:121]
	v_mfma_f32_16x16x32_bf16 v[114:117], v[184:187], v[192:195], v[114:117]
	v_mfma_f32_16x16x32_bf16 v[98:101], v[184:187], v[200:203], v[98:101]
	v_mfma_f32_16x16x32_bf16 v[102:105], v[176:179], v[200:203], v[102:105]
	v_mfma_f32_16x16x32_bf16 v[86:89], v[176:179], v[208:211], v[86:89]
	v_mfma_f32_16x16x32_bf16 v[82:85], v[184:187], v[208:211], v[82:85]
	v_mfma_f32_16x16x32_bf16 v[66:69], v[184:187], v[216:219], v[66:69]
	v_mfma_f32_16x16x32_bf16 v[70:73], v[176:179], v[216:219], v[70:73]
	s_barrier
; #define PG8_STAGEA(bufoff, gbase) PG8_STAGE_(bufoff, gbase, voffA)
; #define PG8_STAGEB(bufoff, gbase) PG8_STAGE_(bufoff, gbase, voffB)
; #define PG8_LDA(dst, b, h) do { _Pragma("unroll") for (int m = 0; m < 4; ++m) _Pragma("unroll") for (int k = 0; k < 2; ++k) dst[m][k] = *(const LAS bf16x8*)(lds + PG8_SA(b, h) + aoff + m * 2048 + k * 1024); } while (0)
; #define PG8_MMA(ai, bj, At, Bt_) do { __builtin_amdgcn_s_setprio(1); _Pragma("unroll") for (int m = 0; m < 4; ++m) _Pragma("unroll") for (int n = 0; n < 2; ++n) _Pragma("unroll") for (int k = 0; k < 2; ++k) \
;         acc[ai][bj][m][n] = __builtin_amdgcn_mfma_f32_16x16x32_bf16(Bt_[n][k], At[m][k], acc[ai][bj][m][n], 0, 0, 0); __builtin_amdgcn_s_setprio(0); } while (0)
; #define PG8_WAIT_V(n) asm volatile("s_waitcnt vmcnt(" #n ")" ::: "memory")
; #define PG8_WAIT_L(n) asm volatile("s_waitcnt lgkmcnt(" #n ")" ::: "memory")
; #define PG8_BAR __builtin_amdgcn_s_barrier()
; #define PG8_SCHED __builtin_amdgcn_sched_barrier(0)
; template <int EK, int SK = -1>
; __device__ __forceinline__ void gemm_phase(LAS unsigned char* lds, const bf16_t* A, const bf16_t* Bt, int nM, int N, int K, const EpiArgs& E) {
;     ...
;             PG8_LDA(At, 1, 1); PG8_STAGEB(PG8_SB(1, 0), b3); PG8_STAGEB(PG8_SB(1, 1), b3 + hstep); PG8_STAGEA(PG8_SA(1, 0), a3);
;             PG8_WAIT_V(8); PG8_WAIT_L(0); PG8_BAR; PG8_MMA(1, 0, At, B0); PG8_MMA(1, 1, At, B1); PG8_BAR; PG8_SCHED;
;         }
;         if (wr == 0) PG8_BAR;
	s_add_i32 s44, s73, s52
	v_lshl_add_u64 v[220:221], v[220:221], 0, s[22:23]
	s_mov_b32 m0, s44
	ds_read_b128 v[188:191], v155 offset:49152
	ds_read_b128 v[192:195], v155 offset:50176
	ds_read_b128 v[196:199], v155 offset:51200
	ds_read_b128 v[200:203], v155 offset:52224
	ds_read_b128 v[204:207], v155 offset:53248
	ds_read_b128 v[208:211], v155 offset:54272
	ds_read_b128 v[212:215], v155 offset:55296
	ds_read_b128 v[216:219], v155 offset:56320
	global_load_lds_dwordx4 v[220:221], off
	s_add_i32 m0, s44, 0x2000
	s_add_u32 s42, s42, 0xb0080
	v_lshl_add_u64 v[220:221], v[222:223], 0, s[22:23]
	s_addc_u32 s43, s43, 0
	s_add_i32 s44, s74, s52
	global_load_lds_dwordx4 v[220:221], off
	v_lshl_add_u64 v[220:221], s[42:43], 0, v[132:133]
	s_mov_b32 m0, s44
	s_nop 0
	global_load_lds_dwordx4 v[220:221], off
	v_lshl_add_u64 v[220:221], s[42:43], 0, v[136:137]
	s_add_i32 m0, s44, 0x2000
	s_nop 0
	global_load_lds_dwordx4 v[220:221], off
	v_lshl_add_u64 v[220:221], v[224:225], 0, s[22:23]
	s_mov_b32 m0, s58
	s_nop 0
	global_load_lds_dwordx4 v[220:221], off
	v_lshl_add_u64 v[220:221], v[226:227], 0, s[22:23]
	s_mov_b32 m0, s59
	s_nop 0
	global_load_lds_dwordx4 v[220:221], off
	s_waitcnt vmcnt(8)
	s_waitcnt lgkmcnt(0)
	s_barrier
	s_waitcnt lgkmcnt(0)
	v_mfma_f32_16x16x32_bf16 v[62:65], v[156:159], v[188:191], v[62:65]
	v_mfma_f32_16x16x32_bf16 v[58:61], v[164:167], v[188:191], v[58:61]
	v_mfma_f32_16x16x32_bf16 v[42:45], v[164:167], v[196:199], v[42:45]
	v_mfma_f32_16x16x32_bf16 v[46:49], v[156:159], v[196:199], v[46:49]
	v_mfma_f32_16x16x32_bf16 v[30:33], v[156:159], v[204:207], v[30:33]
	v_mfma_f32_16x16x32_bf16 v[26:29], v[164:167], v[204:207], v[26:29]
	v_mfma_f32_16x16x32_bf16 v[10:13], v[164:167], v[212:215], v[10:13]
	v_mfma_f32_16x16x32_bf16 v[14:17], v[156:159], v[212:215], v[14:17]
	v_mfma_f32_16x16x32_bf16 v[62:65], v[160:163], v[192:195], v[62:65]
	v_mfma_f32_16x16x32_bf16 v[58:61], v[168:171], v[192:195], v[58:61]
	v_mfma_f32_16x16x32_bf16 v[42:45], v[168:171], v[200:203], v[42:45]
	v_mfma_f32_16x16x32_bf16 v[46:49], v[160:163], v[200:203], v[46:49]
	v_mfma_f32_16x16x32_bf16 v[30:33], v[160:163], v[208:211], v[30:33]
	v_mfma_f32_16x16x32_bf16 v[26:29], v[168:171], v[208:211], v[26:29]
	v_mfma_f32_16x16x32_bf16 v[10:13], v[168:171], v[216:219], v[10:13]
	v_mfma_f32_16x16x32_bf16 v[14:17], v[160:163], v[216:219], v[14:17]
	v_mfma_f32_16x16x32_bf16 v[54:57], v[172:175], v[188:191], v[54:57]
	v_mfma_f32_16x16x32_bf16 v[50:53], v[180:183], v[188:191], v[50:53]
	v_mfma_f32_16x16x32_bf16 v[34:37], v[180:183], v[196:199], v[34:37]
	v_mfma_f32_16x16x32_bf16 v[38:41], v[172:175], v[196:199], v[38:41]
	v_mfma_f32_16x16x32_bf16 v[22:25], v[172:175], v[204:207], v[22:25]
	v_mfma_f32_16x16x32_bf16 v[18:21], v[180:183], v[204:207], v[18:21]
	v_mfma_f32_16x16x32_bf16 v[2:5], v[180:183], v[212:215], v[2:5]
	v_mfma_f32_16x16x32_bf16 v[6:9], v[172:175], v[212:215], v[6:9]
	v_mfma_f32_16x16x32_bf16 v[54:57], v[176:179], v[192:195], v[54:57]
	v_mfma_f32_16x16x32_bf16 v[50:53], v[184:187], v[192:195], v[50:53]
	v_mfma_f32_16x16x32_bf16 v[34:37], v[184:187], v[200:203], v[34:37]
	v_mfma_f32_16x16x32_bf16 v[38:41], v[176:179], v[200:203], v[38:41]
	v_mfma_f32_16x16x32_bf16 v[22:25], v[176:179], v[208:211], v[22:25]
	v_mfma_f32_16x16x32_bf16 v[18:21], v[184:187], v[208:211], v[18:21]
	v_mfma_f32_16x16x32_bf16 v[2:5], v[184:187], v[216:219], v[2:5]
	v_mfma_f32_16x16x32_bf16 v[6:9], v[176:179], v[216:219], v[6:9]
	s_barrier
	s_add_i32 s72, s72, 2
	s_add_u32 s40, s40, 0x100
	s_addc_u32 s41, s41, 0
	s_cmp_gt_u32 s72, 41
	s_cbranch_scc0 .LBB0_1401
	s_and_b64 vcc, exec, s[26:27]
	s_cbranch_vccz .LBB0_1404
	s_barrier
